# v43: v33 + 506 flat_load converted to global_load where the next wait is a full vmcnt(0) lgkmcnt(0) drain
# baseline (speedup 1.0000x reference)
; __device__ __forceinline__ float sumsq4(f32x4 x) { return (x[0] * x[0] + x[1] * x[1]) + (x[2] * x[2] + x[3] * x[3]); }
;     __device__ __forceinline__ void fused(AccT& acc, const Unit& u, int wr, int wc, int fr, int fq, LAS unsigned char* lx, int tid) const {
;     ...
;                 const int row = EPI_ROW(u, ai, m); float s1 = 0.f, s2 = 0.f;
; #pragma unroll
;                 for (int bj = 0; bj < 2; ++bj) {
;                     const half8 rv = *(const half8*)(res + (size_t)row * DM + EPI_COL(u, bj));
; #pragma unroll
;                     for (int e = 0; e < 4; ++e) { acc[ai][bj][m][0][e] += ALPHA * (float)rv[e]; acc[ai][bj][m][1][e] += ALPHA * (float)rv[4 + e]; }
;                     const f32x4 a0 = acc[ai][bj][m][0], a1 = acc[ai][bj][m][1];
;                     s1 += ((a0[0] + a0[1]) + (a0[2] + a0[3])) + ((a1[0] + a1[1]) + (a1[2] + a1[3])); s2 += sumsq4(a0) + sumsq4(a1);
;                 }
;                 s1 += __shfl_xor(s1, 16); s1 += __shfl_xor(s1, 32); s2 += __shfl_xor(s2, 16); s2 += __shfl_xor(s2, 32);
;                 if (fq == 0) P[(ai * 128 + wr * 64 + m * 16 + fr) * 4 + wc] = (f32x2){s1, s2};
.LBB0_86:
	v_mov_b32_e32 v239, v216
	s_lshl_b32 s10, s61, 8
	v_ashrrev_i32_e32 v140, 2, v239
	v_and_b32_e32 v238, 0xffffffc0, v140
	v_bfe_u32 v141, v239, 6, 2
	v_and_b32_e32 v229, 15, v239
	v_bfe_u32 v142, v239, 4, 2
	v_add_u32_e32 v140, s10, v238
	v_or_b32_e32 v158, v140, v229
	s_lshl_b32 s0, s16, 8
	v_lshlrev_b32_e32 v140, 5, v141
	v_lshlrev_b32_e32 v143, 3, v142
	v_and_b32_e32 v144, 64, v237
	v_or3_b32 v140, v140, s0, v143
	v_xor_b32_e32 v143, 16, v237
	v_add_u32_e32 v144, 64, v144
	v_cmp_lt_i32_e32 vcc, v143, v144
	v_readlane_b32 s0, v253, 5
	v_ashrrev_i32_e32 v159, 31, v158
	v_cndmask_b32_e32 v143, v237, v143, vcc
	v_lshlrev_b32_e32 v241, 2, v143
	v_xor_b32_e32 v143, 32, v237
	v_cmp_lt_i32_e32 vcc, v143, v144
	v_lshl_add_u32 v154, v141, 3, s0
	v_readlane_b32 s0, v255, 2
	v_cndmask_b32_e32 v143, v237, v143, vcc
	v_lshlrev_b32_e32 v240, 2, v143
	v_cmp_eq_u32_e32 vcc, 0, v142
	v_lshlrev_b64 v[142:143], 11, v[158:159]
	v_readlane_b32 s1, v255, 3
	v_ashrrev_i32_e32 v141, 31, v140
	v_mov_b32_e32 v166, v118
	v_lshl_add_u64 v[144:145], s[0:1], 0, v[142:143]
	v_lshl_add_u64 v[144:145], v[140:141], 1, v[144:145]
	global_load_dwordx4 v[148:151], v[144:145], off
	global_load_dwordx4 v[162:165], v[144:145], off offset:256
	s_mov_b32 s0, 0x3fd744fd
	v_pk_mov_b32 v[118:119], v[118:119], v[116:117] op_sel:[1,0]
	v_mov_b32_e32 v167, v116
	v_mov_b32_e32 v116, v120
	v_or_b32_e32 v155, v238, v229
	s_waitcnt vmcnt(0) lgkmcnt(0)
	v_cvt_f32_f16_sdwa v156, v148 dst_sel:DWORD dst_unused:UNUSED_PAD src0_sel:WORD_1
	v_cvt_f32_f16_e32 v144, v164
	v_cvt_f32_f16_sdwa v145, v164 dst_sel:DWORD dst_unused:UNUSED_PAD src0_sel:WORD_1
	v_cvt_f32_f16_sdwa v164, v150 dst_sel:DWORD dst_unused:UNUSED_PAD src0_sel:WORD_1
	v_pk_fma_f32 v[126:127], v[144:145], s[0:1], v[126:127] op_sel_hi:[1,0,1]
	v_cvt_f32_f16_e32 v144, v165
	v_cvt_f32_f16_sdwa v145, v165 dst_sel:DWORD dst_unused:UNUSED_PAD src0_sel:WORD_1
	v_mov_b32_e32 v146, v127
	v_pk_fma_f32 v[128:129], v[144:145], s[0:1], v[128:129] op_sel_hi:[1,0,1]
	s_nop 0
	v_mov_b32_e32 v147, v129
	v_mov_b32_e32 v144, v126
	v_mov_b32_e32 v145, v128
	v_pk_mul_f32 v[146:147], v[146:147], v[146:147]
	s_nop 0
	v_pk_fma_f32 v[144:145], v[144:145], v[144:145], v[146:147]
	v_mov_b32_e32 v146, v122
	v_pk_add_f32 v[152:153], v[144:145], v[144:145] op_sel_hi:[0,1]
	v_cvt_f32_f16_e32 v145, v162
	v_cvt_f32_f16_e32 v144, v148
	v_mov_b32_e32 v147, v114
	v_pk_mov_b32 v[122:123], v[122:123], v[114:115] op_sel:[1,0]
	v_mov_b32_e32 v157, v145
	v_pk_fma_f32 v[144:145], v[144:145], s[0:1], v[146:147] op_sel_hi:[1,0,1]
	v_cvt_f32_f16_e32 v147, v163
	v_pk_fma_f32 v[122:123], v[156:157], s[0:1], v[122:123] op_sel_hi:[1,0,1]
	v_cvt_f32_f16_e32 v156, v149
	v_cvt_f32_f16_sdwa v157, v162 dst_sel:DWORD dst_unused:UNUSED_PAD src0_sel:WORD_1
	v_mov_b32_e32 v165, v147
	v_mov_b32_e32 v114, v124
	v_pk_fma_f32 v[118:119], v[164:165], s[0:1], v[118:119] op_sel_hi:[1,0,1]
	v_cvt_f32_f16_sdwa v164, v149 dst_sel:DWORD dst_unused:UNUSED_PAD src0_sel:WORD_1
	v_mov_b32_e32 v165, v157
	v_pk_fma_f32 v[148:149], v[156:157], s[0:1], v[114:115] op_sel_hi:[1,0,1]
	v_cvt_f32_f16_e32 v156, v151
	v_cvt_f32_f16_sdwa v157, v163 dst_sel:DWORD dst_unused:UNUSED_PAD src0_sel:WORD_1
	v_cvt_f32_f16_e32 v146, v150
	v_cvt_f32_f16_sdwa v162, v151 dst_sel:DWORD dst_unused:UNUSED_PAD src0_sel:WORD_1
	v_mov_b32_e32 v114, v125
	v_mov_b32_e32 v163, v157
	v_pk_fma_f32 v[150:151], v[156:157], s[0:1], v[116:117] op_sel_hi:[1,0,1]
	v_pk_fma_f32 v[114:115], v[164:165], s[0:1], v[114:115] op_sel_hi:[1,0,1]
	v_mov_b32_e32 v116, v121
	v_pk_mul_f32 v[120:121], v[144:145], v[144:145]
	v_pk_mul_f32 v[124:125], v[122:123], v[122:123]
	v_pk_fma_f32 v[146:147], v[146:147], s[0:1], v[166:167] op_sel_hi:[1,0,1]
	v_pk_fma_f32 v[116:117], v[162:163], s[0:1], v[116:117] op_sel_hi:[1,0,1]
	v_pk_mul_f32 v[156:157], v[148:149], v[148:149]
	v_pk_mul_f32 v[162:163], v[114:115], v[114:115]
	v_pk_mov_b32 v[120:121], v[144:145], v[120:121] op_sel:[1,0]
	v_pk_mov_b32 v[124:125], v[148:149], v[124:125] op_sel:[1,0]
	v_pk_mul_f32 v[164:165], v[146:147], v[146:147]
	v_pk_add_f32 v[120:121], v[120:121], v[124:125]
	v_pk_mov_b32 v[124:125], v[146:147], v[156:157] op_sel:[1,0]
	v_pk_mov_b32 v[156:157], v[150:151], v[162:163] op_sel:[1,0]
	v_pk_mul_f32 v[166:167], v[118:119], v[118:119]
	v_pk_add_f32 v[124:125], v[124:125], v[156:157]
	v_pk_mul_f32 v[168:169], v[150:151], v[150:151]
	v_pk_mul_f32 v[170:171], v[116:117], v[116:117]
	v_pk_add_f32 v[120:121], v[120:121], v[124:125]
	v_mov_b32_e32 v124, v126
	v_mov_b32_e32 v125, v164
	v_pk_mov_b32 v[156:157], v[126:127], v[166:167] op_sel:[1,0]
	v_pk_mov_b32 v[162:163], v[128:129], v[170:171] op_sel:[1,0]
	v_pk_add_f32 v[124:125], v[124:125], v[156:157]
	v_mov_b32_e32 v156, v128
	v_mov_b32_e32 v157, v168
	v_pk_add_f32 v[156:157], v[156:157], v[162:163]
	v_pk_mul_f32 v[162:163], v[148:149], v[114:115]
	v_pk_add_f32 v[124:125], v[124:125], v[156:157]
	v_pk_mul_f32 v[156:157], v[144:145], v[122:123]
	v_pk_add_f32 v[120:121], v[120:121], v[124:125]
	v_pk_add_f32 v[124:125], v[144:145], v[122:123]
	v_pk_mul_f32 v[164:165], v[150:151], v[116:117]
	v_mov_b32_e32 v125, v157
	v_pk_add_f32 v[156:157], v[148:149], v[114:115]
	v_mov_b32_e32 v152, v1
	v_mov_b32_e32 v157, v163
	v_pk_add_f32 v[124:125], v[124:125], v[156:157]
	v_pk_add_f32 v[156:157], v[146:147], v[118:119]
	v_pk_mul_f32 v[162:163], v[146:147], v[118:119]
	v_lshl_add_u32 v115, v155, 5, v154
	v_mov_b32_e32 v157, v163
	v_pk_add_f32 v[162:163], v[150:151], v[116:117]
	s_nop 0
	v_mov_b32_e32 v163, v165
	v_pk_add_f32 v[156:157], v[156:157], v[162:163]
	s_nop 0
	v_pk_add_f32 v[124:125], v[124:125], v[156:157]
	s_nop 0
	v_pk_add_f32 v[124:125], v[124:125], v[152:153]
	s_nop 0
	v_pk_add_f32 v[120:121], v[120:121], v[124:125]
	ds_bpermute_b32 v124, v241, v120
	ds_bpermute_b32 v125, v241, v121
	s_waitcnt lgkmcnt(0)
	v_pk_add_f32 v[120:121], v[120:121], v[124:125]
	ds_bpermute_b32 v124, v240, v120
	ds_bpermute_b32 v125, v240, v121
	s_and_saveexec_b64 s[0:1], vcc
	s_cbranch_execz .LBB0_88
	s_waitcnt lgkmcnt(0)
	v_pk_add_f32 v[120:121], v[120:121], v[124:125]
	ds_write_b64 v115, v[120:121]
; __device__ __forceinline__ float sumsq4(f32x4 x) { return (x[0] * x[0] + x[1] * x[1]) + (x[2] * x[2] + x[3] * x[3]); }
;     __device__ __forceinline__ void fused(AccT& acc, const Unit& u, int wr, int wc, int fr, int fq, LAS unsigned char* lx, int tid) const {
;     ...
;                 const int row = EPI_ROW(u, ai, m); float s1 = 0.f, s2 = 0.f;
; #pragma unroll
;                 for (int bj = 0; bj < 2; ++bj) {
;                     const half8 rv = *(const half8*)(res + (size_t)row * DM + EPI_COL(u, bj));
; #pragma unroll
;                     for (int e = 0; e < 4; ++e) { acc[ai][bj][m][0][e] += ALPHA * (float)rv[e]; acc[ai][bj][m][1][e] += ALPHA * (float)rv[4 + e]; }
;                     const f32x4 a0 = acc[ai][bj][m][0], a1 = acc[ai][bj][m][1];
;                     s1 += ((a0[0] + a0[1]) + (a0[2] + a0[3])) + ((a1[0] + a1[1]) + (a1[2] + a1[3])); s2 += sumsq4(a0) + sumsq4(a1);
;                 }
;                 s1 += __shfl_xor(s1, 16); s1 += __shfl_xor(s1, 32); s2 += __shfl_xor(s2, 16); s2 += __shfl_xor(s2, 32);
;                 if (fq == 0) P[(ai * 128 + wr * 64 + m * 16 + fr) * 4 + wc] = (f32x2){s1, s2};
.LBB0_88:
	s_or_b64 exec, exec, s[0:1]
	v_or_b32_e32 v120, 16, v158
	v_ashrrev_i32_e32 v121, 31, v120
	v_readlane_b32 s0, v255, 2
	v_lshlrev_b64 v[120:121], 11, v[120:121]
	v_readlane_b32 s1, v255, 3
	v_mov_b32_e32 v170, v102
	v_pk_mov_b32 v[102:103], v[102:103], v[100:101] op_sel:[1,0]
	s_waitcnt lgkmcnt(0)
	v_lshl_add_u64 v[124:125], s[0:1], 0, v[120:121]
	v_lshl_add_u64 v[124:125], v[140:141], 1, v[124:125]
	global_load_dwordx4 v[154:157], v[124:125], off
	global_load_dwordx4 v[164:167], v[124:125], off offset:256
	s_mov_b32 s0, 0x3fd744fd
	v_mov_b32_e32 v171, v100
	v_mov_b32_e32 v100, v104
	s_waitcnt vmcnt(0) lgkmcnt(0)
	v_cvt_f32_f16_sdwa v168, v156 dst_sel:DWORD dst_unused:UNUSED_PAD src0_sel:WORD_1
	v_cvt_f32_f16_e32 v124, v166
	v_cvt_f32_f16_sdwa v125, v166 dst_sel:DWORD dst_unused:UNUSED_PAD src0_sel:WORD_1
	v_cvt_f32_f16_sdwa v166, v154 dst_sel:DWORD dst_unused:UNUSED_PAD src0_sel:WORD_1
	v_pk_fma_f32 v[110:111], v[124:125], s[0:1], v[110:111] op_sel_hi:[1,0,1]
	v_cvt_f32_f16_e32 v124, v167
	v_cvt_f32_f16_sdwa v125, v167 dst_sel:DWORD dst_unused:UNUSED_PAD src0_sel:WORD_1
	v_mov_b32_e32 v152, v111
	v_pk_fma_f32 v[112:113], v[124:125], s[0:1], v[112:113] op_sel_hi:[1,0,1]
	s_nop 0
	v_mov_b32_e32 v153, v113
	v_mov_b32_e32 v124, v110
	v_mov_b32_e32 v125, v112
	v_pk_mul_f32 v[152:153], v[152:153], v[152:153]
	s_nop 0
	v_pk_fma_f32 v[124:125], v[124:125], v[124:125], v[152:153]
	v_mov_b32_e32 v152, v106
	v_pk_add_f32 v[162:163], v[124:125], v[124:125] op_sel_hi:[0,1]
	v_cvt_f32_f16_e32 v125, v164
	v_cvt_f32_f16_e32 v124, v154
	v_mov_b32_e32 v153, v98
	v_pk_mov_b32 v[106:107], v[106:107], v[98:99] op_sel:[1,0]
	v_mov_b32_e32 v167, v125
	v_pk_fma_f32 v[124:125], v[124:125], s[0:1], v[152:153] op_sel_hi:[1,0,1]
	v_cvt_f32_f16_e32 v153, v165
	v_pk_fma_f32 v[106:107], v[166:167], s[0:1], v[106:107] op_sel_hi:[1,0,1]
	v_cvt_f32_f16_e32 v166, v155
	v_cvt_f32_f16_sdwa v167, v164 dst_sel:DWORD dst_unused:UNUSED_PAD src0_sel:WORD_1
	v_mov_b32_e32 v169, v153
	v_pk_fma_f32 v[102:103], v[168:169], s[0:1], v[102:103] op_sel_hi:[1,0,1]
	v_cvt_f32_f16_sdwa v168, v155 dst_sel:DWORD dst_unused:UNUSED_PAD src0_sel:WORD_1
	v_mov_b32_e32 v98, v108
	v_cvt_f32_f16_e32 v164, v157
	v_cvt_f32_f16_sdwa v165, v165 dst_sel:DWORD dst_unused:UNUSED_PAD src0_sel:WORD_1
	v_cvt_f32_f16_e32 v152, v156
	v_pk_fma_f32 v[154:155], v[166:167], s[0:1], v[98:99] op_sel_hi:[1,0,1]
	v_cvt_f32_f16_sdwa v166, v157 dst_sel:DWORD dst_unused:UNUSED_PAD src0_sel:WORD_1
	v_mov_b32_e32 v169, v167
	v_mov_b32_e32 v98, v109
	v_mov_b32_e32 v167, v165
	v_pk_fma_f32 v[156:157], v[164:165], s[0:1], v[100:101] op_sel_hi:[1,0,1]
	v_pk_fma_f32 v[98:99], v[168:169], s[0:1], v[98:99] op_sel_hi:[1,0,1]
	v_mov_b32_e32 v100, v105
	v_pk_mul_f32 v[104:105], v[124:125], v[124:125]
	v_pk_mul_f32 v[108:109], v[106:107], v[106:107]
	v_pk_fma_f32 v[152:153], v[152:153], s[0:1], v[170:171] op_sel_hi:[1,0,1]
	v_pk_fma_f32 v[100:101], v[166:167], s[0:1], v[100:101] op_sel_hi:[1,0,1]
	v_pk_mul_f32 v[164:165], v[154:155], v[154:155]
	v_pk_mul_f32 v[166:167], v[98:99], v[98:99]
	v_pk_mov_b32 v[104:105], v[124:125], v[104:105] op_sel:[1,0]
	v_pk_mov_b32 v[108:109], v[154:155], v[108:109] op_sel:[1,0]
	v_pk_mul_f32 v[168:169], v[152:153], v[152:153]
	v_pk_add_f32 v[104:105], v[104:105], v[108:109]
	v_pk_mov_b32 v[108:109], v[152:153], v[164:165] op_sel:[1,0]
	v_pk_mov_b32 v[164:165], v[156:157], v[166:167] op_sel:[1,0]
	v_pk_mul_f32 v[170:171], v[102:103], v[102:103]
	v_pk_add_f32 v[108:109], v[108:109], v[164:165]
	v_pk_mul_f32 v[172:173], v[156:157], v[156:157]
	v_pk_mul_f32 v[174:175], v[100:101], v[100:101]
	v_pk_add_f32 v[104:105], v[104:105], v[108:109]
	v_mov_b32_e32 v108, v110
	v_mov_b32_e32 v109, v168
	v_pk_mov_b32 v[164:165], v[110:111], v[170:171] op_sel:[1,0]
	v_pk_mov_b32 v[166:167], v[112:113], v[174:175] op_sel:[1,0]
	v_pk_add_f32 v[108:109], v[108:109], v[164:165]
	v_mov_b32_e32 v164, v112
	v_mov_b32_e32 v165, v172
	v_pk_add_f32 v[164:165], v[164:165], v[166:167]
	v_pk_mul_f32 v[166:167], v[154:155], v[98:99]
	v_pk_add_f32 v[108:109], v[108:109], v[164:165]
	v_pk_mul_f32 v[164:165], v[124:125], v[106:107]
	v_pk_add_f32 v[104:105], v[104:105], v[108:109]
	v_pk_add_f32 v[108:109], v[124:125], v[106:107]
	v_pk_mul_f32 v[168:169], v[156:157], v[100:101]
	v_mov_b32_e32 v109, v165
	v_pk_add_f32 v[164:165], v[154:155], v[98:99]
	v_mov_b32_e32 v162, v1
	v_mov_b32_e32 v165, v167
	v_pk_add_f32 v[108:109], v[108:109], v[164:165]
	v_pk_add_f32 v[164:165], v[152:153], v[102:103]
	v_pk_mul_f32 v[166:167], v[152:153], v[102:103]
	s_nop 0
	v_mov_b32_e32 v165, v167
	v_pk_add_f32 v[166:167], v[156:157], v[100:101]
	s_nop 0
	v_mov_b32_e32 v167, v169
	v_pk_add_f32 v[164:165], v[164:165], v[166:167]
	s_nop 0
	v_pk_add_f32 v[108:109], v[108:109], v[164:165]
	s_nop 0
	v_pk_add_f32 v[108:109], v[108:109], v[162:163]
	s_nop 0
	v_pk_add_f32 v[104:105], v[104:105], v[108:109]
	ds_bpermute_b32 v108, v241, v104
	ds_bpermute_b32 v109, v241, v105
	s_waitcnt lgkmcnt(0)
	v_pk_add_f32 v[104:105], v[104:105], v[108:109]
	ds_bpermute_b32 v108, v240, v104
	ds_bpermute_b32 v109, v240, v105
	s_and_saveexec_b64 s[0:1], vcc
	s_cbranch_execz .LBB0_90
	s_waitcnt lgkmcnt(0)
	v_pk_add_f32 v[104:105], v[104:105], v[108:109]
	ds_write_b64 v115, v[104:105] offset:512
; __device__ __forceinline__ float sumsq4(f32x4 x) { return (x[0] * x[0] + x[1] * x[1]) + (x[2] * x[2] + x[3] * x[3]); }
;     __device__ __forceinline__ void fused(AccT& acc, const Unit& u, int wr, int wc, int fr, int fq, LAS unsigned char* lx, int tid) const {
;     ...
;                 const int row = EPI_ROW(u, ai, m); float s1 = 0.f, s2 = 0.f;
; #pragma unroll
;                 for (int bj = 0; bj < 2; ++bj) {
;                     const half8 rv = *(const half8*)(res + (size_t)row * DM + EPI_COL(u, bj));
; #pragma unroll
;                     for (int e = 0; e < 4; ++e) { acc[ai][bj][m][0][e] += ALPHA * (float)rv[e]; acc[ai][bj][m][1][e] += ALPHA * (float)rv[4 + e]; }
;                     const f32x4 a0 = acc[ai][bj][m][0], a1 = acc[ai][bj][m][1];
;                     s1 += ((a0[0] + a0[1]) + (a0[2] + a0[3])) + ((a1[0] + a1[1]) + (a1[2] + a1[3])); s2 += sumsq4(a0) + sumsq4(a1);
;                 }
;                 s1 += __shfl_xor(s1, 16); s1 += __shfl_xor(s1, 32); s2 += __shfl_xor(s2, 16); s2 += __shfl_xor(s2, 32);
;                 if (fq == 0) P[(ai * 128 + wr * 64 + m * 16 + fr) * 4 + wc] = (f32x2){s1, s2};
.LBB0_90:
	s_or_b64 exec, exec, s[0:1]
	v_or_b32_e32 v104, 32, v158
	v_ashrrev_i32_e32 v105, 31, v104
	v_readlane_b32 s0, v255, 2
	v_lshlrev_b64 v[104:105], 11, v[104:105]
	v_readlane_b32 s1, v255, 3
	v_mov_b32_e32 v176, v86
	v_pk_mov_b32 v[86:87], v[86:87], v[84:85] op_sel:[1,0]
	s_waitcnt lgkmcnt(0)
	v_lshl_add_u64 v[108:109], s[0:1], 0, v[104:105]
	v_lshl_add_u64 v[108:109], v[140:141], 1, v[108:109]
	global_load_dwordx4 v[164:167], v[108:109], off
	global_load_dwordx4 v[170:173], v[108:109], off offset:256
	s_mov_b32 s0, 0x3fd744fd
	v_mov_b32_e32 v177, v84
	v_mov_b32_e32 v84, v88
	s_waitcnt vmcnt(0) lgkmcnt(0)
	v_cvt_f32_f16_sdwa v174, v166 dst_sel:DWORD dst_unused:UNUSED_PAD src0_sel:WORD_1
	v_cvt_f32_f16_e32 v108, v172
	v_cvt_f32_f16_sdwa v109, v172 dst_sel:DWORD dst_unused:UNUSED_PAD src0_sel:WORD_1
	v_cvt_f32_f16_sdwa v172, v164 dst_sel:DWORD dst_unused:UNUSED_PAD src0_sel:WORD_1
	v_pk_fma_f32 v[94:95], v[108:109], s[0:1], v[94:95] op_sel_hi:[1,0,1]
	v_cvt_f32_f16_e32 v108, v173
	v_cvt_f32_f16_sdwa v109, v173 dst_sel:DWORD dst_unused:UNUSED_PAD src0_sel:WORD_1
	v_mov_b32_e32 v162, v95
	v_pk_fma_f32 v[96:97], v[108:109], s[0:1], v[96:97] op_sel_hi:[1,0,1]
	s_nop 0
	v_mov_b32_e32 v163, v97
	v_mov_b32_e32 v108, v94
	v_mov_b32_e32 v109, v96
	v_pk_mul_f32 v[162:163], v[162:163], v[162:163]
	s_nop 0
	v_pk_fma_f32 v[108:109], v[108:109], v[108:109], v[162:163]
	v_mov_b32_e32 v162, v90
	v_pk_add_f32 v[168:169], v[108:109], v[108:109] op_sel_hi:[0,1]
	v_cvt_f32_f16_e32 v109, v170
	v_cvt_f32_f16_e32 v108, v164
	v_mov_b32_e32 v163, v82
	v_pk_mov_b32 v[90:91], v[90:91], v[82:83] op_sel:[1,0]
	v_mov_b32_e32 v173, v109
	v_pk_fma_f32 v[108:109], v[108:109], s[0:1], v[162:163] op_sel_hi:[1,0,1]
	v_cvt_f32_f16_e32 v163, v171
	v_pk_fma_f32 v[90:91], v[172:173], s[0:1], v[90:91] op_sel_hi:[1,0,1]
	v_cvt_f32_f16_e32 v172, v165
	v_cvt_f32_f16_sdwa v173, v170 dst_sel:DWORD dst_unused:UNUSED_PAD src0_sel:WORD_1
	v_mov_b32_e32 v175, v163
	v_pk_fma_f32 v[86:87], v[174:175], s[0:1], v[86:87] op_sel_hi:[1,0,1]
	v_cvt_f32_f16_sdwa v174, v165 dst_sel:DWORD dst_unused:UNUSED_PAD src0_sel:WORD_1
	v_mov_b32_e32 v82, v92
	v_cvt_f32_f16_e32 v170, v167
	v_cvt_f32_f16_sdwa v171, v171 dst_sel:DWORD dst_unused:UNUSED_PAD src0_sel:WORD_1
	v_cvt_f32_f16_e32 v162, v166
	v_pk_fma_f32 v[164:165], v[172:173], s[0:1], v[82:83] op_sel_hi:[1,0,1]
	v_cvt_f32_f16_sdwa v172, v167 dst_sel:DWORD dst_unused:UNUSED_PAD src0_sel:WORD_1
	v_mov_b32_e32 v175, v173
	v_mov_b32_e32 v82, v93
	v_mov_b32_e32 v173, v171
	v_pk_fma_f32 v[166:167], v[170:171], s[0:1], v[84:85] op_sel_hi:[1,0,1]
	v_pk_fma_f32 v[82:83], v[174:175], s[0:1], v[82:83] op_sel_hi:[1,0,1]
	v_mov_b32_e32 v84, v89
	v_pk_mul_f32 v[88:89], v[108:109], v[108:109]
	v_pk_mul_f32 v[92:93], v[90:91], v[90:91]
	v_pk_fma_f32 v[162:163], v[162:163], s[0:1], v[176:177] op_sel_hi:[1,0,1]
	v_pk_fma_f32 v[84:85], v[172:173], s[0:1], v[84:85] op_sel_hi:[1,0,1]
	v_pk_mul_f32 v[170:171], v[164:165], v[164:165]
	v_pk_mul_f32 v[172:173], v[82:83], v[82:83]
	v_pk_mov_b32 v[88:89], v[108:109], v[88:89] op_sel:[1,0]
	v_pk_mov_b32 v[92:93], v[164:165], v[92:93] op_sel:[1,0]
	v_pk_mul_f32 v[174:175], v[162:163], v[162:163]
	v_pk_add_f32 v[88:89], v[88:89], v[92:93]
	v_pk_mov_b32 v[92:93], v[162:163], v[170:171] op_sel:[1,0]
	v_pk_mov_b32 v[170:171], v[166:167], v[172:173] op_sel:[1,0]
	v_pk_mul_f32 v[176:177], v[86:87], v[86:87]
	v_pk_add_f32 v[92:93], v[92:93], v[170:171]
	v_pk_mul_f32 v[178:179], v[166:167], v[166:167]
	v_pk_mul_f32 v[180:181], v[84:85], v[84:85]
	v_pk_add_f32 v[88:89], v[88:89], v[92:93]
	v_mov_b32_e32 v92, v94
	v_mov_b32_e32 v93, v174
	v_pk_mov_b32 v[170:171], v[94:95], v[176:177] op_sel:[1,0]
	v_pk_mov_b32 v[172:173], v[96:97], v[180:181] op_sel:[1,0]
	v_pk_add_f32 v[92:93], v[92:93], v[170:171]
	v_mov_b32_e32 v170, v96
	v_mov_b32_e32 v171, v178
	v_pk_add_f32 v[170:171], v[170:171], v[172:173]
	v_pk_mul_f32 v[172:173], v[164:165], v[82:83]
	v_pk_add_f32 v[92:93], v[92:93], v[170:171]
	v_pk_mul_f32 v[170:171], v[108:109], v[90:91]
	v_pk_add_f32 v[88:89], v[88:89], v[92:93]
	v_pk_add_f32 v[92:93], v[108:109], v[90:91]
	v_pk_mul_f32 v[174:175], v[166:167], v[84:85]
	v_mov_b32_e32 v93, v171
	v_pk_add_f32 v[170:171], v[164:165], v[82:83]
	v_mov_b32_e32 v168, v1
	v_mov_b32_e32 v171, v173
	v_pk_add_f32 v[92:93], v[92:93], v[170:171]
	v_pk_add_f32 v[170:171], v[162:163], v[86:87]
	v_pk_mul_f32 v[172:173], v[162:163], v[86:87]
	s_nop 0
	v_mov_b32_e32 v171, v173
	v_pk_add_f32 v[172:173], v[166:167], v[84:85]
	s_nop 0
	v_mov_b32_e32 v173, v175
	v_pk_add_f32 v[170:171], v[170:171], v[172:173]
	s_nop 0
	v_pk_add_f32 v[92:93], v[92:93], v[170:171]
	s_nop 0
	v_pk_add_f32 v[92:93], v[92:93], v[168:169]
	s_nop 0
	v_pk_add_f32 v[88:89], v[88:89], v[92:93]
	ds_bpermute_b32 v92, v241, v88
	ds_bpermute_b32 v93, v241, v89
	s_waitcnt lgkmcnt(0)
	v_pk_add_f32 v[88:89], v[88:89], v[92:93]
	ds_bpermute_b32 v92, v240, v88
	ds_bpermute_b32 v93, v240, v89
	s_and_saveexec_b64 s[0:1], vcc
	s_cbranch_execz .LBB0_92
	s_waitcnt lgkmcnt(0)
	v_pk_add_f32 v[88:89], v[88:89], v[92:93]
	ds_write_b64 v115, v[88:89] offset:1024
; __device__ __forceinline__ float sumsq4(f32x4 x) { return (x[0] * x[0] + x[1] * x[1]) + (x[2] * x[2] + x[3] * x[3]); }
;     __device__ __forceinline__ void fused(AccT& acc, const Unit& u, int wr, int wc, int fr, int fq, LAS unsigned char* lx, int tid) const {
;     ...
;                 const int row = EPI_ROW(u, ai, m); float s1 = 0.f, s2 = 0.f;
; #pragma unroll
;                 for (int bj = 0; bj < 2; ++bj) {
;                     const half8 rv = *(const half8*)(res + (size_t)row * DM + EPI_COL(u, bj));
; #pragma unroll
;                     for (int e = 0; e < 4; ++e) { acc[ai][bj][m][0][e] += ALPHA * (float)rv[e]; acc[ai][bj][m][1][e] += ALPHA * (float)rv[4 + e]; }
;                     const f32x4 a0 = acc[ai][bj][m][0], a1 = acc[ai][bj][m][1];
;                     s1 += ((a0[0] + a0[1]) + (a0[2] + a0[3])) + ((a1[0] + a1[1]) + (a1[2] + a1[3])); s2 += sumsq4(a0) + sumsq4(a1);
;                 }
;                 s1 += __shfl_xor(s1, 16); s1 += __shfl_xor(s1, 32); s2 += __shfl_xor(s2, 16); s2 += __shfl_xor(s2, 32);
;                 if (fq == 0) P[(ai * 128 + wr * 64 + m * 16 + fr) * 4 + wc] = (f32x2){s1, s2};
.LBB0_92:
	s_or_b64 exec, exec, s[0:1]
	v_or_b32_e32 v88, 48, v158
	v_ashrrev_i32_e32 v89, 31, v88
	v_readlane_b32 s0, v255, 2
	v_lshlrev_b64 v[88:89], 11, v[88:89]
	v_readlane_b32 s1, v255, 3
	v_mov_b32_e32 v182, v70
	v_pk_mov_b32 v[70:71], v[70:71], v[68:69] op_sel:[1,0]
	s_waitcnt lgkmcnt(0)
	v_lshl_add_u64 v[92:93], s[0:1], 0, v[88:89]
	v_lshl_add_u64 v[92:93], v[140:141], 1, v[92:93]
	global_load_dwordx4 v[170:173], v[92:93], off
	global_load_dwordx4 v[176:179], v[92:93], off offset:256
	s_mov_b32 s0, 0x3fd744fd
	v_mov_b32_e32 v183, v68
	v_mov_b32_e32 v68, v72
	s_waitcnt vmcnt(0) lgkmcnt(0)
	v_cvt_f32_f16_sdwa v180, v172 dst_sel:DWORD dst_unused:UNUSED_PAD src0_sel:WORD_1
	v_cvt_f32_f16_e32 v92, v178
	v_cvt_f32_f16_sdwa v93, v178 dst_sel:DWORD dst_unused:UNUSED_PAD src0_sel:WORD_1
	v_cvt_f32_f16_sdwa v178, v170 dst_sel:DWORD dst_unused:UNUSED_PAD src0_sel:WORD_1
	v_pk_fma_f32 v[78:79], v[92:93], s[0:1], v[78:79] op_sel_hi:[1,0,1]
	v_cvt_f32_f16_e32 v92, v179
	v_cvt_f32_f16_sdwa v93, v179 dst_sel:DWORD dst_unused:UNUSED_PAD src0_sel:WORD_1
	v_mov_b32_e32 v168, v79
	v_pk_fma_f32 v[80:81], v[92:93], s[0:1], v[80:81] op_sel_hi:[1,0,1]
	s_nop 0
	v_mov_b32_e32 v169, v81
	v_mov_b32_e32 v92, v78
	v_mov_b32_e32 v93, v80
	v_pk_mul_f32 v[168:169], v[168:169], v[168:169]
	s_nop 0
	v_pk_fma_f32 v[92:93], v[92:93], v[92:93], v[168:169]
	v_mov_b32_e32 v168, v74
	v_pk_add_f32 v[174:175], v[92:93], v[92:93] op_sel_hi:[0,1]
	v_cvt_f32_f16_e32 v93, v176
	v_cvt_f32_f16_e32 v92, v170
	v_mov_b32_e32 v169, v66
	v_pk_mov_b32 v[74:75], v[74:75], v[66:67] op_sel:[1,0]
	v_mov_b32_e32 v179, v93
	v_pk_fma_f32 v[92:93], v[92:93], s[0:1], v[168:169] op_sel_hi:[1,0,1]
	v_cvt_f32_f16_e32 v169, v177
	v_pk_fma_f32 v[74:75], v[178:179], s[0:1], v[74:75] op_sel_hi:[1,0,1]
	v_cvt_f32_f16_e32 v178, v171
	v_cvt_f32_f16_sdwa v179, v176 dst_sel:DWORD dst_unused:UNUSED_PAD src0_sel:WORD_1
	v_mov_b32_e32 v181, v169
	v_pk_fma_f32 v[70:71], v[180:181], s[0:1], v[70:71] op_sel_hi:[1,0,1]
	v_cvt_f32_f16_sdwa v180, v171 dst_sel:DWORD dst_unused:UNUSED_PAD src0_sel:WORD_1
	v_mov_b32_e32 v66, v76
	v_cvt_f32_f16_e32 v176, v173
	v_cvt_f32_f16_sdwa v177, v177 dst_sel:DWORD dst_unused:UNUSED_PAD src0_sel:WORD_1
	v_cvt_f32_f16_e32 v168, v172
	v_pk_fma_f32 v[170:171], v[178:179], s[0:1], v[66:67] op_sel_hi:[1,0,1]
	v_cvt_f32_f16_sdwa v178, v173 dst_sel:DWORD dst_unused:UNUSED_PAD src0_sel:WORD_1
	v_mov_b32_e32 v181, v179
	v_mov_b32_e32 v66, v77
	v_mov_b32_e32 v179, v177
	v_pk_fma_f32 v[172:173], v[176:177], s[0:1], v[68:69] op_sel_hi:[1,0,1]
	v_pk_fma_f32 v[66:67], v[180:181], s[0:1], v[66:67] op_sel_hi:[1,0,1]
	v_mov_b32_e32 v68, v73
	v_pk_mul_f32 v[72:73], v[92:93], v[92:93]
	v_pk_mul_f32 v[76:77], v[74:75], v[74:75]
	v_pk_fma_f32 v[168:169], v[168:169], s[0:1], v[182:183] op_sel_hi:[1,0,1]
	v_pk_fma_f32 v[68:69], v[178:179], s[0:1], v[68:69] op_sel_hi:[1,0,1]
	v_pk_mul_f32 v[176:177], v[170:171], v[170:171]
	v_pk_mul_f32 v[178:179], v[66:67], v[66:67]
	v_pk_mov_b32 v[72:73], v[92:93], v[72:73] op_sel:[1,0]
	v_pk_mov_b32 v[76:77], v[170:171], v[76:77] op_sel:[1,0]
	v_pk_mul_f32 v[180:181], v[168:169], v[168:169]
	v_pk_add_f32 v[72:73], v[72:73], v[76:77]
	v_pk_mov_b32 v[76:77], v[168:169], v[176:177] op_sel:[1,0]
	v_pk_mov_b32 v[176:177], v[172:173], v[178:179] op_sel:[1,0]
	v_pk_mul_f32 v[182:183], v[70:71], v[70:71]
	v_pk_add_f32 v[76:77], v[76:77], v[176:177]
	v_pk_mul_f32 v[184:185], v[172:173], v[172:173]
	v_pk_mul_f32 v[186:187], v[68:69], v[68:69]
	v_pk_add_f32 v[72:73], v[72:73], v[76:77]
	v_mov_b32_e32 v76, v78
	v_mov_b32_e32 v77, v180
	v_pk_mov_b32 v[176:177], v[78:79], v[182:183] op_sel:[1,0]
	v_pk_mov_b32 v[178:179], v[80:81], v[186:187] op_sel:[1,0]
	v_pk_add_f32 v[76:77], v[76:77], v[176:177]
	v_mov_b32_e32 v176, v80
	v_mov_b32_e32 v177, v184
	v_pk_add_f32 v[176:177], v[176:177], v[178:179]
	v_pk_mul_f32 v[178:179], v[170:171], v[66:67]
	v_pk_add_f32 v[76:77], v[76:77], v[176:177]
	v_pk_mul_f32 v[176:177], v[92:93], v[74:75]
	v_pk_add_f32 v[72:73], v[72:73], v[76:77]
	v_pk_add_f32 v[76:77], v[92:93], v[74:75]
	v_pk_mul_f32 v[180:181], v[172:173], v[68:69]
	v_mov_b32_e32 v77, v177
	v_pk_add_f32 v[176:177], v[170:171], v[66:67]
	v_mov_b32_e32 v174, v1
	v_mov_b32_e32 v177, v179
	v_pk_add_f32 v[76:77], v[76:77], v[176:177]
	v_pk_add_f32 v[176:177], v[168:169], v[70:71]
	v_pk_mul_f32 v[178:179], v[168:169], v[70:71]
	s_nop 0
	v_mov_b32_e32 v177, v179
	v_pk_add_f32 v[178:179], v[172:173], v[68:69]
	s_nop 0
	v_mov_b32_e32 v179, v181
	v_pk_add_f32 v[176:177], v[176:177], v[178:179]
	s_nop 0
	v_pk_add_f32 v[76:77], v[76:77], v[176:177]
	s_nop 0
	v_pk_add_f32 v[76:77], v[76:77], v[174:175]
	s_nop 0
	v_pk_add_f32 v[72:73], v[72:73], v[76:77]
	ds_bpermute_b32 v76, v241, v72
	ds_bpermute_b32 v77, v241, v73
	s_waitcnt lgkmcnt(0)
	v_pk_add_f32 v[72:73], v[72:73], v[76:77]
	ds_bpermute_b32 v76, v240, v72
	ds_bpermute_b32 v77, v240, v73
	s_and_saveexec_b64 s[0:1], vcc
	s_cbranch_execz .LBB0_94
	s_waitcnt lgkmcnt(0)
	v_pk_add_f32 v[72:73], v[72:73], v[76:77]
	ds_write_b64 v115, v[72:73] offset:1536
; __device__ __forceinline__ float sumsq4(f32x4 x) { return (x[0] * x[0] + x[1] * x[1]) + (x[2] * x[2] + x[3] * x[3]); }
;     __device__ __forceinline__ void fused(AccT& acc, const Unit& u, int wr, int wc, int fr, int fq, LAS unsigned char* lx, int tid) const {
;     ...
;                 const int row = EPI_ROW(u, ai, m); float s1 = 0.f, s2 = 0.f;
; #pragma unroll
;                 for (int bj = 0; bj < 2; ++bj) {
;                     const half8 rv = *(const half8*)(res + (size_t)row * DM + EPI_COL(u, bj));
; #pragma unroll
;                     for (int e = 0; e < 4; ++e) { acc[ai][bj][m][0][e] += ALPHA * (float)rv[e]; acc[ai][bj][m][1][e] += ALPHA * (float)rv[4 + e]; }
;                     const f32x4 a0 = acc[ai][bj][m][0], a1 = acc[ai][bj][m][1];
;                     s1 += ((a0[0] + a0[1]) + (a0[2] + a0[3])) + ((a1[0] + a1[1]) + (a1[2] + a1[3])); s2 += sumsq4(a0) + sumsq4(a1);
;                 }
;                 s1 += __shfl_xor(s1, 16); s1 += __shfl_xor(s1, 32); s2 += __shfl_xor(s2, 16); s2 += __shfl_xor(s2, 32);
;                 if (fq == 0) P[(ai * 128 + wr * 64 + m * 16 + fr) * 4 + wc] = (f32x2){s1, s2};
.LBB0_94:
	s_or_b64 exec, exec, s[0:1]
	v_add_u32_e32 v72, 0x80, v158
	v_ashrrev_i32_e32 v73, 31, v72
	v_readlane_b32 s0, v255, 2
	v_lshlrev_b64 v[72:73], 11, v[72:73]
	v_readlane_b32 s1, v255, 3
	v_mov_b32_e32 v188, v54
	v_pk_mov_b32 v[54:55], v[54:55], v[52:53] op_sel:[1,0]
	s_waitcnt lgkmcnt(0)
	v_lshl_add_u64 v[76:77], s[0:1], 0, v[72:73]
	v_lshl_add_u64 v[76:77], v[140:141], 1, v[76:77]
	global_load_dwordx4 v[176:179], v[76:77], off
	global_load_dwordx4 v[182:185], v[76:77], off offset:256
	s_mov_b32 s0, 0x3fd744fd
	v_mov_b32_e32 v189, v52
	v_mov_b32_e32 v52, v56
	s_waitcnt vmcnt(0) lgkmcnt(0)
	v_cvt_f32_f16_sdwa v186, v178 dst_sel:DWORD dst_unused:UNUSED_PAD src0_sel:WORD_1
	v_cvt_f32_f16_e32 v76, v184
	v_cvt_f32_f16_sdwa v77, v184 dst_sel:DWORD dst_unused:UNUSED_PAD src0_sel:WORD_1
	v_cvt_f32_f16_sdwa v184, v176 dst_sel:DWORD dst_unused:UNUSED_PAD src0_sel:WORD_1
	v_pk_fma_f32 v[62:63], v[76:77], s[0:1], v[62:63] op_sel_hi:[1,0,1]
	v_cvt_f32_f16_e32 v76, v185
	v_cvt_f32_f16_sdwa v77, v185 dst_sel:DWORD dst_unused:UNUSED_PAD src0_sel:WORD_1
	v_mov_b32_e32 v174, v63
	v_pk_fma_f32 v[64:65], v[76:77], s[0:1], v[64:65] op_sel_hi:[1,0,1]
	s_nop 0
	v_mov_b32_e32 v175, v65
	v_mov_b32_e32 v76, v62
	v_mov_b32_e32 v77, v64
	v_pk_mul_f32 v[174:175], v[174:175], v[174:175]
	s_nop 0
	v_pk_fma_f32 v[76:77], v[76:77], v[76:77], v[174:175]
	v_mov_b32_e32 v174, v58
	v_pk_add_f32 v[180:181], v[76:77], v[76:77] op_sel_hi:[0,1]
	v_cvt_f32_f16_e32 v77, v182
	v_cvt_f32_f16_e32 v76, v176
	v_mov_b32_e32 v175, v50
	v_pk_mov_b32 v[58:59], v[58:59], v[50:51] op_sel:[1,0]
	v_mov_b32_e32 v185, v77
	v_pk_fma_f32 v[76:77], v[76:77], s[0:1], v[174:175] op_sel_hi:[1,0,1]
	v_cvt_f32_f16_e32 v175, v183
	v_pk_fma_f32 v[58:59], v[184:185], s[0:1], v[58:59] op_sel_hi:[1,0,1]
	v_cvt_f32_f16_e32 v184, v177
	v_cvt_f32_f16_sdwa v185, v182 dst_sel:DWORD dst_unused:UNUSED_PAD src0_sel:WORD_1
	v_mov_b32_e32 v187, v175
	v_pk_fma_f32 v[54:55], v[186:187], s[0:1], v[54:55] op_sel_hi:[1,0,1]
	v_cvt_f32_f16_sdwa v186, v177 dst_sel:DWORD dst_unused:UNUSED_PAD src0_sel:WORD_1
	v_mov_b32_e32 v50, v60
	v_cvt_f32_f16_e32 v182, v179
	v_cvt_f32_f16_sdwa v183, v183 dst_sel:DWORD dst_unused:UNUSED_PAD src0_sel:WORD_1
	v_cvt_f32_f16_e32 v174, v178
	v_pk_fma_f32 v[176:177], v[184:185], s[0:1], v[50:51] op_sel_hi:[1,0,1]
	v_cvt_f32_f16_sdwa v184, v179 dst_sel:DWORD dst_unused:UNUSED_PAD src0_sel:WORD_1
	v_mov_b32_e32 v187, v185
	v_mov_b32_e32 v50, v61
	v_mov_b32_e32 v185, v183
	v_pk_fma_f32 v[178:179], v[182:183], s[0:1], v[52:53] op_sel_hi:[1,0,1]
	v_pk_fma_f32 v[50:51], v[186:187], s[0:1], v[50:51] op_sel_hi:[1,0,1]
	v_mov_b32_e32 v52, v57
	v_pk_mul_f32 v[56:57], v[76:77], v[76:77]
	v_pk_mul_f32 v[60:61], v[58:59], v[58:59]
	v_pk_fma_f32 v[174:175], v[174:175], s[0:1], v[188:189] op_sel_hi:[1,0,1]
	v_pk_fma_f32 v[52:53], v[184:185], s[0:1], v[52:53] op_sel_hi:[1,0,1]
	v_pk_mul_f32 v[182:183], v[176:177], v[176:177]
	v_pk_mul_f32 v[184:185], v[50:51], v[50:51]
	v_pk_mov_b32 v[56:57], v[76:77], v[56:57] op_sel:[1,0]
	v_pk_mov_b32 v[60:61], v[176:177], v[60:61] op_sel:[1,0]
	v_pk_mul_f32 v[186:187], v[174:175], v[174:175]
	v_pk_add_f32 v[56:57], v[56:57], v[60:61]
	v_pk_mov_b32 v[60:61], v[174:175], v[182:183] op_sel:[1,0]
	v_pk_mov_b32 v[182:183], v[178:179], v[184:185] op_sel:[1,0]
	v_pk_mul_f32 v[188:189], v[54:55], v[54:55]
	v_pk_add_f32 v[60:61], v[60:61], v[182:183]
	v_pk_mul_f32 v[190:191], v[178:179], v[178:179]
	v_pk_mul_f32 v[192:193], v[52:53], v[52:53]
	v_pk_add_f32 v[56:57], v[56:57], v[60:61]
	v_mov_b32_e32 v60, v62
	v_mov_b32_e32 v61, v186
	v_pk_mov_b32 v[182:183], v[62:63], v[188:189] op_sel:[1,0]
	v_pk_mov_b32 v[184:185], v[64:65], v[192:193] op_sel:[1,0]
	v_pk_add_f32 v[60:61], v[60:61], v[182:183]
	v_mov_b32_e32 v182, v64
	v_mov_b32_e32 v183, v190
	v_pk_add_f32 v[182:183], v[182:183], v[184:185]
	v_pk_mul_f32 v[184:185], v[176:177], v[50:51]
	v_pk_add_f32 v[60:61], v[60:61], v[182:183]
	v_pk_mul_f32 v[182:183], v[76:77], v[58:59]
	v_pk_add_f32 v[56:57], v[56:57], v[60:61]
	v_pk_add_f32 v[60:61], v[76:77], v[58:59]
	v_pk_mul_f32 v[186:187], v[178:179], v[52:53]
	v_mov_b32_e32 v61, v183
	v_pk_add_f32 v[182:183], v[176:177], v[50:51]
	v_mov_b32_e32 v180, v1
	v_mov_b32_e32 v183, v185
	v_pk_add_f32 v[60:61], v[60:61], v[182:183]
	v_pk_add_f32 v[182:183], v[174:175], v[54:55]
	v_pk_mul_f32 v[184:185], v[174:175], v[54:55]
	s_nop 0
	v_mov_b32_e32 v183, v185
	v_pk_add_f32 v[184:185], v[178:179], v[52:53]
	s_nop 0
	v_mov_b32_e32 v185, v187
	v_pk_add_f32 v[182:183], v[182:183], v[184:185]
	s_nop 0
	v_pk_add_f32 v[60:61], v[60:61], v[182:183]
	s_nop 0
	v_pk_add_f32 v[60:61], v[60:61], v[180:181]
	s_nop 0
	v_pk_add_f32 v[56:57], v[56:57], v[60:61]
	ds_bpermute_b32 v60, v241, v56
	ds_bpermute_b32 v61, v241, v57
	s_waitcnt lgkmcnt(0)
	v_pk_add_f32 v[56:57], v[56:57], v[60:61]
	ds_bpermute_b32 v60, v240, v56
	ds_bpermute_b32 v61, v240, v57
	s_and_saveexec_b64 s[0:1], vcc
	s_cbranch_execz .LBB0_96
	s_waitcnt lgkmcnt(0)
	v_pk_add_f32 v[56:57], v[56:57], v[60:61]
	ds_write_b64 v115, v[56:57] offset:4096
; __device__ __forceinline__ float sumsq4(f32x4 x) { return (x[0] * x[0] + x[1] * x[1]) + (x[2] * x[2] + x[3] * x[3]); }
;     __device__ __forceinline__ void fused(AccT& acc, const Unit& u, int wr, int wc, int fr, int fq, LAS unsigned char* lx, int tid) const {
;     ...
;                 const int row = EPI_ROW(u, ai, m); float s1 = 0.f, s2 = 0.f;
; #pragma unroll
;                 for (int bj = 0; bj < 2; ++bj) {
;                     const half8 rv = *(const half8*)(res + (size_t)row * DM + EPI_COL(u, bj));
; #pragma unroll
;                     for (int e = 0; e < 4; ++e) { acc[ai][bj][m][0][e] += ALPHA * (float)rv[e]; acc[ai][bj][m][1][e] += ALPHA * (float)rv[4 + e]; }
;                     const f32x4 a0 = acc[ai][bj][m][0], a1 = acc[ai][bj][m][1];
;                     s1 += ((a0[0] + a0[1]) + (a0[2] + a0[3])) + ((a1[0] + a1[1]) + (a1[2] + a1[3])); s2 += sumsq4(a0) + sumsq4(a1);
;                 }
;                 s1 += __shfl_xor(s1, 16); s1 += __shfl_xor(s1, 32); s2 += __shfl_xor(s2, 16); s2 += __shfl_xor(s2, 32);
;                 if (fq == 0) P[(ai * 128 + wr * 64 + m * 16 + fr) * 4 + wc] = (f32x2){s1, s2};
.LBB0_96:
	s_or_b64 exec, exec, s[0:1]
	v_add_u32_e32 v56, 0x90, v158
	v_ashrrev_i32_e32 v57, 31, v56
	v_readlane_b32 s0, v255, 2
	v_lshlrev_b64 v[56:57], 11, v[56:57]
	v_readlane_b32 s1, v255, 3
	v_mov_b32_e32 v194, v38
	v_pk_mov_b32 v[38:39], v[38:39], v[36:37] op_sel:[1,0]
	s_waitcnt lgkmcnt(0)
	v_lshl_add_u64 v[60:61], s[0:1], 0, v[56:57]
	v_lshl_add_u64 v[60:61], v[140:141], 1, v[60:61]
	global_load_dwordx4 v[182:185], v[60:61], off
	global_load_dwordx4 v[188:191], v[60:61], off offset:256
	s_mov_b32 s0, 0x3fd744fd
	v_mov_b32_e32 v195, v36
	v_mov_b32_e32 v36, v40
	s_waitcnt vmcnt(0) lgkmcnt(0)
	v_cvt_f32_f16_sdwa v192, v184 dst_sel:DWORD dst_unused:UNUSED_PAD src0_sel:WORD_1
	v_cvt_f32_f16_e32 v60, v190
	v_cvt_f32_f16_sdwa v61, v190 dst_sel:DWORD dst_unused:UNUSED_PAD src0_sel:WORD_1
	v_cvt_f32_f16_sdwa v190, v182 dst_sel:DWORD dst_unused:UNUSED_PAD src0_sel:WORD_1
	v_pk_fma_f32 v[46:47], v[60:61], s[0:1], v[46:47] op_sel_hi:[1,0,1]
	v_cvt_f32_f16_e32 v60, v191
	v_cvt_f32_f16_sdwa v61, v191 dst_sel:DWORD dst_unused:UNUSED_PAD src0_sel:WORD_1
	v_mov_b32_e32 v180, v47
	v_pk_fma_f32 v[48:49], v[60:61], s[0:1], v[48:49] op_sel_hi:[1,0,1]
	s_nop 0
	v_mov_b32_e32 v181, v49
	v_mov_b32_e32 v60, v46
	v_mov_b32_e32 v61, v48
	v_pk_mul_f32 v[180:181], v[180:181], v[180:181]
	s_nop 0
	v_pk_fma_f32 v[60:61], v[60:61], v[60:61], v[180:181]
	v_mov_b32_e32 v180, v42
	v_pk_add_f32 v[186:187], v[60:61], v[60:61] op_sel_hi:[0,1]
	v_cvt_f32_f16_e32 v61, v188
	v_cvt_f32_f16_e32 v60, v182
	v_mov_b32_e32 v181, v34
	v_pk_mov_b32 v[42:43], v[42:43], v[34:35] op_sel:[1,0]
	v_mov_b32_e32 v191, v61
	v_pk_fma_f32 v[60:61], v[60:61], s[0:1], v[180:181] op_sel_hi:[1,0,1]
	v_cvt_f32_f16_e32 v181, v189
	v_pk_fma_f32 v[42:43], v[190:191], s[0:1], v[42:43] op_sel_hi:[1,0,1]
	v_cvt_f32_f16_e32 v190, v183
	v_cvt_f32_f16_sdwa v191, v188 dst_sel:DWORD dst_unused:UNUSED_PAD src0_sel:WORD_1
	v_mov_b32_e32 v193, v181
	v_pk_fma_f32 v[38:39], v[192:193], s[0:1], v[38:39] op_sel_hi:[1,0,1]
	v_cvt_f32_f16_sdwa v192, v183 dst_sel:DWORD dst_unused:UNUSED_PAD src0_sel:WORD_1
	v_mov_b32_e32 v34, v44
	v_cvt_f32_f16_e32 v188, v185
	v_cvt_f32_f16_sdwa v189, v189 dst_sel:DWORD dst_unused:UNUSED_PAD src0_sel:WORD_1
	v_cvt_f32_f16_e32 v180, v184
	v_pk_fma_f32 v[182:183], v[190:191], s[0:1], v[34:35] op_sel_hi:[1,0,1]
	v_cvt_f32_f16_sdwa v190, v185 dst_sel:DWORD dst_unused:UNUSED_PAD src0_sel:WORD_1
	v_mov_b32_e32 v193, v191
	v_mov_b32_e32 v34, v45
	v_mov_b32_e32 v191, v189
	v_pk_fma_f32 v[184:185], v[188:189], s[0:1], v[36:37] op_sel_hi:[1,0,1]
	v_pk_fma_f32 v[34:35], v[192:193], s[0:1], v[34:35] op_sel_hi:[1,0,1]
	v_mov_b32_e32 v36, v41
	v_pk_mul_f32 v[40:41], v[60:61], v[60:61]
	v_pk_mul_f32 v[44:45], v[42:43], v[42:43]
	v_pk_fma_f32 v[180:181], v[180:181], s[0:1], v[194:195] op_sel_hi:[1,0,1]
	v_pk_fma_f32 v[36:37], v[190:191], s[0:1], v[36:37] op_sel_hi:[1,0,1]
	v_pk_mul_f32 v[188:189], v[182:183], v[182:183]
	v_pk_mul_f32 v[190:191], v[34:35], v[34:35]
	v_pk_mov_b32 v[40:41], v[60:61], v[40:41] op_sel:[1,0]
	v_pk_mov_b32 v[44:45], v[182:183], v[44:45] op_sel:[1,0]
	v_pk_mul_f32 v[192:193], v[180:181], v[180:181]
	v_pk_add_f32 v[40:41], v[40:41], v[44:45]
	v_pk_mov_b32 v[44:45], v[180:181], v[188:189] op_sel:[1,0]
	v_pk_mov_b32 v[188:189], v[184:185], v[190:191] op_sel:[1,0]
	v_pk_mul_f32 v[194:195], v[38:39], v[38:39]
	v_pk_add_f32 v[44:45], v[44:45], v[188:189]
	v_pk_mul_f32 v[196:197], v[184:185], v[184:185]
	v_pk_mul_f32 v[198:199], v[36:37], v[36:37]
	v_pk_add_f32 v[40:41], v[40:41], v[44:45]
	v_mov_b32_e32 v44, v46
	v_mov_b32_e32 v45, v192
	v_pk_mov_b32 v[188:189], v[46:47], v[194:195] op_sel:[1,0]
	v_pk_mov_b32 v[190:191], v[48:49], v[198:199] op_sel:[1,0]
	v_pk_add_f32 v[44:45], v[44:45], v[188:189]
	v_mov_b32_e32 v188, v48
	v_mov_b32_e32 v189, v196
	v_pk_add_f32 v[188:189], v[188:189], v[190:191]
	v_pk_mul_f32 v[190:191], v[182:183], v[34:35]
	v_pk_add_f32 v[44:45], v[44:45], v[188:189]
	v_pk_mul_f32 v[188:189], v[60:61], v[42:43]
	v_pk_add_f32 v[40:41], v[40:41], v[44:45]
	v_pk_add_f32 v[44:45], v[60:61], v[42:43]
	v_pk_mul_f32 v[192:193], v[184:185], v[36:37]
	v_mov_b32_e32 v45, v189
	v_pk_add_f32 v[188:189], v[182:183], v[34:35]
	v_mov_b32_e32 v186, v1
	v_mov_b32_e32 v189, v191
	v_pk_add_f32 v[44:45], v[44:45], v[188:189]
	v_pk_add_f32 v[188:189], v[180:181], v[38:39]
	v_pk_mul_f32 v[190:191], v[180:181], v[38:39]
	s_nop 0
	v_mov_b32_e32 v189, v191
	v_pk_add_f32 v[190:191], v[184:185], v[36:37]
	s_nop 0
	v_mov_b32_e32 v191, v193
	v_pk_add_f32 v[188:189], v[188:189], v[190:191]
	s_nop 0
	v_pk_add_f32 v[44:45], v[44:45], v[188:189]
	s_nop 0
	v_pk_add_f32 v[44:45], v[44:45], v[186:187]
	s_nop 0
	v_pk_add_f32 v[40:41], v[40:41], v[44:45]
	ds_bpermute_b32 v44, v241, v40
	ds_bpermute_b32 v45, v241, v41
	s_waitcnt lgkmcnt(0)
	v_pk_add_f32 v[40:41], v[40:41], v[44:45]
	ds_bpermute_b32 v44, v240, v40
	ds_bpermute_b32 v45, v240, v41
	s_and_saveexec_b64 s[0:1], vcc
	s_cbranch_execz .LBB0_98
	s_waitcnt lgkmcnt(0)
	v_pk_add_f32 v[40:41], v[40:41], v[44:45]
	ds_write_b64 v115, v[40:41] offset:4608
; __device__ __forceinline__ float sumsq4(f32x4 x) { return (x[0] * x[0] + x[1] * x[1]) + (x[2] * x[2] + x[3] * x[3]); }
;     __device__ __forceinline__ void fused(AccT& acc, const Unit& u, int wr, int wc, int fr, int fq, LAS unsigned char* lx, int tid) const {
;     ...
;                 const int row = EPI_ROW(u, ai, m); float s1 = 0.f, s2 = 0.f;
; #pragma unroll
;                 for (int bj = 0; bj < 2; ++bj) {
;                     const half8 rv = *(const half8*)(res + (size_t)row * DM + EPI_COL(u, bj));
; #pragma unroll
;                     for (int e = 0; e < 4; ++e) { acc[ai][bj][m][0][e] += ALPHA * (float)rv[e]; acc[ai][bj][m][1][e] += ALPHA * (float)rv[4 + e]; }
;                     const f32x4 a0 = acc[ai][bj][m][0], a1 = acc[ai][bj][m][1];
;                     s1 += ((a0[0] + a0[1]) + (a0[2] + a0[3])) + ((a1[0] + a1[1]) + (a1[2] + a1[3])); s2 += sumsq4(a0) + sumsq4(a1);
;                 }
;                 s1 += __shfl_xor(s1, 16); s1 += __shfl_xor(s1, 32); s2 += __shfl_xor(s2, 16); s2 += __shfl_xor(s2, 32);
;                 if (fq == 0) P[(ai * 128 + wr * 64 + m * 16 + fr) * 4 + wc] = (f32x2){s1, s2};
.LBB0_98:
	s_or_b64 exec, exec, s[0:1]
	v_add_u32_e32 v40, 0xa0, v158
	v_ashrrev_i32_e32 v41, 31, v40
	v_readlane_b32 s0, v255, 2
	s_waitcnt lgkmcnt(0)
	v_lshlrev_b64 v[44:45], 11, v[40:41]
	v_readlane_b32 s1, v255, 3
	v_mov_b32_e32 v188, v26
	v_mov_b32_e32 v189, v18
	v_lshl_add_u64 v[40:41], s[0:1], 0, v[44:45]
	v_lshl_add_u64 v[40:41], v[140:141], 1, v[40:41]
	global_load_dwordx4 v[196:199], v[40:41], off
	global_load_dwordx4 v[200:203], v[40:41], off offset:256
	s_mov_b32 s0, 0x3fd744fd
	v_mov_b32_e32 v190, v22
	v_pk_mov_b32 v[26:27], v[26:27], v[18:19] op_sel:[1,0]
	v_pk_mov_b32 v[22:23], v[22:23], v[20:21] op_sel:[1,0]
	v_mov_b32_e32 v18, v28
	v_mov_b32_e32 v191, v20
	v_mov_b32_e32 v20, v24
	s_waitcnt vmcnt(0) lgkmcnt(0)
	v_cvt_f32_f16_sdwa v192, v196 dst_sel:DWORD dst_unused:UNUSED_PAD src0_sel:WORD_1
	v_cvt_f32_f16_e32 v40, v202
	v_cvt_f32_f16_sdwa v41, v202 dst_sel:DWORD dst_unused:UNUSED_PAD src0_sel:WORD_1
	v_cvt_f32_f16_sdwa v202, v198 dst_sel:DWORD dst_unused:UNUSED_PAD src0_sel:WORD_1
	v_pk_fma_f32 v[40:41], v[40:41], s[0:1], v[30:31] op_sel_hi:[1,0,1]
	v_cvt_f32_f16_e32 v30, v203
	v_cvt_f32_f16_sdwa v31, v203 dst_sel:DWORD dst_unused:UNUSED_PAD src0_sel:WORD_1
	v_pk_fma_f32 v[186:187], v[30:31], s[0:1], v[32:33] op_sel_hi:[1,0,1]
	v_mov_b32_e32 v32, v41
	v_mov_b32_e32 v33, v187
	v_mov_b32_e32 v30, v40
	v_mov_b32_e32 v31, v186
	v_pk_mul_f32 v[32:33], v[32:33], v[32:33]
	s_nop 0
	v_pk_fma_f32 v[30:31], v[30:31], v[30:31], v[32:33]
	v_cvt_f32_f16_e32 v33, v200
	v_cvt_f32_f16_e32 v32, v196
	v_pk_add_f32 v[30:31], v[30:31], v[30:31] op_sel_hi:[0,1]
	v_mov_b32_e32 v30, v1
	v_mov_b32_e32 v193, v33
	v_pk_fma_f32 v[188:189], v[32:33], s[0:1], v[188:189] op_sel_hi:[1,0,1]
	v_cvt_f32_f16_e32 v33, v201
	v_pk_fma_f32 v[194:195], v[192:193], s[0:1], v[26:27] op_sel_hi:[1,0,1]
	v_cvt_f32_f16_e32 v32, v198
	v_cvt_f32_f16_sdwa v26, v197 dst_sel:DWORD dst_unused:UNUSED_PAD src0_sel:WORD_1
	v_mov_b32_e32 v203, v33
	v_pk_fma_f32 v[192:193], v[202:203], s[0:1], v[22:23] op_sel_hi:[1,0,1]
	v_cvt_f32_f16_e32 v22, v197
	v_cvt_f32_f16_sdwa v23, v200 dst_sel:DWORD dst_unused:UNUSED_PAD src0_sel:WORD_1
	v_pk_fma_f32 v[190:191], v[32:33], s[0:1], v[190:191] op_sel_hi:[1,0,1]
	v_cvt_f32_f16_sdwa v32, v199 dst_sel:DWORD dst_unused:UNUSED_PAD src0_sel:WORD_1
	v_mov_b32_e32 v27, v23
	v_pk_fma_f32 v[196:197], v[22:23], s[0:1], v[18:19] op_sel_hi:[1,0,1]
	v_cvt_f32_f16_e32 v22, v199
	v_cvt_f32_f16_sdwa v23, v201 dst_sel:DWORD dst_unused:UNUSED_PAD src0_sel:WORD_1
	v_mov_b32_e32 v18, v29
	v_pk_fma_f32 v[200:201], v[26:27], s[0:1], v[18:19] op_sel_hi:[1,0,1]
	v_pk_mul_f32 v[18:19], v[188:189], v[188:189]
	v_mov_b32_e32 v33, v23
	v_pk_fma_f32 v[198:199], v[22:23], s[0:1], v[20:21] op_sel_hi:[1,0,1]
	v_mov_b32_e32 v20, v25
	v_pk_fma_f32 v[202:203], v[32:33], s[0:1], v[20:21] op_sel_hi:[1,0,1]
	v_pk_mul_f32 v[20:21], v[194:195], v[194:195]
	v_pk_mul_f32 v[22:23], v[196:197], v[196:197]
	v_pk_mul_f32 v[24:25], v[200:201], v[200:201]
	v_pk_mov_b32 v[18:19], v[188:189], v[18:19] op_sel:[1,0]
	v_pk_mov_b32 v[20:21], v[196:197], v[20:21] op_sel:[1,0]
	v_pk_mul_f32 v[26:27], v[190:191], v[190:191]
	v_pk_add_f32 v[18:19], v[18:19], v[20:21]
	v_pk_mov_b32 v[20:21], v[190:191], v[22:23] op_sel:[1,0]
	v_pk_mov_b32 v[22:23], v[198:199], v[24:25] op_sel:[1,0]
	v_pk_mul_f32 v[28:29], v[192:193], v[192:193]
	v_pk_add_f32 v[20:21], v[20:21], v[22:23]
	v_pk_mul_f32 v[32:33], v[198:199], v[198:199]
	v_pk_mul_f32 v[204:205], v[202:203], v[202:203]
	v_pk_add_f32 v[18:19], v[18:19], v[20:21]
	v_mov_b32_e32 v20, v40
	v_mov_b32_e32 v21, v26
	v_pk_mov_b32 v[22:23], v[40:41], v[28:29] op_sel:[1,0]
	v_pk_mov_b32 v[24:25], v[186:187], v[204:205] op_sel:[1,0]
	v_pk_add_f32 v[20:21], v[20:21], v[22:23]
	v_mov_b32_e32 v22, v186
	v_mov_b32_e32 v23, v32
	v_pk_add_f32 v[22:23], v[22:23], v[24:25]
	v_pk_mul_f32 v[24:25], v[196:197], v[200:201]
	v_pk_add_f32 v[20:21], v[20:21], v[22:23]
	v_pk_mul_f32 v[22:23], v[188:189], v[194:195]
	v_pk_add_f32 v[18:19], v[18:19], v[20:21]
	v_pk_add_f32 v[20:21], v[188:189], v[194:195]
	v_pk_mul_f32 v[26:27], v[198:199], v[202:203]
	v_mov_b32_e32 v21, v23
	v_pk_add_f32 v[22:23], v[196:197], v[200:201]
	s_nop 0
	v_mov_b32_e32 v23, v25
	v_pk_add_f32 v[20:21], v[20:21], v[22:23]
	v_pk_add_f32 v[22:23], v[190:191], v[192:193]
	v_pk_mul_f32 v[24:25], v[190:191], v[192:193]
	s_nop 0
	v_mov_b32_e32 v23, v25
	v_pk_add_f32 v[24:25], v[198:199], v[202:203]
	s_nop 0
	v_mov_b32_e32 v25, v27
	v_pk_add_f32 v[22:23], v[22:23], v[24:25]
	s_nop 0
	v_pk_add_f32 v[20:21], v[20:21], v[22:23]
	s_nop 0
	v_pk_add_f32 v[20:21], v[20:21], v[30:31]
	s_nop 0
	v_pk_add_f32 v[18:19], v[18:19], v[20:21]
	ds_bpermute_b32 v20, v241, v18
	ds_bpermute_b32 v21, v241, v19
	s_waitcnt lgkmcnt(0)
	v_pk_add_f32 v[18:19], v[18:19], v[20:21]
	ds_bpermute_b32 v20, v240, v18
	ds_bpermute_b32 v21, v240, v19
	s_and_saveexec_b64 s[0:1], vcc
	s_cbranch_execz .LBB0_100
	s_waitcnt lgkmcnt(0)
	v_pk_add_f32 v[18:19], v[18:19], v[20:21]
	ds_write_b64 v115, v[18:19] offset:5120
; __device__ __forceinline__ float sumsq4(f32x4 x) { return (x[0] * x[0] + x[1] * x[1]) + (x[2] * x[2] + x[3] * x[3]); }
;     __device__ __forceinline__ void fused(AccT& acc, const Unit& u, int wr, int wc, int fr, int fq, LAS unsigned char* lx, int tid) const {
;     ...
;                 const int row = EPI_ROW(u, ai, m); float s1 = 0.f, s2 = 0.f;
; #pragma unroll
;                 for (int bj = 0; bj < 2; ++bj) {
;                     const half8 rv = *(const half8*)(res + (size_t)row * DM + EPI_COL(u, bj));
; #pragma unroll
;                     for (int e = 0; e < 4; ++e) { acc[ai][bj][m][0][e] += ALPHA * (float)rv[e]; acc[ai][bj][m][1][e] += ALPHA * (float)rv[4 + e]; }
;                     const f32x4 a0 = acc[ai][bj][m][0], a1 = acc[ai][bj][m][1];
;                     s1 += ((a0[0] + a0[1]) + (a0[2] + a0[3])) + ((a1[0] + a1[1]) + (a1[2] + a1[3])); s2 += sumsq4(a0) + sumsq4(a1);
;                 }
;                 s1 += __shfl_xor(s1, 16); s1 += __shfl_xor(s1, 32); s2 += __shfl_xor(s2, 16); s2 += __shfl_xor(s2, 32);
;                 if (fq == 0) P[(ai * 128 + wr * 64 + m * 16 + fr) * 4 + wc] = (f32x2){s1, s2};
.LBB0_100:
	s_or_b64 exec, exec, s[0:1]
	v_add_u32_e32 v18, 0xb0, v158
	v_ashrrev_i32_e32 v19, 31, v18
	v_readlane_b32 s0, v255, 2
	v_lshlrev_b64 v[204:205], 11, v[18:19]
	v_readlane_b32 s1, v255, 3
	v_mov_b32_e32 v28, v6
	v_pk_mov_b32 v[6:7], v[6:7], v[4:5] op_sel:[1,0]
	v_lshl_add_u64 v[18:19], s[0:1], 0, v[204:205]
	v_lshl_add_u64 v[22:23], v[140:141], 1, v[18:19]
	s_waitcnt lgkmcnt(0)
	global_load_dwordx4 v[18:21], v[22:23], off
	s_nop 0
	global_load_dwordx4 v[22:25], v[22:23], off offset:256
	s_mov_b32 s0, 0x3fd744fd
	v_mov_b32_e32 v29, v4
	v_mov_b32_e32 v4, v8
	s_waitcnt vmcnt(0) lgkmcnt(0)
	v_cvt_f32_f16_e32 v26, v24
	v_cvt_f32_f16_sdwa v27, v24 dst_sel:DWORD dst_unused:UNUSED_PAD src0_sel:WORD_1
	v_cvt_f32_f16_sdwa v24, v18 dst_sel:DWORD dst_unused:UNUSED_PAD src0_sel:WORD_1
	v_pk_fma_f32 v[158:159], v[26:27], s[0:1], v[14:15] op_sel_hi:[1,0,1]
	v_cvt_f32_f16_e32 v14, v25
	v_cvt_f32_f16_sdwa v15, v25 dst_sel:DWORD dst_unused:UNUSED_PAD src0_sel:WORD_1
	v_mov_b32_e32 v26, v10
	v_mov_b32_e32 v27, v2
	v_pk_mov_b32 v[10:11], v[10:11], v[2:3] op_sel:[1,0]
	v_pk_fma_f32 v[206:207], v[14:15], s[0:1], v[16:17] op_sel_hi:[1,0,1]
	v_mov_b32_e32 v16, v159
	v_mov_b32_e32 v17, v207
	v_mov_b32_e32 v14, v158
	v_mov_b32_e32 v15, v206
	v_pk_mul_f32 v[16:17], v[16:17], v[16:17]
	v_mov_b32_e32 v2, v12
	v_pk_fma_f32 v[14:15], v[14:15], v[14:15], v[16:17]
	v_cvt_f32_f16_e32 v17, v22
	v_cvt_f32_f16_e32 v16, v18
	v_pk_add_f32 v[14:15], v[14:15], v[14:15] op_sel_hi:[0,1]
	v_mov_b32_e32 v14, v1
	v_mov_b32_e32 v25, v17
	v_pk_fma_f32 v[208:209], v[16:17], s[0:1], v[26:27] op_sel_hi:[1,0,1]
	v_cvt_f32_f16_e32 v17, v23
	v_cvt_f32_f16_sdwa v26, v20 dst_sel:DWORD dst_unused:UNUSED_PAD src0_sel:WORD_1
	v_cvt_f32_f16_e32 v16, v20
	v_pk_fma_f32 v[220:221], v[24:25], s[0:1], v[10:11] op_sel_hi:[1,0,1]
	v_mov_b32_e32 v27, v17
	v_pk_fma_f32 v[212:213], v[26:27], s[0:1], v[6:7] op_sel_hi:[1,0,1]
	v_cvt_f32_f16_e32 v6, v19
	v_cvt_f32_f16_sdwa v7, v22 dst_sel:DWORD dst_unused:UNUSED_PAD src0_sel:WORD_1
	v_pk_fma_f32 v[210:211], v[16:17], s[0:1], v[28:29] op_sel_hi:[1,0,1]
	v_cvt_f32_f16_sdwa v10, v19 dst_sel:DWORD dst_unused:UNUSED_PAD src0_sel:WORD_1
	v_cvt_f32_f16_sdwa v16, v21 dst_sel:DWORD dst_unused:UNUSED_PAD src0_sel:WORD_1
	v_mov_b32_e32 v11, v7
	v_pk_fma_f32 v[214:215], v[6:7], s[0:1], v[2:3] op_sel_hi:[1,0,1]
	v_cvt_f32_f16_e32 v6, v21
	v_cvt_f32_f16_sdwa v7, v23 dst_sel:DWORD dst_unused:UNUSED_PAD src0_sel:WORD_1
	v_mov_b32_e32 v2, v13
	v_pk_fma_f32 v[224:225], v[10:11], s[0:1], v[2:3] op_sel_hi:[1,0,1]
	v_pk_mul_f32 v[2:3], v[208:209], v[208:209]
	v_mov_b32_e32 v17, v7
	v_pk_fma_f32 v[222:223], v[6:7], s[0:1], v[4:5] op_sel_hi:[1,0,1]
	v_mov_b32_e32 v4, v9
	v_pk_fma_f32 v[226:227], v[16:17], s[0:1], v[4:5] op_sel_hi:[1,0,1]
	v_pk_mul_f32 v[4:5], v[220:221], v[220:221]
	v_pk_mul_f32 v[6:7], v[214:215], v[214:215]
	v_pk_mul_f32 v[8:9], v[224:225], v[224:225]
	v_pk_mov_b32 v[2:3], v[208:209], v[2:3] op_sel:[1,0]
	v_pk_mov_b32 v[4:5], v[214:215], v[4:5] op_sel:[1,0]
	v_pk_mul_f32 v[10:11], v[210:211], v[210:211]
	v_pk_add_f32 v[2:3], v[2:3], v[4:5]
	v_pk_mov_b32 v[4:5], v[210:211], v[6:7] op_sel:[1,0]
	v_pk_mov_b32 v[6:7], v[222:223], v[8:9] op_sel:[1,0]
	v_pk_mul_f32 v[12:13], v[212:213], v[212:213]
	v_pk_add_f32 v[4:5], v[4:5], v[6:7]
	v_pk_mul_f32 v[16:17], v[222:223], v[222:223]
	v_pk_mul_f32 v[18:19], v[226:227], v[226:227]
	v_pk_add_f32 v[2:3], v[2:3], v[4:5]
	v_mov_b32_e32 v4, v158
	v_mov_b32_e32 v5, v10
	v_pk_mov_b32 v[6:7], v[158:159], v[12:13] op_sel:[1,0]
	v_pk_mov_b32 v[8:9], v[206:207], v[18:19] op_sel:[1,0]
	v_pk_add_f32 v[4:5], v[4:5], v[6:7]
	v_mov_b32_e32 v6, v206
	v_mov_b32_e32 v7, v16
	v_pk_add_f32 v[6:7], v[6:7], v[8:9]
	v_pk_mul_f32 v[8:9], v[214:215], v[224:225]
	v_pk_add_f32 v[4:5], v[4:5], v[6:7]
	v_pk_mul_f32 v[6:7], v[208:209], v[220:221]
	v_pk_add_f32 v[2:3], v[2:3], v[4:5]
	v_pk_add_f32 v[4:5], v[208:209], v[220:221]
	v_pk_mul_f32 v[10:11], v[222:223], v[226:227]
	v_mov_b32_e32 v5, v7
	v_pk_add_f32 v[6:7], v[214:215], v[224:225]
	s_nop 0
	v_mov_b32_e32 v7, v9
	v_pk_add_f32 v[4:5], v[4:5], v[6:7]
	v_pk_add_f32 v[6:7], v[210:211], v[212:213]
	v_pk_mul_f32 v[8:9], v[210:211], v[212:213]
	s_nop 0
	v_mov_b32_e32 v7, v9
	v_pk_add_f32 v[8:9], v[222:223], v[226:227]
	s_nop 0
	v_mov_b32_e32 v9, v11
	v_pk_add_f32 v[6:7], v[6:7], v[8:9]
	s_nop 0
	v_pk_add_f32 v[4:5], v[4:5], v[6:7]
	s_nop 0
	v_pk_add_f32 v[4:5], v[4:5], v[14:15]
	s_nop 0
	v_pk_add_f32 v[2:3], v[2:3], v[4:5]
	ds_bpermute_b32 v4, v241, v2
	ds_bpermute_b32 v5, v241, v3
	s_waitcnt lgkmcnt(0)
	v_pk_add_f32 v[2:3], v[2:3], v[4:5]
	ds_bpermute_b32 v4, v240, v2
	ds_bpermute_b32 v5, v240, v3
	s_and_saveexec_b64 s[0:1], vcc
	s_cbranch_execz .LBB0_102
	s_waitcnt lgkmcnt(0)
	v_pk_add_f32 v[2:3], v[2:3], v[4:5]
	ds_write_b64 v115, v[2:3] offset:5632

;     __device__ __forceinline__ void fused(AccT& acc, const Unit& u, int wr, int wc, int fr, int fq, LAS unsigned char* lx, int tid) const {
;     ...
;         if (tid < 64) {
;             unsigned spins = 0;
;             while ((unsigned)__builtin_amdgcn_readfirstlane(__hip_atomic_load(cnt + 64 * u.pm, __ATOMIC_RELAXED, __HIP_MEMORY_SCOPE_AGENT)) < 16u) { __builtin_amdgcn_s_sleep(2); if (++spins > (1u << 22)) break; }
;             __builtin_amdgcn_fence(__ATOMIC_ACQUIRE, "agent");
;             if (tid == 0) flag[0] = 1u;
;         }
.LBB0_108:
	s_waitcnt lgkmcnt(0)
	v_mov_b64_e32 v[4:5], s[16:17]
	global_load_dword v4, v[4:5], off sc1
	s_mov_b64 s[24:25], -1
	s_waitcnt vmcnt(0) lgkmcnt(0)
	v_readfirstlane_b32 s3, v4
	s_cmp_gt_u32 s3, 15
	s_cbranch_scc1 .LBB0_107
	v_mov_b64_e32 v[4:5], s[16:17]
	s_sleep 2
	global_load_dword v4, v[4:5], off sc1
	s_waitcnt vmcnt(0) lgkmcnt(0)
	v_readfirstlane_b32 s3, v4
	s_cmp_lt_u32 s3, 16
	s_cbranch_scc0 .LBB0_107
	v_mov_b64_e32 v[4:5], s[16:17]
	s_sleep 2
	global_load_dword v4, v[4:5], off sc1
	s_waitcnt vmcnt(0) lgkmcnt(0)
	v_readfirstlane_b32 s3, v4
	s_cmp_lt_u32 s3, 16
	s_cbranch_scc0 .LBB0_107
	v_mov_b64_e32 v[4:5], s[16:17]
	s_sleep 2
	global_load_dword v4, v[4:5], off sc1
	s_waitcnt vmcnt(0) lgkmcnt(0)
	v_readfirstlane_b32 s3, v4
	s_cmp_lt_u32 s3, 16
	s_cbranch_scc0 .LBB0_107
	v_mov_b64_e32 v[4:5], s[16:17]
	s_sleep 2
	global_load_dword v4, v[4:5], off sc1
	s_waitcnt vmcnt(0) lgkmcnt(0)
	v_readfirstlane_b32 s3, v4
	s_cmp_lt_u32 s3, 16
	s_cbranch_scc0 .LBB0_107
	s_add_i32 s2, s2, -5
	s_cmp_eq_u32 s2, 0
	s_cselect_b64 s[24:25], -1, 0
	s_sleep 2
	s_branch .LBB0_107

;     __device__ __forceinline__ void fused(AccT& acc, const Unit& u, int wr, int wc, int fr, int fq, LAS unsigned char* lx, int tid) const {
;     ...
;         if (tid < 256) {
;             const unsigned long long* slot = xbuf + (size_t)(u.pm * 256 + tid) * 4; float S1 = 0.f, S2 = 0.f;
; #pragma unroll
;             for (int t = 0; t < 4; ++t) { const unsigned long long w = __hip_atomic_load(slot + t, __ATOMIC_RELAXED, __HIP_MEMORY_SCOPE_AGENT); S1 += __uint_as_float((unsigned)w); S2 += __uint_as_float((unsigned)(w >> 32)); }
;             const float mean = S1 * (1.0f / DM), var = fmaxf(S2 * (1.0f / DM) - mean * mean, 0.f);
;             Sx[tid] = (f32x2){mean, 1.0f / sqrtf(var + LN_EPS)};
;         }
.LBB0_116:
	s_or_b64 exec, exec, s[10:11]
	s_waitcnt vmcnt(0) lgkmcnt(0)
	s_barrier
	s_and_saveexec_b64 s[10:11], s[0:1]
	s_cbranch_execz .LBB0_118
	v_readlane_b32 s0, v255, 17
	v_lshlrev_b64 v[2:3], 5, v[2:3]
	v_readlane_b32 s1, v255, 18
	s_nop 1
	v_lshl_add_u64 v[2:3], s[0:1], 0, v[2:3]
	s_waitcnt lgkmcnt(0)
	global_load_dwordx2 v[4:5], v[2:3], off sc1
	global_load_dwordx2 v[8:9], v[2:3], off offset:8 sc1
	global_load_dwordx2 v[10:11], v[2:3], off offset:16 sc1
	global_load_dwordx2 v[12:13], v[2:3], off offset:24 sc1
	s_mov_b32 s0, 0x3a800000
	s_waitcnt vmcnt(0) lgkmcnt(0)
	v_add_f32_e32 v6, 0, v4
	v_add_f32_e32 v7, 0, v5
	v_add_f32_e32 v6, v6, v8
	v_add_f32_e32 v7, v7, v9
	v_add_f32_e32 v4, v6, v10
	v_add_f32_e32 v5, v7, v11
	v_add_f32_e32 v2, v4, v12
	v_mul_f32_e32 v2, 0x3a800000, v2
	v_add_f32_e32 v3, v5, v13
	v_mul_f32_e32 v4, v2, v2
	v_fma_f32 v3, v3, s0, -v4
	v_max_f32_e32 v3, 0, v3
	v_add_f32_e32 v3, 0x3727c5ac, v3
	s_mov_b32 s0, 0xf800000
	v_cmp_gt_f32_e32 vcc, s0, v3
	v_mul_f32_e32 v4, 0x4f800000, v3
	s_nop 0
	v_cndmask_b32_e32 v3, v3, v4, vcc
	v_sqrt_f32_e32 v4, v3
	s_nop 0
	v_add_u32_e32 v5, -1, v4
	v_fma_f32 v6, -v5, v4, v3
	v_cmp_ge_f32_e64 s[0:1], 0, v6
	v_add_u32_e32 v6, 1, v4
	s_nop 0
	v_cndmask_b32_e64 v5, v4, v5, s[0:1]
	v_fma_f32 v4, -v6, v4, v3
	v_cmp_lt_f32_e64 s[0:1], 0, v4
	s_nop 1
	v_cndmask_b32_e64 v4, v5, v6, s[0:1]
	v_mul_f32_e32 v5, 0x37800000, v4
	v_cndmask_b32_e32 v4, v4, v5, vcc
	v_cmp_class_f32_e32 vcc, v3, v232
	s_nop 1
	v_cndmask_b32_e32 v3, v4, v3, vcc
	v_div_scale_f32 v4, s[0:1], v3, v3, 1.0
	v_rcp_f32_e32 v5, v4
	s_nop 0
	v_fma_f32 v6, -v4, v5, 1.0
	v_fmac_f32_e32 v5, v6, v5
	v_div_scale_f32 v6, vcc, 1.0, v3, 1.0
	v_mul_f32_e32 v7, v6, v5
	v_fma_f32 v8, -v4, v7, v6
	v_fmac_f32_e32 v7, v8, v5
	v_fma_f32 v4, -v4, v7, v6
	v_div_fmas_f32 v4, v4, v5, v7
	v_div_fixup_f32 v3, v4, v3, 1.0
	v_lshl_add_u32 v4, v239, 3, 0
	v_add_u32_e32 v4, 0x22000, v4
	ds_write_b64 v4, v[2:3]

; __device__ __forceinline__ float sumsq4(f32x4 x) { return (x[0] * x[0] + x[1] * x[1]) + (x[2] * x[2] + x[3] * x[3]); }
;     __device__ __forceinline__ void fused(AccT& acc, const Unit& u, int wr, int wc, int fr, int fq, LAS unsigned char* lx, int tid) const {
;     ...
;                 const int row = EPI_ROW(u, ai, m); float s1 = 0.f, s2 = 0.f;
; #pragma unroll
;                 for (int bj = 0; bj < 2; ++bj) {
;                     const half8 rv = *(const half8*)(res + (size_t)row * DM + EPI_COL(u, bj));
; #pragma unroll
;                     for (int e = 0; e < 4; ++e) { acc[ai][bj][m][0][e] += ALPHA * (float)rv[e]; acc[ai][bj][m][1][e] += ALPHA * (float)rv[4 + e]; }
;                     const f32x4 a0 = acc[ai][bj][m][0], a1 = acc[ai][bj][m][1];
;                     s1 += ((a0[0] + a0[1]) + (a0[2] + a0[3])) + ((a1[0] + a1[1]) + (a1[2] + a1[3])); s2 += sumsq4(a0) + sumsq4(a1);
;                 }
;                 s1 += __shfl_xor(s1, 16); s1 += __shfl_xor(s1, 32); s2 += __shfl_xor(s2, 16); s2 += __shfl_xor(s2, 32);
;                 if (fq == 0) P[(ai * 128 + wr * 64 + m * 16 + fr) * 4 + wc] = (f32x2){s1, s2};
.LBB0_161:
	v_mov_b32_e32 v239, v216
	s_lshl_b32 s0, s10, 8
	v_bfe_u32 v141, v239, 6, 2
	v_bfe_u32 v143, v239, 4, 2
	v_lshlrev_b32_e32 v142, 5, v141
	v_lshlrev_b32_e32 v144, 3, v143
	v_and_b32_e32 v145, 64, v237
	v_or3_b32 v142, v142, s0, v144
	v_xor_b32_e32 v144, 16, v237
	v_add_u32_e32 v145, 64, v145
	v_ashrrev_i32_e32 v140, 2, v239
	v_cmp_lt_i32_e32 vcc, v144, v145
	s_lshl_b32 s11, s53, 8
	v_and_b32_e32 v238, 0xffffffc0, v140
	v_cndmask_b32_e32 v144, v237, v144, vcc
	v_and_b32_e32 v229, 15, v239
	v_add_u32_e32 v140, s11, v238
	v_lshlrev_b32_e32 v241, 2, v144
	v_xor_b32_e32 v144, 32, v237
	v_or_b32_e32 v140, v140, v229
	v_cmp_lt_i32_e32 vcc, v144, v145
	v_readlane_b32 s0, v253, 5
	v_mov_b32_e32 v164, v118
	v_cndmask_b32_e32 v144, v237, v144, vcc
	v_lshl_add_u32 v154, v141, 3, s0
	v_ashrrev_i32_e32 v141, 31, v140
	v_readlane_b32 s0, v255, 2
	v_lshlrev_b32_e32 v240, 2, v144
	v_lshlrev_b64 v[144:145], 11, v[140:141]
	v_readlane_b32 s1, v255, 3
	v_cmp_eq_u32_e32 vcc, 0, v143
	v_ashrrev_i32_e32 v143, 31, v142
	v_lshl_add_u64 v[144:145], s[0:1], 0, v[144:145]
	v_lshl_add_u64 v[144:145], v[142:143], 1, v[144:145]
	global_load_dwordx4 v[148:151], v[144:145], off
	global_load_dwordx4 v[156:159], v[144:145], off offset:256
	s_mov_b32 s0, 0x3fd744fd
	v_pk_mov_b32 v[118:119], v[118:119], v[116:117] op_sel:[1,0]
	v_mov_b32_e32 v165, v116
	v_mov_b32_e32 v116, v120
	v_or_b32_e32 v155, v238, v229
	s_waitcnt vmcnt(0) lgkmcnt(0)
	v_cvt_f32_f16_sdwa v162, v150 dst_sel:DWORD dst_unused:UNUSED_PAD src0_sel:WORD_1
	v_cvt_f32_f16_e32 v144, v158
	v_cvt_f32_f16_sdwa v145, v158 dst_sel:DWORD dst_unused:UNUSED_PAD src0_sel:WORD_1
	v_cvt_f32_f16_sdwa v158, v148 dst_sel:DWORD dst_unused:UNUSED_PAD src0_sel:WORD_1
	v_pk_fma_f32 v[126:127], v[144:145], s[0:1], v[126:127] op_sel_hi:[1,0,1]
	v_cvt_f32_f16_e32 v144, v159
	v_cvt_f32_f16_sdwa v145, v159 dst_sel:DWORD dst_unused:UNUSED_PAD src0_sel:WORD_1
	v_mov_b32_e32 v146, v127
	v_pk_fma_f32 v[128:129], v[144:145], s[0:1], v[128:129] op_sel_hi:[1,0,1]
	s_nop 0
	v_mov_b32_e32 v147, v129
	v_mov_b32_e32 v144, v126
	v_mov_b32_e32 v145, v128
	v_pk_mul_f32 v[146:147], v[146:147], v[146:147]
	s_nop 0
	v_pk_fma_f32 v[144:145], v[144:145], v[144:145], v[146:147]
	v_mov_b32_e32 v146, v122
	v_pk_add_f32 v[152:153], v[144:145], v[144:145] op_sel_hi:[0,1]
	v_cvt_f32_f16_e32 v145, v156
	v_cvt_f32_f16_e32 v144, v148
	v_mov_b32_e32 v147, v114
	v_pk_mov_b32 v[122:123], v[122:123], v[114:115] op_sel:[1,0]
	v_mov_b32_e32 v159, v145
	v_pk_fma_f32 v[144:145], v[144:145], s[0:1], v[146:147] op_sel_hi:[1,0,1]
	v_cvt_f32_f16_e32 v147, v157
	v_pk_fma_f32 v[122:123], v[158:159], s[0:1], v[122:123] op_sel_hi:[1,0,1]
	v_cvt_f32_f16_e32 v158, v149
	v_cvt_f32_f16_sdwa v159, v156 dst_sel:DWORD dst_unused:UNUSED_PAD src0_sel:WORD_1
	v_mov_b32_e32 v163, v147
	v_pk_fma_f32 v[118:119], v[162:163], s[0:1], v[118:119] op_sel_hi:[1,0,1]
	v_cvt_f32_f16_sdwa v162, v149 dst_sel:DWORD dst_unused:UNUSED_PAD src0_sel:WORD_1
	v_mov_b32_e32 v114, v124
	v_cvt_f32_f16_e32 v156, v151
	v_cvt_f32_f16_sdwa v157, v157 dst_sel:DWORD dst_unused:UNUSED_PAD src0_sel:WORD_1
	v_cvt_f32_f16_e32 v146, v150
	v_pk_fma_f32 v[148:149], v[158:159], s[0:1], v[114:115] op_sel_hi:[1,0,1]
	v_cvt_f32_f16_sdwa v158, v151 dst_sel:DWORD dst_unused:UNUSED_PAD src0_sel:WORD_1
	v_mov_b32_e32 v163, v159
	v_mov_b32_e32 v114, v125
	v_mov_b32_e32 v159, v157
	v_pk_fma_f32 v[150:151], v[156:157], s[0:1], v[116:117] op_sel_hi:[1,0,1]
	v_pk_fma_f32 v[114:115], v[162:163], s[0:1], v[114:115] op_sel_hi:[1,0,1]
	v_mov_b32_e32 v116, v121
	v_pk_mul_f32 v[120:121], v[144:145], v[144:145]
	v_pk_mul_f32 v[124:125], v[122:123], v[122:123]
	v_pk_fma_f32 v[146:147], v[146:147], s[0:1], v[164:165] op_sel_hi:[1,0,1]
	v_pk_fma_f32 v[116:117], v[158:159], s[0:1], v[116:117] op_sel_hi:[1,0,1]
	v_pk_mul_f32 v[156:157], v[148:149], v[148:149]
	v_pk_mul_f32 v[158:159], v[114:115], v[114:115]
	v_pk_mov_b32 v[120:121], v[144:145], v[120:121] op_sel:[1,0]
	v_pk_mov_b32 v[124:125], v[148:149], v[124:125] op_sel:[1,0]
	v_pk_mul_f32 v[162:163], v[146:147], v[146:147]
	v_pk_add_f32 v[120:121], v[120:121], v[124:125]
	v_pk_mov_b32 v[124:125], v[146:147], v[156:157] op_sel:[1,0]
	v_pk_mov_b32 v[156:157], v[150:151], v[158:159] op_sel:[1,0]
	v_pk_mul_f32 v[164:165], v[118:119], v[118:119]
	v_pk_add_f32 v[124:125], v[124:125], v[156:157]
	v_pk_mul_f32 v[166:167], v[150:151], v[150:151]
	v_pk_mul_f32 v[168:169], v[116:117], v[116:117]
	v_pk_add_f32 v[120:121], v[120:121], v[124:125]
	v_mov_b32_e32 v124, v126
	v_mov_b32_e32 v125, v162
	v_pk_mov_b32 v[156:157], v[126:127], v[164:165] op_sel:[1,0]
	v_pk_mov_b32 v[158:159], v[128:129], v[168:169] op_sel:[1,0]
	v_pk_add_f32 v[124:125], v[124:125], v[156:157]
	v_mov_b32_e32 v156, v128
	v_mov_b32_e32 v157, v166
	v_pk_add_f32 v[156:157], v[156:157], v[158:159]
	v_pk_mul_f32 v[158:159], v[148:149], v[114:115]
	v_pk_add_f32 v[124:125], v[124:125], v[156:157]
	v_pk_mul_f32 v[156:157], v[144:145], v[122:123]
	v_pk_add_f32 v[120:121], v[120:121], v[124:125]
	v_pk_add_f32 v[124:125], v[144:145], v[122:123]
	v_pk_mul_f32 v[162:163], v[150:151], v[116:117]
	v_mov_b32_e32 v125, v157
	v_pk_add_f32 v[156:157], v[148:149], v[114:115]
	v_mov_b32_e32 v152, v1
	v_mov_b32_e32 v157, v159
	v_pk_add_f32 v[124:125], v[124:125], v[156:157]
	v_pk_add_f32 v[156:157], v[146:147], v[118:119]
	v_pk_mul_f32 v[158:159], v[146:147], v[118:119]
	v_lshl_add_u32 v115, v155, 5, v154
	v_mov_b32_e32 v157, v159
	v_pk_add_f32 v[158:159], v[150:151], v[116:117]
	s_nop 0
	v_mov_b32_e32 v159, v163
	v_pk_add_f32 v[156:157], v[156:157], v[158:159]
	s_nop 0
	v_pk_add_f32 v[124:125], v[124:125], v[156:157]
	s_nop 0
	v_pk_add_f32 v[124:125], v[124:125], v[152:153]
	s_nop 0
	v_pk_add_f32 v[120:121], v[120:121], v[124:125]
	ds_bpermute_b32 v124, v241, v120
	ds_bpermute_b32 v125, v241, v121
	s_waitcnt lgkmcnt(0)
	v_pk_add_f32 v[120:121], v[120:121], v[124:125]
	ds_bpermute_b32 v124, v240, v120
	ds_bpermute_b32 v125, v240, v121
	s_and_saveexec_b64 s[0:1], vcc
	s_cbranch_execz .LBB0_163
	s_waitcnt lgkmcnt(0)
	v_pk_add_f32 v[120:121], v[120:121], v[124:125]
	ds_write_b64 v115, v[120:121]
; __device__ __forceinline__ float sumsq4(f32x4 x) { return (x[0] * x[0] + x[1] * x[1]) + (x[2] * x[2] + x[3] * x[3]); }
;     __device__ __forceinline__ void fused(AccT& acc, const Unit& u, int wr, int wc, int fr, int fq, LAS unsigned char* lx, int tid) const {
;     ...
;                 const int row = EPI_ROW(u, ai, m); float s1 = 0.f, s2 = 0.f;
; #pragma unroll
;                 for (int bj = 0; bj < 2; ++bj) {
;                     const half8 rv = *(const half8*)(res + (size_t)row * DM + EPI_COL(u, bj));
; #pragma unroll
;                     for (int e = 0; e < 4; ++e) { acc[ai][bj][m][0][e] += ALPHA * (float)rv[e]; acc[ai][bj][m][1][e] += ALPHA * (float)rv[4 + e]; }
;                     const f32x4 a0 = acc[ai][bj][m][0], a1 = acc[ai][bj][m][1];
;                     s1 += ((a0[0] + a0[1]) + (a0[2] + a0[3])) + ((a1[0] + a1[1]) + (a1[2] + a1[3])); s2 += sumsq4(a0) + sumsq4(a1);
;                 }
;                 s1 += __shfl_xor(s1, 16); s1 += __shfl_xor(s1, 32); s2 += __shfl_xor(s2, 16); s2 += __shfl_xor(s2, 32);
;                 if (fq == 0) P[(ai * 128 + wr * 64 + m * 16 + fr) * 4 + wc] = (f32x2){s1, s2};
.LBB0_163:
	s_or_b64 exec, exec, s[0:1]
	v_or_b32_e32 v120, 16, v140
	v_ashrrev_i32_e32 v121, 31, v120
	v_readlane_b32 s0, v255, 2
	s_waitcnt lgkmcnt(0)
	v_lshlrev_b64 v[124:125], 11, v[120:121]
	v_readlane_b32 s1, v255, 3
	v_mov_b32_e32 v168, v102
	v_pk_mov_b32 v[102:103], v[102:103], v[100:101] op_sel:[1,0]
	v_lshl_add_u64 v[124:125], s[0:1], 0, v[124:125]
	v_lshl_add_u64 v[124:125], v[142:143], 1, v[124:125]
	global_load_dwordx4 v[154:157], v[124:125], off
	global_load_dwordx4 v[162:165], v[124:125], off offset:256
	s_mov_b32 s0, 0x3fd744fd
	v_mov_b32_e32 v169, v100
	v_mov_b32_e32 v100, v104
	s_waitcnt vmcnt(0) lgkmcnt(0)
	v_cvt_f32_f16_sdwa v166, v156 dst_sel:DWORD dst_unused:UNUSED_PAD src0_sel:WORD_1
	v_cvt_f32_f16_e32 v124, v164
	v_cvt_f32_f16_sdwa v125, v164 dst_sel:DWORD dst_unused:UNUSED_PAD src0_sel:WORD_1
	v_cvt_f32_f16_sdwa v164, v154 dst_sel:DWORD dst_unused:UNUSED_PAD src0_sel:WORD_1
	v_pk_fma_f32 v[110:111], v[124:125], s[0:1], v[110:111] op_sel_hi:[1,0,1]
	v_cvt_f32_f16_e32 v124, v165
	v_cvt_f32_f16_sdwa v125, v165 dst_sel:DWORD dst_unused:UNUSED_PAD src0_sel:WORD_1
	v_mov_b32_e32 v152, v111
	v_pk_fma_f32 v[112:113], v[124:125], s[0:1], v[112:113] op_sel_hi:[1,0,1]
	s_nop 0
	v_mov_b32_e32 v153, v113
	v_mov_b32_e32 v124, v110
	v_mov_b32_e32 v125, v112
	v_pk_mul_f32 v[152:153], v[152:153], v[152:153]
	s_nop 0
	v_pk_fma_f32 v[124:125], v[124:125], v[124:125], v[152:153]
	v_mov_b32_e32 v152, v106
	v_pk_add_f32 v[158:159], v[124:125], v[124:125] op_sel_hi:[0,1]
	v_cvt_f32_f16_e32 v125, v162
	v_cvt_f32_f16_e32 v124, v154
	v_mov_b32_e32 v153, v98
	v_pk_mov_b32 v[106:107], v[106:107], v[98:99] op_sel:[1,0]
	v_mov_b32_e32 v165, v125
	v_pk_fma_f32 v[124:125], v[124:125], s[0:1], v[152:153] op_sel_hi:[1,0,1]
	v_cvt_f32_f16_e32 v153, v163
	v_pk_fma_f32 v[106:107], v[164:165], s[0:1], v[106:107] op_sel_hi:[1,0,1]
	v_cvt_f32_f16_e32 v164, v155
	v_cvt_f32_f16_sdwa v165, v162 dst_sel:DWORD dst_unused:UNUSED_PAD src0_sel:WORD_1
	v_mov_b32_e32 v167, v153
	v_pk_fma_f32 v[102:103], v[166:167], s[0:1], v[102:103] op_sel_hi:[1,0,1]
	v_cvt_f32_f16_sdwa v166, v155 dst_sel:DWORD dst_unused:UNUSED_PAD src0_sel:WORD_1
	v_mov_b32_e32 v98, v108
	v_cvt_f32_f16_e32 v162, v157
	v_cvt_f32_f16_sdwa v163, v163 dst_sel:DWORD dst_unused:UNUSED_PAD src0_sel:WORD_1
	v_cvt_f32_f16_e32 v152, v156
	v_pk_fma_f32 v[154:155], v[164:165], s[0:1], v[98:99] op_sel_hi:[1,0,1]
	v_cvt_f32_f16_sdwa v164, v157 dst_sel:DWORD dst_unused:UNUSED_PAD src0_sel:WORD_1
	v_mov_b32_e32 v167, v165
	v_mov_b32_e32 v98, v109
	v_mov_b32_e32 v165, v163
	v_pk_fma_f32 v[156:157], v[162:163], s[0:1], v[100:101] op_sel_hi:[1,0,1]
	v_pk_fma_f32 v[98:99], v[166:167], s[0:1], v[98:99] op_sel_hi:[1,0,1]
	v_mov_b32_e32 v100, v105
	v_pk_mul_f32 v[104:105], v[124:125], v[124:125]
	v_pk_mul_f32 v[108:109], v[106:107], v[106:107]
	v_pk_fma_f32 v[152:153], v[152:153], s[0:1], v[168:169] op_sel_hi:[1,0,1]
	v_pk_fma_f32 v[100:101], v[164:165], s[0:1], v[100:101] op_sel_hi:[1,0,1]
	v_pk_mul_f32 v[162:163], v[154:155], v[154:155]
	v_pk_mul_f32 v[164:165], v[98:99], v[98:99]
	v_pk_mov_b32 v[104:105], v[124:125], v[104:105] op_sel:[1,0]
	v_pk_mov_b32 v[108:109], v[154:155], v[108:109] op_sel:[1,0]
	v_pk_mul_f32 v[166:167], v[152:153], v[152:153]
	v_pk_add_f32 v[104:105], v[104:105], v[108:109]
	v_pk_mov_b32 v[108:109], v[152:153], v[162:163] op_sel:[1,0]
	v_pk_mov_b32 v[162:163], v[156:157], v[164:165] op_sel:[1,0]
	v_pk_mul_f32 v[168:169], v[102:103], v[102:103]
	v_pk_add_f32 v[108:109], v[108:109], v[162:163]
	v_pk_mul_f32 v[170:171], v[156:157], v[156:157]
	v_pk_mul_f32 v[172:173], v[100:101], v[100:101]
	v_pk_add_f32 v[104:105], v[104:105], v[108:109]
	v_mov_b32_e32 v108, v110
	v_mov_b32_e32 v109, v166
	v_pk_mov_b32 v[162:163], v[110:111], v[168:169] op_sel:[1,0]
	v_pk_mov_b32 v[164:165], v[112:113], v[172:173] op_sel:[1,0]
	v_pk_add_f32 v[108:109], v[108:109], v[162:163]
	v_mov_b32_e32 v162, v112
	v_mov_b32_e32 v163, v170
	v_pk_add_f32 v[162:163], v[162:163], v[164:165]
	v_pk_mul_f32 v[164:165], v[154:155], v[98:99]
	v_pk_add_f32 v[108:109], v[108:109], v[162:163]
	v_pk_mul_f32 v[162:163], v[124:125], v[106:107]
	v_pk_add_f32 v[104:105], v[104:105], v[108:109]
	v_pk_add_f32 v[108:109], v[124:125], v[106:107]
	v_pk_mul_f32 v[166:167], v[156:157], v[100:101]
	v_mov_b32_e32 v109, v163
	v_pk_add_f32 v[162:163], v[154:155], v[98:99]
	v_mov_b32_e32 v158, v1
	v_mov_b32_e32 v163, v165
	v_pk_add_f32 v[108:109], v[108:109], v[162:163]
	v_pk_add_f32 v[162:163], v[152:153], v[102:103]
	v_pk_mul_f32 v[164:165], v[152:153], v[102:103]
	s_nop 0
	v_mov_b32_e32 v163, v165
	v_pk_add_f32 v[164:165], v[156:157], v[100:101]
	s_nop 0
	v_mov_b32_e32 v165, v167
	v_pk_add_f32 v[162:163], v[162:163], v[164:165]
	s_nop 0
	v_pk_add_f32 v[108:109], v[108:109], v[162:163]
	s_nop 0
	v_pk_add_f32 v[108:109], v[108:109], v[158:159]
	s_nop 0
	v_pk_add_f32 v[104:105], v[104:105], v[108:109]
	ds_bpermute_b32 v108, v241, v104
	ds_bpermute_b32 v109, v241, v105
	s_waitcnt lgkmcnt(0)
	v_pk_add_f32 v[104:105], v[104:105], v[108:109]
	ds_bpermute_b32 v108, v240, v104
	ds_bpermute_b32 v109, v240, v105
	s_and_saveexec_b64 s[0:1], vcc
	s_cbranch_execz .LBB0_165
	s_waitcnt lgkmcnt(0)
	v_pk_add_f32 v[104:105], v[104:105], v[108:109]
	ds_write_b64 v115, v[104:105] offset:512
; __device__ __forceinline__ float sumsq4(f32x4 x) { return (x[0] * x[0] + x[1] * x[1]) + (x[2] * x[2] + x[3] * x[3]); }
;     __device__ __forceinline__ void fused(AccT& acc, const Unit& u, int wr, int wc, int fr, int fq, LAS unsigned char* lx, int tid) const {
;     ...
;                 const int row = EPI_ROW(u, ai, m); float s1 = 0.f, s2 = 0.f;
; #pragma unroll
;                 for (int bj = 0; bj < 2; ++bj) {
;                     const half8 rv = *(const half8*)(res + (size_t)row * DM + EPI_COL(u, bj));
; #pragma unroll
;                     for (int e = 0; e < 4; ++e) { acc[ai][bj][m][0][e] += ALPHA * (float)rv[e]; acc[ai][bj][m][1][e] += ALPHA * (float)rv[4 + e]; }
;                     const f32x4 a0 = acc[ai][bj][m][0], a1 = acc[ai][bj][m][1];
;                     s1 += ((a0[0] + a0[1]) + (a0[2] + a0[3])) + ((a1[0] + a1[1]) + (a1[2] + a1[3])); s2 += sumsq4(a0) + sumsq4(a1);
;                 }
;                 s1 += __shfl_xor(s1, 16); s1 += __shfl_xor(s1, 32); s2 += __shfl_xor(s2, 16); s2 += __shfl_xor(s2, 32);
;                 if (fq == 0) P[(ai * 128 + wr * 64 + m * 16 + fr) * 4 + wc] = (f32x2){s1, s2};
.LBB0_165:
	s_or_b64 exec, exec, s[0:1]
	v_or_b32_e32 v104, 32, v140
	v_ashrrev_i32_e32 v105, 31, v104
	v_readlane_b32 s0, v255, 2
	s_waitcnt lgkmcnt(0)
	v_lshlrev_b64 v[108:109], 11, v[104:105]
	v_readlane_b32 s1, v255, 3
	v_mov_b32_e32 v174, v86
	v_mov_b32_e32 v175, v84
	v_lshl_add_u64 v[108:109], s[0:1], 0, v[108:109]
	v_lshl_add_u64 v[108:109], v[142:143], 1, v[108:109]
	global_load_dwordx4 v[168:171], v[108:109], off
	global_load_dwordx4 v[164:167], v[108:109], off offset:256
	s_mov_b32 s0, 0x3fd744fd
	v_pk_mov_b32 v[86:87], v[86:87], v[84:85] op_sel:[1,0]
	v_mov_b32_e32 v84, v88
	s_waitcnt vmcnt(0) lgkmcnt(0)
	v_cvt_f32_f16_sdwa v162, v168 dst_sel:DWORD dst_unused:UNUSED_PAD src0_sel:WORD_1
	v_cvt_f32_f16_e32 v108, v166
	v_cvt_f32_f16_sdwa v109, v166 dst_sel:DWORD dst_unused:UNUSED_PAD src0_sel:WORD_1
	v_cvt_f32_f16_sdwa v172, v170 dst_sel:DWORD dst_unused:UNUSED_PAD src0_sel:WORD_1
	v_pk_fma_f32 v[94:95], v[108:109], s[0:1], v[94:95] op_sel_hi:[1,0,1]
	v_cvt_f32_f16_e32 v108, v167
	v_cvt_f32_f16_sdwa v109, v167 dst_sel:DWORD dst_unused:UNUSED_PAD src0_sel:WORD_1
	v_mov_b32_e32 v158, v95
	v_pk_fma_f32 v[96:97], v[108:109], s[0:1], v[96:97] op_sel_hi:[1,0,1]
	s_nop 0
	v_mov_b32_e32 v159, v97
	v_mov_b32_e32 v108, v94
	v_mov_b32_e32 v109, v96
	v_pk_mul_f32 v[158:159], v[158:159], v[158:159]
	s_nop 0
	v_pk_fma_f32 v[108:109], v[108:109], v[108:109], v[158:159]
	v_mov_b32_e32 v158, v90
	v_pk_add_f32 v[166:167], v[108:109], v[108:109] op_sel_hi:[0,1]
	v_cvt_f32_f16_e32 v109, v164
	v_cvt_f32_f16_e32 v108, v168
	v_pk_mov_b32 v[90:91], v[90:91], v[82:83] op_sel:[1,0]
	v_mov_b32_e32 v159, v82
	v_mov_b32_e32 v163, v109
	v_pk_fma_f32 v[162:163], v[162:163], s[0:1], v[90:91] op_sel_hi:[1,0,1]
	v_cvt_f32_f16_e32 v90, v169
	v_cvt_f32_f16_sdwa v91, v164 dst_sel:DWORD dst_unused:UNUSED_PAD src0_sel:WORD_1
	v_pk_fma_f32 v[108:109], v[108:109], s[0:1], v[158:159] op_sel_hi:[1,0,1]
	v_cvt_f32_f16_e32 v159, v165
	v_cvt_f32_f16_sdwa v168, v169 dst_sel:DWORD dst_unused:UNUSED_PAD src0_sel:WORD_1
	v_cvt_f32_f16_e32 v164, v171
	v_cvt_f32_f16_sdwa v165, v165 dst_sel:DWORD dst_unused:UNUSED_PAD src0_sel:WORD_1
	v_cvt_f32_f16_e32 v158, v170
	v_cvt_f32_f16_sdwa v170, v171 dst_sel:DWORD dst_unused:UNUSED_PAD src0_sel:WORD_1
	v_mov_b32_e32 v82, v92
	v_mov_b32_e32 v169, v91
	v_pk_fma_f32 v[90:91], v[90:91], s[0:1], v[82:83] op_sel_hi:[1,0,1]
	v_mov_b32_e32 v82, v93
	v_mov_b32_e32 v171, v165
	v_pk_fma_f32 v[164:165], v[164:165], s[0:1], v[84:85] op_sel_hi:[1,0,1]
	v_pk_fma_f32 v[82:83], v[168:169], s[0:1], v[82:83] op_sel_hi:[1,0,1]
	v_mov_b32_e32 v84, v89
	v_pk_mul_f32 v[88:89], v[108:109], v[108:109]
	v_pk_mul_f32 v[92:93], v[162:163], v[162:163]
	v_mov_b32_e32 v173, v159
	v_pk_fma_f32 v[158:159], v[158:159], s[0:1], v[174:175] op_sel_hi:[1,0,1]
	v_pk_fma_f32 v[84:85], v[170:171], s[0:1], v[84:85] op_sel_hi:[1,0,1]
	v_pk_mul_f32 v[168:169], v[90:91], v[90:91]
	v_pk_mul_f32 v[170:171], v[82:83], v[82:83]
	v_pk_mov_b32 v[88:89], v[108:109], v[88:89] op_sel:[1,0]
	v_pk_mov_b32 v[92:93], v[90:91], v[92:93] op_sel:[1,0]
	v_pk_fma_f32 v[86:87], v[172:173], s[0:1], v[86:87] op_sel_hi:[1,0,1]
	v_pk_add_f32 v[88:89], v[88:89], v[92:93]
	v_pk_mov_b32 v[92:93], v[158:159], v[168:169] op_sel:[1,0]
	v_pk_mov_b32 v[168:169], v[164:165], v[170:171] op_sel:[1,0]
	v_pk_mul_f32 v[172:173], v[158:159], v[158:159]
	v_pk_mul_f32 v[174:175], v[86:87], v[86:87]
	v_pk_add_f32 v[92:93], v[92:93], v[168:169]
	v_pk_mul_f32 v[176:177], v[164:165], v[164:165]
	v_pk_mul_f32 v[178:179], v[84:85], v[84:85]
	v_pk_add_f32 v[88:89], v[88:89], v[92:93]
	v_mov_b32_e32 v92, v94
	v_mov_b32_e32 v93, v172
	v_pk_mov_b32 v[168:169], v[94:95], v[174:175] op_sel:[1,0]
	v_pk_mov_b32 v[170:171], v[96:97], v[178:179] op_sel:[1,0]
	v_pk_add_f32 v[92:93], v[92:93], v[168:169]
	v_mov_b32_e32 v168, v96
	v_mov_b32_e32 v169, v176
	v_pk_add_f32 v[168:169], v[168:169], v[170:171]
	v_pk_mul_f32 v[170:171], v[90:91], v[82:83]
	v_pk_add_f32 v[92:93], v[92:93], v[168:169]
	v_pk_mul_f32 v[168:169], v[108:109], v[162:163]
	v_pk_add_f32 v[88:89], v[88:89], v[92:93]
	v_pk_add_f32 v[92:93], v[108:109], v[162:163]
	v_pk_mul_f32 v[172:173], v[164:165], v[84:85]
	v_mov_b32_e32 v93, v169
	v_pk_add_f32 v[168:169], v[90:91], v[82:83]
	v_mov_b32_e32 v166, v1
	v_mov_b32_e32 v169, v171
	v_pk_add_f32 v[92:93], v[92:93], v[168:169]
	v_pk_add_f32 v[168:169], v[158:159], v[86:87]
	v_pk_mul_f32 v[170:171], v[158:159], v[86:87]
	s_nop 0
	v_mov_b32_e32 v169, v171
	v_pk_add_f32 v[170:171], v[164:165], v[84:85]
	s_nop 0
	v_mov_b32_e32 v171, v173
	v_pk_add_f32 v[168:169], v[168:169], v[170:171]
	s_nop 0
	v_pk_add_f32 v[92:93], v[92:93], v[168:169]
	s_nop 0
	v_pk_add_f32 v[92:93], v[92:93], v[166:167]
	s_nop 0
	v_pk_add_f32 v[88:89], v[88:89], v[92:93]
	ds_bpermute_b32 v92, v241, v88
	ds_bpermute_b32 v93, v241, v89
	s_waitcnt lgkmcnt(0)
	v_pk_add_f32 v[88:89], v[88:89], v[92:93]
	ds_bpermute_b32 v92, v240, v88
	ds_bpermute_b32 v93, v240, v89
	s_and_saveexec_b64 s[0:1], vcc
	s_cbranch_execz .LBB0_167
	s_waitcnt lgkmcnt(0)
	v_pk_add_f32 v[88:89], v[88:89], v[92:93]
	ds_write_b64 v115, v[88:89] offset:1024
; __device__ __forceinline__ float sumsq4(f32x4 x) { return (x[0] * x[0] + x[1] * x[1]) + (x[2] * x[2] + x[3] * x[3]); }
;     __device__ __forceinline__ void fused(AccT& acc, const Unit& u, int wr, int wc, int fr, int fq, LAS unsigned char* lx, int tid) const {
;     ...
;                 const int row = EPI_ROW(u, ai, m); float s1 = 0.f, s2 = 0.f;
; #pragma unroll
;                 for (int bj = 0; bj < 2; ++bj) {
;                     const half8 rv = *(const half8*)(res + (size_t)row * DM + EPI_COL(u, bj));
; #pragma unroll
;                     for (int e = 0; e < 4; ++e) { acc[ai][bj][m][0][e] += ALPHA * (float)rv[e]; acc[ai][bj][m][1][e] += ALPHA * (float)rv[4 + e]; }
;                     const f32x4 a0 = acc[ai][bj][m][0], a1 = acc[ai][bj][m][1];
;                     s1 += ((a0[0] + a0[1]) + (a0[2] + a0[3])) + ((a1[0] + a1[1]) + (a1[2] + a1[3])); s2 += sumsq4(a0) + sumsq4(a1);
;                 }
;                 s1 += __shfl_xor(s1, 16); s1 += __shfl_xor(s1, 32); s2 += __shfl_xor(s2, 16); s2 += __shfl_xor(s2, 32);
;                 if (fq == 0) P[(ai * 128 + wr * 64 + m * 16 + fr) * 4 + wc] = (f32x2){s1, s2};
.LBB0_167:
	s_or_b64 exec, exec, s[0:1]
	v_or_b32_e32 v88, 48, v140
	v_ashrrev_i32_e32 v89, 31, v88
	v_readlane_b32 s0, v255, 2
	s_waitcnt lgkmcnt(0)
	v_lshlrev_b64 v[92:93], 11, v[88:89]
	v_readlane_b32 s1, v255, 3
	v_mov_b32_e32 v180, v70
	v_mov_b32_e32 v181, v68
	v_lshl_add_u64 v[92:93], s[0:1], 0, v[92:93]
	v_lshl_add_u64 v[92:93], v[142:143], 1, v[92:93]
	global_load_dwordx4 v[174:177], v[92:93], off
	global_load_dwordx4 v[170:173], v[92:93], off offset:256
	s_mov_b32 s0, 0x3fd744fd
	v_pk_mov_b32 v[70:71], v[70:71], v[68:69] op_sel:[1,0]
	v_mov_b32_e32 v68, v72
	s_waitcnt vmcnt(0) lgkmcnt(0)
	v_cvt_f32_f16_sdwa v168, v174 dst_sel:DWORD dst_unused:UNUSED_PAD src0_sel:WORD_1
	v_cvt_f32_f16_e32 v92, v172
	v_cvt_f32_f16_sdwa v93, v172 dst_sel:DWORD dst_unused:UNUSED_PAD src0_sel:WORD_1
	v_cvt_f32_f16_sdwa v178, v176 dst_sel:DWORD dst_unused:UNUSED_PAD src0_sel:WORD_1
	v_pk_fma_f32 v[78:79], v[92:93], s[0:1], v[78:79] op_sel_hi:[1,0,1]
	v_cvt_f32_f16_e32 v92, v173
	v_cvt_f32_f16_sdwa v93, v173 dst_sel:DWORD dst_unused:UNUSED_PAD src0_sel:WORD_1
	v_mov_b32_e32 v166, v79
	v_pk_fma_f32 v[80:81], v[92:93], s[0:1], v[80:81] op_sel_hi:[1,0,1]
	s_nop 0
	v_mov_b32_e32 v167, v81
	v_mov_b32_e32 v92, v78
	v_mov_b32_e32 v93, v80
	v_pk_mul_f32 v[166:167], v[166:167], v[166:167]
	s_nop 0
	v_pk_fma_f32 v[92:93], v[92:93], v[92:93], v[166:167]
	v_mov_b32_e32 v166, v74
	v_pk_add_f32 v[172:173], v[92:93], v[92:93] op_sel_hi:[0,1]
	v_cvt_f32_f16_e32 v93, v170
	v_cvt_f32_f16_e32 v92, v174
	v_pk_mov_b32 v[74:75], v[74:75], v[66:67] op_sel:[1,0]
	v_mov_b32_e32 v167, v66
	v_mov_b32_e32 v169, v93
	v_pk_fma_f32 v[168:169], v[168:169], s[0:1], v[74:75] op_sel_hi:[1,0,1]
	v_cvt_f32_f16_e32 v74, v175
	v_cvt_f32_f16_sdwa v75, v170 dst_sel:DWORD dst_unused:UNUSED_PAD src0_sel:WORD_1
	v_pk_fma_f32 v[92:93], v[92:93], s[0:1], v[166:167] op_sel_hi:[1,0,1]
	v_cvt_f32_f16_e32 v167, v171
	v_cvt_f32_f16_sdwa v174, v175 dst_sel:DWORD dst_unused:UNUSED_PAD src0_sel:WORD_1
	v_cvt_f32_f16_e32 v170, v177
	v_cvt_f32_f16_sdwa v171, v171 dst_sel:DWORD dst_unused:UNUSED_PAD src0_sel:WORD_1
	v_cvt_f32_f16_e32 v166, v176
	v_cvt_f32_f16_sdwa v176, v177 dst_sel:DWORD dst_unused:UNUSED_PAD src0_sel:WORD_1
	v_mov_b32_e32 v66, v76
	v_mov_b32_e32 v175, v75
	v_pk_fma_f32 v[74:75], v[74:75], s[0:1], v[66:67] op_sel_hi:[1,0,1]
	v_mov_b32_e32 v66, v77
	v_mov_b32_e32 v177, v171
	v_pk_fma_f32 v[170:171], v[170:171], s[0:1], v[68:69] op_sel_hi:[1,0,1]
	v_pk_fma_f32 v[66:67], v[174:175], s[0:1], v[66:67] op_sel_hi:[1,0,1]
	v_mov_b32_e32 v68, v73
	v_pk_mul_f32 v[72:73], v[92:93], v[92:93]
	v_pk_mul_f32 v[76:77], v[168:169], v[168:169]
	v_mov_b32_e32 v179, v167
	v_pk_fma_f32 v[166:167], v[166:167], s[0:1], v[180:181] op_sel_hi:[1,0,1]
	v_pk_fma_f32 v[68:69], v[176:177], s[0:1], v[68:69] op_sel_hi:[1,0,1]
	v_pk_mul_f32 v[174:175], v[74:75], v[74:75]
	v_pk_mul_f32 v[176:177], v[66:67], v[66:67]
	v_pk_mov_b32 v[72:73], v[92:93], v[72:73] op_sel:[1,0]
	v_pk_mov_b32 v[76:77], v[74:75], v[76:77] op_sel:[1,0]
	v_pk_fma_f32 v[70:71], v[178:179], s[0:1], v[70:71] op_sel_hi:[1,0,1]
	v_pk_add_f32 v[72:73], v[72:73], v[76:77]
	v_pk_mov_b32 v[76:77], v[166:167], v[174:175] op_sel:[1,0]
	v_pk_mov_b32 v[174:175], v[170:171], v[176:177] op_sel:[1,0]
	v_pk_mul_f32 v[178:179], v[166:167], v[166:167]
	v_pk_mul_f32 v[180:181], v[70:71], v[70:71]
	v_pk_add_f32 v[76:77], v[76:77], v[174:175]
	v_pk_mul_f32 v[182:183], v[170:171], v[170:171]
	v_pk_mul_f32 v[184:185], v[68:69], v[68:69]
	v_pk_add_f32 v[72:73], v[72:73], v[76:77]
	v_mov_b32_e32 v76, v78
	v_mov_b32_e32 v77, v178
	v_pk_mov_b32 v[174:175], v[78:79], v[180:181] op_sel:[1,0]
	v_pk_mov_b32 v[176:177], v[80:81], v[184:185] op_sel:[1,0]
	v_pk_add_f32 v[76:77], v[76:77], v[174:175]
	v_mov_b32_e32 v174, v80
	v_mov_b32_e32 v175, v182
	v_pk_add_f32 v[174:175], v[174:175], v[176:177]
	v_pk_mul_f32 v[176:177], v[74:75], v[66:67]
	v_pk_add_f32 v[76:77], v[76:77], v[174:175]
	v_pk_mul_f32 v[174:175], v[92:93], v[168:169]
	v_pk_add_f32 v[72:73], v[72:73], v[76:77]
	v_pk_add_f32 v[76:77], v[92:93], v[168:169]
	v_pk_mul_f32 v[178:179], v[170:171], v[68:69]
	v_mov_b32_e32 v77, v175
	v_pk_add_f32 v[174:175], v[74:75], v[66:67]
	v_mov_b32_e32 v172, v1
	v_mov_b32_e32 v175, v177
	v_pk_add_f32 v[76:77], v[76:77], v[174:175]
	v_pk_add_f32 v[174:175], v[166:167], v[70:71]
	v_pk_mul_f32 v[176:177], v[166:167], v[70:71]
	s_nop 0
	v_mov_b32_e32 v175, v177
	v_pk_add_f32 v[176:177], v[170:171], v[68:69]
	s_nop 0
	v_mov_b32_e32 v177, v179
	v_pk_add_f32 v[174:175], v[174:175], v[176:177]
	s_nop 0
	v_pk_add_f32 v[76:77], v[76:77], v[174:175]
	s_nop 0
	v_pk_add_f32 v[76:77], v[76:77], v[172:173]
	s_nop 0
	v_pk_add_f32 v[72:73], v[72:73], v[76:77]
	ds_bpermute_b32 v76, v241, v72
	ds_bpermute_b32 v77, v241, v73
	s_waitcnt lgkmcnt(0)
	v_pk_add_f32 v[72:73], v[72:73], v[76:77]
	ds_bpermute_b32 v76, v240, v72
	ds_bpermute_b32 v77, v240, v73
	s_and_saveexec_b64 s[0:1], vcc
	s_cbranch_execz .LBB0_169
	s_waitcnt lgkmcnt(0)
	v_pk_add_f32 v[72:73], v[72:73], v[76:77]
	ds_write_b64 v115, v[72:73] offset:1536
; __device__ __forceinline__ float sumsq4(f32x4 x) { return (x[0] * x[0] + x[1] * x[1]) + (x[2] * x[2] + x[3] * x[3]); }
;     __device__ __forceinline__ void fused(AccT& acc, const Unit& u, int wr, int wc, int fr, int fq, LAS unsigned char* lx, int tid) const {
;     ...
;                 const int row = EPI_ROW(u, ai, m); float s1 = 0.f, s2 = 0.f;
; #pragma unroll
;                 for (int bj = 0; bj < 2; ++bj) {
;                     const half8 rv = *(const half8*)(res + (size_t)row * DM + EPI_COL(u, bj));
; #pragma unroll
;                     for (int e = 0; e < 4; ++e) { acc[ai][bj][m][0][e] += ALPHA * (float)rv[e]; acc[ai][bj][m][1][e] += ALPHA * (float)rv[4 + e]; }
;                     const f32x4 a0 = acc[ai][bj][m][0], a1 = acc[ai][bj][m][1];
;                     s1 += ((a0[0] + a0[1]) + (a0[2] + a0[3])) + ((a1[0] + a1[1]) + (a1[2] + a1[3])); s2 += sumsq4(a0) + sumsq4(a1);
;                 }
;                 s1 += __shfl_xor(s1, 16); s1 += __shfl_xor(s1, 32); s2 += __shfl_xor(s2, 16); s2 += __shfl_xor(s2, 32);
;                 if (fq == 0) P[(ai * 128 + wr * 64 + m * 16 + fr) * 4 + wc] = (f32x2){s1, s2};
.LBB0_169:
	s_or_b64 exec, exec, s[0:1]
	v_add_u32_e32 v72, 0x80, v140
	v_ashrrev_i32_e32 v73, 31, v72
	v_readlane_b32 s0, v255, 2
	s_waitcnt lgkmcnt(0)
	v_lshlrev_b64 v[76:77], 11, v[72:73]
	v_readlane_b32 s1, v255, 3
	v_mov_b32_e32 v186, v54
	v_mov_b32_e32 v187, v52
	v_lshl_add_u64 v[76:77], s[0:1], 0, v[76:77]
	v_lshl_add_u64 v[76:77], v[142:143], 1, v[76:77]
	global_load_dwordx4 v[180:183], v[76:77], off
	global_load_dwordx4 v[176:179], v[76:77], off offset:256
	s_mov_b32 s0, 0x3fd744fd
	v_pk_mov_b32 v[54:55], v[54:55], v[52:53] op_sel:[1,0]
	v_mov_b32_e32 v52, v56
	s_waitcnt vmcnt(0) lgkmcnt(0)
	v_cvt_f32_f16_sdwa v174, v180 dst_sel:DWORD dst_unused:UNUSED_PAD src0_sel:WORD_1
	v_cvt_f32_f16_e32 v76, v178
	v_cvt_f32_f16_sdwa v77, v178 dst_sel:DWORD dst_unused:UNUSED_PAD src0_sel:WORD_1
	v_cvt_f32_f16_sdwa v184, v182 dst_sel:DWORD dst_unused:UNUSED_PAD src0_sel:WORD_1
	v_pk_fma_f32 v[62:63], v[76:77], s[0:1], v[62:63] op_sel_hi:[1,0,1]
	v_cvt_f32_f16_e32 v76, v179
	v_cvt_f32_f16_sdwa v77, v179 dst_sel:DWORD dst_unused:UNUSED_PAD src0_sel:WORD_1
	v_mov_b32_e32 v172, v63
	v_pk_fma_f32 v[64:65], v[76:77], s[0:1], v[64:65] op_sel_hi:[1,0,1]
	s_nop 0
	v_mov_b32_e32 v173, v65
	v_mov_b32_e32 v76, v62
	v_mov_b32_e32 v77, v64
	v_pk_mul_f32 v[172:173], v[172:173], v[172:173]
	s_nop 0
	v_pk_fma_f32 v[76:77], v[76:77], v[76:77], v[172:173]
	v_mov_b32_e32 v172, v58
	v_pk_add_f32 v[178:179], v[76:77], v[76:77] op_sel_hi:[0,1]
	v_cvt_f32_f16_e32 v77, v176
	v_cvt_f32_f16_e32 v76, v180
	v_pk_mov_b32 v[58:59], v[58:59], v[50:51] op_sel:[1,0]
	v_mov_b32_e32 v173, v50
	v_mov_b32_e32 v175, v77
	v_pk_fma_f32 v[174:175], v[174:175], s[0:1], v[58:59] op_sel_hi:[1,0,1]
	v_cvt_f32_f16_e32 v58, v181
	v_cvt_f32_f16_sdwa v59, v176 dst_sel:DWORD dst_unused:UNUSED_PAD src0_sel:WORD_1
	v_pk_fma_f32 v[76:77], v[76:77], s[0:1], v[172:173] op_sel_hi:[1,0,1]
	v_cvt_f32_f16_e32 v173, v177
	v_cvt_f32_f16_sdwa v180, v181 dst_sel:DWORD dst_unused:UNUSED_PAD src0_sel:WORD_1
	v_cvt_f32_f16_e32 v176, v183
	v_cvt_f32_f16_sdwa v177, v177 dst_sel:DWORD dst_unused:UNUSED_PAD src0_sel:WORD_1
	v_cvt_f32_f16_e32 v172, v182
	v_cvt_f32_f16_sdwa v182, v183 dst_sel:DWORD dst_unused:UNUSED_PAD src0_sel:WORD_1
	v_mov_b32_e32 v50, v60
	v_mov_b32_e32 v181, v59
	v_pk_fma_f32 v[58:59], v[58:59], s[0:1], v[50:51] op_sel_hi:[1,0,1]
	v_mov_b32_e32 v50, v61
	v_mov_b32_e32 v183, v177
	v_pk_fma_f32 v[176:177], v[176:177], s[0:1], v[52:53] op_sel_hi:[1,0,1]
	v_pk_fma_f32 v[50:51], v[180:181], s[0:1], v[50:51] op_sel_hi:[1,0,1]
	v_mov_b32_e32 v52, v57
	v_pk_mul_f32 v[56:57], v[76:77], v[76:77]
	v_pk_mul_f32 v[60:61], v[174:175], v[174:175]
	v_mov_b32_e32 v185, v173
	v_pk_fma_f32 v[172:173], v[172:173], s[0:1], v[186:187] op_sel_hi:[1,0,1]
	v_pk_fma_f32 v[52:53], v[182:183], s[0:1], v[52:53] op_sel_hi:[1,0,1]
	v_pk_mul_f32 v[180:181], v[58:59], v[58:59]
	v_pk_mul_f32 v[182:183], v[50:51], v[50:51]
	v_pk_mov_b32 v[56:57], v[76:77], v[56:57] op_sel:[1,0]
	v_pk_mov_b32 v[60:61], v[58:59], v[60:61] op_sel:[1,0]
	v_pk_fma_f32 v[54:55], v[184:185], s[0:1], v[54:55] op_sel_hi:[1,0,1]
	v_pk_add_f32 v[56:57], v[56:57], v[60:61]
	v_pk_mov_b32 v[60:61], v[172:173], v[180:181] op_sel:[1,0]
	v_pk_mov_b32 v[180:181], v[176:177], v[182:183] op_sel:[1,0]
	v_pk_mul_f32 v[184:185], v[172:173], v[172:173]
	v_pk_mul_f32 v[186:187], v[54:55], v[54:55]
	v_pk_add_f32 v[60:61], v[60:61], v[180:181]
	v_pk_mul_f32 v[188:189], v[176:177], v[176:177]
	v_pk_mul_f32 v[190:191], v[52:53], v[52:53]
	v_pk_add_f32 v[56:57], v[56:57], v[60:61]
	v_mov_b32_e32 v60, v62
	v_mov_b32_e32 v61, v184
	v_pk_mov_b32 v[180:181], v[62:63], v[186:187] op_sel:[1,0]
	v_pk_mov_b32 v[182:183], v[64:65], v[190:191] op_sel:[1,0]
	v_pk_add_f32 v[60:61], v[60:61], v[180:181]
	v_mov_b32_e32 v180, v64
	v_mov_b32_e32 v181, v188
	v_pk_add_f32 v[180:181], v[180:181], v[182:183]
	v_pk_mul_f32 v[182:183], v[58:59], v[50:51]
	v_pk_add_f32 v[60:61], v[60:61], v[180:181]
	v_pk_mul_f32 v[180:181], v[76:77], v[174:175]
	v_pk_add_f32 v[56:57], v[56:57], v[60:61]
	v_pk_add_f32 v[60:61], v[76:77], v[174:175]
	v_pk_mul_f32 v[184:185], v[176:177], v[52:53]
	v_mov_b32_e32 v61, v181
	v_pk_add_f32 v[180:181], v[58:59], v[50:51]
	v_mov_b32_e32 v178, v1
	v_mov_b32_e32 v181, v183
	v_pk_add_f32 v[60:61], v[60:61], v[180:181]
	v_pk_add_f32 v[180:181], v[172:173], v[54:55]
	v_pk_mul_f32 v[182:183], v[172:173], v[54:55]
	s_nop 0
	v_mov_b32_e32 v181, v183
	v_pk_add_f32 v[182:183], v[176:177], v[52:53]
	s_nop 0
	v_mov_b32_e32 v183, v185
	v_pk_add_f32 v[180:181], v[180:181], v[182:183]
	s_nop 0
	v_pk_add_f32 v[60:61], v[60:61], v[180:181]
	s_nop 0
	v_pk_add_f32 v[60:61], v[60:61], v[178:179]
	s_nop 0
	v_pk_add_f32 v[56:57], v[56:57], v[60:61]
	ds_bpermute_b32 v60, v241, v56
	ds_bpermute_b32 v61, v241, v57
	s_waitcnt lgkmcnt(0)
	v_pk_add_f32 v[56:57], v[56:57], v[60:61]
	ds_bpermute_b32 v60, v240, v56
	ds_bpermute_b32 v61, v240, v57
	s_and_saveexec_b64 s[0:1], vcc
	s_cbranch_execz .LBB0_171
	s_waitcnt lgkmcnt(0)
	v_pk_add_f32 v[56:57], v[56:57], v[60:61]
	ds_write_b64 v115, v[56:57] offset:4096
; __device__ __forceinline__ float sumsq4(f32x4 x) { return (x[0] * x[0] + x[1] * x[1]) + (x[2] * x[2] + x[3] * x[3]); }
;     __device__ __forceinline__ void fused(AccT& acc, const Unit& u, int wr, int wc, int fr, int fq, LAS unsigned char* lx, int tid) const {
;     ...
;                 const int row = EPI_ROW(u, ai, m); float s1 = 0.f, s2 = 0.f;
; #pragma unroll
;                 for (int bj = 0; bj < 2; ++bj) {
;                     const half8 rv = *(const half8*)(res + (size_t)row * DM + EPI_COL(u, bj));
; #pragma unroll
;                     for (int e = 0; e < 4; ++e) { acc[ai][bj][m][0][e] += ALPHA * (float)rv[e]; acc[ai][bj][m][1][e] += ALPHA * (float)rv[4 + e]; }
;                     const f32x4 a0 = acc[ai][bj][m][0], a1 = acc[ai][bj][m][1];
;                     s1 += ((a0[0] + a0[1]) + (a0[2] + a0[3])) + ((a1[0] + a1[1]) + (a1[2] + a1[3])); s2 += sumsq4(a0) + sumsq4(a1);
;                 }
;                 s1 += __shfl_xor(s1, 16); s1 += __shfl_xor(s1, 32); s2 += __shfl_xor(s2, 16); s2 += __shfl_xor(s2, 32);
;                 if (fq == 0) P[(ai * 128 + wr * 64 + m * 16 + fr) * 4 + wc] = (f32x2){s1, s2};
.LBB0_171:
	s_or_b64 exec, exec, s[0:1]
	v_add_u32_e32 v56, 0x90, v140
	v_ashrrev_i32_e32 v57, 31, v56
	v_readlane_b32 s0, v255, 2
	s_waitcnt lgkmcnt(0)
	v_lshlrev_b64 v[60:61], 11, v[56:57]
	v_readlane_b32 s1, v255, 3
	v_mov_b32_e32 v192, v38
	v_mov_b32_e32 v193, v36
	v_lshl_add_u64 v[60:61], s[0:1], 0, v[60:61]
	v_lshl_add_u64 v[60:61], v[142:143], 1, v[60:61]
	global_load_dwordx4 v[186:189], v[60:61], off
	global_load_dwordx4 v[182:185], v[60:61], off offset:256
	s_mov_b32 s0, 0x3fd744fd
	v_pk_mov_b32 v[38:39], v[38:39], v[36:37] op_sel:[1,0]
	v_mov_b32_e32 v36, v40
	s_waitcnt vmcnt(0) lgkmcnt(0)
	v_cvt_f32_f16_sdwa v180, v186 dst_sel:DWORD dst_unused:UNUSED_PAD src0_sel:WORD_1
	v_cvt_f32_f16_e32 v60, v184
	v_cvt_f32_f16_sdwa v61, v184 dst_sel:DWORD dst_unused:UNUSED_PAD src0_sel:WORD_1
	v_cvt_f32_f16_sdwa v190, v188 dst_sel:DWORD dst_unused:UNUSED_PAD src0_sel:WORD_1
	v_pk_fma_f32 v[46:47], v[60:61], s[0:1], v[46:47] op_sel_hi:[1,0,1]
	v_cvt_f32_f16_e32 v60, v185
	v_cvt_f32_f16_sdwa v61, v185 dst_sel:DWORD dst_unused:UNUSED_PAD src0_sel:WORD_1
	v_mov_b32_e32 v178, v47
	v_pk_fma_f32 v[48:49], v[60:61], s[0:1], v[48:49] op_sel_hi:[1,0,1]
	s_nop 0
	v_mov_b32_e32 v179, v49
	v_mov_b32_e32 v60, v46
	v_mov_b32_e32 v61, v48
	v_pk_mul_f32 v[178:179], v[178:179], v[178:179]
	s_nop 0
	v_pk_fma_f32 v[60:61], v[60:61], v[60:61], v[178:179]
	v_mov_b32_e32 v178, v42
	v_pk_add_f32 v[184:185], v[60:61], v[60:61] op_sel_hi:[0,1]
	v_cvt_f32_f16_e32 v61, v182
	v_cvt_f32_f16_e32 v60, v186
	v_pk_mov_b32 v[42:43], v[42:43], v[34:35] op_sel:[1,0]
	v_mov_b32_e32 v179, v34
	v_mov_b32_e32 v181, v61
	v_pk_fma_f32 v[180:181], v[180:181], s[0:1], v[42:43] op_sel_hi:[1,0,1]
	v_cvt_f32_f16_e32 v42, v187
	v_cvt_f32_f16_sdwa v43, v182 dst_sel:DWORD dst_unused:UNUSED_PAD src0_sel:WORD_1
	v_pk_fma_f32 v[60:61], v[60:61], s[0:1], v[178:179] op_sel_hi:[1,0,1]
	v_cvt_f32_f16_e32 v179, v183
	v_cvt_f32_f16_sdwa v186, v187 dst_sel:DWORD dst_unused:UNUSED_PAD src0_sel:WORD_1
	v_cvt_f32_f16_e32 v182, v189
	v_cvt_f32_f16_sdwa v183, v183 dst_sel:DWORD dst_unused:UNUSED_PAD src0_sel:WORD_1
	v_cvt_f32_f16_e32 v178, v188
	v_cvt_f32_f16_sdwa v188, v189 dst_sel:DWORD dst_unused:UNUSED_PAD src0_sel:WORD_1
	v_mov_b32_e32 v34, v44
	v_mov_b32_e32 v187, v43
	v_pk_fma_f32 v[42:43], v[42:43], s[0:1], v[34:35] op_sel_hi:[1,0,1]
	v_mov_b32_e32 v34, v45
	v_mov_b32_e32 v189, v183
	v_pk_fma_f32 v[182:183], v[182:183], s[0:1], v[36:37] op_sel_hi:[1,0,1]
	v_pk_fma_f32 v[34:35], v[186:187], s[0:1], v[34:35] op_sel_hi:[1,0,1]
	v_mov_b32_e32 v36, v41
	v_pk_mul_f32 v[40:41], v[60:61], v[60:61]
	v_pk_mul_f32 v[44:45], v[180:181], v[180:181]
	v_mov_b32_e32 v191, v179
	v_pk_fma_f32 v[178:179], v[178:179], s[0:1], v[192:193] op_sel_hi:[1,0,1]
	v_pk_fma_f32 v[36:37], v[188:189], s[0:1], v[36:37] op_sel_hi:[1,0,1]
	v_pk_mul_f32 v[186:187], v[42:43], v[42:43]
	v_pk_mul_f32 v[188:189], v[34:35], v[34:35]
	v_pk_mov_b32 v[40:41], v[60:61], v[40:41] op_sel:[1,0]
	v_pk_mov_b32 v[44:45], v[42:43], v[44:45] op_sel:[1,0]
	v_pk_fma_f32 v[38:39], v[190:191], s[0:1], v[38:39] op_sel_hi:[1,0,1]
	v_pk_add_f32 v[40:41], v[40:41], v[44:45]
	v_pk_mov_b32 v[44:45], v[178:179], v[186:187] op_sel:[1,0]
	v_pk_mov_b32 v[186:187], v[182:183], v[188:189] op_sel:[1,0]
	v_pk_mul_f32 v[190:191], v[178:179], v[178:179]
	v_pk_mul_f32 v[192:193], v[38:39], v[38:39]
	v_pk_add_f32 v[44:45], v[44:45], v[186:187]
	v_pk_mul_f32 v[194:195], v[182:183], v[182:183]
	v_pk_mul_f32 v[196:197], v[36:37], v[36:37]
	v_pk_add_f32 v[40:41], v[40:41], v[44:45]
	v_mov_b32_e32 v44, v46
	v_mov_b32_e32 v45, v190
	v_pk_mov_b32 v[186:187], v[46:47], v[192:193] op_sel:[1,0]
	v_pk_mov_b32 v[188:189], v[48:49], v[196:197] op_sel:[1,0]
	v_pk_add_f32 v[44:45], v[44:45], v[186:187]
	v_mov_b32_e32 v186, v48
	v_mov_b32_e32 v187, v194
	v_pk_add_f32 v[186:187], v[186:187], v[188:189]
	v_pk_mul_f32 v[188:189], v[42:43], v[34:35]
	v_pk_add_f32 v[44:45], v[44:45], v[186:187]
	v_pk_mul_f32 v[186:187], v[60:61], v[180:181]
	v_pk_add_f32 v[40:41], v[40:41], v[44:45]
	v_pk_add_f32 v[44:45], v[60:61], v[180:181]
	v_pk_mul_f32 v[190:191], v[182:183], v[36:37]
	v_mov_b32_e32 v45, v187
	v_pk_add_f32 v[186:187], v[42:43], v[34:35]
	v_mov_b32_e32 v184, v1
	v_mov_b32_e32 v187, v189
	v_pk_add_f32 v[44:45], v[44:45], v[186:187]
	v_pk_add_f32 v[186:187], v[178:179], v[38:39]
	v_pk_mul_f32 v[188:189], v[178:179], v[38:39]
	s_nop 0
	v_mov_b32_e32 v187, v189
	v_pk_add_f32 v[188:189], v[182:183], v[36:37]
	s_nop 0
	v_mov_b32_e32 v189, v191
	v_pk_add_f32 v[186:187], v[186:187], v[188:189]
	s_nop 0
	v_pk_add_f32 v[44:45], v[44:45], v[186:187]
	s_nop 0
	v_pk_add_f32 v[44:45], v[44:45], v[184:185]
	s_nop 0
	v_pk_add_f32 v[40:41], v[40:41], v[44:45]
	ds_bpermute_b32 v44, v241, v40
	ds_bpermute_b32 v45, v241, v41
	s_waitcnt lgkmcnt(0)
	v_pk_add_f32 v[40:41], v[40:41], v[44:45]
	ds_bpermute_b32 v44, v240, v40
	ds_bpermute_b32 v45, v240, v41
	s_and_saveexec_b64 s[0:1], vcc
	s_cbranch_execz .LBB0_173
	s_waitcnt lgkmcnt(0)
	v_pk_add_f32 v[40:41], v[40:41], v[44:45]
	ds_write_b64 v115, v[40:41] offset:4608
; __device__ __forceinline__ float sumsq4(f32x4 x) { return (x[0] * x[0] + x[1] * x[1]) + (x[2] * x[2] + x[3] * x[3]); }
;     __device__ __forceinline__ void fused(AccT& acc, const Unit& u, int wr, int wc, int fr, int fq, LAS unsigned char* lx, int tid) const {
;     ...
;                 const int row = EPI_ROW(u, ai, m); float s1 = 0.f, s2 = 0.f;
; #pragma unroll
;                 for (int bj = 0; bj < 2; ++bj) {
;                     const half8 rv = *(const half8*)(res + (size_t)row * DM + EPI_COL(u, bj));
; #pragma unroll
;                     for (int e = 0; e < 4; ++e) { acc[ai][bj][m][0][e] += ALPHA * (float)rv[e]; acc[ai][bj][m][1][e] += ALPHA * (float)rv[4 + e]; }
;                     const f32x4 a0 = acc[ai][bj][m][0], a1 = acc[ai][bj][m][1];
;                     s1 += ((a0[0] + a0[1]) + (a0[2] + a0[3])) + ((a1[0] + a1[1]) + (a1[2] + a1[3])); s2 += sumsq4(a0) + sumsq4(a1);
;                 }
;                 s1 += __shfl_xor(s1, 16); s1 += __shfl_xor(s1, 32); s2 += __shfl_xor(s2, 16); s2 += __shfl_xor(s2, 32);
;                 if (fq == 0) P[(ai * 128 + wr * 64 + m * 16 + fr) * 4 + wc] = (f32x2){s1, s2};
.LBB0_173:
	s_or_b64 exec, exec, s[0:1]
	v_add_u32_e32 v184, 0xa0, v140
	v_ashrrev_i32_e32 v185, 31, v184
	v_readlane_b32 s0, v255, 2
	v_lshlrev_b64 v[40:41], 11, v[184:185]
	v_readlane_b32 s1, v255, 3
	v_mov_b32_e32 v186, v26
	v_mov_b32_e32 v187, v18
	v_lshl_add_u64 v[40:41], s[0:1], 0, v[40:41]
	v_lshl_add_u64 v[40:41], v[142:143], 1, v[40:41]
	global_load_dwordx4 v[196:199], v[40:41], off
	global_load_dwordx4 v[200:203], v[40:41], off offset:256
	s_mov_b32 s0, 0x3fd744fd
	v_mov_b32_e32 v188, v22
	v_pk_mov_b32 v[26:27], v[26:27], v[18:19] op_sel:[1,0]
	v_pk_mov_b32 v[22:23], v[22:23], v[20:21] op_sel:[1,0]
	v_mov_b32_e32 v18, v28
	v_mov_b32_e32 v189, v20
	v_mov_b32_e32 v20, v24
	s_waitcnt vmcnt(0) lgkmcnt(0)
	v_cvt_f32_f16_sdwa v190, v196 dst_sel:DWORD dst_unused:UNUSED_PAD src0_sel:WORD_1
	v_cvt_f32_f16_e32 v40, v202
	v_cvt_f32_f16_sdwa v41, v202 dst_sel:DWORD dst_unused:UNUSED_PAD src0_sel:WORD_1
	v_cvt_f32_f16_sdwa v192, v198 dst_sel:DWORD dst_unused:UNUSED_PAD src0_sel:WORD_1
	v_pk_fma_f32 v[40:41], v[40:41], s[0:1], v[30:31] op_sel_hi:[1,0,1]
	v_cvt_f32_f16_e32 v30, v203
	v_cvt_f32_f16_sdwa v31, v203 dst_sel:DWORD dst_unused:UNUSED_PAD src0_sel:WORD_1
	v_pk_fma_f32 v[44:45], v[30:31], s[0:1], v[32:33] op_sel_hi:[1,0,1]
	v_mov_b32_e32 v32, v41
	v_mov_b32_e32 v33, v45
	v_mov_b32_e32 v30, v40
	v_mov_b32_e32 v31, v44
	v_pk_mul_f32 v[32:33], v[32:33], v[32:33]
	s_nop 0
	v_pk_fma_f32 v[30:31], v[30:31], v[30:31], v[32:33]
	v_cvt_f32_f16_e32 v33, v200
	v_cvt_f32_f16_e32 v32, v196
	v_pk_add_f32 v[30:31], v[30:31], v[30:31] op_sel_hi:[0,1]
	v_mov_b32_e32 v30, v1
	v_mov_b32_e32 v191, v33
	v_pk_fma_f32 v[186:187], v[32:33], s[0:1], v[186:187] op_sel_hi:[1,0,1]
	v_cvt_f32_f16_e32 v33, v201
	v_pk_fma_f32 v[194:195], v[190:191], s[0:1], v[26:27] op_sel_hi:[1,0,1]
	v_cvt_f32_f16_e32 v32, v198
	v_cvt_f32_f16_sdwa v26, v197 dst_sel:DWORD dst_unused:UNUSED_PAD src0_sel:WORD_1
	v_mov_b32_e32 v193, v33
	v_pk_fma_f32 v[190:191], v[192:193], s[0:1], v[22:23] op_sel_hi:[1,0,1]
	v_cvt_f32_f16_e32 v22, v197
	v_cvt_f32_f16_sdwa v23, v200 dst_sel:DWORD dst_unused:UNUSED_PAD src0_sel:WORD_1
	v_pk_fma_f32 v[188:189], v[32:33], s[0:1], v[188:189] op_sel_hi:[1,0,1]
	v_cvt_f32_f16_sdwa v32, v199 dst_sel:DWORD dst_unused:UNUSED_PAD src0_sel:WORD_1
	v_mov_b32_e32 v27, v23
	v_pk_fma_f32 v[192:193], v[22:23], s[0:1], v[18:19] op_sel_hi:[1,0,1]
	v_cvt_f32_f16_e32 v22, v199
	v_cvt_f32_f16_sdwa v23, v201 dst_sel:DWORD dst_unused:UNUSED_PAD src0_sel:WORD_1
	v_mov_b32_e32 v18, v29
	v_pk_fma_f32 v[198:199], v[26:27], s[0:1], v[18:19] op_sel_hi:[1,0,1]
	v_pk_mul_f32 v[18:19], v[186:187], v[186:187]
	v_mov_b32_e32 v33, v23
	v_pk_fma_f32 v[196:197], v[22:23], s[0:1], v[20:21] op_sel_hi:[1,0,1]
	v_mov_b32_e32 v20, v25
	v_pk_fma_f32 v[200:201], v[32:33], s[0:1], v[20:21] op_sel_hi:[1,0,1]
	v_pk_mul_f32 v[20:21], v[194:195], v[194:195]
	v_pk_mul_f32 v[22:23], v[192:193], v[192:193]
	v_pk_mul_f32 v[24:25], v[198:199], v[198:199]
	v_pk_mov_b32 v[18:19], v[186:187], v[18:19] op_sel:[1,0]
	v_pk_mov_b32 v[20:21], v[192:193], v[20:21] op_sel:[1,0]
	v_pk_mul_f32 v[26:27], v[188:189], v[188:189]
	v_pk_add_f32 v[18:19], v[18:19], v[20:21]
	v_pk_mov_b32 v[20:21], v[188:189], v[22:23] op_sel:[1,0]
	v_pk_mov_b32 v[22:23], v[196:197], v[24:25] op_sel:[1,0]
	v_pk_mul_f32 v[28:29], v[190:191], v[190:191]
	v_pk_add_f32 v[20:21], v[20:21], v[22:23]
	v_pk_mul_f32 v[32:33], v[196:197], v[196:197]
	v_pk_mul_f32 v[202:203], v[200:201], v[200:201]
	v_pk_add_f32 v[18:19], v[18:19], v[20:21]
	v_mov_b32_e32 v20, v40
	v_mov_b32_e32 v21, v26
	v_pk_mov_b32 v[22:23], v[40:41], v[28:29] op_sel:[1,0]
	v_pk_mov_b32 v[24:25], v[44:45], v[202:203] op_sel:[1,0]
	v_pk_add_f32 v[20:21], v[20:21], v[22:23]
	v_mov_b32_e32 v22, v44
	v_mov_b32_e32 v23, v32
	v_pk_add_f32 v[22:23], v[22:23], v[24:25]
	v_pk_mul_f32 v[24:25], v[192:193], v[198:199]
	v_pk_add_f32 v[20:21], v[20:21], v[22:23]
	v_pk_mul_f32 v[22:23], v[186:187], v[194:195]
	v_pk_add_f32 v[18:19], v[18:19], v[20:21]
	v_pk_add_f32 v[20:21], v[186:187], v[194:195]
	v_pk_mul_f32 v[26:27], v[196:197], v[200:201]
	v_mov_b32_e32 v21, v23
	v_pk_add_f32 v[22:23], v[192:193], v[198:199]
	s_nop 0
	v_mov_b32_e32 v23, v25
	v_pk_add_f32 v[20:21], v[20:21], v[22:23]
	v_pk_add_f32 v[22:23], v[188:189], v[190:191]
	v_pk_mul_f32 v[24:25], v[188:189], v[190:191]
	s_nop 0
	v_mov_b32_e32 v23, v25
	v_pk_add_f32 v[24:25], v[196:197], v[200:201]
	s_nop 0
	v_mov_b32_e32 v25, v27
	v_pk_add_f32 v[22:23], v[22:23], v[24:25]
	s_nop 0
	v_pk_add_f32 v[20:21], v[20:21], v[22:23]
	s_nop 0
	v_pk_add_f32 v[20:21], v[20:21], v[30:31]
	s_nop 0
	v_pk_add_f32 v[18:19], v[18:19], v[20:21]
	ds_bpermute_b32 v20, v241, v18
	ds_bpermute_b32 v21, v241, v19
	s_waitcnt lgkmcnt(0)
	v_pk_add_f32 v[18:19], v[18:19], v[20:21]
	ds_bpermute_b32 v20, v240, v18
	ds_bpermute_b32 v21, v240, v19
	s_and_saveexec_b64 s[0:1], vcc
	s_cbranch_execz .LBB0_175
	s_waitcnt lgkmcnt(0)
	v_pk_add_f32 v[18:19], v[18:19], v[20:21]
	ds_write_b64 v115, v[18:19] offset:5120
; __device__ __forceinline__ float sumsq4(f32x4 x) { return (x[0] * x[0] + x[1] * x[1]) + (x[2] * x[2] + x[3] * x[3]); }
;     __device__ __forceinline__ void fused(AccT& acc, const Unit& u, int wr, int wc, int fr, int fq, LAS unsigned char* lx, int tid) const {
;     ...
;                 const int row = EPI_ROW(u, ai, m); float s1 = 0.f, s2 = 0.f;
; #pragma unroll
;                 for (int bj = 0; bj < 2; ++bj) {
;                     const half8 rv = *(const half8*)(res + (size_t)row * DM + EPI_COL(u, bj));
; #pragma unroll
;                     for (int e = 0; e < 4; ++e) { acc[ai][bj][m][0][e] += ALPHA * (float)rv[e]; acc[ai][bj][m][1][e] += ALPHA * (float)rv[4 + e]; }
;                     const f32x4 a0 = acc[ai][bj][m][0], a1 = acc[ai][bj][m][1];
;                     s1 += ((a0[0] + a0[1]) + (a0[2] + a0[3])) + ((a1[0] + a1[1]) + (a1[2] + a1[3])); s2 += sumsq4(a0) + sumsq4(a1);
;                 }
;                 s1 += __shfl_xor(s1, 16); s1 += __shfl_xor(s1, 32); s2 += __shfl_xor(s2, 16); s2 += __shfl_xor(s2, 32);
;                 if (fq == 0) P[(ai * 128 + wr * 64 + m * 16 + fr) * 4 + wc] = (f32x2){s1, s2};
.LBB0_175:
	s_or_b64 exec, exec, s[0:1]
	v_add_u32_e32 v206, 0xb0, v140
	v_ashrrev_i32_e32 v207, 31, v206
	v_readlane_b32 s0, v255, 2
	v_lshlrev_b64 v[18:19], 11, v[206:207]
	v_readlane_b32 s1, v255, 3
	v_mov_b32_e32 v28, v6
	v_pk_mov_b32 v[6:7], v[6:7], v[4:5] op_sel:[1,0]
	v_lshl_add_u64 v[18:19], s[0:1], 0, v[18:19]
	v_lshl_add_u64 v[22:23], v[142:143], 1, v[18:19]
	s_waitcnt lgkmcnt(0)
	global_load_dwordx4 v[18:21], v[22:23], off
	s_nop 0
	global_load_dwordx4 v[22:25], v[22:23], off offset:256
	s_mov_b32 s0, 0x3fd744fd
	v_mov_b32_e32 v29, v4
	v_mov_b32_e32 v4, v8
	s_waitcnt vmcnt(0) lgkmcnt(0)
	v_cvt_f32_f16_e32 v26, v24
	v_cvt_f32_f16_sdwa v27, v24 dst_sel:DWORD dst_unused:UNUSED_PAD src0_sel:WORD_1
	v_cvt_f32_f16_sdwa v24, v18 dst_sel:DWORD dst_unused:UNUSED_PAD src0_sel:WORD_1
	v_pk_fma_f32 v[202:203], v[26:27], s[0:1], v[14:15] op_sel_hi:[1,0,1]
	v_cvt_f32_f16_e32 v14, v25
	v_cvt_f32_f16_sdwa v15, v25 dst_sel:DWORD dst_unused:UNUSED_PAD src0_sel:WORD_1
	v_mov_b32_e32 v26, v10
	v_mov_b32_e32 v27, v2
	v_pk_mov_b32 v[10:11], v[10:11], v[2:3] op_sel:[1,0]
	v_pk_fma_f32 v[204:205], v[14:15], s[0:1], v[16:17] op_sel_hi:[1,0,1]
	v_mov_b32_e32 v16, v203
	v_mov_b32_e32 v17, v205
	v_mov_b32_e32 v14, v202
	v_mov_b32_e32 v15, v204
	v_pk_mul_f32 v[16:17], v[16:17], v[16:17]
	v_mov_b32_e32 v2, v12
	v_pk_fma_f32 v[14:15], v[14:15], v[14:15], v[16:17]
	v_cvt_f32_f16_e32 v17, v22
	v_cvt_f32_f16_e32 v16, v18
	v_pk_add_f32 v[14:15], v[14:15], v[14:15] op_sel_hi:[0,1]
	v_mov_b32_e32 v14, v1
	v_mov_b32_e32 v25, v17
	v_pk_fma_f32 v[208:209], v[16:17], s[0:1], v[26:27] op_sel_hi:[1,0,1]
	v_cvt_f32_f16_e32 v17, v23
	v_cvt_f32_f16_sdwa v26, v20 dst_sel:DWORD dst_unused:UNUSED_PAD src0_sel:WORD_1
	v_cvt_f32_f16_e32 v16, v20
	v_pk_fma_f32 v[220:221], v[24:25], s[0:1], v[10:11] op_sel_hi:[1,0,1]
	v_mov_b32_e32 v27, v17
	v_pk_fma_f32 v[212:213], v[26:27], s[0:1], v[6:7] op_sel_hi:[1,0,1]
	v_cvt_f32_f16_e32 v6, v19
	v_cvt_f32_f16_sdwa v7, v22 dst_sel:DWORD dst_unused:UNUSED_PAD src0_sel:WORD_1
	v_pk_fma_f32 v[210:211], v[16:17], s[0:1], v[28:29] op_sel_hi:[1,0,1]
	v_cvt_f32_f16_sdwa v10, v19 dst_sel:DWORD dst_unused:UNUSED_PAD src0_sel:WORD_1
	v_cvt_f32_f16_sdwa v16, v21 dst_sel:DWORD dst_unused:UNUSED_PAD src0_sel:WORD_1
	v_mov_b32_e32 v11, v7
	v_pk_fma_f32 v[214:215], v[6:7], s[0:1], v[2:3] op_sel_hi:[1,0,1]
	v_cvt_f32_f16_e32 v6, v21
	v_cvt_f32_f16_sdwa v7, v23 dst_sel:DWORD dst_unused:UNUSED_PAD src0_sel:WORD_1
	v_mov_b32_e32 v2, v13
	v_pk_fma_f32 v[224:225], v[10:11], s[0:1], v[2:3] op_sel_hi:[1,0,1]
	v_pk_mul_f32 v[2:3], v[208:209], v[208:209]
	v_mov_b32_e32 v17, v7
	v_pk_fma_f32 v[222:223], v[6:7], s[0:1], v[4:5] op_sel_hi:[1,0,1]
	v_mov_b32_e32 v4, v9
	v_pk_fma_f32 v[226:227], v[16:17], s[0:1], v[4:5] op_sel_hi:[1,0,1]
	v_pk_mul_f32 v[4:5], v[220:221], v[220:221]
	v_pk_mul_f32 v[6:7], v[214:215], v[214:215]
	v_pk_mul_f32 v[8:9], v[224:225], v[224:225]
	v_pk_mov_b32 v[2:3], v[208:209], v[2:3] op_sel:[1,0]
	v_pk_mov_b32 v[4:5], v[214:215], v[4:5] op_sel:[1,0]
	v_pk_mul_f32 v[10:11], v[210:211], v[210:211]
	v_pk_add_f32 v[2:3], v[2:3], v[4:5]
	v_pk_mov_b32 v[4:5], v[210:211], v[6:7] op_sel:[1,0]
	v_pk_mov_b32 v[6:7], v[222:223], v[8:9] op_sel:[1,0]
	v_pk_mul_f32 v[12:13], v[212:213], v[212:213]
	v_pk_add_f32 v[4:5], v[4:5], v[6:7]
	v_pk_mul_f32 v[16:17], v[222:223], v[222:223]
	v_pk_mul_f32 v[18:19], v[226:227], v[226:227]
	v_pk_add_f32 v[2:3], v[2:3], v[4:5]
	v_mov_b32_e32 v4, v202
	v_mov_b32_e32 v5, v10
	v_pk_mov_b32 v[6:7], v[202:203], v[12:13] op_sel:[1,0]
	v_pk_mov_b32 v[8:9], v[204:205], v[18:19] op_sel:[1,0]
	v_pk_add_f32 v[4:5], v[4:5], v[6:7]
	v_mov_b32_e32 v6, v204
	v_mov_b32_e32 v7, v16
	v_pk_add_f32 v[6:7], v[6:7], v[8:9]
	v_pk_mul_f32 v[8:9], v[214:215], v[224:225]
	v_pk_add_f32 v[4:5], v[4:5], v[6:7]
	v_pk_mul_f32 v[6:7], v[208:209], v[220:221]
	v_pk_add_f32 v[2:3], v[2:3], v[4:5]
	v_pk_add_f32 v[4:5], v[208:209], v[220:221]
	v_pk_mul_f32 v[10:11], v[222:223], v[226:227]
	v_mov_b32_e32 v5, v7
	v_pk_add_f32 v[6:7], v[214:215], v[224:225]
	s_nop 0
	v_mov_b32_e32 v7, v9
	v_pk_add_f32 v[4:5], v[4:5], v[6:7]
	v_pk_add_f32 v[6:7], v[210:211], v[212:213]
	v_pk_mul_f32 v[8:9], v[210:211], v[212:213]
	s_nop 0
	v_mov_b32_e32 v7, v9
	v_pk_add_f32 v[8:9], v[222:223], v[226:227]
	s_nop 0
	v_mov_b32_e32 v9, v11
	v_pk_add_f32 v[6:7], v[6:7], v[8:9]
	s_nop 0
	v_pk_add_f32 v[4:5], v[4:5], v[6:7]
	s_nop 0
	v_pk_add_f32 v[4:5], v[4:5], v[14:15]
	s_nop 0
	v_pk_add_f32 v[2:3], v[2:3], v[4:5]
	ds_bpermute_b32 v4, v241, v2
	ds_bpermute_b32 v5, v241, v3
	s_waitcnt lgkmcnt(0)
	v_pk_add_f32 v[2:3], v[2:3], v[4:5]
	ds_bpermute_b32 v4, v240, v2
	ds_bpermute_b32 v5, v240, v3
	s_and_saveexec_b64 s[0:1], vcc
	s_cbranch_execz .LBB0_177
	s_waitcnt lgkmcnt(0)
	v_pk_add_f32 v[2:3], v[2:3], v[4:5]
	ds_write_b64 v115, v[2:3] offset:5632

;     __device__ __forceinline__ void fused(AccT& acc, const Unit& u, int wr, int wc, int fr, int fq, LAS unsigned char* lx, int tid) const {
;     ...
;         if (tid < 64) {
;             unsigned spins = 0;
;             while ((unsigned)__builtin_amdgcn_readfirstlane(__hip_atomic_load(cnt + 64 * u.pm, __ATOMIC_RELAXED, __HIP_MEMORY_SCOPE_AGENT)) < 16u) { __builtin_amdgcn_s_sleep(2); if (++spins > (1u << 22)) break; }
;             __builtin_amdgcn_fence(__ATOMIC_ACQUIRE, "agent");
;             if (tid == 0) flag[0] = 1u;
;         }
.LBB0_183:
	s_waitcnt lgkmcnt(0)
	v_mov_b64_e32 v[4:5], s[16:17]
	global_load_dword v4, v[4:5], off sc1
	s_mov_b64 s[18:19], -1
	s_waitcnt vmcnt(0) lgkmcnt(0)
	v_readfirstlane_b32 s3, v4
	s_cmp_gt_u32 s3, 15
	s_cbranch_scc1 .LBB0_182
	v_mov_b64_e32 v[4:5], s[16:17]
	s_sleep 2
	global_load_dword v4, v[4:5], off sc1
	s_waitcnt vmcnt(0) lgkmcnt(0)
	v_readfirstlane_b32 s3, v4
	s_cmp_lt_u32 s3, 16
	s_cbranch_scc0 .LBB0_182
	v_mov_b64_e32 v[4:5], s[16:17]
	s_sleep 2
	global_load_dword v4, v[4:5], off sc1
	s_waitcnt vmcnt(0) lgkmcnt(0)
	v_readfirstlane_b32 s3, v4
	s_cmp_lt_u32 s3, 16
	s_cbranch_scc0 .LBB0_182
	v_mov_b64_e32 v[4:5], s[16:17]
	s_sleep 2
	global_load_dword v4, v[4:5], off sc1
	s_waitcnt vmcnt(0) lgkmcnt(0)
	v_readfirstlane_b32 s3, v4
	s_cmp_lt_u32 s3, 16
	s_cbranch_scc0 .LBB0_182
	v_mov_b64_e32 v[4:5], s[16:17]
	s_sleep 2
	global_load_dword v4, v[4:5], off sc1
	s_waitcnt vmcnt(0) lgkmcnt(0)
	v_readfirstlane_b32 s3, v4
	s_cmp_lt_u32 s3, 16
	s_cbranch_scc0 .LBB0_182
	s_add_i32 s2, s2, -5
	s_cmp_eq_u32 s2, 0
	s_cselect_b64 s[18:19], -1, 0
	s_sleep 2
	s_branch .LBB0_182

; __device__ __forceinline__ void tr_load(const TrDesc& d, int tid, float (&v)[8]) {
;     const int nn = tid & 63, np = d.n0 + nn; int col = np; const float* s = d.src;
;     if (d.mode == 1) { if (np >= 1216) col = -1; else if (np >= 1152) { const int i = np - 1152; col = 1152 + (i >> 1) + 32 * (i & 1); } }
;     else if (d.mode == 2) { const int h = np / 192, dd = np % 192; if (dd >= 128) { const int i = dd - 128; col = 192 * h + 128 + (i >> 1) + 32 * (i & 1); } }
;     else if (d.mode == 3) { col = (np >> 8) * 128 + (np & 127); if ((np >> 7) & 1) s = d.src2; }
; #pragma unroll
;     for (int i = 0; i < 8; ++i) { const int kk = (tid >> 6) + 8 * i; float x = 0.f;
;         if (col >= 0) { x = s[(size_t)(d.k0 + kk) * d.ld_src + col]; if (d.rs) x *= d.rs[d.k0 + kk]; if (d.mode == 2) x *= QSCALE * 8.0f; }
;         v[i] = x; }
.LBB0_227:
	s_cmp_lg_u64 s[54:55], 0
	v_ashrrev_i32_e32 v2, 6, v14
	v_lshl_add_u64 v[12:13], v[0:1], 2, s[6:7]
	s_cselect_b64 s[6:7], -1, 0
	v_cmp_gt_i32_e64 s[8:9], 0, v0
	v_cmp_lt_i32_e32 vcc, -1, v0
	v_add_u32_e32 v10, s88, v2
	v_mov_b32_e32 v2, 0
	v_cndmask_b32_e64 v0, 0, 1, s[6:7]
	v_ashrrev_i32_e32 v11, 31, v10
	v_cmp_ne_u32_e64 s[6:7], 1, v0
	v_mov_b32_e32 v3, v2
	s_and_saveexec_b64 s[52:53], vcc
	s_cbranch_execz .LBB0_248
	v_mul_lo_u32 v0, s51, v10
	v_mul_lo_u32 v4, s50, v11
	v_mad_u64_u32 v[2:3], s[20:21], s50, v10, 0
	v_add3_u32 v3, v3, v4, v0
	v_lshl_add_u64 v[2:3], v[2:3], 2, v[12:13]
	flat_load_dword v0, v[2:3]
	s_and_b64 vcc, exec, s[6:7]
	v_lshl_add_u64 v[2:3], v[10:11], 2, s[54:55]
	s_cbranch_vccnz .LBB0_230
	global_load_dword v4, v[2:3], off
	s_waitcnt vmcnt(0) lgkmcnt(0)
	v_mul_f32_e32 v0, v0, v4
.LBB0_230:
	v_add_u32_e32 v4, 8, v10
	v_ashrrev_i32_e32 v5, 31, v4
	v_mul_lo_u32 v6, s50, v5
	v_mul_lo_u32 v7, s51, v4
	v_mad_u64_u32 v[4:5], s[20:21], s50, v4, 0
	v_add3_u32 v5, v5, v6, v7
	v_lshl_add_u64 v[4:5], v[4:5], 2, v[12:13]
	flat_load_dword v4, v[4:5]
	s_and_b64 vcc, exec, s[6:7]
	s_cbranch_vccnz .LBB0_232
	global_load_dword v2, v[2:3], off offset:32
	s_waitcnt vmcnt(0) lgkmcnt(0)
	v_mul_f32_e32 v4, v4, v2

; __device__ __forceinline__ void tr_load(const TrDesc& d, int tid, float (&v)[8]) {
;     const int nn = tid & 63, np = d.n0 + nn; int col = np; const float* s = d.src;
;     if (d.mode == 1) { if (np >= 1216) col = -1; else if (np >= 1152) { const int i = np - 1152; col = 1152 + (i >> 1) + 32 * (i & 1); } }
;     else if (d.mode == 2) { const int h = np / 192, dd = np % 192; if (dd >= 128) { const int i = dd - 128; col = 192 * h + 128 + (i >> 1) + 32 * (i & 1); } }
;     else if (d.mode == 3) { col = (np >> 8) * 128 + (np & 127); if ((np >> 7) & 1) s = d.src2; }
; #pragma unroll
;     for (int i = 0; i < 8; ++i) { const int kk = (tid >> 6) + 8 * i; float x = 0.f;
;         if (col >= 0) { x = s[(size_t)(d.k0 + kk) * d.ld_src + col]; if (d.rs) x *= d.rs[d.k0 + kk]; if (d.mode == 2) x *= QSCALE * 8.0f; }
;         v[i] = x; }
.LBB0_234:
	v_add_u32_e32 v0, 16, v10
	v_ashrrev_i32_e32 v4, 31, v0
	v_mul_lo_u32 v7, s50, v4
	v_mul_lo_u32 v9, s51, v0
	v_mad_u64_u32 v[4:5], s[20:21], s50, v0, 0
	v_add3_u32 v5, v5, v7, v9
	v_lshl_add_u64 v[4:5], v[4:5], 2, v[12:13]
	flat_load_dword v0, v[4:5]
	s_and_b64 vcc, exec, s[6:7]
	s_cbranch_vccnz .LBB0_236
	v_lshl_add_u64 v[4:5], v[10:11], 2, s[54:55]
	global_load_dword v4, v[4:5], off offset:64
	s_waitcnt vmcnt(0) lgkmcnt(0)
	v_mul_f32_e32 v0, v0, v4
.LBB0_236:
	v_add_u32_e32 v4, 24, v10
	v_ashrrev_i32_e32 v5, 31, v4
	v_mul_lo_u32 v7, s50, v5
	v_mul_lo_u32 v9, s51, v4
	v_mad_u64_u32 v[4:5], s[20:21], s50, v4, 0
	v_add3_u32 v5, v5, v7, v9
	v_lshl_add_u64 v[4:5], v[4:5], 2, v[12:13]
	flat_load_dword v5, v[4:5]
	s_and_b64 vcc, exec, s[6:7]
	s_cbranch_vccnz .LBB0_238
	v_lshl_add_u64 v[18:19], v[10:11], 2, s[54:55]
	global_load_dword v4, v[18:19], off offset:96
	s_waitcnt vmcnt(0) lgkmcnt(0)
	v_mul_f32_e32 v5, v5, v4

; __device__ __forceinline__ void tr_load(const TrDesc& d, int tid, float (&v)[8]) {
;     const int nn = tid & 63, np = d.n0 + nn; int col = np; const float* s = d.src;
;     if (d.mode == 1) { if (np >= 1216) col = -1; else if (np >= 1152) { const int i = np - 1152; col = 1152 + (i >> 1) + 32 * (i & 1); } }
;     else if (d.mode == 2) { const int h = np / 192, dd = np % 192; if (dd >= 128) { const int i = dd - 128; col = 192 * h + 128 + (i >> 1) + 32 * (i & 1); } }
;     else if (d.mode == 3) { col = (np >> 8) * 128 + (np & 127); if ((np >> 7) & 1) s = d.src2; }
; #pragma unroll
;     for (int i = 0; i < 8; ++i) { const int kk = (tid >> 6) + 8 * i; float x = 0.f;
;         if (col >= 0) { x = s[(size_t)(d.k0 + kk) * d.ld_src + col]; if (d.rs) x *= d.rs[d.k0 + kk]; if (d.mode == 2) x *= QSCALE * 8.0f; }
;         v[i] = x; }
.LBB0_240:
	v_add_u32_e32 v0, 32, v10
	v_ashrrev_i32_e32 v6, 31, v0
	v_mul_lo_u32 v9, s50, v6
	v_mul_lo_u32 v15, s51, v0
	v_mad_u64_u32 v[6:7], s[20:21], s50, v0, 0
	v_add3_u32 v7, v7, v9, v15
	v_lshl_add_u64 v[6:7], v[6:7], 2, v[12:13]
	flat_load_dword v0, v[6:7]
	s_and_b64 vcc, exec, s[6:7]
	s_cbranch_vccnz .LBB0_242
	v_lshl_add_u64 v[6:7], v[10:11], 2, s[54:55]
	global_load_dword v6, v[6:7], off offset:128
	s_waitcnt vmcnt(0) lgkmcnt(0)
	v_mul_f32_e32 v0, v0, v6
.LBB0_242:
	v_add_u32_e32 v6, 40, v10
	v_ashrrev_i32_e32 v7, 31, v6
	v_mul_lo_u32 v9, s50, v7
	v_mul_lo_u32 v15, s51, v6
	v_mad_u64_u32 v[6:7], s[20:21], s50, v6, 0
	v_add3_u32 v7, v7, v9, v15
	v_lshl_add_u64 v[6:7], v[6:7], 2, v[12:13]
	flat_load_dword v7, v[6:7]
	s_and_b64 vcc, exec, s[6:7]
	s_cbranch_vccnz .LBB0_244
	v_lshl_add_u64 v[18:19], v[10:11], 2, s[54:55]
	global_load_dword v6, v[18:19], off offset:160
	s_waitcnt vmcnt(0) lgkmcnt(0)
	v_mul_f32_e32 v7, v7, v6

; __device__ __forceinline__ void tr_load(const TrDesc& d, int tid, float (&v)[8]) {
;     const int nn = tid & 63, np = d.n0 + nn; int col = np; const float* s = d.src;
;     if (d.mode == 1) { if (np >= 1216) col = -1; else if (np >= 1152) { const int i = np - 1152; col = 1152 + (i >> 1) + 32 * (i & 1); } }
;     else if (d.mode == 2) { const int h = np / 192, dd = np % 192; if (dd >= 128) { const int i = dd - 128; col = 192 * h + 128 + (i >> 1) + 32 * (i & 1); } }
;     else if (d.mode == 3) { col = (np >> 8) * 128 + (np & 127); if ((np >> 7) & 1) s = d.src2; }
; #pragma unroll
;     for (int i = 0; i < 8; ++i) { const int kk = (tid >> 6) + 8 * i; float x = 0.f;
;         if (col >= 0) { x = s[(size_t)(d.k0 + kk) * d.ld_src + col]; if (d.rs) x *= d.rs[d.k0 + kk]; if (d.mode == 2) x *= QSCALE * 8.0f; }
;         v[i] = x; }
.LBB0_254:
	v_add_u32_e32 v0, 48, v10
	v_ashrrev_i32_e32 v8, 31, v0
	v_mul_lo_u32 v15, s50, v8
	v_mul_lo_u32 v17, s51, v0
	v_mad_u64_u32 v[8:9], s[20:21], s50, v0, 0
	v_add3_u32 v9, v9, v15, v17
	v_lshl_add_u64 v[8:9], v[8:9], 2, v[12:13]
	flat_load_dword v0, v[8:9]
	s_and_b64 vcc, exec, s[6:7]
	s_cbranch_vccnz .LBB0_256
	v_lshl_add_u64 v[8:9], v[10:11], 2, s[54:55]
	global_load_dword v8, v[8:9], off offset:192
	s_waitcnt vmcnt(0) lgkmcnt(0)
	v_mul_f32_e32 v0, v0, v8
.LBB0_256:
	v_add_u32_e32 v8, 56, v10
	v_ashrrev_i32_e32 v9, 31, v8
	v_mul_lo_u32 v15, s50, v9
	v_mul_lo_u32 v17, s51, v8
	v_mad_u64_u32 v[8:9], s[20:21], s50, v8, 0
	v_add3_u32 v9, v9, v15, v17
	v_lshl_add_u64 v[8:9], v[8:9], 2, v[12:13]
	flat_load_dword v9, v[8:9]
	s_and_b64 vcc, exec, s[6:7]
	s_cbranch_vccnz .LBB0_258
	v_lshl_add_u64 v[10:11], v[10:11], 2, s[54:55]
	global_load_dword v8, v[10:11], off offset:224
	s_waitcnt vmcnt(0) lgkmcnt(0)
	v_mul_f32_e32 v9, v9, v8

; __device__ __forceinline__ void tr_load(const TrDesc& d, int tid, float (&v)[8]) {
;     const int nn = tid & 63, np = d.n0 + nn; int col = np; const float* s = d.src;
;     if (d.mode == 1) { if (np >= 1216) col = -1; else if (np >= 1152) { const int i = np - 1152; col = 1152 + (i >> 1) + 32 * (i & 1); } }
;     else if (d.mode == 2) { const int h = np / 192, dd = np % 192; if (dd >= 128) { const int i = dd - 128; col = 192 * h + 128 + (i >> 1) + 32 * (i & 1); } }
;     else if (d.mode == 3) { col = (np >> 8) * 128 + (np & 127); if ((np >> 7) & 1) s = d.src2; }
; #pragma unroll
;     for (int i = 0; i < 8; ++i) { const int kk = (tid >> 6) + 8 * i; float x = 0.f;
;         if (col >= 0) { x = s[(size_t)(d.k0 + kk) * d.ld_src + col]; if (d.rs) x *= d.rs[d.k0 + kk]; if (d.mode == 2) x *= QSCALE * 8.0f; }
;         v[i] = x; }
.LBB0_284:
	s_cmp_lg_u64 s[50:51], 0
	v_cmp_gt_i32_e64 s[6:7], 0, v0
	s_cselect_b64 s[56:57], -1, 0
	s_and_saveexec_b64 s[54:55], s[6:7]
	s_xor_b64 s[54:55], exec, s[54:55]
	v_mov_b32_e32 v2, s89
	s_or_saveexec_b64 s[54:55], s[54:55]
	v_add_u32_e32 v12, s60, v17
	v_lshl_add_u64 v[14:15], v[0:1], 2, s[4:5]
	v_cndmask_b32_e64 v0, 0, 1, s[56:57]
	v_mov_b32_e32 v3, 0
	v_ashrrev_i32_e32 v13, 31, v12
	v_cmp_ne_u32_e64 s[4:5], 1, v0
	s_movk_i32 s63, 0x4000
	s_mov_b32 s62, 0x2aaaaaab
	s_xor_b64 exec, exec, s[54:55]
	s_cbranch_execz .LBB0_304
	v_mul_lo_u32 v0, s53, v12
	v_mul_lo_u32 v4, s52, v13
	v_mad_u64_u32 v[2:3], s[56:57], s52, v12, 0
	v_add3_u32 v3, v3, v4, v0
	v_lshl_add_u64 v[2:3], v[2:3], 2, v[14:15]
	flat_load_dword v0, v[2:3]
	s_and_b64 vcc, exec, s[4:5]
	v_lshl_add_u64 v[2:3], v[12:13], 2, s[50:51]
	s_cbranch_vccnz .LBB0_289
	global_load_dword v4, v[2:3], off
	s_waitcnt vmcnt(0) lgkmcnt(0)
	v_mul_f32_e32 v0, v0, v4
.LBB0_289:
	v_add_u32_e32 v4, 8, v12
	v_ashrrev_i32_e32 v5, 31, v4
	v_mul_lo_u32 v6, s52, v5
	v_mul_lo_u32 v7, s53, v4
	v_mad_u64_u32 v[4:5], s[56:57], s52, v4, 0
	v_add3_u32 v5, v5, v6, v7
	v_lshl_add_u64 v[4:5], v[4:5], 2, v[14:15]
	flat_load_dword v4, v[4:5]
	s_and_b64 vcc, exec, s[4:5]
	s_cbranch_vccnz .LBB0_291
	global_load_dword v2, v[2:3], off offset:32
	s_waitcnt vmcnt(0) lgkmcnt(0)
	v_mul_f32_e32 v4, v4, v2

; __device__ __forceinline__ void tr_load(const TrDesc& d, int tid, float (&v)[8]) {
;     const int nn = tid & 63, np = d.n0 + nn; int col = np; const float* s = d.src;
;     if (d.mode == 1) { if (np >= 1216) col = -1; else if (np >= 1152) { const int i = np - 1152; col = 1152 + (i >> 1) + 32 * (i & 1); } }
;     else if (d.mode == 2) { const int h = np / 192, dd = np % 192; if (dd >= 128) { const int i = dd - 128; col = 192 * h + 128 + (i >> 1) + 32 * (i & 1); } }
;     else if (d.mode == 3) { col = (np >> 8) * 128 + (np & 127); if ((np >> 7) & 1) s = d.src2; }
; #pragma unroll
;     for (int i = 0; i < 8; ++i) { const int kk = (tid >> 6) + 8 * i; float x = 0.f;
;         if (col >= 0) { x = s[(size_t)(d.k0 + kk) * d.ld_src + col]; if (d.rs) x *= d.rs[d.k0 + kk]; if (d.mode == 2) x *= QSCALE * 8.0f; }
;         v[i] = x; }
.LBB0_293:
	v_add_u32_e32 v0, 16, v12
	v_ashrrev_i32_e32 v4, 31, v0
	v_mul_lo_u32 v7, s52, v4
	v_mul_lo_u32 v9, s53, v0
	v_mad_u64_u32 v[4:5], s[56:57], s52, v0, 0
	v_add3_u32 v5, v5, v7, v9
	v_lshl_add_u64 v[4:5], v[4:5], 2, v[14:15]
	flat_load_dword v0, v[4:5]
	s_and_b64 vcc, exec, s[4:5]
	s_cbranch_vccnz .LBB0_295
	v_lshl_add_u64 v[4:5], v[12:13], 2, s[50:51]
	global_load_dword v4, v[4:5], off offset:64
	s_waitcnt vmcnt(0) lgkmcnt(0)
	v_mul_f32_e32 v0, v0, v4
.LBB0_295:
	v_add_u32_e32 v4, 24, v12
	v_ashrrev_i32_e32 v5, 31, v4
	v_mul_lo_u32 v7, s52, v5
	v_mul_lo_u32 v9, s53, v4
	v_mad_u64_u32 v[4:5], s[56:57], s52, v4, 0
	v_add3_u32 v5, v5, v7, v9
	v_lshl_add_u64 v[4:5], v[4:5], 2, v[14:15]
	flat_load_dword v5, v[4:5]
	s_and_b64 vcc, exec, s[4:5]
	s_cbranch_vccnz .LBB0_297
	v_lshl_add_u64 v[22:23], v[12:13], 2, s[50:51]
	global_load_dword v4, v[22:23], off offset:96
	s_waitcnt vmcnt(0) lgkmcnt(0)
	v_mul_f32_e32 v5, v5, v4

; __device__ __forceinline__ void tr_load(const TrDesc& d, int tid, float (&v)[8]) {
;     const int nn = tid & 63, np = d.n0 + nn; int col = np; const float* s = d.src;
;     if (d.mode == 1) { if (np >= 1216) col = -1; else if (np >= 1152) { const int i = np - 1152; col = 1152 + (i >> 1) + 32 * (i & 1); } }
;     else if (d.mode == 2) { const int h = np / 192, dd = np % 192; if (dd >= 128) { const int i = dd - 128; col = 192 * h + 128 + (i >> 1) + 32 * (i & 1); } }
;     else if (d.mode == 3) { col = (np >> 8) * 128 + (np & 127); if ((np >> 7) & 1) s = d.src2; }
; #pragma unroll
;     for (int i = 0; i < 8; ++i) { const int kk = (tid >> 6) + 8 * i; float x = 0.f;
;         if (col >= 0) { x = s[(size_t)(d.k0 + kk) * d.ld_src + col]; if (d.rs) x *= d.rs[d.k0 + kk]; if (d.mode == 2) x *= QSCALE * 8.0f; }
;         v[i] = x; }
.LBB0_299:
	v_add_u32_e32 v0, 32, v12
	v_ashrrev_i32_e32 v6, 31, v0
	v_mul_lo_u32 v9, s52, v6
	v_mul_lo_u32 v11, s53, v0
	v_mad_u64_u32 v[6:7], s[56:57], s52, v0, 0
	v_add3_u32 v7, v7, v9, v11
	v_lshl_add_u64 v[6:7], v[6:7], 2, v[14:15]
	flat_load_dword v0, v[6:7]
	s_and_b64 vcc, exec, s[4:5]
	s_cbranch_vccnz .LBB0_301
	v_lshl_add_u64 v[6:7], v[12:13], 2, s[50:51]
	global_load_dword v6, v[6:7], off offset:128
	s_waitcnt vmcnt(0) lgkmcnt(0)
	v_mul_f32_e32 v0, v0, v6
.LBB0_301:
	v_add_u32_e32 v6, 40, v12
	v_ashrrev_i32_e32 v7, 31, v6
	v_mul_lo_u32 v9, s52, v7
	v_mul_lo_u32 v11, s53, v6
	v_mad_u64_u32 v[6:7], s[56:57], s52, v6, 0
	v_add3_u32 v7, v7, v9, v11
	v_lshl_add_u64 v[6:7], v[6:7], 2, v[14:15]
	flat_load_dword v7, v[6:7]
	s_and_b64 vcc, exec, s[4:5]
	s_cbranch_vccnz .LBB0_303
	v_lshl_add_u64 v[22:23], v[12:13], 2, s[50:51]
	global_load_dword v6, v[22:23], off offset:160
	s_waitcnt vmcnt(0) lgkmcnt(0)
	v_mul_f32_e32 v7, v7, v6

; __device__ __forceinline__ void tr_load(const TrDesc& d, int tid, float (&v)[8]) {
;     const int nn = tid & 63, np = d.n0 + nn; int col = np; const float* s = d.src;
;     if (d.mode == 1) { if (np >= 1216) col = -1; else if (np >= 1152) { const int i = np - 1152; col = 1152 + (i >> 1) + 32 * (i & 1); } }
;     else if (d.mode == 2) { const int h = np / 192, dd = np % 192; if (dd >= 128) { const int i = dd - 128; col = 192 * h + 128 + (i >> 1) + 32 * (i & 1); } }
;     else if (d.mode == 3) { col = (np >> 8) * 128 + (np & 127); if ((np >> 7) & 1) s = d.src2; }
; #pragma unroll
;     for (int i = 0; i < 8; ++i) { const int kk = (tid >> 6) + 8 * i; float x = 0.f;
;         if (col >= 0) { x = s[(size_t)(d.k0 + kk) * d.ld_src + col]; if (d.rs) x *= d.rs[d.k0 + kk]; if (d.mode == 2) x *= QSCALE * 8.0f; }
;         v[i] = x; }
.LBB0_310:
	s_or_saveexec_b64 s[6:7], s[6:7]
	v_readlane_b32 s56, v255, 15
	v_mov_b32_e32 v9, 0
	v_readlane_b32 s57, v255, 16
	s_xor_b64 exec, exec, s[6:7]
	s_cbranch_execz .LBB0_261
	v_add_u32_e32 v0, 48, v12
	v_ashrrev_i32_e32 v8, 31, v0
	v_mul_lo_u32 v11, s52, v8
	v_mul_lo_u32 v21, s53, v0
	v_mad_u64_u32 v[8:9], s[54:55], s52, v0, 0
	v_add3_u32 v9, v9, v11, v21
	v_lshl_add_u64 v[8:9], v[8:9], 2, v[14:15]
	flat_load_dword v0, v[8:9]
	s_and_b64 vcc, exec, s[4:5]
	s_cbranch_vccnz .LBB0_313
	v_lshl_add_u64 v[8:9], v[12:13], 2, s[50:51]
	global_load_dword v8, v[8:9], off offset:192
	s_waitcnt vmcnt(0) lgkmcnt(0)
	v_mul_f32_e32 v0, v0, v8
.LBB0_313:
	v_add_u32_e32 v8, 56, v12
	v_ashrrev_i32_e32 v9, 31, v8
	v_mul_lo_u32 v11, s52, v9
	v_mul_lo_u32 v21, s53, v8
	v_mad_u64_u32 v[8:9], s[52:53], s52, v8, 0
	v_add3_u32 v9, v9, v11, v21
	v_lshl_add_u64 v[8:9], v[8:9], 2, v[14:15]
	flat_load_dword v9, v[8:9]
	s_and_b64 vcc, exec, s[4:5]
	s_cbranch_vccnz .LBB0_260
	v_lshl_add_u64 v[12:13], v[12:13], 2, s[50:51]
	global_load_dword v8, v[12:13], off offset:224
	s_waitcnt vmcnt(0) lgkmcnt(0)
	v_mul_f32_e32 v9, v9, v8
	s_branch .LBB0_260

; __device__ __forceinline__ void conv_weights_A(const Params& p, int l, LAS float* scr) {
;     ...
;         else { const int g = (k0 - 256) >> 6, c = (k0 - 256) & 63; const float* wp = w_pool + (g * 64 + c) * 64; const float* sc = psc + 64 * g; const float* wo = w_out + (size_t)(256 + 64 * g) * DM + n;
; #pragma unroll 32
;                for (int j = 0; j < 64; ++j) { const float bv = sc[j] * wo[(size_t)j * DM]; a0 += wp[j] * bv; a1 += wp[64 + j] * bv; a2 += wp[128 + j] * bv; a3 += wp[192 + j] * bv; } }
.LBB0_322:
	v_add_co_u32_e32 v14, vcc, 0xfffe1000, v6
	s_mov_b32 s2, 0x10000
	s_nop 0
	v_addc_co_u32_e32 v15, vcc, -1, v7, vcc
	global_load_dword v0, v[14:15], off
	v_lshl_add_u64 v[14:15], v[8:9], 0, s[24:25]
	v_add_co_u32_e32 v14, vcc, s2, v14
	v_lshl_add_u64 v[16:17], v[4:5], 0, s[24:25]
	s_nop 0
	v_addc_co_u32_e32 v15, vcc, 0, v15, vcc
	global_load_dwordx4 v[20:23], v[16:17], off
	global_load_dwordx4 v[24:27], v[14:15], off
	global_load_dwordx4 v[28:31], v[14:15], off offset:256
	s_add_u32 s24, s24, 0x80
	s_addc_u32 s25, s25, 0
	s_cmpk_lg_i32 s24, 0x100
	s_waitcnt vmcnt(0) lgkmcnt(0)
	v_mul_f32_e32 v0, v20, v0
	v_mov_b32_e32 v32, v24
	v_mov_b32_e32 v33, v28
	v_pk_fma_f32 v[12:13], v[0:1], v[32:33], v[12:13] op_sel_hi:[0,1,1]
	global_load_dwordx4 v[32:35], v[14:15], off offset:512
	global_load_dwordx4 v[36:39], v[14:15], off offset:768
	v_mov_b32_e32 v28, v25
	s_waitcnt vmcnt(0) lgkmcnt(0)
	v_mov_b32_e32 v40, v32
	v_mov_b32_e32 v41, v36
	v_pk_fma_f32 v[10:11], v[0:1], v[40:41], v[10:11] op_sel_hi:[0,1,1]
	v_add_co_u32_e32 v40, vcc, s21, v6
	v_mov_b32_e32 v36, v33
	s_nop 0
	v_addc_co_u32_e32 v41, vcc, -1, v7, vcc
	global_load_dword v0, v[40:41], off
	v_add_co_u32_e32 v20, vcc, s22, v6
	s_waitcnt vmcnt(0) lgkmcnt(0)
	v_mul_f32_e32 v0, v21, v0
	v_addc_co_u32_e32 v21, vcc, -1, v7, vcc
	v_pk_fma_f32 v[12:13], v[0:1], v[28:29], v[12:13] op_sel_hi:[0,1,1]
	v_pk_fma_f32 v[10:11], v[0:1], v[36:37], v[10:11] op_sel_hi:[0,1,1]
	global_load_dword v0, v[20:21], off
	v_mov_b32_e32 v20, v26
	v_mov_b32_e32 v21, v30
	v_mov_b32_e32 v30, v27
	s_waitcnt vmcnt(0) lgkmcnt(0)
	v_mul_f32_e32 v0, v22, v0
	v_pk_fma_f32 v[12:13], v[0:1], v[20:21], v[12:13] op_sel_hi:[0,1,1]
	v_mov_b32_e32 v20, v34
	v_mov_b32_e32 v21, v38
	v_pk_fma_f32 v[10:11], v[0:1], v[20:21], v[10:11] op_sel_hi:[0,1,1]
	v_add_co_u32_e32 v20, vcc, s26, v6
	v_mov_b32_e32 v38, v35
	s_nop 0
	v_addc_co_u32_e32 v21, vcc, -1, v7, vcc
	global_load_dword v0, v[20:21], off
	v_add_co_u32_e32 v20, vcc, s68, v6
	s_waitcnt vmcnt(0) lgkmcnt(0)
	v_mul_f32_e32 v0, v23, v0
	v_addc_co_u32_e32 v21, vcc, -1, v7, vcc
	v_pk_fma_f32 v[28:29], v[0:1], v[30:31], v[12:13] op_sel_hi:[0,1,1]
	v_pk_fma_f32 v[36:37], v[0:1], v[38:39], v[10:11] op_sel_hi:[0,1,1]
	global_load_dwordx4 v[10:13], v[16:17], off offset:16
	global_load_dword v0, v[20:21], off
	s_nop 0
	global_load_dwordx4 v[20:23], v[14:15], off offset:16
	global_load_dwordx4 v[24:27], v[14:15], off offset:272
	s_waitcnt vmcnt(0) lgkmcnt(0)
	v_mov_b32_e32 v30, v20
	v_mul_f32_e32 v0, v10, v0
	v_mov_b32_e32 v31, v24
	v_pk_fma_f32 v[38:39], v[0:1], v[30:31], v[28:29] op_sel_hi:[0,1,1]
	global_load_dwordx4 v[28:31], v[14:15], off offset:528
	global_load_dwordx4 v[32:35], v[14:15], off offset:784
	v_mov_b32_e32 v24, v21
	s_waitcnt vmcnt(0) lgkmcnt(0)
	v_mov_b32_e32 v40, v28
	v_mov_b32_e32 v41, v32
	v_pk_fma_f32 v[36:37], v[0:1], v[40:41], v[36:37] op_sel_hi:[0,1,1]
	v_add_co_u32_e32 v40, vcc, s69, v6
	v_mov_b32_e32 v32, v29
	s_nop 0
	v_addc_co_u32_e32 v41, vcc, -1, v7, vcc
	global_load_dword v0, v[40:41], off
	s_waitcnt vmcnt(0) lgkmcnt(0)
	v_mul_f32_e32 v0, v11, v0
	v_pk_fma_f32 v[10:11], v[0:1], v[24:25], v[38:39] op_sel_hi:[0,1,1]
	v_add_co_u32_e32 v24, vcc, s70, v6
	v_pk_fma_f32 v[20:21], v[0:1], v[32:33], v[36:37] op_sel_hi:[0,1,1]
	s_nop 0
	v_addc_co_u32_e32 v25, vcc, -1, v7, vcc
	global_load_dword v0, v[24:25], off
	v_mov_b32_e32 v24, v22
	v_mov_b32_e32 v25, v26
	v_mov_b32_e32 v26, v23
	s_waitcnt vmcnt(0) lgkmcnt(0)
	v_mul_f32_e32 v0, v12, v0
	v_pk_fma_f32 v[10:11], v[0:1], v[24:25], v[10:11] op_sel_hi:[0,1,1]
	v_mov_b32_e32 v24, v30
	v_mov_b32_e32 v25, v34
	v_pk_fma_f32 v[20:21], v[0:1], v[24:25], v[20:21] op_sel_hi:[0,1,1]
	v_add_co_u32_e32 v24, vcc, s71, v6
	v_mov_b32_e32 v34, v31
	s_nop 0
	v_addc_co_u32_e32 v25, vcc, -1, v7, vcc
	global_load_dword v0, v[24:25], off
	s_waitcnt vmcnt(0) lgkmcnt(0)
	v_mul_f32_e32 v0, v13, v0
	v_pk_fma_f32 v[36:37], v[0:1], v[34:35], v[20:21] op_sel_hi:[0,1,1]
	v_add_co_u32_e32 v20, vcc, s72, v6
	v_pk_fma_f32 v[28:29], v[0:1], v[26:27], v[10:11] op_sel_hi:[0,1,1]
	s_nop 0
	v_addc_co_u32_e32 v21, vcc, -1, v7, vcc
	global_load_dwordx4 v[10:13], v[16:17], off offset:32
	global_load_dword v0, v[20:21], off
	s_nop 0
	global_load_dwordx4 v[20:23], v[14:15], off offset:32
	global_load_dwordx4 v[24:27], v[14:15], off offset:288
	s_waitcnt vmcnt(0) lgkmcnt(0)
	v_mov_b32_e32 v30, v20
	v_mul_f32_e32 v0, v10, v0
	v_mov_b32_e32 v31, v24
	v_pk_fma_f32 v[38:39], v[0:1], v[30:31], v[28:29] op_sel_hi:[0,1,1]
	global_load_dwordx4 v[28:31], v[14:15], off offset:544
	global_load_dwordx4 v[32:35], v[14:15], off offset:800
	v_mov_b32_e32 v24, v21
	s_waitcnt vmcnt(0) lgkmcnt(0)
	v_mov_b32_e32 v40, v28
	v_mov_b32_e32 v41, v32
	v_pk_fma_f32 v[36:37], v[0:1], v[40:41], v[36:37] op_sel_hi:[0,1,1]
	v_add_co_u32_e32 v40, vcc, s73, v6
	v_mov_b32_e32 v32, v29
	s_nop 0
	v_addc_co_u32_e32 v41, vcc, -1, v7, vcc
	global_load_dword v0, v[40:41], off
	s_waitcnt vmcnt(0) lgkmcnt(0)
	v_mul_f32_e32 v0, v11, v0
	v_pk_fma_f32 v[10:11], v[0:1], v[24:25], v[38:39] op_sel_hi:[0,1,1]
	v_add_co_u32_e32 v24, vcc, s74, v6
	v_pk_fma_f32 v[20:21], v[0:1], v[32:33], v[36:37] op_sel_hi:[0,1,1]
	s_nop 0
	v_addc_co_u32_e32 v25, vcc, -1, v7, vcc
	global_load_dword v0, v[24:25], off
	v_mov_b32_e32 v24, v22
	v_mov_b32_e32 v25, v26
	v_mov_b32_e32 v26, v23
	s_waitcnt vmcnt(0) lgkmcnt(0)
	v_mul_f32_e32 v0, v12, v0
	v_pk_fma_f32 v[10:11], v[0:1], v[24:25], v[10:11] op_sel_hi:[0,1,1]
	v_mov_b32_e32 v24, v30
	v_mov_b32_e32 v25, v34
	v_pk_fma_f32 v[20:21], v[0:1], v[24:25], v[20:21] op_sel_hi:[0,1,1]
	v_add_co_u32_e32 v24, vcc, s75, v6
	v_mov_b32_e32 v34, v31
	s_nop 0
	v_addc_co_u32_e32 v25, vcc, -1, v7, vcc
	global_load_dword v0, v[24:25], off
	s_waitcnt vmcnt(0) lgkmcnt(0)
; __device__ __forceinline__ void conv_weights_A(const Params& p, int l, LAS float* scr) {
;     ...
;         else { const int g = (k0 - 256) >> 6, c = (k0 - 256) & 63; const float* wp = w_pool + (g * 64 + c) * 64; const float* sc = psc + 64 * g; const float* wo = w_out + (size_t)(256 + 64 * g) * DM + n;
; #pragma unroll 32
;                for (int j = 0; j < 64; ++j) { const float bv = sc[j] * wo[(size_t)j * DM]; a0 += wp[j] * bv; a1 += wp[64 + j] * bv; a2 += wp[128 + j] * bv; a3 += wp[192 + j] * bv; } }
	v_mul_f32_e32 v0, v13, v0
	v_pk_fma_f32 v[36:37], v[0:1], v[34:35], v[20:21] op_sel_hi:[0,1,1]
	v_add_co_u32_e32 v20, vcc, s76, v6
	v_pk_fma_f32 v[28:29], v[0:1], v[26:27], v[10:11] op_sel_hi:[0,1,1]
	s_nop 0
	v_addc_co_u32_e32 v21, vcc, -1, v7, vcc
	global_load_dwordx4 v[10:13], v[16:17], off offset:48
	global_load_dword v0, v[20:21], off
	s_nop 0
	global_load_dwordx4 v[20:23], v[14:15], off offset:48
	global_load_dwordx4 v[24:27], v[14:15], off offset:304
	s_waitcnt vmcnt(0) lgkmcnt(0)
	v_mov_b32_e32 v30, v20
	v_mul_f32_e32 v0, v10, v0
	v_mov_b32_e32 v31, v24
	v_pk_fma_f32 v[38:39], v[0:1], v[30:31], v[28:29] op_sel_hi:[0,1,1]
	global_load_dwordx4 v[28:31], v[14:15], off offset:560
	global_load_dwordx4 v[32:35], v[14:15], off offset:816
	v_mov_b32_e32 v24, v21
	s_waitcnt vmcnt(0) lgkmcnt(0)
	v_mov_b32_e32 v40, v28
	v_mov_b32_e32 v41, v32
	v_pk_fma_f32 v[36:37], v[0:1], v[40:41], v[36:37] op_sel_hi:[0,1,1]
	v_add_co_u32_e32 v40, vcc, s77, v6
	v_mov_b32_e32 v32, v29
	s_nop 0
	v_addc_co_u32_e32 v41, vcc, -1, v7, vcc
	global_load_dword v0, v[40:41], off
	s_waitcnt vmcnt(0) lgkmcnt(0)
	v_mul_f32_e32 v0, v11, v0
	v_pk_fma_f32 v[10:11], v[0:1], v[24:25], v[38:39] op_sel_hi:[0,1,1]
	v_add_co_u32_e32 v24, vcc, s78, v6
	v_pk_fma_f32 v[20:21], v[0:1], v[32:33], v[36:37] op_sel_hi:[0,1,1]
	s_nop 0
	v_addc_co_u32_e32 v25, vcc, -1, v7, vcc
	global_load_dword v0, v[24:25], off
	v_mov_b32_e32 v24, v22
	v_mov_b32_e32 v25, v26
	v_mov_b32_e32 v26, v23
	s_waitcnt vmcnt(0) lgkmcnt(0)
	v_mul_f32_e32 v0, v12, v0
	v_pk_fma_f32 v[10:11], v[0:1], v[24:25], v[10:11] op_sel_hi:[0,1,1]
	v_mov_b32_e32 v24, v30
	v_mov_b32_e32 v25, v34
	v_pk_fma_f32 v[20:21], v[0:1], v[24:25], v[20:21] op_sel_hi:[0,1,1]
	v_add_co_u32_e32 v24, vcc, s79, v6
	v_mov_b32_e32 v34, v31
	s_nop 0
	v_addc_co_u32_e32 v25, vcc, -1, v7, vcc
	global_load_dword v0, v[24:25], off
	s_waitcnt vmcnt(0) lgkmcnt(0)
	v_mul_f32_e32 v0, v13, v0
	v_pk_fma_f32 v[36:37], v[0:1], v[34:35], v[20:21] op_sel_hi:[0,1,1]
	v_add_co_u32_e32 v20, vcc, s80, v6
	v_pk_fma_f32 v[28:29], v[0:1], v[26:27], v[10:11] op_sel_hi:[0,1,1]
	s_nop 0
	v_addc_co_u32_e32 v21, vcc, -1, v7, vcc
	global_load_dwordx4 v[10:13], v[16:17], off offset:64
	global_load_dword v0, v[20:21], off
	s_nop 0
	global_load_dwordx4 v[20:23], v[14:15], off offset:64
	global_load_dwordx4 v[24:27], v[14:15], off offset:320
	s_waitcnt vmcnt(0) lgkmcnt(0)
	v_mul_f32_e32 v0, v10, v0
	v_mov_b32_e32 v30, v20
	v_mov_b32_e32 v31, v24
	v_pk_fma_f32 v[38:39], v[0:1], v[30:31], v[28:29] op_sel_hi:[0,1,1]
	global_load_dwordx4 v[28:31], v[14:15], off offset:576
	global_load_dwordx4 v[32:35], v[14:15], off offset:832
	v_mov_b32_e32 v24, v21
	s_waitcnt vmcnt(0) lgkmcnt(0)
	v_mov_b32_e32 v40, v28
	v_mov_b32_e32 v41, v32
	v_pk_fma_f32 v[36:37], v[0:1], v[40:41], v[36:37] op_sel_hi:[0,1,1]
	v_add_co_u32_e32 v40, vcc, s81, v6
	v_mov_b32_e32 v32, v29
	s_nop 0
	v_addc_co_u32_e32 v41, vcc, -1, v7, vcc
	global_load_dword v0, v[40:41], off
	s_waitcnt vmcnt(0) lgkmcnt(0)
	v_mul_f32_e32 v0, v11, v0
	v_pk_fma_f32 v[10:11], v[0:1], v[24:25], v[38:39] op_sel_hi:[0,1,1]
	v_add_co_u32_e32 v24, vcc, s82, v6
	v_pk_fma_f32 v[20:21], v[0:1], v[32:33], v[36:37] op_sel_hi:[0,1,1]
	s_nop 0
	v_addc_co_u32_e32 v25, vcc, -1, v7, vcc
	global_load_dword v0, v[24:25], off
	v_mov_b32_e32 v24, v22
	v_mov_b32_e32 v25, v26
	v_mov_b32_e32 v26, v23
	s_waitcnt vmcnt(0) lgkmcnt(0)
	v_mul_f32_e32 v0, v12, v0
	v_pk_fma_f32 v[10:11], v[0:1], v[24:25], v[10:11] op_sel_hi:[0,1,1]
	v_mov_b32_e32 v24, v30
	v_mov_b32_e32 v25, v34
	v_pk_fma_f32 v[20:21], v[0:1], v[24:25], v[20:21] op_sel_hi:[0,1,1]
	v_add_co_u32_e32 v24, vcc, s83, v6
	v_mov_b32_e32 v34, v31
	s_nop 0
	v_addc_co_u32_e32 v25, vcc, -1, v7, vcc
	global_load_dword v0, v[24:25], off
	s_waitcnt vmcnt(0) lgkmcnt(0)
	v_mul_f32_e32 v0, v13, v0
	v_pk_fma_f32 v[36:37], v[0:1], v[34:35], v[20:21] op_sel_hi:[0,1,1]
	v_add_co_u32_e32 v20, vcc, s86, v6
	v_pk_fma_f32 v[28:29], v[0:1], v[26:27], v[10:11] op_sel_hi:[0,1,1]
	s_nop 0
	v_addc_co_u32_e32 v21, vcc, -1, v7, vcc
	global_load_dwordx4 v[10:13], v[16:17], off offset:80
	global_load_dword v0, v[20:21], off
	s_nop 0
	global_load_dwordx4 v[20:23], v[14:15], off offset:80
	global_load_dwordx4 v[24:27], v[14:15], off offset:336
	s_waitcnt vmcnt(0) lgkmcnt(0)
	v_mul_f32_e32 v0, v10, v0
	v_mov_b32_e32 v30, v20
	v_mov_b32_e32 v31, v24
	v_pk_fma_f32 v[38:39], v[0:1], v[30:31], v[28:29] op_sel_hi:[0,1,1]
	global_load_dwordx4 v[28:31], v[14:15], off offset:592
	global_load_dwordx4 v[32:35], v[14:15], off offset:848
	v_mov_b32_e32 v24, v21
	s_waitcnt vmcnt(0) lgkmcnt(0)
	v_mov_b32_e32 v40, v28
	v_mov_b32_e32 v41, v32
	v_pk_fma_f32 v[36:37], v[0:1], v[40:41], v[36:37] op_sel_hi:[0,1,1]
	v_add_co_u32_e32 v40, vcc, s87, v6
	v_mov_b32_e32 v32, v29
	s_nop 0
	v_addc_co_u32_e32 v41, vcc, -1, v7, vcc
	global_load_dword v0, v[40:41], off
	s_waitcnt vmcnt(0) lgkmcnt(0)
; __device__ __forceinline__ void conv_weights_A(const Params& p, int l, LAS float* scr) {
;     ...
;         else { const int g = (k0 - 256) >> 6, c = (k0 - 256) & 63; const float* wp = w_pool + (g * 64 + c) * 64; const float* sc = psc + 64 * g; const float* wo = w_out + (size_t)(256 + 64 * g) * DM + n;
; #pragma unroll 32
;                for (int j = 0; j < 64; ++j) { const float bv = sc[j] * wo[(size_t)j * DM]; a0 += wp[j] * bv; a1 += wp[64 + j] * bv; a2 += wp[128 + j] * bv; a3 += wp[192 + j] * bv; } }
	v_mul_f32_e32 v0, v11, v0
	v_pk_fma_f32 v[10:11], v[0:1], v[24:25], v[38:39] op_sel_hi:[0,1,1]
	v_add_co_u32_e32 v24, vcc, s84, v6
	v_pk_fma_f32 v[20:21], v[0:1], v[32:33], v[36:37] op_sel_hi:[0,1,1]
	s_nop 0
	v_addc_co_u32_e32 v25, vcc, -1, v7, vcc
	global_load_dword v0, v[24:25], off
	v_mov_b32_e32 v24, v22
	v_mov_b32_e32 v25, v26
	v_mov_b32_e32 v26, v23
	s_waitcnt vmcnt(0) lgkmcnt(0)
	v_mul_f32_e32 v0, v12, v0
	v_pk_fma_f32 v[10:11], v[0:1], v[24:25], v[10:11] op_sel_hi:[0,1,1]
	v_mov_b32_e32 v24, v30
	v_mov_b32_e32 v25, v34
	v_pk_fma_f32 v[20:21], v[0:1], v[24:25], v[20:21] op_sel_hi:[0,1,1]
	v_add_co_u32_e32 v24, vcc, s85, v6
	v_mov_b32_e32 v34, v31
	s_nop 0
	v_addc_co_u32_e32 v25, vcc, -1, v7, vcc
	global_load_dword v0, v[24:25], off
	s_waitcnt vmcnt(0) lgkmcnt(0)
	v_mul_f32_e32 v0, v13, v0
	v_pk_fma_f32 v[36:37], v[0:1], v[34:35], v[20:21] op_sel_hi:[0,1,1]
	v_add_co_u32_e32 v20, vcc, s97, v6
	v_pk_fma_f32 v[28:29], v[0:1], v[26:27], v[10:11] op_sel_hi:[0,1,1]
	s_nop 0
	v_addc_co_u32_e32 v21, vcc, -1, v7, vcc
	global_load_dwordx4 v[10:13], v[16:17], off offset:96
	global_load_dword v0, v[20:21], off
	s_nop 0
	global_load_dwordx4 v[20:23], v[14:15], off offset:96
	global_load_dwordx4 v[24:27], v[14:15], off offset:352
	s_waitcnt vmcnt(0) lgkmcnt(0)
	v_mul_f32_e32 v0, v10, v0
	v_mov_b32_e32 v30, v20
	v_mov_b32_e32 v31, v24
	v_pk_fma_f32 v[38:39], v[0:1], v[30:31], v[28:29] op_sel_hi:[0,1,1]
	global_load_dwordx4 v[28:31], v[14:15], off offset:608
	global_load_dwordx4 v[32:35], v[14:15], off offset:864
	v_mov_b32_e32 v24, v21
	s_waitcnt vmcnt(0) lgkmcnt(0)
	v_mov_b32_e32 v40, v28
	v_mov_b32_e32 v41, v32
	v_pk_fma_f32 v[36:37], v[0:1], v[40:41], v[36:37] op_sel_hi:[0,1,1]
	v_add_co_u32_e32 v40, vcc, s90, v6
	v_mov_b32_e32 v32, v29
	s_nop 0
	v_addc_co_u32_e32 v41, vcc, -1, v7, vcc
	global_load_dword v0, v[40:41], off
	s_waitcnt vmcnt(0) lgkmcnt(0)
	v_mul_f32_e32 v0, v11, v0
	v_pk_fma_f32 v[10:11], v[0:1], v[24:25], v[38:39] op_sel_hi:[0,1,1]
	v_add_co_u32_e32 v24, vcc, s91, v6
	v_pk_fma_f32 v[20:21], v[0:1], v[32:33], v[36:37] op_sel_hi:[0,1,1]
	s_nop 0
	v_addc_co_u32_e32 v25, vcc, -1, v7, vcc
	global_load_dword v0, v[24:25], off
	v_mov_b32_e32 v24, v22
	v_mov_b32_e32 v25, v26
	v_mov_b32_e32 v26, v23
	s_waitcnt vmcnt(0) lgkmcnt(0)
	v_mul_f32_e32 v0, v12, v0
	v_pk_fma_f32 v[10:11], v[0:1], v[24:25], v[10:11] op_sel_hi:[0,1,1]
	v_mov_b32_e32 v24, v30
	v_mov_b32_e32 v25, v34
	v_pk_fma_f32 v[20:21], v[0:1], v[24:25], v[20:21] op_sel_hi:[0,1,1]
	v_add_co_u32_e32 v24, vcc, s36, v6
	v_mov_b32_e32 v34, v31
	s_nop 0
	v_addc_co_u32_e32 v25, vcc, -1, v7, vcc
	global_load_dword v0, v[24:25], off
	s_waitcnt vmcnt(0) lgkmcnt(0)
	v_mul_f32_e32 v0, v13, v0
	v_pk_fma_f32 v[28:29], v[0:1], v[26:27], v[10:11] op_sel_hi:[0,1,1]
	global_load_dwordx4 v[10:13], v[16:17], off offset:112
	v_add_co_u32_e32 v16, vcc, s37, v6
	v_pk_fma_f32 v[32:33], v[0:1], v[34:35], v[20:21] op_sel_hi:[0,1,1]
	s_nop 0
	v_addc_co_u32_e32 v17, vcc, -1, v7, vcc
	global_load_dword v0, v[16:17], off
	global_load_dwordx4 v[20:23], v[14:15], off offset:112
	global_load_dwordx4 v[24:27], v[14:15], off offset:368
	s_waitcnt vmcnt(0) lgkmcnt(0)
	v_mul_f32_e32 v0, v10, v0
	v_mov_b32_e32 v16, v20
	v_mov_b32_e32 v17, v24
	v_pk_fma_f32 v[34:35], v[0:1], v[16:17], v[28:29] op_sel_hi:[0,1,1]
	global_load_dwordx4 v[28:31], v[14:15], off offset:624
	s_nop 0
	global_load_dwordx4 v[14:17], v[14:15], off offset:880
	v_mov_b32_e32 v24, v21
	s_waitcnt vmcnt(0) lgkmcnt(0)
	v_mov_b32_e32 v36, v28
	v_mov_b32_e32 v37, v14
	v_pk_fma_f32 v[32:33], v[0:1], v[36:37], v[32:33] op_sel_hi:[0,1,1]
	v_add_co_u32_e32 v36, vcc, s96, v6
	v_mov_b32_e32 v14, v29
	s_nop 0
	v_addc_co_u32_e32 v37, vcc, -1, v7, vcc
	global_load_dword v0, v[36:37], off
	v_add_co_u32_e32 v20, vcc, s48, v6
	s_waitcnt vmcnt(0) lgkmcnt(0)
	v_mul_f32_e32 v0, v11, v0
	v_addc_co_u32_e32 v21, vcc, -1, v7, vcc
	v_pk_fma_f32 v[10:11], v[0:1], v[24:25], v[34:35] op_sel_hi:[0,1,1]
	v_pk_fma_f32 v[14:15], v[0:1], v[14:15], v[32:33] op_sel_hi:[0,1,1]
	global_load_dword v0, v[20:21], off
	v_mov_b32_e32 v20, v22
	v_mov_b32_e32 v21, v26
	v_mov_b32_e32 v26, v23
	s_waitcnt vmcnt(0) lgkmcnt(0)
	v_mul_f32_e32 v0, v12, v0
	v_pk_fma_f32 v[10:11], v[0:1], v[20:21], v[10:11] op_sel_hi:[0,1,1]
	v_mov_b32_e32 v20, v30
	v_mov_b32_e32 v21, v16
	v_pk_fma_f32 v[14:15], v[0:1], v[20:21], v[14:15] op_sel_hi:[0,1,1]
	global_load_dword v0, v[6:7], off
	v_mov_b32_e32 v16, v31
	v_lshl_add_u64 v[6:7], v[6:7], 0, s[94:95]
	s_waitcnt vmcnt(0) lgkmcnt(0)
	v_mul_f32_e32 v0, v13, v0
	v_pk_fma_f32 v[12:13], v[0:1], v[26:27], v[10:11] op_sel_hi:[0,1,1]
	v_pk_fma_f32 v[10:11], v[0:1], v[16:17], v[14:15] op_sel_hi:[0,1,1]
	s_cbranch_scc1 .LBB0_322

; __device__ __forceinline__ void conv_weights_A(const Params& p, int l, LAS float* scr) {
;     ...
;         if (k0 < 256) { const float* wp = w_pw + k0 * 256; const float* wo = w_out + n;
; #pragma unroll 32
;             for (int j = 0; j < 256; ++j) { const float bv = wo[(size_t)j * DM]; a0 += wp[j] * bv; a1 += wp[256 + j] * bv; a2 += wp[512 + j] * bv; a3 += wp[768 + j] * bv; } }
.LBB0_325:
	v_add_co_u32_e32 v8, vcc, 0xfffe1000, v4
	s_nop 1
	v_addc_co_u32_e32 v9, vcc, -1, v5, vcc
	global_load_dword v0, v[8:9], off
	v_lshl_add_u64 v[8:9], v[6:7], 0, s[24:25]
	v_add_co_u32_e32 v8, vcc, 0x40000, v8
	s_add_u32 s24, s24, 0x80
	s_nop 0
	v_addc_co_u32_e32 v9, vcc, 0, v9, vcc
	global_load_dwordx4 v[14:17], v[8:9], off
	global_load_dwordx4 v[20:23], v[8:9], off offset:1024
	s_addc_u32 s25, s25, 0
	s_cmpk_eq_i32 s24, 0x400
	s_waitcnt vmcnt(0) lgkmcnt(0)
	v_mov_b32_e32 v24, v14
	v_mov_b32_e32 v25, v20
	v_pk_fma_f32 v[12:13], v[0:1], v[24:25], v[12:13] op_sel_hi:[0,1,1]
	global_load_dwordx4 v[24:27], v[8:9], off offset:2048
	global_load_dwordx4 v[28:31], v[8:9], off offset:3072
	v_mov_b32_e32 v20, v15
	s_waitcnt vmcnt(0) lgkmcnt(0)
	v_mov_b32_e32 v32, v24
	v_mov_b32_e32 v33, v28
	v_pk_fma_f32 v[10:11], v[0:1], v[32:33], v[10:11] op_sel_hi:[0,1,1]
	v_add_co_u32_e32 v32, vcc, s21, v4
	v_mov_b32_e32 v28, v25
	s_nop 0
	v_addc_co_u32_e32 v33, vcc, -1, v5, vcc
	global_load_dword v0, v[32:33], off
	v_add_co_u32_e32 v14, vcc, s22, v4
	s_waitcnt vmcnt(0) lgkmcnt(0)
	v_pk_fma_f32 v[12:13], v[0:1], v[20:21], v[12:13] op_sel_hi:[0,1,1]
	v_addc_co_u32_e32 v15, vcc, -1, v5, vcc
	v_pk_fma_f32 v[10:11], v[0:1], v[28:29], v[10:11] op_sel_hi:[0,1,1]
	global_load_dword v0, v[14:15], off
	v_mov_b32_e32 v14, v16
	v_mov_b32_e32 v15, v22
	v_mov_b32_e32 v22, v17
	s_waitcnt vmcnt(0) lgkmcnt(0)
	v_pk_fma_f32 v[12:13], v[0:1], v[14:15], v[12:13] op_sel_hi:[0,1,1]
	v_mov_b32_e32 v14, v26
	v_mov_b32_e32 v15, v30
	v_pk_fma_f32 v[10:11], v[0:1], v[14:15], v[10:11] op_sel_hi:[0,1,1]
	v_add_co_u32_e32 v14, vcc, s26, v4
	v_mov_b32_e32 v30, v27
	s_nop 0
	v_addc_co_u32_e32 v15, vcc, -1, v5, vcc
	global_load_dword v0, v[14:15], off
	s_waitcnt vmcnt(0) lgkmcnt(0)
	v_pk_fma_f32 v[28:29], v[0:1], v[30:31], v[10:11] op_sel_hi:[0,1,1]
	v_add_co_u32_e32 v10, vcc, s68, v4
	v_pk_fma_f32 v[20:21], v[0:1], v[22:23], v[12:13] op_sel_hi:[0,1,1]
	s_nop 0
	v_addc_co_u32_e32 v11, vcc, -1, v5, vcc
	global_load_dword v0, v[10:11], off
	s_nop 0
	global_load_dwordx4 v[10:13], v[8:9], off offset:16
	global_load_dwordx4 v[14:17], v[8:9], off offset:1040
	s_waitcnt vmcnt(0) lgkmcnt(0)
	v_mov_b32_e32 v22, v10
	v_mov_b32_e32 v23, v14
	v_pk_fma_f32 v[30:31], v[0:1], v[22:23], v[20:21] op_sel_hi:[0,1,1]
	global_load_dwordx4 v[20:23], v[8:9], off offset:2064
	global_load_dwordx4 v[24:27], v[8:9], off offset:3088
	v_mov_b32_e32 v14, v11
	s_waitcnt vmcnt(0) lgkmcnt(0)
	v_mov_b32_e32 v32, v20
	v_mov_b32_e32 v33, v24
	v_pk_fma_f32 v[28:29], v[0:1], v[32:33], v[28:29] op_sel_hi:[0,1,1]
	v_add_co_u32_e32 v32, vcc, s69, v4
	v_mov_b32_e32 v24, v21
	s_nop 0
	v_addc_co_u32_e32 v33, vcc, -1, v5, vcc
	global_load_dword v0, v[32:33], off
	v_add_co_u32_e32 v20, vcc, s70, v4
	s_waitcnt vmcnt(0) lgkmcnt(0)
	v_pk_fma_f32 v[10:11], v[0:1], v[14:15], v[30:31] op_sel_hi:[0,1,1]
	v_addc_co_u32_e32 v21, vcc, -1, v5, vcc
	v_pk_fma_f32 v[14:15], v[0:1], v[24:25], v[28:29] op_sel_hi:[0,1,1]
	global_load_dword v0, v[20:21], off
	v_mov_b32_e32 v20, v12
	v_mov_b32_e32 v21, v16
	v_mov_b32_e32 v16, v13
	s_waitcnt vmcnt(0) lgkmcnt(0)
	v_pk_fma_f32 v[10:11], v[0:1], v[20:21], v[10:11] op_sel_hi:[0,1,1]
	v_mov_b32_e32 v20, v22
	v_mov_b32_e32 v21, v26
	v_pk_fma_f32 v[14:15], v[0:1], v[20:21], v[14:15] op_sel_hi:[0,1,1]
	v_add_co_u32_e32 v20, vcc, s71, v4
	v_mov_b32_e32 v26, v23
	s_nop 0
	v_addc_co_u32_e32 v21, vcc, -1, v5, vcc
	global_load_dword v0, v[20:21], off
	s_waitcnt vmcnt(0) lgkmcnt(0)
	v_pk_fma_f32 v[20:21], v[0:1], v[16:17], v[10:11] op_sel_hi:[0,1,1]
	v_add_co_u32_e32 v10, vcc, s72, v4
	v_pk_fma_f32 v[28:29], v[0:1], v[26:27], v[14:15] op_sel_hi:[0,1,1]
	s_nop 0
	v_addc_co_u32_e32 v11, vcc, -1, v5, vcc
	global_load_dword v0, v[10:11], off
	s_nop 0
	global_load_dwordx4 v[10:13], v[8:9], off offset:32
	global_load_dwordx4 v[14:17], v[8:9], off offset:1056
	s_waitcnt vmcnt(0) lgkmcnt(0)
	v_mov_b32_e32 v22, v10
	v_mov_b32_e32 v23, v14
	v_pk_fma_f32 v[30:31], v[0:1], v[22:23], v[20:21] op_sel_hi:[0,1,1]
	global_load_dwordx4 v[20:23], v[8:9], off offset:2080
	global_load_dwordx4 v[24:27], v[8:9], off offset:3104
	v_mov_b32_e32 v14, v11
	s_waitcnt vmcnt(0) lgkmcnt(0)
	v_mov_b32_e32 v32, v20
	v_mov_b32_e32 v33, v24
	v_pk_fma_f32 v[28:29], v[0:1], v[32:33], v[28:29] op_sel_hi:[0,1,1]
	v_add_co_u32_e32 v32, vcc, s73, v4
	v_mov_b32_e32 v24, v21
	s_nop 0
	v_addc_co_u32_e32 v33, vcc, -1, v5, vcc
	global_load_dword v0, v[32:33], off
	v_add_co_u32_e32 v20, vcc, s74, v4
	s_waitcnt vmcnt(0) lgkmcnt(0)
	v_pk_fma_f32 v[10:11], v[0:1], v[14:15], v[30:31] op_sel_hi:[0,1,1]
	v_addc_co_u32_e32 v21, vcc, -1, v5, vcc
	v_pk_fma_f32 v[14:15], v[0:1], v[24:25], v[28:29] op_sel_hi:[0,1,1]
	global_load_dword v0, v[20:21], off
	v_mov_b32_e32 v20, v12
	v_mov_b32_e32 v21, v16
	v_mov_b32_e32 v16, v13
	s_waitcnt vmcnt(0) lgkmcnt(0)
	v_pk_fma_f32 v[10:11], v[0:1], v[20:21], v[10:11] op_sel_hi:[0,1,1]
	v_mov_b32_e32 v20, v22
	v_mov_b32_e32 v21, v26
	v_pk_fma_f32 v[14:15], v[0:1], v[20:21], v[14:15] op_sel_hi:[0,1,1]
	v_add_co_u32_e32 v20, vcc, s75, v4
	v_mov_b32_e32 v26, v23
	s_nop 0
	v_addc_co_u32_e32 v21, vcc, -1, v5, vcc
	global_load_dword v0, v[20:21], off
	s_waitcnt vmcnt(0) lgkmcnt(0)
	v_pk_fma_f32 v[20:21], v[0:1], v[16:17], v[10:11] op_sel_hi:[0,1,1]
	v_add_co_u32_e32 v10, vcc, s76, v4
	v_pk_fma_f32 v[28:29], v[0:1], v[26:27], v[14:15] op_sel_hi:[0,1,1]
	s_nop 0
	v_addc_co_u32_e32 v11, vcc, -1, v5, vcc
	global_load_dword v0, v[10:11], off
	s_nop 0
	global_load_dwordx4 v[10:13], v[8:9], off offset:48
	global_load_dwordx4 v[14:17], v[8:9], off offset:1072
	s_waitcnt vmcnt(0) lgkmcnt(0)
; __device__ __forceinline__ void conv_weights_A(const Params& p, int l, LAS float* scr) {
;     ...
;         if (k0 < 256) { const float* wp = w_pw + k0 * 256; const float* wo = w_out + n;
; #pragma unroll 32
;             for (int j = 0; j < 256; ++j) { const float bv = wo[(size_t)j * DM]; a0 += wp[j] * bv; a1 += wp[256 + j] * bv; a2 += wp[512 + j] * bv; a3 += wp[768 + j] * bv; } }
	v_mov_b32_e32 v22, v10
	v_mov_b32_e32 v23, v14
	v_pk_fma_f32 v[30:31], v[0:1], v[22:23], v[20:21] op_sel_hi:[0,1,1]
	global_load_dwordx4 v[20:23], v[8:9], off offset:2096
	global_load_dwordx4 v[24:27], v[8:9], off offset:3120
	v_mov_b32_e32 v14, v11
	s_waitcnt vmcnt(0) lgkmcnt(0)
	v_mov_b32_e32 v32, v20
	v_mov_b32_e32 v33, v24
	v_pk_fma_f32 v[28:29], v[0:1], v[32:33], v[28:29] op_sel_hi:[0,1,1]
	v_add_co_u32_e32 v32, vcc, s77, v4
	v_mov_b32_e32 v24, v21
	s_nop 0
	v_addc_co_u32_e32 v33, vcc, -1, v5, vcc
	global_load_dword v0, v[32:33], off
	v_add_co_u32_e32 v20, vcc, s78, v4
	s_waitcnt vmcnt(0) lgkmcnt(0)
	v_pk_fma_f32 v[10:11], v[0:1], v[14:15], v[30:31] op_sel_hi:[0,1,1]
	v_addc_co_u32_e32 v21, vcc, -1, v5, vcc
	v_pk_fma_f32 v[14:15], v[0:1], v[24:25], v[28:29] op_sel_hi:[0,1,1]
	global_load_dword v0, v[20:21], off
	v_mov_b32_e32 v20, v12
	v_mov_b32_e32 v21, v16
	v_mov_b32_e32 v16, v13
	s_waitcnt vmcnt(0) lgkmcnt(0)
	v_pk_fma_f32 v[10:11], v[0:1], v[20:21], v[10:11] op_sel_hi:[0,1,1]
	v_mov_b32_e32 v20, v22
	v_mov_b32_e32 v21, v26
	v_pk_fma_f32 v[14:15], v[0:1], v[20:21], v[14:15] op_sel_hi:[0,1,1]
	v_add_co_u32_e32 v20, vcc, s79, v4
	v_mov_b32_e32 v26, v23
	s_nop 0
	v_addc_co_u32_e32 v21, vcc, -1, v5, vcc
	global_load_dword v0, v[20:21], off
	s_waitcnt vmcnt(0) lgkmcnt(0)
	v_pk_fma_f32 v[20:21], v[0:1], v[16:17], v[10:11] op_sel_hi:[0,1,1]
	v_add_co_u32_e32 v10, vcc, s80, v4
	v_pk_fma_f32 v[28:29], v[0:1], v[26:27], v[14:15] op_sel_hi:[0,1,1]
	s_nop 0
	v_addc_co_u32_e32 v11, vcc, -1, v5, vcc
	global_load_dword v0, v[10:11], off
	s_nop 0
	global_load_dwordx4 v[10:13], v[8:9], off offset:64
	global_load_dwordx4 v[14:17], v[8:9], off offset:1088
	s_waitcnt vmcnt(0) lgkmcnt(0)
	v_mov_b32_e32 v22, v10
	v_mov_b32_e32 v23, v14
	v_pk_fma_f32 v[30:31], v[0:1], v[22:23], v[20:21] op_sel_hi:[0,1,1]
	global_load_dwordx4 v[20:23], v[8:9], off offset:2112
	global_load_dwordx4 v[24:27], v[8:9], off offset:3136
	v_mov_b32_e32 v14, v11
	s_waitcnt vmcnt(0) lgkmcnt(0)
	v_mov_b32_e32 v32, v20
	v_mov_b32_e32 v33, v24
	v_pk_fma_f32 v[28:29], v[0:1], v[32:33], v[28:29] op_sel_hi:[0,1,1]
	v_add_co_u32_e32 v32, vcc, s81, v4
	v_mov_b32_e32 v24, v21
	s_nop 0
	v_addc_co_u32_e32 v33, vcc, -1, v5, vcc
	global_load_dword v0, v[32:33], off
	v_add_co_u32_e32 v20, vcc, s82, v4
	s_waitcnt vmcnt(0) lgkmcnt(0)
	v_pk_fma_f32 v[10:11], v[0:1], v[14:15], v[30:31] op_sel_hi:[0,1,1]
	v_addc_co_u32_e32 v21, vcc, -1, v5, vcc
	v_pk_fma_f32 v[14:15], v[0:1], v[24:25], v[28:29] op_sel_hi:[0,1,1]
	global_load_dword v0, v[20:21], off
	v_mov_b32_e32 v20, v12
	v_mov_b32_e32 v21, v16
	v_mov_b32_e32 v16, v13
	s_waitcnt vmcnt(0) lgkmcnt(0)
	v_pk_fma_f32 v[10:11], v[0:1], v[20:21], v[10:11] op_sel_hi:[0,1,1]
	v_mov_b32_e32 v20, v22
	v_mov_b32_e32 v21, v26
	v_pk_fma_f32 v[14:15], v[0:1], v[20:21], v[14:15] op_sel_hi:[0,1,1]
	v_add_co_u32_e32 v20, vcc, s83, v4
	v_mov_b32_e32 v26, v23
	s_nop 0
	v_addc_co_u32_e32 v21, vcc, -1, v5, vcc
	global_load_dword v0, v[20:21], off
	s_waitcnt vmcnt(0) lgkmcnt(0)
	v_pk_fma_f32 v[20:21], v[0:1], v[16:17], v[10:11] op_sel_hi:[0,1,1]
	v_add_co_u32_e32 v10, vcc, s86, v4
	v_pk_fma_f32 v[28:29], v[0:1], v[26:27], v[14:15] op_sel_hi:[0,1,1]
	s_nop 0
	v_addc_co_u32_e32 v11, vcc, -1, v5, vcc
	global_load_dword v0, v[10:11], off
	s_nop 0
	global_load_dwordx4 v[10:13], v[8:9], off offset:80
	global_load_dwordx4 v[14:17], v[8:9], off offset:1104
	s_waitcnt vmcnt(0) lgkmcnt(0)
	v_mov_b32_e32 v22, v10
	v_mov_b32_e32 v23, v14
	v_pk_fma_f32 v[30:31], v[0:1], v[22:23], v[20:21] op_sel_hi:[0,1,1]
	global_load_dwordx4 v[20:23], v[8:9], off offset:2128
	global_load_dwordx4 v[24:27], v[8:9], off offset:3152
	v_mov_b32_e32 v14, v11
	s_waitcnt vmcnt(0) lgkmcnt(0)
	v_mov_b32_e32 v32, v20
	v_mov_b32_e32 v33, v24
	v_pk_fma_f32 v[28:29], v[0:1], v[32:33], v[28:29] op_sel_hi:[0,1,1]
	v_add_co_u32_e32 v32, vcc, s87, v4
	v_mov_b32_e32 v24, v21
	s_nop 0
	v_addc_co_u32_e32 v33, vcc, -1, v5, vcc
	global_load_dword v0, v[32:33], off
	v_add_co_u32_e32 v20, vcc, s84, v4
	s_waitcnt vmcnt(0) lgkmcnt(0)
; __device__ __forceinline__ void conv_weights_A(const Params& p, int l, LAS float* scr) {
;     ...
;         if (k0 < 256) { const float* wp = w_pw + k0 * 256; const float* wo = w_out + n;
; #pragma unroll 32
;             for (int j = 0; j < 256; ++j) { const float bv = wo[(size_t)j * DM]; a0 += wp[j] * bv; a1 += wp[256 + j] * bv; a2 += wp[512 + j] * bv; a3 += wp[768 + j] * bv; } }
	v_pk_fma_f32 v[10:11], v[0:1], v[14:15], v[30:31] op_sel_hi:[0,1,1]
	v_addc_co_u32_e32 v21, vcc, -1, v5, vcc
	v_pk_fma_f32 v[14:15], v[0:1], v[24:25], v[28:29] op_sel_hi:[0,1,1]
	global_load_dword v0, v[20:21], off
	v_mov_b32_e32 v20, v12
	v_mov_b32_e32 v21, v16
	v_mov_b32_e32 v16, v13
	s_waitcnt vmcnt(0) lgkmcnt(0)
	v_pk_fma_f32 v[10:11], v[0:1], v[20:21], v[10:11] op_sel_hi:[0,1,1]
	v_mov_b32_e32 v20, v22
	v_mov_b32_e32 v21, v26
	v_pk_fma_f32 v[14:15], v[0:1], v[20:21], v[14:15] op_sel_hi:[0,1,1]
	v_add_co_u32_e32 v20, vcc, s85, v4
	v_mov_b32_e32 v26, v23
	s_nop 0
	v_addc_co_u32_e32 v21, vcc, -1, v5, vcc
	global_load_dword v0, v[20:21], off
	s_waitcnt vmcnt(0) lgkmcnt(0)
	v_pk_fma_f32 v[20:21], v[0:1], v[16:17], v[10:11] op_sel_hi:[0,1,1]
	v_add_co_u32_e32 v10, vcc, s97, v4
	v_pk_fma_f32 v[28:29], v[0:1], v[26:27], v[14:15] op_sel_hi:[0,1,1]
	s_nop 0
	v_addc_co_u32_e32 v11, vcc, -1, v5, vcc
	global_load_dword v0, v[10:11], off
	s_nop 0
	global_load_dwordx4 v[10:13], v[8:9], off offset:96
	global_load_dwordx4 v[14:17], v[8:9], off offset:1120
	s_waitcnt vmcnt(0) lgkmcnt(0)
	v_mov_b32_e32 v22, v10
	v_mov_b32_e32 v23, v14
	v_pk_fma_f32 v[30:31], v[0:1], v[22:23], v[20:21] op_sel_hi:[0,1,1]
	global_load_dwordx4 v[20:23], v[8:9], off offset:2144
	global_load_dwordx4 v[24:27], v[8:9], off offset:3168
	v_mov_b32_e32 v14, v11
	s_waitcnt vmcnt(0) lgkmcnt(0)
	v_mov_b32_e32 v32, v20
	v_mov_b32_e32 v33, v24
	v_pk_fma_f32 v[28:29], v[0:1], v[32:33], v[28:29] op_sel_hi:[0,1,1]
	v_add_co_u32_e32 v32, vcc, s90, v4
	v_mov_b32_e32 v24, v21
	s_nop 0
	v_addc_co_u32_e32 v33, vcc, -1, v5, vcc
	global_load_dword v0, v[32:33], off
	v_add_co_u32_e32 v20, vcc, s91, v4
	s_waitcnt vmcnt(0) lgkmcnt(0)
	v_pk_fma_f32 v[10:11], v[0:1], v[14:15], v[30:31] op_sel_hi:[0,1,1]
	v_addc_co_u32_e32 v21, vcc, -1, v5, vcc
	v_pk_fma_f32 v[14:15], v[0:1], v[24:25], v[28:29] op_sel_hi:[0,1,1]
	global_load_dword v0, v[20:21], off
	v_mov_b32_e32 v20, v12
	v_mov_b32_e32 v21, v16
	v_mov_b32_e32 v16, v13
	s_waitcnt vmcnt(0) lgkmcnt(0)
	v_pk_fma_f32 v[10:11], v[0:1], v[20:21], v[10:11] op_sel_hi:[0,1,1]
	v_mov_b32_e32 v20, v22
	v_mov_b32_e32 v21, v26
	v_pk_fma_f32 v[14:15], v[0:1], v[20:21], v[14:15] op_sel_hi:[0,1,1]
	v_add_co_u32_e32 v20, vcc, s36, v4
	v_mov_b32_e32 v26, v23
	s_nop 0
	v_addc_co_u32_e32 v21, vcc, -1, v5, vcc
	global_load_dword v0, v[20:21], off
	s_waitcnt vmcnt(0) lgkmcnt(0)
	v_pk_fma_f32 v[20:21], v[0:1], v[16:17], v[10:11] op_sel_hi:[0,1,1]
	v_add_co_u32_e32 v10, vcc, s37, v4
	v_pk_fma_f32 v[28:29], v[0:1], v[26:27], v[14:15] op_sel_hi:[0,1,1]
	s_nop 0
	v_addc_co_u32_e32 v11, vcc, -1, v5, vcc
	global_load_dword v0, v[10:11], off
	s_nop 0
	global_load_dwordx4 v[10:13], v[8:9], off offset:112
	global_load_dwordx4 v[14:17], v[8:9], off offset:1136
	s_waitcnt vmcnt(0) lgkmcnt(0)
	v_mov_b32_e32 v22, v10
	v_mov_b32_e32 v23, v14
	v_pk_fma_f32 v[30:31], v[0:1], v[22:23], v[20:21] op_sel_hi:[0,1,1]
	global_load_dwordx4 v[20:23], v[8:9], off offset:2160
	global_load_dwordx4 v[24:27], v[8:9], off offset:3184
	v_mov_b32_e32 v14, v11
	s_waitcnt vmcnt(0) lgkmcnt(0)
	v_mov_b32_e32 v8, v20
	v_mov_b32_e32 v9, v24
	v_pk_fma_f32 v[8:9], v[0:1], v[8:9], v[28:29] op_sel_hi:[0,1,1]
	v_add_co_u32_e32 v28, vcc, s96, v4
	v_mov_b32_e32 v24, v21
	s_nop 0
	v_addc_co_u32_e32 v29, vcc, -1, v5, vcc
	global_load_dword v0, v[28:29], off
	s_waitcnt vmcnt(0) lgkmcnt(0)
	v_pk_fma_f32 v[10:11], v[0:1], v[14:15], v[30:31] op_sel_hi:[0,1,1]
	v_add_co_u32_e32 v14, vcc, s48, v4
	v_pk_fma_f32 v[8:9], v[0:1], v[24:25], v[8:9] op_sel_hi:[0,1,1]
	s_nop 0
	v_addc_co_u32_e32 v15, vcc, -1, v5, vcc
	global_load_dword v0, v[14:15], off
	v_mov_b32_e32 v14, v12
	v_mov_b32_e32 v15, v16
	v_mov_b32_e32 v16, v13
	s_waitcnt vmcnt(0) lgkmcnt(0)
	v_pk_fma_f32 v[10:11], v[0:1], v[14:15], v[10:11] op_sel_hi:[0,1,1]
	v_mov_b32_e32 v14, v22
	v_mov_b32_e32 v15, v26
	v_pk_fma_f32 v[8:9], v[0:1], v[14:15], v[8:9] op_sel_hi:[0,1,1]
	global_load_dword v0, v[4:5], off
	v_mov_b32_e32 v26, v23
	v_lshl_add_u64 v[4:5], v[4:5], 0, s[94:95]
	s_waitcnt vmcnt(0) lgkmcnt(0)
	v_pk_fma_f32 v[12:13], v[0:1], v[16:17], v[10:11] op_sel_hi:[0,1,1]
	v_pk_fma_f32 v[10:11], v[0:1], v[26:27], v[8:9] op_sel_hi:[0,1,1]
	s_cbranch_scc0 .LBB0_325
	s_branch .LBB0_319

; __device__ __forceinline__ float sumsq4(f32x4 x) { return (x[0] * x[0] + x[1] * x[1]) + (x[2] * x[2] + x[3] * x[3]); }
;     __device__ __forceinline__ void fused(AccT& acc, const Unit& u, int wr, int wc, int fr, int fq, LAS unsigned char* lx, int tid) const {
;     ...
;                 const int row = EPI_ROW(u, ai, m); float s1 = 0.f, s2 = 0.f;
; #pragma unroll
;                 for (int bj = 0; bj < 2; ++bj) {
;                     const half8 rv = *(const half8*)(res + (size_t)row * DM + EPI_COL(u, bj));
; #pragma unroll
;                     for (int e = 0; e < 4; ++e) { acc[ai][bj][m][0][e] += ALPHA * (float)rv[e]; acc[ai][bj][m][1][e] += ALPHA * (float)rv[4 + e]; }
;                     const f32x4 a0 = acc[ai][bj][m][0], a1 = acc[ai][bj][m][1];
;                     s1 += ((a0[0] + a0[1]) + (a0[2] + a0[3])) + ((a1[0] + a1[1]) + (a1[2] + a1[3])); s2 += sumsq4(a0) + sumsq4(a1);
;                 }
;                 s1 += __shfl_xor(s1, 16); s1 += __shfl_xor(s1, 32); s2 += __shfl_xor(s2, 16); s2 += __shfl_xor(s2, 32);
;                 if (fq == 0) P[(ai * 128 + wr * 64 + m * 16 + fr) * 4 + wc] = (f32x2){s1, s2};
.LBB0_382:
	v_mov_b32_e32 v239, v216
	s_lshl_b32 s11, s16, 8
	v_ashrrev_i32_e32 v140, 2, v239
	v_and_b32_e32 v238, 0xffffffc0, v140
	v_bfe_u32 v141, v239, 6, 2
	v_and_b32_e32 v229, 15, v239
	v_bfe_u32 v142, v239, 4, 2
	v_add_u32_e32 v140, s11, v238
	v_or_b32_e32 v158, v140, v229
	s_lshl_b32 s0, s10, 8
	v_lshlrev_b32_e32 v140, 5, v141
	v_lshlrev_b32_e32 v143, 3, v142
	v_and_b32_e32 v144, 64, v237
	v_or3_b32 v140, v140, s0, v143
	v_xor_b32_e32 v143, 16, v237
	v_add_u32_e32 v144, 64, v144
	v_cmp_lt_i32_e32 vcc, v143, v144
	v_readlane_b32 s0, v253, 5
	v_ashrrev_i32_e32 v159, 31, v158
	v_cndmask_b32_e32 v143, v237, v143, vcc
	v_lshlrev_b32_e32 v241, 2, v143
	v_xor_b32_e32 v143, 32, v237
	v_cmp_lt_i32_e32 vcc, v143, v144
	v_lshl_add_u32 v154, v141, 3, s0
	v_readlane_b32 s0, v255, 0
	v_cndmask_b32_e32 v143, v237, v143, vcc
	v_lshlrev_b32_e32 v240, 2, v143
	v_cmp_eq_u32_e32 vcc, 0, v142
	v_lshlrev_b64 v[142:143], 11, v[158:159]
	v_readlane_b32 s1, v255, 1
	v_ashrrev_i32_e32 v141, 31, v140
	v_mov_b32_e32 v166, v118
	v_lshl_add_u64 v[144:145], s[0:1], 0, v[142:143]
	v_lshl_add_u64 v[144:145], v[140:141], 1, v[144:145]
	global_load_dwordx4 v[148:151], v[144:145], off
	global_load_dwordx4 v[162:165], v[144:145], off offset:256
	s_mov_b32 s0, 0x3fd744fd
	v_pk_mov_b32 v[118:119], v[118:119], v[116:117] op_sel:[1,0]
	v_mov_b32_e32 v167, v116
	v_mov_b32_e32 v116, v120
	v_or_b32_e32 v155, v238, v229
	s_waitcnt vmcnt(0) lgkmcnt(0)
	v_cvt_f32_f16_sdwa v156, v148 dst_sel:DWORD dst_unused:UNUSED_PAD src0_sel:WORD_1
	v_cvt_f32_f16_e32 v144, v164
	v_cvt_f32_f16_sdwa v145, v164 dst_sel:DWORD dst_unused:UNUSED_PAD src0_sel:WORD_1
	v_cvt_f32_f16_sdwa v164, v150 dst_sel:DWORD dst_unused:UNUSED_PAD src0_sel:WORD_1
	v_pk_fma_f32 v[126:127], v[144:145], s[0:1], v[126:127] op_sel_hi:[1,0,1]
	v_cvt_f32_f16_e32 v144, v165
	v_cvt_f32_f16_sdwa v145, v165 dst_sel:DWORD dst_unused:UNUSED_PAD src0_sel:WORD_1
	v_mov_b32_e32 v146, v127
	v_pk_fma_f32 v[128:129], v[144:145], s[0:1], v[128:129] op_sel_hi:[1,0,1]
	s_nop 0
	v_mov_b32_e32 v147, v129
	v_mov_b32_e32 v144, v126
	v_mov_b32_e32 v145, v128
	v_pk_mul_f32 v[146:147], v[146:147], v[146:147]
	s_nop 0
	v_pk_fma_f32 v[144:145], v[144:145], v[144:145], v[146:147]
	v_mov_b32_e32 v146, v122
	v_pk_add_f32 v[152:153], v[144:145], v[144:145] op_sel_hi:[0,1]
	v_cvt_f32_f16_e32 v145, v162
	v_cvt_f32_f16_e32 v144, v148
	v_mov_b32_e32 v147, v114
	v_pk_mov_b32 v[122:123], v[122:123], v[114:115] op_sel:[1,0]
	v_mov_b32_e32 v157, v145
	v_pk_fma_f32 v[144:145], v[144:145], s[0:1], v[146:147] op_sel_hi:[1,0,1]
	v_cvt_f32_f16_e32 v147, v163
	v_pk_fma_f32 v[122:123], v[156:157], s[0:1], v[122:123] op_sel_hi:[1,0,1]
	v_cvt_f32_f16_e32 v156, v149
	v_cvt_f32_f16_sdwa v157, v162 dst_sel:DWORD dst_unused:UNUSED_PAD src0_sel:WORD_1
	v_mov_b32_e32 v165, v147
	v_mov_b32_e32 v114, v124
	v_pk_fma_f32 v[118:119], v[164:165], s[0:1], v[118:119] op_sel_hi:[1,0,1]
	v_cvt_f32_f16_sdwa v164, v149 dst_sel:DWORD dst_unused:UNUSED_PAD src0_sel:WORD_1
	v_mov_b32_e32 v165, v157
	v_pk_fma_f32 v[148:149], v[156:157], s[0:1], v[114:115] op_sel_hi:[1,0,1]
	v_cvt_f32_f16_e32 v156, v151
	v_cvt_f32_f16_sdwa v157, v163 dst_sel:DWORD dst_unused:UNUSED_PAD src0_sel:WORD_1
	v_cvt_f32_f16_e32 v146, v150
	v_cvt_f32_f16_sdwa v162, v151 dst_sel:DWORD dst_unused:UNUSED_PAD src0_sel:WORD_1
	v_mov_b32_e32 v114, v125
	v_mov_b32_e32 v163, v157
	v_pk_fma_f32 v[150:151], v[156:157], s[0:1], v[116:117] op_sel_hi:[1,0,1]
	v_pk_fma_f32 v[114:115], v[164:165], s[0:1], v[114:115] op_sel_hi:[1,0,1]
	v_mov_b32_e32 v116, v121
	v_pk_mul_f32 v[120:121], v[144:145], v[144:145]
	v_pk_mul_f32 v[124:125], v[122:123], v[122:123]
	v_pk_fma_f32 v[146:147], v[146:147], s[0:1], v[166:167] op_sel_hi:[1,0,1]
	v_pk_fma_f32 v[116:117], v[162:163], s[0:1], v[116:117] op_sel_hi:[1,0,1]
	v_pk_mul_f32 v[156:157], v[148:149], v[148:149]
	v_pk_mul_f32 v[162:163], v[114:115], v[114:115]
	v_pk_mov_b32 v[120:121], v[144:145], v[120:121] op_sel:[1,0]
	v_pk_mov_b32 v[124:125], v[148:149], v[124:125] op_sel:[1,0]
	v_pk_mul_f32 v[164:165], v[146:147], v[146:147]
	v_pk_add_f32 v[120:121], v[120:121], v[124:125]
	v_pk_mov_b32 v[124:125], v[146:147], v[156:157] op_sel:[1,0]
	v_pk_mov_b32 v[156:157], v[150:151], v[162:163] op_sel:[1,0]
	v_pk_mul_f32 v[166:167], v[118:119], v[118:119]
	v_pk_add_f32 v[124:125], v[124:125], v[156:157]
	v_pk_mul_f32 v[168:169], v[150:151], v[150:151]
	v_pk_mul_f32 v[170:171], v[116:117], v[116:117]
	v_pk_add_f32 v[120:121], v[120:121], v[124:125]
	v_mov_b32_e32 v124, v126
	v_mov_b32_e32 v125, v164
	v_pk_mov_b32 v[156:157], v[126:127], v[166:167] op_sel:[1,0]
	v_pk_mov_b32 v[162:163], v[128:129], v[170:171] op_sel:[1,0]
	v_pk_add_f32 v[124:125], v[124:125], v[156:157]
	v_mov_b32_e32 v156, v128
	v_mov_b32_e32 v157, v168
	v_pk_add_f32 v[156:157], v[156:157], v[162:163]
	v_pk_mul_f32 v[162:163], v[148:149], v[114:115]
	v_pk_add_f32 v[124:125], v[124:125], v[156:157]
	v_pk_mul_f32 v[156:157], v[144:145], v[122:123]
	v_pk_add_f32 v[120:121], v[120:121], v[124:125]
	v_pk_add_f32 v[124:125], v[144:145], v[122:123]
	v_pk_mul_f32 v[164:165], v[150:151], v[116:117]
	v_mov_b32_e32 v125, v157
	v_pk_add_f32 v[156:157], v[148:149], v[114:115]
	v_mov_b32_e32 v152, v1
	v_mov_b32_e32 v157, v163
	v_pk_add_f32 v[124:125], v[124:125], v[156:157]
	v_pk_add_f32 v[156:157], v[146:147], v[118:119]
	v_pk_mul_f32 v[162:163], v[146:147], v[118:119]
	v_lshl_add_u32 v115, v155, 5, v154
	v_mov_b32_e32 v157, v163
	v_pk_add_f32 v[162:163], v[150:151], v[116:117]
	s_nop 0
	v_mov_b32_e32 v163, v165
	v_pk_add_f32 v[156:157], v[156:157], v[162:163]
	s_nop 0
	v_pk_add_f32 v[124:125], v[124:125], v[156:157]
	s_nop 0
	v_pk_add_f32 v[124:125], v[124:125], v[152:153]
	s_nop 0
	v_pk_add_f32 v[120:121], v[120:121], v[124:125]
	ds_bpermute_b32 v124, v241, v120
	ds_bpermute_b32 v125, v241, v121
	s_waitcnt lgkmcnt(0)
	v_pk_add_f32 v[120:121], v[120:121], v[124:125]
	ds_bpermute_b32 v124, v240, v120
	ds_bpermute_b32 v125, v240, v121
	s_and_saveexec_b64 s[0:1], vcc
	s_cbranch_execz .LBB0_384
	s_waitcnt lgkmcnt(0)
	v_pk_add_f32 v[120:121], v[120:121], v[124:125]
	ds_write_b64 v115, v[120:121]
; __device__ __forceinline__ float sumsq4(f32x4 x) { return (x[0] * x[0] + x[1] * x[1]) + (x[2] * x[2] + x[3] * x[3]); }
;     __device__ __forceinline__ void fused(AccT& acc, const Unit& u, int wr, int wc, int fr, int fq, LAS unsigned char* lx, int tid) const {
;     ...
;                 const int row = EPI_ROW(u, ai, m); float s1 = 0.f, s2 = 0.f;
; #pragma unroll
;                 for (int bj = 0; bj < 2; ++bj) {
;                     const half8 rv = *(const half8*)(res + (size_t)row * DM + EPI_COL(u, bj));
; #pragma unroll
;                     for (int e = 0; e < 4; ++e) { acc[ai][bj][m][0][e] += ALPHA * (float)rv[e]; acc[ai][bj][m][1][e] += ALPHA * (float)rv[4 + e]; }
;                     const f32x4 a0 = acc[ai][bj][m][0], a1 = acc[ai][bj][m][1];
;                     s1 += ((a0[0] + a0[1]) + (a0[2] + a0[3])) + ((a1[0] + a1[1]) + (a1[2] + a1[3])); s2 += sumsq4(a0) + sumsq4(a1);
;                 }
;                 s1 += __shfl_xor(s1, 16); s1 += __shfl_xor(s1, 32); s2 += __shfl_xor(s2, 16); s2 += __shfl_xor(s2, 32);
;                 if (fq == 0) P[(ai * 128 + wr * 64 + m * 16 + fr) * 4 + wc] = (f32x2){s1, s2};
.LBB0_384:
	s_or_b64 exec, exec, s[0:1]
	v_or_b32_e32 v120, 16, v158
	v_ashrrev_i32_e32 v121, 31, v120
	v_readlane_b32 s0, v255, 0
	v_lshlrev_b64 v[120:121], 11, v[120:121]
	v_readlane_b32 s1, v255, 1
	v_mov_b32_e32 v170, v102
	v_pk_mov_b32 v[102:103], v[102:103], v[100:101] op_sel:[1,0]
	s_waitcnt lgkmcnt(0)
	v_lshl_add_u64 v[124:125], s[0:1], 0, v[120:121]
	v_lshl_add_u64 v[124:125], v[140:141], 1, v[124:125]
	global_load_dwordx4 v[154:157], v[124:125], off
	global_load_dwordx4 v[164:167], v[124:125], off offset:256
	s_mov_b32 s0, 0x3fd744fd
	v_mov_b32_e32 v171, v100
	v_mov_b32_e32 v100, v104
	s_waitcnt vmcnt(0) lgkmcnt(0)
	v_cvt_f32_f16_sdwa v168, v156 dst_sel:DWORD dst_unused:UNUSED_PAD src0_sel:WORD_1
	v_cvt_f32_f16_e32 v124, v166
	v_cvt_f32_f16_sdwa v125, v166 dst_sel:DWORD dst_unused:UNUSED_PAD src0_sel:WORD_1
	v_cvt_f32_f16_sdwa v166, v154 dst_sel:DWORD dst_unused:UNUSED_PAD src0_sel:WORD_1
	v_pk_fma_f32 v[110:111], v[124:125], s[0:1], v[110:111] op_sel_hi:[1,0,1]
	v_cvt_f32_f16_e32 v124, v167
	v_cvt_f32_f16_sdwa v125, v167 dst_sel:DWORD dst_unused:UNUSED_PAD src0_sel:WORD_1
	v_mov_b32_e32 v152, v111
	v_pk_fma_f32 v[112:113], v[124:125], s[0:1], v[112:113] op_sel_hi:[1,0,1]
	s_nop 0
	v_mov_b32_e32 v153, v113
	v_mov_b32_e32 v124, v110
	v_mov_b32_e32 v125, v112
	v_pk_mul_f32 v[152:153], v[152:153], v[152:153]
	s_nop 0
	v_pk_fma_f32 v[124:125], v[124:125], v[124:125], v[152:153]
	v_mov_b32_e32 v152, v106
	v_pk_add_f32 v[162:163], v[124:125], v[124:125] op_sel_hi:[0,1]
	v_cvt_f32_f16_e32 v125, v164
	v_cvt_f32_f16_e32 v124, v154
	v_mov_b32_e32 v153, v98
	v_pk_mov_b32 v[106:107], v[106:107], v[98:99] op_sel:[1,0]
	v_mov_b32_e32 v167, v125
	v_pk_fma_f32 v[124:125], v[124:125], s[0:1], v[152:153] op_sel_hi:[1,0,1]
	v_cvt_f32_f16_e32 v153, v165
	v_pk_fma_f32 v[106:107], v[166:167], s[0:1], v[106:107] op_sel_hi:[1,0,1]
	v_cvt_f32_f16_e32 v166, v155
	v_cvt_f32_f16_sdwa v167, v164 dst_sel:DWORD dst_unused:UNUSED_PAD src0_sel:WORD_1
	v_mov_b32_e32 v169, v153
	v_pk_fma_f32 v[102:103], v[168:169], s[0:1], v[102:103] op_sel_hi:[1,0,1]
	v_cvt_f32_f16_sdwa v168, v155 dst_sel:DWORD dst_unused:UNUSED_PAD src0_sel:WORD_1
	v_mov_b32_e32 v98, v108
	v_cvt_f32_f16_e32 v164, v157
	v_cvt_f32_f16_sdwa v165, v165 dst_sel:DWORD dst_unused:UNUSED_PAD src0_sel:WORD_1
	v_cvt_f32_f16_e32 v152, v156
	v_pk_fma_f32 v[154:155], v[166:167], s[0:1], v[98:99] op_sel_hi:[1,0,1]
	v_cvt_f32_f16_sdwa v166, v157 dst_sel:DWORD dst_unused:UNUSED_PAD src0_sel:WORD_1
	v_mov_b32_e32 v169, v167
	v_mov_b32_e32 v98, v109
	v_mov_b32_e32 v167, v165
	v_pk_fma_f32 v[156:157], v[164:165], s[0:1], v[100:101] op_sel_hi:[1,0,1]
	v_pk_fma_f32 v[98:99], v[168:169], s[0:1], v[98:99] op_sel_hi:[1,0,1]
	v_mov_b32_e32 v100, v105
	v_pk_mul_f32 v[104:105], v[124:125], v[124:125]
	v_pk_mul_f32 v[108:109], v[106:107], v[106:107]
	v_pk_fma_f32 v[152:153], v[152:153], s[0:1], v[170:171] op_sel_hi:[1,0,1]
	v_pk_fma_f32 v[100:101], v[166:167], s[0:1], v[100:101] op_sel_hi:[1,0,1]
	v_pk_mul_f32 v[164:165], v[154:155], v[154:155]
	v_pk_mul_f32 v[166:167], v[98:99], v[98:99]
	v_pk_mov_b32 v[104:105], v[124:125], v[104:105] op_sel:[1,0]
	v_pk_mov_b32 v[108:109], v[154:155], v[108:109] op_sel:[1,0]
	v_pk_mul_f32 v[168:169], v[152:153], v[152:153]
	v_pk_add_f32 v[104:105], v[104:105], v[108:109]
	v_pk_mov_b32 v[108:109], v[152:153], v[164:165] op_sel:[1,0]
	v_pk_mov_b32 v[164:165], v[156:157], v[166:167] op_sel:[1,0]
	v_pk_mul_f32 v[170:171], v[102:103], v[102:103]
	v_pk_add_f32 v[108:109], v[108:109], v[164:165]
	v_pk_mul_f32 v[172:173], v[156:157], v[156:157]
	v_pk_mul_f32 v[174:175], v[100:101], v[100:101]
	v_pk_add_f32 v[104:105], v[104:105], v[108:109]
	v_mov_b32_e32 v108, v110
	v_mov_b32_e32 v109, v168
	v_pk_mov_b32 v[164:165], v[110:111], v[170:171] op_sel:[1,0]
	v_pk_mov_b32 v[166:167], v[112:113], v[174:175] op_sel:[1,0]
	v_pk_add_f32 v[108:109], v[108:109], v[164:165]
	v_mov_b32_e32 v164, v112
	v_mov_b32_e32 v165, v172
	v_pk_add_f32 v[164:165], v[164:165], v[166:167]
	v_pk_mul_f32 v[166:167], v[154:155], v[98:99]
	v_pk_add_f32 v[108:109], v[108:109], v[164:165]
	v_pk_mul_f32 v[164:165], v[124:125], v[106:107]
	v_pk_add_f32 v[104:105], v[104:105], v[108:109]
	v_pk_add_f32 v[108:109], v[124:125], v[106:107]
	v_pk_mul_f32 v[168:169], v[156:157], v[100:101]
	v_mov_b32_e32 v109, v165
	v_pk_add_f32 v[164:165], v[154:155], v[98:99]
	v_mov_b32_e32 v162, v1
	v_mov_b32_e32 v165, v167
	v_pk_add_f32 v[108:109], v[108:109], v[164:165]
	v_pk_add_f32 v[164:165], v[152:153], v[102:103]
	v_pk_mul_f32 v[166:167], v[152:153], v[102:103]
	s_nop 0
	v_mov_b32_e32 v165, v167
	v_pk_add_f32 v[166:167], v[156:157], v[100:101]
	s_nop 0
	v_mov_b32_e32 v167, v169
	v_pk_add_f32 v[164:165], v[164:165], v[166:167]
	s_nop 0
	v_pk_add_f32 v[108:109], v[108:109], v[164:165]
	s_nop 0
	v_pk_add_f32 v[108:109], v[108:109], v[162:163]
	s_nop 0
	v_pk_add_f32 v[104:105], v[104:105], v[108:109]
	ds_bpermute_b32 v108, v241, v104
	ds_bpermute_b32 v109, v241, v105
	s_waitcnt lgkmcnt(0)
	v_pk_add_f32 v[104:105], v[104:105], v[108:109]
	ds_bpermute_b32 v108, v240, v104
	ds_bpermute_b32 v109, v240, v105
	s_and_saveexec_b64 s[0:1], vcc
	s_cbranch_execz .LBB0_386
	s_waitcnt lgkmcnt(0)
	v_pk_add_f32 v[104:105], v[104:105], v[108:109]
	ds_write_b64 v115, v[104:105] offset:512
; __device__ __forceinline__ float sumsq4(f32x4 x) { return (x[0] * x[0] + x[1] * x[1]) + (x[2] * x[2] + x[3] * x[3]); }
;     __device__ __forceinline__ void fused(AccT& acc, const Unit& u, int wr, int wc, int fr, int fq, LAS unsigned char* lx, int tid) const {
;     ...
;                 const int row = EPI_ROW(u, ai, m); float s1 = 0.f, s2 = 0.f;
; #pragma unroll
;                 for (int bj = 0; bj < 2; ++bj) {
;                     const half8 rv = *(const half8*)(res + (size_t)row * DM + EPI_COL(u, bj));
; #pragma unroll
;                     for (int e = 0; e < 4; ++e) { acc[ai][bj][m][0][e] += ALPHA * (float)rv[e]; acc[ai][bj][m][1][e] += ALPHA * (float)rv[4 + e]; }
;                     const f32x4 a0 = acc[ai][bj][m][0], a1 = acc[ai][bj][m][1];
;                     s1 += ((a0[0] + a0[1]) + (a0[2] + a0[3])) + ((a1[0] + a1[1]) + (a1[2] + a1[3])); s2 += sumsq4(a0) + sumsq4(a1);
;                 }
;                 s1 += __shfl_xor(s1, 16); s1 += __shfl_xor(s1, 32); s2 += __shfl_xor(s2, 16); s2 += __shfl_xor(s2, 32);
;                 if (fq == 0) P[(ai * 128 + wr * 64 + m * 16 + fr) * 4 + wc] = (f32x2){s1, s2};
.LBB0_386:
	s_or_b64 exec, exec, s[0:1]
	v_or_b32_e32 v104, 32, v158
	v_ashrrev_i32_e32 v105, 31, v104
	v_readlane_b32 s0, v255, 0
	v_lshlrev_b64 v[104:105], 11, v[104:105]
	v_readlane_b32 s1, v255, 1
	v_mov_b32_e32 v176, v86
	v_pk_mov_b32 v[86:87], v[86:87], v[84:85] op_sel:[1,0]
	s_waitcnt lgkmcnt(0)
	v_lshl_add_u64 v[108:109], s[0:1], 0, v[104:105]
	v_lshl_add_u64 v[108:109], v[140:141], 1, v[108:109]
	global_load_dwordx4 v[164:167], v[108:109], off
	global_load_dwordx4 v[170:173], v[108:109], off offset:256
	s_mov_b32 s0, 0x3fd744fd
	v_mov_b32_e32 v177, v84
	v_mov_b32_e32 v84, v88
	s_waitcnt vmcnt(0) lgkmcnt(0)
	v_cvt_f32_f16_sdwa v174, v166 dst_sel:DWORD dst_unused:UNUSED_PAD src0_sel:WORD_1
	v_cvt_f32_f16_e32 v108, v172
	v_cvt_f32_f16_sdwa v109, v172 dst_sel:DWORD dst_unused:UNUSED_PAD src0_sel:WORD_1
	v_cvt_f32_f16_sdwa v172, v164 dst_sel:DWORD dst_unused:UNUSED_PAD src0_sel:WORD_1
	v_pk_fma_f32 v[94:95], v[108:109], s[0:1], v[94:95] op_sel_hi:[1,0,1]
	v_cvt_f32_f16_e32 v108, v173
	v_cvt_f32_f16_sdwa v109, v173 dst_sel:DWORD dst_unused:UNUSED_PAD src0_sel:WORD_1
	v_mov_b32_e32 v162, v95
	v_pk_fma_f32 v[96:97], v[108:109], s[0:1], v[96:97] op_sel_hi:[1,0,1]
	s_nop 0
	v_mov_b32_e32 v163, v97
	v_mov_b32_e32 v108, v94
	v_mov_b32_e32 v109, v96
	v_pk_mul_f32 v[162:163], v[162:163], v[162:163]
	s_nop 0
	v_pk_fma_f32 v[108:109], v[108:109], v[108:109], v[162:163]
	v_mov_b32_e32 v162, v90
	v_pk_add_f32 v[168:169], v[108:109], v[108:109] op_sel_hi:[0,1]
	v_cvt_f32_f16_e32 v109, v170
	v_cvt_f32_f16_e32 v108, v164
	v_mov_b32_e32 v163, v82
	v_pk_mov_b32 v[90:91], v[90:91], v[82:83] op_sel:[1,0]
	v_mov_b32_e32 v173, v109
	v_pk_fma_f32 v[108:109], v[108:109], s[0:1], v[162:163] op_sel_hi:[1,0,1]
	v_cvt_f32_f16_e32 v163, v171
	v_pk_fma_f32 v[90:91], v[172:173], s[0:1], v[90:91] op_sel_hi:[1,0,1]
	v_cvt_f32_f16_e32 v172, v165
	v_cvt_f32_f16_sdwa v173, v170 dst_sel:DWORD dst_unused:UNUSED_PAD src0_sel:WORD_1
	v_mov_b32_e32 v175, v163
	v_pk_fma_f32 v[86:87], v[174:175], s[0:1], v[86:87] op_sel_hi:[1,0,1]
	v_cvt_f32_f16_sdwa v174, v165 dst_sel:DWORD dst_unused:UNUSED_PAD src0_sel:WORD_1
	v_mov_b32_e32 v82, v92
	v_cvt_f32_f16_e32 v170, v167
	v_cvt_f32_f16_sdwa v171, v171 dst_sel:DWORD dst_unused:UNUSED_PAD src0_sel:WORD_1
	v_cvt_f32_f16_e32 v162, v166
	v_pk_fma_f32 v[164:165], v[172:173], s[0:1], v[82:83] op_sel_hi:[1,0,1]
	v_cvt_f32_f16_sdwa v172, v167 dst_sel:DWORD dst_unused:UNUSED_PAD src0_sel:WORD_1
	v_mov_b32_e32 v175, v173
	v_mov_b32_e32 v82, v93
	v_mov_b32_e32 v173, v171
	v_pk_fma_f32 v[166:167], v[170:171], s[0:1], v[84:85] op_sel_hi:[1,0,1]
	v_pk_fma_f32 v[82:83], v[174:175], s[0:1], v[82:83] op_sel_hi:[1,0,1]
	v_mov_b32_e32 v84, v89
	v_pk_mul_f32 v[88:89], v[108:109], v[108:109]
	v_pk_mul_f32 v[92:93], v[90:91], v[90:91]
	v_pk_fma_f32 v[162:163], v[162:163], s[0:1], v[176:177] op_sel_hi:[1,0,1]
	v_pk_fma_f32 v[84:85], v[172:173], s[0:1], v[84:85] op_sel_hi:[1,0,1]
	v_pk_mul_f32 v[170:171], v[164:165], v[164:165]
	v_pk_mul_f32 v[172:173], v[82:83], v[82:83]
	v_pk_mov_b32 v[88:89], v[108:109], v[88:89] op_sel:[1,0]
	v_pk_mov_b32 v[92:93], v[164:165], v[92:93] op_sel:[1,0]
	v_pk_mul_f32 v[174:175], v[162:163], v[162:163]
	v_pk_add_f32 v[88:89], v[88:89], v[92:93]
	v_pk_mov_b32 v[92:93], v[162:163], v[170:171] op_sel:[1,0]
	v_pk_mov_b32 v[170:171], v[166:167], v[172:173] op_sel:[1,0]
	v_pk_mul_f32 v[176:177], v[86:87], v[86:87]
	v_pk_add_f32 v[92:93], v[92:93], v[170:171]
	v_pk_mul_f32 v[178:179], v[166:167], v[166:167]
	v_pk_mul_f32 v[180:181], v[84:85], v[84:85]
	v_pk_add_f32 v[88:89], v[88:89], v[92:93]
	v_mov_b32_e32 v92, v94
	v_mov_b32_e32 v93, v174
	v_pk_mov_b32 v[170:171], v[94:95], v[176:177] op_sel:[1,0]
	v_pk_mov_b32 v[172:173], v[96:97], v[180:181] op_sel:[1,0]
	v_pk_add_f32 v[92:93], v[92:93], v[170:171]
	v_mov_b32_e32 v170, v96
	v_mov_b32_e32 v171, v178
	v_pk_add_f32 v[170:171], v[170:171], v[172:173]
	v_pk_mul_f32 v[172:173], v[164:165], v[82:83]
	v_pk_add_f32 v[92:93], v[92:93], v[170:171]
	v_pk_mul_f32 v[170:171], v[108:109], v[90:91]
	v_pk_add_f32 v[88:89], v[88:89], v[92:93]
	v_pk_add_f32 v[92:93], v[108:109], v[90:91]
	v_pk_mul_f32 v[174:175], v[166:167], v[84:85]
	v_mov_b32_e32 v93, v171
	v_pk_add_f32 v[170:171], v[164:165], v[82:83]
	v_mov_b32_e32 v168, v1
	v_mov_b32_e32 v171, v173
	v_pk_add_f32 v[92:93], v[92:93], v[170:171]
	v_pk_add_f32 v[170:171], v[162:163], v[86:87]
	v_pk_mul_f32 v[172:173], v[162:163], v[86:87]
	s_nop 0
	v_mov_b32_e32 v171, v173
	v_pk_add_f32 v[172:173], v[166:167], v[84:85]
	s_nop 0
	v_mov_b32_e32 v173, v175
	v_pk_add_f32 v[170:171], v[170:171], v[172:173]
	s_nop 0
	v_pk_add_f32 v[92:93], v[92:93], v[170:171]
	s_nop 0
	v_pk_add_f32 v[92:93], v[92:93], v[168:169]
	s_nop 0
	v_pk_add_f32 v[88:89], v[88:89], v[92:93]
	ds_bpermute_b32 v92, v241, v88
	ds_bpermute_b32 v93, v241, v89
	s_waitcnt lgkmcnt(0)
	v_pk_add_f32 v[88:89], v[88:89], v[92:93]
	ds_bpermute_b32 v92, v240, v88
	ds_bpermute_b32 v93, v240, v89
	s_and_saveexec_b64 s[0:1], vcc
	s_cbranch_execz .LBB0_388
	s_waitcnt lgkmcnt(0)
	v_pk_add_f32 v[88:89], v[88:89], v[92:93]
	ds_write_b64 v115, v[88:89] offset:1024
; __device__ __forceinline__ float sumsq4(f32x4 x) { return (x[0] * x[0] + x[1] * x[1]) + (x[2] * x[2] + x[3] * x[3]); }
;     __device__ __forceinline__ void fused(AccT& acc, const Unit& u, int wr, int wc, int fr, int fq, LAS unsigned char* lx, int tid) const {
;     ...
;                 const int row = EPI_ROW(u, ai, m); float s1 = 0.f, s2 = 0.f;
; #pragma unroll
;                 for (int bj = 0; bj < 2; ++bj) {
;                     const half8 rv = *(const half8*)(res + (size_t)row * DM + EPI_COL(u, bj));
; #pragma unroll
;                     for (int e = 0; e < 4; ++e) { acc[ai][bj][m][0][e] += ALPHA * (float)rv[e]; acc[ai][bj][m][1][e] += ALPHA * (float)rv[4 + e]; }
;                     const f32x4 a0 = acc[ai][bj][m][0], a1 = acc[ai][bj][m][1];
;                     s1 += ((a0[0] + a0[1]) + (a0[2] + a0[3])) + ((a1[0] + a1[1]) + (a1[2] + a1[3])); s2 += sumsq4(a0) + sumsq4(a1);
;                 }
;                 s1 += __shfl_xor(s1, 16); s1 += __shfl_xor(s1, 32); s2 += __shfl_xor(s2, 16); s2 += __shfl_xor(s2, 32);
;                 if (fq == 0) P[(ai * 128 + wr * 64 + m * 16 + fr) * 4 + wc] = (f32x2){s1, s2};
.LBB0_388:
	s_or_b64 exec, exec, s[0:1]
	v_or_b32_e32 v88, 48, v158
	v_ashrrev_i32_e32 v89, 31, v88
	v_readlane_b32 s0, v255, 0
	v_lshlrev_b64 v[88:89], 11, v[88:89]
	v_readlane_b32 s1, v255, 1
	v_mov_b32_e32 v182, v70
	v_pk_mov_b32 v[70:71], v[70:71], v[68:69] op_sel:[1,0]
	s_waitcnt lgkmcnt(0)
	v_lshl_add_u64 v[92:93], s[0:1], 0, v[88:89]
	v_lshl_add_u64 v[92:93], v[140:141], 1, v[92:93]
	global_load_dwordx4 v[170:173], v[92:93], off
	global_load_dwordx4 v[176:179], v[92:93], off offset:256
	s_mov_b32 s0, 0x3fd744fd
	v_mov_b32_e32 v183, v68
	v_mov_b32_e32 v68, v72
	s_waitcnt vmcnt(0) lgkmcnt(0)
	v_cvt_f32_f16_sdwa v180, v172 dst_sel:DWORD dst_unused:UNUSED_PAD src0_sel:WORD_1
	v_cvt_f32_f16_e32 v92, v178
	v_cvt_f32_f16_sdwa v93, v178 dst_sel:DWORD dst_unused:UNUSED_PAD src0_sel:WORD_1
	v_cvt_f32_f16_sdwa v178, v170 dst_sel:DWORD dst_unused:UNUSED_PAD src0_sel:WORD_1
	v_pk_fma_f32 v[78:79], v[92:93], s[0:1], v[78:79] op_sel_hi:[1,0,1]
	v_cvt_f32_f16_e32 v92, v179
	v_cvt_f32_f16_sdwa v93, v179 dst_sel:DWORD dst_unused:UNUSED_PAD src0_sel:WORD_1
	v_mov_b32_e32 v168, v79
	v_pk_fma_f32 v[80:81], v[92:93], s[0:1], v[80:81] op_sel_hi:[1,0,1]
	s_nop 0
	v_mov_b32_e32 v169, v81
	v_mov_b32_e32 v92, v78
	v_mov_b32_e32 v93, v80
	v_pk_mul_f32 v[168:169], v[168:169], v[168:169]
	s_nop 0
	v_pk_fma_f32 v[92:93], v[92:93], v[92:93], v[168:169]
	v_mov_b32_e32 v168, v74
	v_pk_add_f32 v[174:175], v[92:93], v[92:93] op_sel_hi:[0,1]
	v_cvt_f32_f16_e32 v93, v176
	v_cvt_f32_f16_e32 v92, v170
	v_mov_b32_e32 v169, v66
	v_pk_mov_b32 v[74:75], v[74:75], v[66:67] op_sel:[1,0]
	v_mov_b32_e32 v179, v93
	v_pk_fma_f32 v[92:93], v[92:93], s[0:1], v[168:169] op_sel_hi:[1,0,1]
	v_cvt_f32_f16_e32 v169, v177
	v_pk_fma_f32 v[74:75], v[178:179], s[0:1], v[74:75] op_sel_hi:[1,0,1]
	v_cvt_f32_f16_e32 v178, v171
	v_cvt_f32_f16_sdwa v179, v176 dst_sel:DWORD dst_unused:UNUSED_PAD src0_sel:WORD_1
	v_mov_b32_e32 v181, v169
	v_pk_fma_f32 v[70:71], v[180:181], s[0:1], v[70:71] op_sel_hi:[1,0,1]
	v_cvt_f32_f16_sdwa v180, v171 dst_sel:DWORD dst_unused:UNUSED_PAD src0_sel:WORD_1
	v_mov_b32_e32 v66, v76
	v_cvt_f32_f16_e32 v176, v173
	v_cvt_f32_f16_sdwa v177, v177 dst_sel:DWORD dst_unused:UNUSED_PAD src0_sel:WORD_1
	v_cvt_f32_f16_e32 v168, v172
	v_pk_fma_f32 v[170:171], v[178:179], s[0:1], v[66:67] op_sel_hi:[1,0,1]
	v_cvt_f32_f16_sdwa v178, v173 dst_sel:DWORD dst_unused:UNUSED_PAD src0_sel:WORD_1
	v_mov_b32_e32 v181, v179
	v_mov_b32_e32 v66, v77
	v_mov_b32_e32 v179, v177
	v_pk_fma_f32 v[172:173], v[176:177], s[0:1], v[68:69] op_sel_hi:[1,0,1]
	v_pk_fma_f32 v[66:67], v[180:181], s[0:1], v[66:67] op_sel_hi:[1,0,1]
	v_mov_b32_e32 v68, v73
	v_pk_mul_f32 v[72:73], v[92:93], v[92:93]
	v_pk_mul_f32 v[76:77], v[74:75], v[74:75]
	v_pk_fma_f32 v[168:169], v[168:169], s[0:1], v[182:183] op_sel_hi:[1,0,1]
	v_pk_fma_f32 v[68:69], v[178:179], s[0:1], v[68:69] op_sel_hi:[1,0,1]
	v_pk_mul_f32 v[176:177], v[170:171], v[170:171]
	v_pk_mul_f32 v[178:179], v[66:67], v[66:67]
	v_pk_mov_b32 v[72:73], v[92:93], v[72:73] op_sel:[1,0]
	v_pk_mov_b32 v[76:77], v[170:171], v[76:77] op_sel:[1,0]
	v_pk_mul_f32 v[180:181], v[168:169], v[168:169]
	v_pk_add_f32 v[72:73], v[72:73], v[76:77]
	v_pk_mov_b32 v[76:77], v[168:169], v[176:177] op_sel:[1,0]
	v_pk_mov_b32 v[176:177], v[172:173], v[178:179] op_sel:[1,0]
	v_pk_mul_f32 v[182:183], v[70:71], v[70:71]
	v_pk_add_f32 v[76:77], v[76:77], v[176:177]
	v_pk_mul_f32 v[184:185], v[172:173], v[172:173]
	v_pk_mul_f32 v[186:187], v[68:69], v[68:69]
	v_pk_add_f32 v[72:73], v[72:73], v[76:77]
	v_mov_b32_e32 v76, v78
	v_mov_b32_e32 v77, v180
	v_pk_mov_b32 v[176:177], v[78:79], v[182:183] op_sel:[1,0]
	v_pk_mov_b32 v[178:179], v[80:81], v[186:187] op_sel:[1,0]
	v_pk_add_f32 v[76:77], v[76:77], v[176:177]
	v_mov_b32_e32 v176, v80
	v_mov_b32_e32 v177, v184
	v_pk_add_f32 v[176:177], v[176:177], v[178:179]
	v_pk_mul_f32 v[178:179], v[170:171], v[66:67]
	v_pk_add_f32 v[76:77], v[76:77], v[176:177]
	v_pk_mul_f32 v[176:177], v[92:93], v[74:75]
	v_pk_add_f32 v[72:73], v[72:73], v[76:77]
	v_pk_add_f32 v[76:77], v[92:93], v[74:75]
	v_pk_mul_f32 v[180:181], v[172:173], v[68:69]
	v_mov_b32_e32 v77, v177
	v_pk_add_f32 v[176:177], v[170:171], v[66:67]
	v_mov_b32_e32 v174, v1
	v_mov_b32_e32 v177, v179
	v_pk_add_f32 v[76:77], v[76:77], v[176:177]
	v_pk_add_f32 v[176:177], v[168:169], v[70:71]
	v_pk_mul_f32 v[178:179], v[168:169], v[70:71]
	s_nop 0
	v_mov_b32_e32 v177, v179
	v_pk_add_f32 v[178:179], v[172:173], v[68:69]
	s_nop 0
	v_mov_b32_e32 v179, v181
	v_pk_add_f32 v[176:177], v[176:177], v[178:179]
	s_nop 0
	v_pk_add_f32 v[76:77], v[76:77], v[176:177]
	s_nop 0
	v_pk_add_f32 v[76:77], v[76:77], v[174:175]
	s_nop 0
	v_pk_add_f32 v[72:73], v[72:73], v[76:77]
	ds_bpermute_b32 v76, v241, v72
	ds_bpermute_b32 v77, v241, v73
	s_waitcnt lgkmcnt(0)
	v_pk_add_f32 v[72:73], v[72:73], v[76:77]
	ds_bpermute_b32 v76, v240, v72
	ds_bpermute_b32 v77, v240, v73
	s_and_saveexec_b64 s[0:1], vcc
	s_cbranch_execz .LBB0_390
	s_waitcnt lgkmcnt(0)
	v_pk_add_f32 v[72:73], v[72:73], v[76:77]
	ds_write_b64 v115, v[72:73] offset:1536
; __device__ __forceinline__ float sumsq4(f32x4 x) { return (x[0] * x[0] + x[1] * x[1]) + (x[2] * x[2] + x[3] * x[3]); }
;     __device__ __forceinline__ void fused(AccT& acc, const Unit& u, int wr, int wc, int fr, int fq, LAS unsigned char* lx, int tid) const {
;     ...
;                 const int row = EPI_ROW(u, ai, m); float s1 = 0.f, s2 = 0.f;
; #pragma unroll
;                 for (int bj = 0; bj < 2; ++bj) {
;                     const half8 rv = *(const half8*)(res + (size_t)row * DM + EPI_COL(u, bj));
; #pragma unroll
;                     for (int e = 0; e < 4; ++e) { acc[ai][bj][m][0][e] += ALPHA * (float)rv[e]; acc[ai][bj][m][1][e] += ALPHA * (float)rv[4 + e]; }
;                     const f32x4 a0 = acc[ai][bj][m][0], a1 = acc[ai][bj][m][1];
;                     s1 += ((a0[0] + a0[1]) + (a0[2] + a0[3])) + ((a1[0] + a1[1]) + (a1[2] + a1[3])); s2 += sumsq4(a0) + sumsq4(a1);
;                 }
;                 s1 += __shfl_xor(s1, 16); s1 += __shfl_xor(s1, 32); s2 += __shfl_xor(s2, 16); s2 += __shfl_xor(s2, 32);
;                 if (fq == 0) P[(ai * 128 + wr * 64 + m * 16 + fr) * 4 + wc] = (f32x2){s1, s2};
.LBB0_390:
	s_or_b64 exec, exec, s[0:1]
	v_add_u32_e32 v72, 0x80, v158
	v_ashrrev_i32_e32 v73, 31, v72
	v_readlane_b32 s0, v255, 0
	v_lshlrev_b64 v[72:73], 11, v[72:73]
	v_readlane_b32 s1, v255, 1
	v_mov_b32_e32 v188, v54
	v_pk_mov_b32 v[54:55], v[54:55], v[52:53] op_sel:[1,0]
	s_waitcnt lgkmcnt(0)
	v_lshl_add_u64 v[76:77], s[0:1], 0, v[72:73]
	v_lshl_add_u64 v[76:77], v[140:141], 1, v[76:77]
	global_load_dwordx4 v[176:179], v[76:77], off
	global_load_dwordx4 v[182:185], v[76:77], off offset:256
	s_mov_b32 s0, 0x3fd744fd
	v_mov_b32_e32 v189, v52
	v_mov_b32_e32 v52, v56
	s_waitcnt vmcnt(0) lgkmcnt(0)
	v_cvt_f32_f16_sdwa v186, v178 dst_sel:DWORD dst_unused:UNUSED_PAD src0_sel:WORD_1
	v_cvt_f32_f16_e32 v76, v184
	v_cvt_f32_f16_sdwa v77, v184 dst_sel:DWORD dst_unused:UNUSED_PAD src0_sel:WORD_1
	v_cvt_f32_f16_sdwa v184, v176 dst_sel:DWORD dst_unused:UNUSED_PAD src0_sel:WORD_1
	v_pk_fma_f32 v[62:63], v[76:77], s[0:1], v[62:63] op_sel_hi:[1,0,1]
	v_cvt_f32_f16_e32 v76, v185
	v_cvt_f32_f16_sdwa v77, v185 dst_sel:DWORD dst_unused:UNUSED_PAD src0_sel:WORD_1
	v_mov_b32_e32 v174, v63
	v_pk_fma_f32 v[64:65], v[76:77], s[0:1], v[64:65] op_sel_hi:[1,0,1]
	s_nop 0
	v_mov_b32_e32 v175, v65
	v_mov_b32_e32 v76, v62
	v_mov_b32_e32 v77, v64
	v_pk_mul_f32 v[174:175], v[174:175], v[174:175]
	s_nop 0
	v_pk_fma_f32 v[76:77], v[76:77], v[76:77], v[174:175]
	v_mov_b32_e32 v174, v58
	v_pk_add_f32 v[180:181], v[76:77], v[76:77] op_sel_hi:[0,1]
	v_cvt_f32_f16_e32 v77, v182
	v_cvt_f32_f16_e32 v76, v176
	v_mov_b32_e32 v175, v50
	v_pk_mov_b32 v[58:59], v[58:59], v[50:51] op_sel:[1,0]
	v_mov_b32_e32 v185, v77
	v_pk_fma_f32 v[76:77], v[76:77], s[0:1], v[174:175] op_sel_hi:[1,0,1]
	v_cvt_f32_f16_e32 v175, v183
	v_pk_fma_f32 v[58:59], v[184:185], s[0:1], v[58:59] op_sel_hi:[1,0,1]
	v_cvt_f32_f16_e32 v184, v177
	v_cvt_f32_f16_sdwa v185, v182 dst_sel:DWORD dst_unused:UNUSED_PAD src0_sel:WORD_1
	v_mov_b32_e32 v187, v175
	v_pk_fma_f32 v[54:55], v[186:187], s[0:1], v[54:55] op_sel_hi:[1,0,1]
	v_cvt_f32_f16_sdwa v186, v177 dst_sel:DWORD dst_unused:UNUSED_PAD src0_sel:WORD_1
	v_mov_b32_e32 v50, v60
	v_cvt_f32_f16_e32 v182, v179
	v_cvt_f32_f16_sdwa v183, v183 dst_sel:DWORD dst_unused:UNUSED_PAD src0_sel:WORD_1
	v_cvt_f32_f16_e32 v174, v178
	v_pk_fma_f32 v[176:177], v[184:185], s[0:1], v[50:51] op_sel_hi:[1,0,1]
	v_cvt_f32_f16_sdwa v184, v179 dst_sel:DWORD dst_unused:UNUSED_PAD src0_sel:WORD_1
	v_mov_b32_e32 v187, v185
	v_mov_b32_e32 v50, v61
	v_mov_b32_e32 v185, v183
	v_pk_fma_f32 v[178:179], v[182:183], s[0:1], v[52:53] op_sel_hi:[1,0,1]
	v_pk_fma_f32 v[50:51], v[186:187], s[0:1], v[50:51] op_sel_hi:[1,0,1]
	v_mov_b32_e32 v52, v57
	v_pk_mul_f32 v[56:57], v[76:77], v[76:77]
	v_pk_mul_f32 v[60:61], v[58:59], v[58:59]
	v_pk_fma_f32 v[174:175], v[174:175], s[0:1], v[188:189] op_sel_hi:[1,0,1]
	v_pk_fma_f32 v[52:53], v[184:185], s[0:1], v[52:53] op_sel_hi:[1,0,1]
	v_pk_mul_f32 v[182:183], v[176:177], v[176:177]
	v_pk_mul_f32 v[184:185], v[50:51], v[50:51]
	v_pk_mov_b32 v[56:57], v[76:77], v[56:57] op_sel:[1,0]
	v_pk_mov_b32 v[60:61], v[176:177], v[60:61] op_sel:[1,0]
	v_pk_mul_f32 v[186:187], v[174:175], v[174:175]
	v_pk_add_f32 v[56:57], v[56:57], v[60:61]
	v_pk_mov_b32 v[60:61], v[174:175], v[182:183] op_sel:[1,0]
	v_pk_mov_b32 v[182:183], v[178:179], v[184:185] op_sel:[1,0]
	v_pk_mul_f32 v[188:189], v[54:55], v[54:55]
	v_pk_add_f32 v[60:61], v[60:61], v[182:183]
	v_pk_mul_f32 v[190:191], v[178:179], v[178:179]
	v_pk_mul_f32 v[192:193], v[52:53], v[52:53]
	v_pk_add_f32 v[56:57], v[56:57], v[60:61]
	v_mov_b32_e32 v60, v62
	v_mov_b32_e32 v61, v186
	v_pk_mov_b32 v[182:183], v[62:63], v[188:189] op_sel:[1,0]
	v_pk_mov_b32 v[184:185], v[64:65], v[192:193] op_sel:[1,0]
	v_pk_add_f32 v[60:61], v[60:61], v[182:183]
	v_mov_b32_e32 v182, v64
	v_mov_b32_e32 v183, v190
	v_pk_add_f32 v[182:183], v[182:183], v[184:185]
	v_pk_mul_f32 v[184:185], v[176:177], v[50:51]
	v_pk_add_f32 v[60:61], v[60:61], v[182:183]
	v_pk_mul_f32 v[182:183], v[76:77], v[58:59]
	v_pk_add_f32 v[56:57], v[56:57], v[60:61]
	v_pk_add_f32 v[60:61], v[76:77], v[58:59]
	v_pk_mul_f32 v[186:187], v[178:179], v[52:53]
	v_mov_b32_e32 v61, v183
	v_pk_add_f32 v[182:183], v[176:177], v[50:51]
	v_mov_b32_e32 v180, v1
	v_mov_b32_e32 v183, v185
	v_pk_add_f32 v[60:61], v[60:61], v[182:183]
	v_pk_add_f32 v[182:183], v[174:175], v[54:55]
	v_pk_mul_f32 v[184:185], v[174:175], v[54:55]
	s_nop 0
	v_mov_b32_e32 v183, v185
	v_pk_add_f32 v[184:185], v[178:179], v[52:53]
	s_nop 0
	v_mov_b32_e32 v185, v187
	v_pk_add_f32 v[182:183], v[182:183], v[184:185]
	s_nop 0
	v_pk_add_f32 v[60:61], v[60:61], v[182:183]
	s_nop 0
	v_pk_add_f32 v[60:61], v[60:61], v[180:181]
	s_nop 0
	v_pk_add_f32 v[56:57], v[56:57], v[60:61]
	ds_bpermute_b32 v60, v241, v56
	ds_bpermute_b32 v61, v241, v57
	s_waitcnt lgkmcnt(0)
	v_pk_add_f32 v[56:57], v[56:57], v[60:61]
	ds_bpermute_b32 v60, v240, v56
	ds_bpermute_b32 v61, v240, v57
	s_and_saveexec_b64 s[0:1], vcc
	s_cbranch_execz .LBB0_392
	s_waitcnt lgkmcnt(0)
	v_pk_add_f32 v[56:57], v[56:57], v[60:61]
	ds_write_b64 v115, v[56:57] offset:4096
; __device__ __forceinline__ float sumsq4(f32x4 x) { return (x[0] * x[0] + x[1] * x[1]) + (x[2] * x[2] + x[3] * x[3]); }
;     __device__ __forceinline__ void fused(AccT& acc, const Unit& u, int wr, int wc, int fr, int fq, LAS unsigned char* lx, int tid) const {
;     ...
;                 const int row = EPI_ROW(u, ai, m); float s1 = 0.f, s2 = 0.f;
; #pragma unroll
;                 for (int bj = 0; bj < 2; ++bj) {
;                     const half8 rv = *(const half8*)(res + (size_t)row * DM + EPI_COL(u, bj));
; #pragma unroll
;                     for (int e = 0; e < 4; ++e) { acc[ai][bj][m][0][e] += ALPHA * (float)rv[e]; acc[ai][bj][m][1][e] += ALPHA * (float)rv[4 + e]; }
;                     const f32x4 a0 = acc[ai][bj][m][0], a1 = acc[ai][bj][m][1];
;                     s1 += ((a0[0] + a0[1]) + (a0[2] + a0[3])) + ((a1[0] + a1[1]) + (a1[2] + a1[3])); s2 += sumsq4(a0) + sumsq4(a1);
;                 }
;                 s1 += __shfl_xor(s1, 16); s1 += __shfl_xor(s1, 32); s2 += __shfl_xor(s2, 16); s2 += __shfl_xor(s2, 32);
;                 if (fq == 0) P[(ai * 128 + wr * 64 + m * 16 + fr) * 4 + wc] = (f32x2){s1, s2};
.LBB0_392:
	s_or_b64 exec, exec, s[0:1]
	v_add_u32_e32 v56, 0x90, v158
	v_ashrrev_i32_e32 v57, 31, v56
	v_readlane_b32 s0, v255, 0
	v_lshlrev_b64 v[56:57], 11, v[56:57]
	v_readlane_b32 s1, v255, 1
	v_mov_b32_e32 v194, v38
	v_pk_mov_b32 v[38:39], v[38:39], v[36:37] op_sel:[1,0]
	s_waitcnt lgkmcnt(0)
	v_lshl_add_u64 v[60:61], s[0:1], 0, v[56:57]
	v_lshl_add_u64 v[60:61], v[140:141], 1, v[60:61]
	global_load_dwordx4 v[182:185], v[60:61], off
	global_load_dwordx4 v[188:191], v[60:61], off offset:256
	s_mov_b32 s0, 0x3fd744fd
	v_mov_b32_e32 v195, v36
	v_mov_b32_e32 v36, v40
	s_waitcnt vmcnt(0) lgkmcnt(0)
	v_cvt_f32_f16_sdwa v192, v184 dst_sel:DWORD dst_unused:UNUSED_PAD src0_sel:WORD_1
	v_cvt_f32_f16_e32 v60, v190
	v_cvt_f32_f16_sdwa v61, v190 dst_sel:DWORD dst_unused:UNUSED_PAD src0_sel:WORD_1
	v_cvt_f32_f16_sdwa v190, v182 dst_sel:DWORD dst_unused:UNUSED_PAD src0_sel:WORD_1
	v_pk_fma_f32 v[46:47], v[60:61], s[0:1], v[46:47] op_sel_hi:[1,0,1]
	v_cvt_f32_f16_e32 v60, v191
	v_cvt_f32_f16_sdwa v61, v191 dst_sel:DWORD dst_unused:UNUSED_PAD src0_sel:WORD_1
	v_mov_b32_e32 v180, v47
	v_pk_fma_f32 v[48:49], v[60:61], s[0:1], v[48:49] op_sel_hi:[1,0,1]
	s_nop 0
	v_mov_b32_e32 v181, v49
	v_mov_b32_e32 v60, v46
	v_mov_b32_e32 v61, v48
	v_pk_mul_f32 v[180:181], v[180:181], v[180:181]
	s_nop 0
	v_pk_fma_f32 v[60:61], v[60:61], v[60:61], v[180:181]
	v_mov_b32_e32 v180, v42
	v_pk_add_f32 v[186:187], v[60:61], v[60:61] op_sel_hi:[0,1]
	v_cvt_f32_f16_e32 v61, v188
	v_cvt_f32_f16_e32 v60, v182
	v_mov_b32_e32 v181, v34
	v_pk_mov_b32 v[42:43], v[42:43], v[34:35] op_sel:[1,0]
	v_mov_b32_e32 v191, v61
	v_pk_fma_f32 v[60:61], v[60:61], s[0:1], v[180:181] op_sel_hi:[1,0,1]
	v_cvt_f32_f16_e32 v181, v189
	v_pk_fma_f32 v[42:43], v[190:191], s[0:1], v[42:43] op_sel_hi:[1,0,1]
	v_cvt_f32_f16_e32 v190, v183
	v_cvt_f32_f16_sdwa v191, v188 dst_sel:DWORD dst_unused:UNUSED_PAD src0_sel:WORD_1
	v_mov_b32_e32 v193, v181
	v_pk_fma_f32 v[38:39], v[192:193], s[0:1], v[38:39] op_sel_hi:[1,0,1]
	v_cvt_f32_f16_sdwa v192, v183 dst_sel:DWORD dst_unused:UNUSED_PAD src0_sel:WORD_1
	v_mov_b32_e32 v34, v44
	v_cvt_f32_f16_e32 v188, v185
	v_cvt_f32_f16_sdwa v189, v189 dst_sel:DWORD dst_unused:UNUSED_PAD src0_sel:WORD_1
	v_cvt_f32_f16_e32 v180, v184
	v_pk_fma_f32 v[182:183], v[190:191], s[0:1], v[34:35] op_sel_hi:[1,0,1]
	v_cvt_f32_f16_sdwa v190, v185 dst_sel:DWORD dst_unused:UNUSED_PAD src0_sel:WORD_1
	v_mov_b32_e32 v193, v191
	v_mov_b32_e32 v34, v45
	v_mov_b32_e32 v191, v189
	v_pk_fma_f32 v[184:185], v[188:189], s[0:1], v[36:37] op_sel_hi:[1,0,1]
	v_pk_fma_f32 v[34:35], v[192:193], s[0:1], v[34:35] op_sel_hi:[1,0,1]
	v_mov_b32_e32 v36, v41
	v_pk_mul_f32 v[40:41], v[60:61], v[60:61]
	v_pk_mul_f32 v[44:45], v[42:43], v[42:43]
	v_pk_fma_f32 v[180:181], v[180:181], s[0:1], v[194:195] op_sel_hi:[1,0,1]
	v_pk_fma_f32 v[36:37], v[190:191], s[0:1], v[36:37] op_sel_hi:[1,0,1]
	v_pk_mul_f32 v[188:189], v[182:183], v[182:183]
	v_pk_mul_f32 v[190:191], v[34:35], v[34:35]
	v_pk_mov_b32 v[40:41], v[60:61], v[40:41] op_sel:[1,0]
	v_pk_mov_b32 v[44:45], v[182:183], v[44:45] op_sel:[1,0]
	v_pk_mul_f32 v[192:193], v[180:181], v[180:181]
	v_pk_add_f32 v[40:41], v[40:41], v[44:45]
	v_pk_mov_b32 v[44:45], v[180:181], v[188:189] op_sel:[1,0]
	v_pk_mov_b32 v[188:189], v[184:185], v[190:191] op_sel:[1,0]
	v_pk_mul_f32 v[194:195], v[38:39], v[38:39]
	v_pk_add_f32 v[44:45], v[44:45], v[188:189]
	v_pk_mul_f32 v[196:197], v[184:185], v[184:185]
	v_pk_mul_f32 v[198:199], v[36:37], v[36:37]
	v_pk_add_f32 v[40:41], v[40:41], v[44:45]
	v_mov_b32_e32 v44, v46
	v_mov_b32_e32 v45, v192
	v_pk_mov_b32 v[188:189], v[46:47], v[194:195] op_sel:[1,0]
	v_pk_mov_b32 v[190:191], v[48:49], v[198:199] op_sel:[1,0]
	v_pk_add_f32 v[44:45], v[44:45], v[188:189]
	v_mov_b32_e32 v188, v48
	v_mov_b32_e32 v189, v196
	v_pk_add_f32 v[188:189], v[188:189], v[190:191]
	v_pk_mul_f32 v[190:191], v[182:183], v[34:35]
	v_pk_add_f32 v[44:45], v[44:45], v[188:189]
	v_pk_mul_f32 v[188:189], v[60:61], v[42:43]
	v_pk_add_f32 v[40:41], v[40:41], v[44:45]
	v_pk_add_f32 v[44:45], v[60:61], v[42:43]
	v_pk_mul_f32 v[192:193], v[184:185], v[36:37]
	v_mov_b32_e32 v45, v189
	v_pk_add_f32 v[188:189], v[182:183], v[34:35]
	v_mov_b32_e32 v186, v1
	v_mov_b32_e32 v189, v191
	v_pk_add_f32 v[44:45], v[44:45], v[188:189]
	v_pk_add_f32 v[188:189], v[180:181], v[38:39]
	v_pk_mul_f32 v[190:191], v[180:181], v[38:39]
	s_nop 0
	v_mov_b32_e32 v189, v191
	v_pk_add_f32 v[190:191], v[184:185], v[36:37]
	s_nop 0
	v_mov_b32_e32 v191, v193
	v_pk_add_f32 v[188:189], v[188:189], v[190:191]
	s_nop 0
	v_pk_add_f32 v[44:45], v[44:45], v[188:189]
	s_nop 0
	v_pk_add_f32 v[44:45], v[44:45], v[186:187]
	s_nop 0
	v_pk_add_f32 v[40:41], v[40:41], v[44:45]
	ds_bpermute_b32 v44, v241, v40
	ds_bpermute_b32 v45, v241, v41
	s_waitcnt lgkmcnt(0)
	v_pk_add_f32 v[40:41], v[40:41], v[44:45]
	ds_bpermute_b32 v44, v240, v40
	ds_bpermute_b32 v45, v240, v41
	s_and_saveexec_b64 s[0:1], vcc
	s_cbranch_execz .LBB0_394
	s_waitcnt lgkmcnt(0)
	v_pk_add_f32 v[40:41], v[40:41], v[44:45]
	ds_write_b64 v115, v[40:41] offset:4608
; __device__ __forceinline__ float sumsq4(f32x4 x) { return (x[0] * x[0] + x[1] * x[1]) + (x[2] * x[2] + x[3] * x[3]); }
;     __device__ __forceinline__ void fused(AccT& acc, const Unit& u, int wr, int wc, int fr, int fq, LAS unsigned char* lx, int tid) const {
;     ...
;                 const int row = EPI_ROW(u, ai, m); float s1 = 0.f, s2 = 0.f;
; #pragma unroll
;                 for (int bj = 0; bj < 2; ++bj) {
;                     const half8 rv = *(const half8*)(res + (size_t)row * DM + EPI_COL(u, bj));
; #pragma unroll
;                     for (int e = 0; e < 4; ++e) { acc[ai][bj][m][0][e] += ALPHA * (float)rv[e]; acc[ai][bj][m][1][e] += ALPHA * (float)rv[4 + e]; }
;                     const f32x4 a0 = acc[ai][bj][m][0], a1 = acc[ai][bj][m][1];
;                     s1 += ((a0[0] + a0[1]) + (a0[2] + a0[3])) + ((a1[0] + a1[1]) + (a1[2] + a1[3])); s2 += sumsq4(a0) + sumsq4(a1);
;                 }
;                 s1 += __shfl_xor(s1, 16); s1 += __shfl_xor(s1, 32); s2 += __shfl_xor(s2, 16); s2 += __shfl_xor(s2, 32);
;                 if (fq == 0) P[(ai * 128 + wr * 64 + m * 16 + fr) * 4 + wc] = (f32x2){s1, s2};
.LBB0_394:
	s_or_b64 exec, exec, s[0:1]
	v_add_u32_e32 v40, 0xa0, v158
	v_ashrrev_i32_e32 v41, 31, v40
	v_readlane_b32 s0, v255, 0
	s_waitcnt lgkmcnt(0)
	v_lshlrev_b64 v[44:45], 11, v[40:41]
	v_readlane_b32 s1, v255, 1
	v_mov_b32_e32 v188, v26
	v_mov_b32_e32 v189, v18
	v_lshl_add_u64 v[40:41], s[0:1], 0, v[44:45]
	v_lshl_add_u64 v[40:41], v[140:141], 1, v[40:41]
	global_load_dwordx4 v[196:199], v[40:41], off
	global_load_dwordx4 v[200:203], v[40:41], off offset:256
	s_mov_b32 s0, 0x3fd744fd
	v_mov_b32_e32 v190, v22
	v_pk_mov_b32 v[26:27], v[26:27], v[18:19] op_sel:[1,0]
	v_pk_mov_b32 v[22:23], v[22:23], v[20:21] op_sel:[1,0]
	v_mov_b32_e32 v18, v28
	v_mov_b32_e32 v191, v20
	v_mov_b32_e32 v20, v24
	s_waitcnt vmcnt(0) lgkmcnt(0)
	v_cvt_f32_f16_sdwa v192, v196 dst_sel:DWORD dst_unused:UNUSED_PAD src0_sel:WORD_1
	v_cvt_f32_f16_e32 v40, v202
	v_cvt_f32_f16_sdwa v41, v202 dst_sel:DWORD dst_unused:UNUSED_PAD src0_sel:WORD_1
	v_cvt_f32_f16_sdwa v202, v198 dst_sel:DWORD dst_unused:UNUSED_PAD src0_sel:WORD_1
	v_pk_fma_f32 v[40:41], v[40:41], s[0:1], v[30:31] op_sel_hi:[1,0,1]
	v_cvt_f32_f16_e32 v30, v203
	v_cvt_f32_f16_sdwa v31, v203 dst_sel:DWORD dst_unused:UNUSED_PAD src0_sel:WORD_1
	v_pk_fma_f32 v[186:187], v[30:31], s[0:1], v[32:33] op_sel_hi:[1,0,1]
	v_mov_b32_e32 v32, v41
	v_mov_b32_e32 v33, v187
	v_mov_b32_e32 v30, v40
	v_mov_b32_e32 v31, v186
	v_pk_mul_f32 v[32:33], v[32:33], v[32:33]
	s_nop 0
	v_pk_fma_f32 v[30:31], v[30:31], v[30:31], v[32:33]
	v_cvt_f32_f16_e32 v33, v200
	v_cvt_f32_f16_e32 v32, v196
	v_pk_add_f32 v[30:31], v[30:31], v[30:31] op_sel_hi:[0,1]
	v_mov_b32_e32 v30, v1
	v_mov_b32_e32 v193, v33
	v_pk_fma_f32 v[188:189], v[32:33], s[0:1], v[188:189] op_sel_hi:[1,0,1]
	v_cvt_f32_f16_e32 v33, v201
	v_pk_fma_f32 v[194:195], v[192:193], s[0:1], v[26:27] op_sel_hi:[1,0,1]
	v_cvt_f32_f16_e32 v32, v198
	v_cvt_f32_f16_sdwa v26, v197 dst_sel:DWORD dst_unused:UNUSED_PAD src0_sel:WORD_1
	v_mov_b32_e32 v203, v33
	v_pk_fma_f32 v[192:193], v[202:203], s[0:1], v[22:23] op_sel_hi:[1,0,1]
	v_cvt_f32_f16_e32 v22, v197
	v_cvt_f32_f16_sdwa v23, v200 dst_sel:DWORD dst_unused:UNUSED_PAD src0_sel:WORD_1
	v_pk_fma_f32 v[190:191], v[32:33], s[0:1], v[190:191] op_sel_hi:[1,0,1]
	v_cvt_f32_f16_sdwa v32, v199 dst_sel:DWORD dst_unused:UNUSED_PAD src0_sel:WORD_1
	v_mov_b32_e32 v27, v23
	v_pk_fma_f32 v[196:197], v[22:23], s[0:1], v[18:19] op_sel_hi:[1,0,1]
	v_cvt_f32_f16_e32 v22, v199
	v_cvt_f32_f16_sdwa v23, v201 dst_sel:DWORD dst_unused:UNUSED_PAD src0_sel:WORD_1
	v_mov_b32_e32 v18, v29
	v_pk_fma_f32 v[200:201], v[26:27], s[0:1], v[18:19] op_sel_hi:[1,0,1]
	v_pk_mul_f32 v[18:19], v[188:189], v[188:189]
	v_mov_b32_e32 v33, v23
	v_pk_fma_f32 v[198:199], v[22:23], s[0:1], v[20:21] op_sel_hi:[1,0,1]
	v_mov_b32_e32 v20, v25
	v_pk_fma_f32 v[202:203], v[32:33], s[0:1], v[20:21] op_sel_hi:[1,0,1]
	v_pk_mul_f32 v[20:21], v[194:195], v[194:195]
	v_pk_mul_f32 v[22:23], v[196:197], v[196:197]
	v_pk_mul_f32 v[24:25], v[200:201], v[200:201]
	v_pk_mov_b32 v[18:19], v[188:189], v[18:19] op_sel:[1,0]
	v_pk_mov_b32 v[20:21], v[196:197], v[20:21] op_sel:[1,0]
	v_pk_mul_f32 v[26:27], v[190:191], v[190:191]
	v_pk_add_f32 v[18:19], v[18:19], v[20:21]
	v_pk_mov_b32 v[20:21], v[190:191], v[22:23] op_sel:[1,0]
	v_pk_mov_b32 v[22:23], v[198:199], v[24:25] op_sel:[1,0]
	v_pk_mul_f32 v[28:29], v[192:193], v[192:193]
	v_pk_add_f32 v[20:21], v[20:21], v[22:23]
	v_pk_mul_f32 v[32:33], v[198:199], v[198:199]
	v_pk_mul_f32 v[204:205], v[202:203], v[202:203]
	v_pk_add_f32 v[18:19], v[18:19], v[20:21]
	v_mov_b32_e32 v20, v40
	v_mov_b32_e32 v21, v26
	v_pk_mov_b32 v[22:23], v[40:41], v[28:29] op_sel:[1,0]
	v_pk_mov_b32 v[24:25], v[186:187], v[204:205] op_sel:[1,0]
	v_pk_add_f32 v[20:21], v[20:21], v[22:23]
	v_mov_b32_e32 v22, v186
	v_mov_b32_e32 v23, v32
	v_pk_add_f32 v[22:23], v[22:23], v[24:25]
	v_pk_mul_f32 v[24:25], v[196:197], v[200:201]
	v_pk_add_f32 v[20:21], v[20:21], v[22:23]
	v_pk_mul_f32 v[22:23], v[188:189], v[194:195]
	v_pk_add_f32 v[18:19], v[18:19], v[20:21]
	v_pk_add_f32 v[20:21], v[188:189], v[194:195]
	v_pk_mul_f32 v[26:27], v[198:199], v[202:203]
	v_mov_b32_e32 v21, v23
	v_pk_add_f32 v[22:23], v[196:197], v[200:201]
	s_nop 0
	v_mov_b32_e32 v23, v25
	v_pk_add_f32 v[20:21], v[20:21], v[22:23]
	v_pk_add_f32 v[22:23], v[190:191], v[192:193]
	v_pk_mul_f32 v[24:25], v[190:191], v[192:193]
	s_nop 0
	v_mov_b32_e32 v23, v25
	v_pk_add_f32 v[24:25], v[198:199], v[202:203]
	s_nop 0
	v_mov_b32_e32 v25, v27
	v_pk_add_f32 v[22:23], v[22:23], v[24:25]
	s_nop 0
	v_pk_add_f32 v[20:21], v[20:21], v[22:23]
	s_nop 0
	v_pk_add_f32 v[20:21], v[20:21], v[30:31]
	s_nop 0
	v_pk_add_f32 v[18:19], v[18:19], v[20:21]
	ds_bpermute_b32 v20, v241, v18
	ds_bpermute_b32 v21, v241, v19
	s_waitcnt lgkmcnt(0)
	v_pk_add_f32 v[18:19], v[18:19], v[20:21]
	ds_bpermute_b32 v20, v240, v18
	ds_bpermute_b32 v21, v240, v19
	s_and_saveexec_b64 s[0:1], vcc
	s_cbranch_execz .LBB0_396
	s_waitcnt lgkmcnt(0)
	v_pk_add_f32 v[18:19], v[18:19], v[20:21]
	ds_write_b64 v115, v[18:19] offset:5120
; __device__ __forceinline__ float sumsq4(f32x4 x) { return (x[0] * x[0] + x[1] * x[1]) + (x[2] * x[2] + x[3] * x[3]); }
;     __device__ __forceinline__ void fused(AccT& acc, const Unit& u, int wr, int wc, int fr, int fq, LAS unsigned char* lx, int tid) const {
;     ...
;                 const int row = EPI_ROW(u, ai, m); float s1 = 0.f, s2 = 0.f;
; #pragma unroll
;                 for (int bj = 0; bj < 2; ++bj) {
;                     const half8 rv = *(const half8*)(res + (size_t)row * DM + EPI_COL(u, bj));
; #pragma unroll
;                     for (int e = 0; e < 4; ++e) { acc[ai][bj][m][0][e] += ALPHA * (float)rv[e]; acc[ai][bj][m][1][e] += ALPHA * (float)rv[4 + e]; }
;                     const f32x4 a0 = acc[ai][bj][m][0], a1 = acc[ai][bj][m][1];
;                     s1 += ((a0[0] + a0[1]) + (a0[2] + a0[3])) + ((a1[0] + a1[1]) + (a1[2] + a1[3])); s2 += sumsq4(a0) + sumsq4(a1);
;                 }
;                 s1 += __shfl_xor(s1, 16); s1 += __shfl_xor(s1, 32); s2 += __shfl_xor(s2, 16); s2 += __shfl_xor(s2, 32);
;                 if (fq == 0) P[(ai * 128 + wr * 64 + m * 16 + fr) * 4 + wc] = (f32x2){s1, s2};
.LBB0_396:
	s_or_b64 exec, exec, s[0:1]
	v_add_u32_e32 v18, 0xb0, v158
	v_ashrrev_i32_e32 v19, 31, v18
	v_readlane_b32 s0, v255, 0
	v_lshlrev_b64 v[204:205], 11, v[18:19]
	v_readlane_b32 s1, v255, 1
	v_mov_b32_e32 v28, v6
	v_pk_mov_b32 v[6:7], v[6:7], v[4:5] op_sel:[1,0]
	v_lshl_add_u64 v[18:19], s[0:1], 0, v[204:205]
	v_lshl_add_u64 v[22:23], v[140:141], 1, v[18:19]
	s_waitcnt lgkmcnt(0)
	global_load_dwordx4 v[18:21], v[22:23], off
	s_nop 0
	global_load_dwordx4 v[22:25], v[22:23], off offset:256
	s_mov_b32 s0, 0x3fd744fd
	v_mov_b32_e32 v29, v4
	v_mov_b32_e32 v4, v8
	s_waitcnt vmcnt(0) lgkmcnt(0)
	v_cvt_f32_f16_e32 v26, v24
	v_cvt_f32_f16_sdwa v27, v24 dst_sel:DWORD dst_unused:UNUSED_PAD src0_sel:WORD_1
	v_cvt_f32_f16_sdwa v24, v18 dst_sel:DWORD dst_unused:UNUSED_PAD src0_sel:WORD_1
	v_pk_fma_f32 v[158:159], v[26:27], s[0:1], v[14:15] op_sel_hi:[1,0,1]
	v_cvt_f32_f16_e32 v14, v25
	v_cvt_f32_f16_sdwa v15, v25 dst_sel:DWORD dst_unused:UNUSED_PAD src0_sel:WORD_1
	v_mov_b32_e32 v26, v10
	v_mov_b32_e32 v27, v2
	v_pk_mov_b32 v[10:11], v[10:11], v[2:3] op_sel:[1,0]
	v_pk_fma_f32 v[206:207], v[14:15], s[0:1], v[16:17] op_sel_hi:[1,0,1]
	v_mov_b32_e32 v16, v159
	v_mov_b32_e32 v17, v207
	v_mov_b32_e32 v14, v158
	v_mov_b32_e32 v15, v206
	v_pk_mul_f32 v[16:17], v[16:17], v[16:17]
	v_mov_b32_e32 v2, v12
	v_pk_fma_f32 v[14:15], v[14:15], v[14:15], v[16:17]
	v_cvt_f32_f16_e32 v17, v22
	v_cvt_f32_f16_e32 v16, v18
	v_pk_add_f32 v[14:15], v[14:15], v[14:15] op_sel_hi:[0,1]
	v_mov_b32_e32 v14, v1
	v_mov_b32_e32 v25, v17
	v_pk_fma_f32 v[208:209], v[16:17], s[0:1], v[26:27] op_sel_hi:[1,0,1]
	v_cvt_f32_f16_e32 v17, v23
	v_cvt_f32_f16_sdwa v26, v20 dst_sel:DWORD dst_unused:UNUSED_PAD src0_sel:WORD_1
	v_cvt_f32_f16_e32 v16, v20
	v_pk_fma_f32 v[220:221], v[24:25], s[0:1], v[10:11] op_sel_hi:[1,0,1]
	v_mov_b32_e32 v27, v17
	v_pk_fma_f32 v[212:213], v[26:27], s[0:1], v[6:7] op_sel_hi:[1,0,1]
	v_cvt_f32_f16_e32 v6, v19
	v_cvt_f32_f16_sdwa v7, v22 dst_sel:DWORD dst_unused:UNUSED_PAD src0_sel:WORD_1
	v_pk_fma_f32 v[210:211], v[16:17], s[0:1], v[28:29] op_sel_hi:[1,0,1]
	v_cvt_f32_f16_sdwa v10, v19 dst_sel:DWORD dst_unused:UNUSED_PAD src0_sel:WORD_1
	v_cvt_f32_f16_sdwa v16, v21 dst_sel:DWORD dst_unused:UNUSED_PAD src0_sel:WORD_1
	v_mov_b32_e32 v11, v7
	v_pk_fma_f32 v[214:215], v[6:7], s[0:1], v[2:3] op_sel_hi:[1,0,1]
	v_cvt_f32_f16_e32 v6, v21
	v_cvt_f32_f16_sdwa v7, v23 dst_sel:DWORD dst_unused:UNUSED_PAD src0_sel:WORD_1
	v_mov_b32_e32 v2, v13
	v_pk_fma_f32 v[224:225], v[10:11], s[0:1], v[2:3] op_sel_hi:[1,0,1]
	v_pk_mul_f32 v[2:3], v[208:209], v[208:209]
	v_mov_b32_e32 v17, v7
	v_pk_fma_f32 v[222:223], v[6:7], s[0:1], v[4:5] op_sel_hi:[1,0,1]
	v_mov_b32_e32 v4, v9
	v_pk_fma_f32 v[226:227], v[16:17], s[0:1], v[4:5] op_sel_hi:[1,0,1]
	v_pk_mul_f32 v[4:5], v[220:221], v[220:221]
	v_pk_mul_f32 v[6:7], v[214:215], v[214:215]
	v_pk_mul_f32 v[8:9], v[224:225], v[224:225]
	v_pk_mov_b32 v[2:3], v[208:209], v[2:3] op_sel:[1,0]
	v_pk_mov_b32 v[4:5], v[214:215], v[4:5] op_sel:[1,0]
	v_pk_mul_f32 v[10:11], v[210:211], v[210:211]
	v_pk_add_f32 v[2:3], v[2:3], v[4:5]
	v_pk_mov_b32 v[4:5], v[210:211], v[6:7] op_sel:[1,0]
	v_pk_mov_b32 v[6:7], v[222:223], v[8:9] op_sel:[1,0]
	v_pk_mul_f32 v[12:13], v[212:213], v[212:213]
	v_pk_add_f32 v[4:5], v[4:5], v[6:7]
	v_pk_mul_f32 v[16:17], v[222:223], v[222:223]
	v_pk_mul_f32 v[18:19], v[226:227], v[226:227]
	v_pk_add_f32 v[2:3], v[2:3], v[4:5]
	v_mov_b32_e32 v4, v158
	v_mov_b32_e32 v5, v10
	v_pk_mov_b32 v[6:7], v[158:159], v[12:13] op_sel:[1,0]
	v_pk_mov_b32 v[8:9], v[206:207], v[18:19] op_sel:[1,0]
	v_pk_add_f32 v[4:5], v[4:5], v[6:7]
	v_mov_b32_e32 v6, v206
	v_mov_b32_e32 v7, v16
	v_pk_add_f32 v[6:7], v[6:7], v[8:9]
	v_pk_mul_f32 v[8:9], v[214:215], v[224:225]
	v_pk_add_f32 v[4:5], v[4:5], v[6:7]
	v_pk_mul_f32 v[6:7], v[208:209], v[220:221]
	v_pk_add_f32 v[2:3], v[2:3], v[4:5]
	v_pk_add_f32 v[4:5], v[208:209], v[220:221]
	v_pk_mul_f32 v[10:11], v[222:223], v[226:227]
	v_mov_b32_e32 v5, v7
	v_pk_add_f32 v[6:7], v[214:215], v[224:225]
	s_nop 0
	v_mov_b32_e32 v7, v9
	v_pk_add_f32 v[4:5], v[4:5], v[6:7]
	v_pk_add_f32 v[6:7], v[210:211], v[212:213]
	v_pk_mul_f32 v[8:9], v[210:211], v[212:213]
	s_nop 0
	v_mov_b32_e32 v7, v9
	v_pk_add_f32 v[8:9], v[222:223], v[226:227]
	s_nop 0
	v_mov_b32_e32 v9, v11
	v_pk_add_f32 v[6:7], v[6:7], v[8:9]
	s_nop 0
	v_pk_add_f32 v[4:5], v[4:5], v[6:7]
	s_nop 0
	v_pk_add_f32 v[4:5], v[4:5], v[14:15]
	s_nop 0
	v_pk_add_f32 v[2:3], v[2:3], v[4:5]
	ds_bpermute_b32 v4, v241, v2
	ds_bpermute_b32 v5, v241, v3
	s_waitcnt lgkmcnt(0)
	v_pk_add_f32 v[2:3], v[2:3], v[4:5]
	ds_bpermute_b32 v4, v240, v2
	ds_bpermute_b32 v5, v240, v3
	s_and_saveexec_b64 s[0:1], vcc
	s_cbranch_execz .LBB0_398
	s_waitcnt lgkmcnt(0)
	v_pk_add_f32 v[2:3], v[2:3], v[4:5]
	ds_write_b64 v115, v[2:3] offset:5632

; #define LAS __attribute__((address_space(3)))
; __device__ __forceinline__ unsigned pk4_fp8(float a, float b, float c, float d) { int w = 0; w = __builtin_amdgcn_cvt_pk_fp8_f32(a, b, w, false); w = __builtin_amdgcn_cvt_pk_fp8_f32(c, d, w, true); return (unsigned)w; }
; __device__ __forceinline__ void convpool_phase(const Params& p, int l, LAS float* hb) {
;     ...
;         for (int i = 0; i < 4; ++i) { const int ci = tid + 512 * i, rr = ci >> 5, c8 = (ci & 31) * 8, t = t0 - 15 + rr; av[i] = half8{}; gv[i] = half8{};
;             if (ci < 62 * 32 && t >= s0 && t < s1) { av[i] = *(const half8*)(U + (size_t)t * LDU + c8); gv[i] = *(const half8*)(U + (size_t)t * LDU + 256 + c8); } }
;         { const int tt = tid >> 4, q4 = (tid & 15) * 4, t = t0 + tt, pos = posof(t);
;           const half4 x = *(const half4*)(U + (size_t)t * LDU + 1152 + q4);
;           const f32x2 c2 = *(const f32x2*)(cosT + pos * 32 + (q4 >> 1)), s2 = *(const f32x2*)(sinT + pos * 32 + (q4 >> 1));
;           const float a0 = (float)x[0], a1 = (float)x[1], a2 = (float)x[2], a3 = (float)x[3];
;           const unsigned w2 = pk4_fp8(a0 * c2[0] - a1 * s2[0], a0 * s2[0] + a1 * c2[0], a2 * c2[1] - a3 * s2[1], a2 * s2[1] + a3 * c2[1]);
;           unsigned char* kp = Kb + (size_t)t * LDK + 128 + q4;
; #pragma unroll
;           for (int h = 0; h < 4; ++h) *(unsigned*)(kp + 192 * h) = w2; }
; #pragma unroll
;         for (int i = 0; i < 3; ++i) { const int ci = tid + 512 * i; if (ci < 47 * 32) { LAS float* d = pb + (ci >> 5) * 256 + (ci & 31) * 8;
;             *(LAS f32x4*)d = (f32x4){(float)pv[i][0], (float)pv[i][1], (float)pv[i][2], (float)pv[i][3]}; *(LAS f32x4*)(d + 4) = (f32x4){(float)pv[i][4], (float)pv[i][5], (float)pv[i][6], (float)pv[i][7]}; } }
.LBB0_441:
	s_or_b64 exec, exec, s[0:1]
	v_add_u32_e32 v133, s2, v111
	v_cmp_le_i32_e32 vcc, s20, v133
	s_and_b64 s[0:1], s[16:17], vcc
	v_cmp_gt_i32_e32 vcc, s21, v133
	s_and_b64 s[2:3], s[0:1], vcc
	v_mov_b32_e32 v30, 0
	v_mov_b32_e32 v31, 0
	v_mov_b32_e32 v32, 0
	v_mov_b32_e32 v33, 0
	v_mov_b32_e32 v26, 0
	v_mov_b32_e32 v27, 0
	v_mov_b32_e32 v28, 0
	v_mov_b32_e32 v29, 0
	s_and_saveexec_b64 s[0:1], s[2:3]
	s_cbranch_execz .LBB0_443
	v_mad_i64_i32 v[30:31], s[2:3], v133, s61, v[62:63]
	global_load_dwordx4 v[26:29], v[30:31], off
	s_nop 0
	global_load_dwordx4 v[30:33], v[30:31], off offset:512
.LBB0_443:
	s_or_b64 exec, exec, s[0:1]
	v_add_u32_e32 v133, s50, v98
	v_lshlrev_b32_e32 v136, 5, v133
	v_cmp_gt_i32_e32 vcc, s63, v133
	v_and_b32_e32 v137, 0x1ffe0, v136
	v_mad_i64_i32 v[134:135], s[0:1], v133, s61, v[64:65]
	v_cndmask_b32_e32 v136, v137, v136, vcc
	v_ashrrev_i32_e32 v137, 31, v136
	v_lshlrev_b64 v[136:137], 2, v[136:137]
	v_lshl_add_u64 v[138:139], v[54:55], 0, v[136:137]
	v_lshl_add_u64 v[136:137], v[56:57], 0, v[136:137]
	global_load_dwordx2 v[138:139], v[138:139], off
	s_nop 0
	global_load_dwordx2 v[136:137], v[136:137], off
	s_nop 0
	global_load_dwordx2 v[134:135], v[134:135], off offset:2304
	v_readlane_b32 s0, v255, 8
	v_readlane_b32 s1, v255, 9
	s_waitcnt vmcnt(0) lgkmcnt(0)
	v_cvt_f32_f16_e32 v140, v134
	v_cvt_f32_f16_sdwa v141, v134 dst_sel:DWORD dst_unused:UNUSED_PAD src0_sel:WORD_1
	v_cvt_f32_f16_e32 v142, v135
	v_cvt_f32_f16_sdwa v143, v135 dst_sel:DWORD dst_unused:UNUSED_PAD src0_sel:WORD_1
	v_mul_f32_e32 v141, v136, v141
	v_mul_f32_e32 v136, v136, v140
	v_fma_mix_f32 v141, v138, v134, -v141 op_sel_hi:[0,1,0]
	v_fma_mix_f32 v134, v138, v134, v136 op_sel:[0,1,0] op_sel_hi:[0,1,0]
	v_mov_b32_e32 v138, v1
	v_cvt_pk_fp8_f32 v138, v141, v134
	v_mul_f32_e32 v136, v137, v143
	v_mul_f32_e32 v137, v137, v142
	v_fma_mix_f32 v136, v139, v135, -v136 op_sel_hi:[0,1,0]
	v_fma_mix_f32 v135, v139, v135, v137 op_sel:[0,1,0] op_sel_hi:[0,1,0]
	v_cvt_pk_fp8_f32 v138, v136, v135 op_sel:[0,0,1]
	v_mov_b64_e32 v[134:135], s[0:1]
	s_movk_i32 s0, 0x300
	v_mad_i64_i32 v[134:135], s[0:1], v133, s0, v[134:135]
	v_lshl_add_u64 v[134:135], v[134:135], 0, v[0:1]
	s_mov_b64 s[0:1], 0x6c00080
	v_lshl_add_u64 v[136:137], v[134:135], 0, s[0:1]
	v_add_co_u32_e32 v134, vcc, 0x6c00000, v134
	s_nop 1
	v_addc_co_u32_e32 v135, vcc, 0, v135, vcc
	flat_store_dword v[134:135], v138 offset:128
	flat_store_dword v[136:137], v138 offset:192
	flat_store_dword v[136:137], v138 offset:384
	flat_store_dword v[136:137], v138 offset:576
	s_and_saveexec_b64 s[0:1], s[4:5]
	s_cbranch_execz .LBB0_465
	v_cvt_f32_f16_sdwa v135, v50 dst_sel:DWORD dst_unused:UNUSED_PAD src0_sel:WORD_1
	v_cvt_f32_f16_e32 v134, v50
	v_cvt_f32_f16_sdwa v137, v51 dst_sel:DWORD dst_unused:UNUSED_PAD src0_sel:WORD_1
	v_cvt_f32_f16_e32 v136, v51
	ds_write_b128 v112, v[134:137]
	v_cvt_f32_f16_sdwa v135, v52 dst_sel:DWORD dst_unused:UNUSED_PAD src0_sel:WORD_1
	v_cvt_f32_f16_e32 v134, v52
	v_cvt_f32_f16_sdwa v137, v53 dst_sel:DWORD dst_unused:UNUSED_PAD src0_sel:WORD_1
	v_cvt_f32_f16_e32 v136, v53
	ds_write_b128 v112, v[134:137] offset:16
	s_or_b64 exec, exec, s[0:1]
	s_and_saveexec_b64 s[0:1], s[6:7]
	s_cbranch_execnz .LBB0_466

; #define LAS __attribute__((address_space(3)))
; #define WBAR() do { asm volatile("s_waitcnt vmcnt(0) lgkmcnt(0)" ::: "memory"); __builtin_amdgcn_s_barrier(); asm volatile("" ::: "memory"); } while (0)
; __device__ __forceinline__ void attn_unit(const unsigned char* __restrict__ Qb, const unsigned char* __restrict__ Kh, const unsigned char* __restrict__ VTh, f16* __restrict__ Ob, int seq, LAS char* lds) {
;     ...
;     const unsigned char* Qw = Qb + (long)(wid * 32 + r32) * LDQ + hi * 32;
; #pragma unroll
;     for (int st = 0; st < 3; ++st) { const v4i x = *(const v4i*)(Qw + 64 * st), y = *(const v4i*)(Qw + 64 * st + 16); qf[st] = (v8i){x[0], x[1], x[2], x[3], y[0], y[1], y[2], y[3]}; }
;     const int sw = (r32 >> 2) & 3;
;     const int ka0 = r32 * 192 + (((2 * hi) ^ sw) << 4), ka1 = r32 * 192 + (((2 * hi + 1) ^ sw) << 4);
;     const int va0 = r32 * 64 + (((2 * hi) ^ sw) << 4), va1 = r32 * 64 + (((2 * hi + 1) ^ sw) << 4);
;     ...
;     f32x16 pA0, pA1, pB0, pB1; float dlA, dlB, alA, alB; v8i pa; const int NT = seq / 64;
;     const int NS = NT >> 1;
;     WBAR();
; __global__ void __launch_bounds__(512, 2) mega_fwd(Params p) {
;     ...
;                     if (uidx < 256) { h = xcd >> 1; const int qb = (xcd & 1) * 32 + slot; seq0 = 0; seqlen = TP; row0 = qb * 256; }
;                     else { const int sq = xcd >> 1; h = 2 * (xcd & 1) + (slot >> 4); const int qb = slot & 15; seq0 = TP + sq * 4096; seqlen = 4096; row0 = seq0 + qb * 256; }
;                     att::attn_unit(Qb + (size_t)row0 * LDQ + 192 * h, Kb + (size_t)seq0 * LDK + 192 * h, Vb + ((size_t)h * (T / 64) + (seq0 >> 6)) * (128 * 64),
;                                       CAT + (size_t)row0 * LDC + 512 + 128 * h, seqlen, (LAS char*)lds);
.LBB0_506:
	s_mul_i32 s1, s88, 0x300
	s_mul_hi_u32 s0, s88, 0x300
	s_add_u32 s1, s34, s1
	s_addc_u32 s4, s35, s0
	s_mul_i32 s5, s10, 0xc0
	s_add_u32 s0, s1, s5
	s_addc_u32 s1, s4, 0
	s_mul_i32 s6, s2, 0x300
	v_readlane_b32 s8, v255, 4
	s_mul_hi_u32 s4, s2, 0x300
	v_readlane_b32 s9, v255, 5
	s_add_u32 s6, s8, s6
	s_addc_u32 s4, s9, s4
	s_add_u32 s24, s6, s5
	s_addc_u32 s25, s4, 0
	s_mov_b32 s11, s89
	s_lshr_b32 s4, s2, 6
	s_mov_b32 s5, s89
	s_lshl_b64 s[6:7], s[10:11], 22
	s_lshl_b64 s[4:5], s[4:5], 13
	v_readlane_b32 s8, v255, 6
	v_readlane_b32 s9, v255, 7
	s_add_u32 s2, s8, s6
	s_addc_u32 s6, s9, s7
	v_mov_b32_e32 v2, v216
	s_add_u32 s52, s2, s4
	s_addc_u32 s53, s6, s5
	v_readfirstlane_b32 s14, v2
	s_ashr_i32 s22, s14, 6
	v_and_b32_e32 v238, 31, v2
	s_lshl_b32 s4, s22, 5
	v_bfe_u32 v239, v2, 5, 1
	v_or_b32_e32 v0, s4, v238
	v_mov_b64_e32 v[4:5], s[0:1]
	s_movk_i32 s0, 0x300
	v_mad_i64_i32 v[4:5], s[0:1], v0, s0, v[4:5]
	v_lshlrev_b32_e32 v0, 5, v239
	v_lshl_add_u64 v[4:5], v[4:5], 0, v[0:1]
	global_load_dwordx4 v[184:187], v[4:5], off
	global_load_dwordx4 v[188:191], v[4:5], off offset:16
	global_load_dwordx4 v[176:179], v[4:5], off offset:64
	global_load_dwordx4 v[180:183], v[4:5], off offset:80
	global_load_dwordx4 v[168:171], v[4:5], off offset:128
	global_load_dwordx4 v[172:175], v[4:5], off offset:144
	s_mov_b32 s2, s4
	v_writelane_b32 v255, s2, 17
	s_mul_hi_i32 s0, s22, 0x66666667
	s_lshr_b32 s1, s0, 31
	v_writelane_b32 v255, s3, 18
	s_ashr_i32 s2, s0, 3
	s_add_i32 s2, s2, s1
	s_mul_i32 s0, s2, 20
	v_mov_b32_e32 v0, v216
	s_sub_i32 s4, s22, s0
	s_waitcnt vmcnt(0) lgkmcnt(0)
	s_barrier
	s_cmp_lt_i32 s4, 8
	v_lshlrev_b32_e32 v0, 4, v0
	s_cselect_b64 s[54:55], -1, 0
	s_cmp_gt_i32 s4, 7
	v_and_b32_e32 v0, 0x3f0, v0
	s_cselect_b64 s[56:57], -1, 0
	s_waitcnt lgkmcnt(0)
	v_or_b32_e32 v3, 0xffffe000, v0
	s_mov_b64 s[0:1], -1
	s_and_b64 vcc, exec, s[56:57]
	v_readfirstlane_b32 s17, v0
	s_cbranch_vccz .LBB0_508
	s_lshl_b32 s17, s4, 10
	v_add_u32_e32 v4, s17, v3
	v_mul_u32_u24_sdwa v5, v4, s27 dst_sel:DWORD dst_unused:UNUSED_PAD src0_sel:WORD_0 src1_sel:DWORD
	v_lshrrev_b32_e32 v6, 23, v5
	v_mul_lo_u16_e32 v7, 0xc0, v6
	v_lshl_add_u32 v6, s2, 6, v6
	s_movk_i32 s0, 0x300
	v_lshrrev_b32_e32 v5, 21, v5
	v_sub_u16_e32 v4, v4, v7
	v_mul_lo_u32 v6, v6, s0
	v_and_b32_e32 v5, 48, v5
	v_bitop3_b32 v4, v5, v6, v4 bitop3:0xde
	s_mov_b64 s[0:1], s[24:25]
	s_cbranch_execnz .LBB0_510
	s_branch .LBB0_509

; __device__ __forceinline__ unsigned pk4_fp8(float a, float b, float c, float d) { int w = 0; w = __builtin_amdgcn_cvt_pk_fp8_f32(a, b, w, false); w = __builtin_amdgcn_cvt_pk_fp8_f32(c, d, w, true); return (unsigned)w; }
; __device__ __forceinline__ unsigned char one_fp8(float a) { return (unsigned char)(__builtin_amdgcn_cvt_pk_fp8_f32(a, a, 0, false) & 0xFF); }
;     __device__ __forceinline__ void operator()(const AccT& acc, const Unit& u, int wr, int wc, int fr, int fq) const {
;     ...
;                 const int row = EPI_ROW(u, ai, m);
;                 const float r = __builtin_amdgcn_rsqf(ssq_kv[row] * (1.0f / 128.0f) + RMS_EPS);
;                 const int c = wc * 32 + 8 * fq;
;                 const f32x4 k0 = acc[ai][0][m][0] * r, k1 = acc[ai][0][m][1] * r;
;                 u32x2 w; w.x = pk4_fp8(k0[0], k0[1], k0[2], k0[3]); w.y = pk4_fp8(k1[0], k1[1], k1[2], k1[3]);
;                 *(u32x2*)(Kb + (size_t)row * LDK + 192 * u.pn + c) = w;
;                 const int tile = row >> 6, k = row & 63, a = k >> 5, cc = k & 31, pos = 32 * ((cc >> 2) & 1) + 16 * a + (cc & 3) + 4 * (cc >> 3);
;                 unsigned char* vt = VT + ((size_t)(u.pn * (T / 64) + tile) * 128 + c) * 64 + (pos & 15);
; #pragma unroll
;                 for (int e = 0; e < 8; ++e) { const float v = (e < 4 ? acc[ai][1][m][0][e & 3] : acc[ai][1][m][1][e & 3]) * r;
;                     vt[e * 64 + ((((pos >> 4) ^ (((c + e) >> 2) & 3)) & 3) << 4)] = one_fp8(v); }
.LBB0_637:
	v_mov_b32_e32 v142, v216
	v_readlane_b32 s18, v255, 4
	v_ashrrev_i32_e32 v0, 2, v142
	v_and_b32_e32 v0, 0xffffffc0, v0
	v_and_b32_e32 v151, 15, v142
	v_lshl_add_u32 v152, s2, 8, v0
	v_or_b32_e32 v146, v152, v151
	v_ashrrev_i32_e32 v147, 31, v146
	v_lshl_add_u64 v[154:155], v[146:147], 2, s[38:39]
	global_load_dword v166, v[154:155], off
	global_load_dword v167, v[154:155], off offset:64
	global_load_dword v168, v[154:155], off offset:128
	global_load_dword v169, v[154:155], off offset:192
	global_load_dword v170, v[154:155], off offset:512
	global_load_dword v171, v[154:155], off offset:576
	global_load_dword v172, v[154:155], off offset:640
	global_load_dword v173, v[154:155], off offset:704
	v_mov_b32_e32 v154, v1
	v_mov_b32_e32 v155, v1
	v_readlane_b32 s19, v255, 5
	v_lshrrev_b32_e32 v157, 1, v142
	s_mul_i32 s0, s3, 0xc0
	s_lshl_b32 s2, s3, 9
	v_ashrrev_i32_e32 v144, 6, v152
	s_movk_i32 s13, 0x300
	v_bfe_u32 v156, v142, 4, 2
	v_and_b32_e32 v0, 0x60, v157
	s_ashr_i32 s1, s0, 31
	v_add_u32_e32 v144, s2, v144
	v_lshl_or_b32 v0, v156, 3, v0
	v_ashrrev_i32_e32 v145, 31, v144
	v_readlane_b32 s20, v255, 6
	v_lshlrev_b64 v[144:145], 13, v[144:145]
	v_readlane_b32 s21, v255, 7
	v_mov_b32_e32 v158, v1
	v_lshlrev_b32_e32 v156, 1, v156
	v_and_b32_e32 v153, 3, v142
	v_lshlrev_b32_e32 v142, 6, v0
	v_mov_b32_e32 v143, v1
	v_mov_b32_e32 v161, v1
	s_and_b64 vcc, exec, s[4:5]
	s_waitcnt vmcnt(0) lgkmcnt(0)
	v_fmamk_f32 v147, v166, 0x3c000000, v236
	v_rsq_f32_e32 v148, v147
	s_nop 0
	v_pk_mul_f32 v[126:127], v[126:127], v[148:149] op_sel_hi:[1,0]
	v_pk_mul_f32 v[122:123], v[122:123], v[148:149] op_sel_hi:[1,0]
	v_cvt_pk_fp8_f32 v154, v126, v127
	v_cvt_pk_fp8_f32 v155, v122, v123
	v_pk_mul_f32 v[128:129], v[128:129], v[148:149] op_sel_hi:[1,0]
	v_pk_mul_f32 v[124:125], v[124:125], v[148:149] op_sel_hi:[1,0]
	v_cvt_pk_fp8_f32 v154, v128, v129 op_sel:[0,0,1]
	v_cvt_pk_fp8_f32 v155, v124, v125 op_sel:[0,0,1]
	v_mov_b64_e32 v[122:123], s[18:19]
	v_mad_i64_i32 v[124:125], s[18:19], v146, s13, v[122:123]
	v_lshl_add_u64 v[124:125], v[124:125], 0, s[0:1]
	v_lshl_add_u64 v[124:125], v[124:125], 0, v[0:1]
	v_mul_f32_e32 v118, v118, v148
	flat_store_dwordx2 v[124:125], v[154:155]
	v_lshl_add_u64 v[124:125], s[20:21], 0, v[144:145]
	v_cvt_pk_fp8_f32 v158, v118, v118
	v_bitop3_b32 v118, v156, v157, 2 bitop3:0x28
	v_lshl_add_u64 v[144:145], v[124:125], 0, v[142:143]
	v_lshlrev_b32_e32 v124, 4, v118
	v_mul_f32_e32 v118, v119, v148
	v_and_or_b32 v128, v157, 4, v153
	v_mov_b32_e32 v129, v1
	v_cvt_pk_fp8_f32 v161, v118, v118
	v_bitop3_b32 v118, v156, v157, 2 bitop3:0x78
	v_lshl_add_u64 v[146:147], v[144:145], 0, v[128:129]
	v_and_b32_e32 v154, 2, v157
	v_mov_b32_e32 v125, v1
	v_lshlrev_b32_e32 v157, 4, v118
	v_lshl_add_u64 v[126:127], v[146:147], 0, v[124:125]
	v_or_b32_e32 v118, 64, v157
	v_mov_b32_e32 v119, v1
	flat_store_byte v[126:127], v158
	v_lshl_add_u64 v[158:159], v[146:147], 0, v[118:119]
	flat_store_byte v[158:159], v161
	v_mul_f32_e32 v120, v120, v148
	v_mov_b32_e32 v158, v1
	v_cvt_pk_fp8_f32 v158, v120, v120
	v_mul_f32_e32 v120, v121, v148
	v_and_b32_e32 v155, 2, v156
	v_mov_b32_e32 v121, v1
	flat_store_byte v[126:127], v158 offset:128
	v_mov_b32_e32 v158, v1
	v_cvt_pk_fp8_f32 v158, v120, v120
	v_or_b32_e32 v120, 0xc0, v157
	v_mul_f32_e32 v114, v114, v148
	v_mov_b32_e32 v157, v1
	v_lshl_add_u64 v[126:127], v[146:147], 0, v[120:121]
	v_cvt_pk_fp8_f32 v157, v114, v114
	v_bitop3_b32 v114, v155, v154, 1 bitop3:0x36
	flat_store_byte v[126:127], v158
	v_lshlrev_b32_e32 v126, 4, v114
	v_mul_f32_e32 v114, v115, v148
	v_mov_b32_e32 v115, v1
	v_cvt_pk_fp8_f32 v115, v114, v114
	v_mov_b32_e32 v127, v1
	v_lshl_add_u64 v[158:159], v[146:147], 0, v[126:127]
	v_mul_f32_e32 v114, v116, v148
	flat_store_byte v[158:159], v115 offset:320
	v_mov_b32_e32 v115, v1
	v_cvt_pk_fp8_f32 v115, v114, v114
	v_mul_f32_e32 v114, v117, v148
	v_or_b32_e32 v116, 16, v151
	flat_store_byte v[158:159], v157 offset:256
	flat_store_byte v[158:159], v115 offset:384
	v_mov_b32_e32 v115, v1
	v_cvt_pk_fp8_f32 v115, v114, v114
	v_or_b32_e32 v114, v152, v116
	flat_store_byte v[158:159], v115 offset:448
	v_ashrrev_i32_e32 v115, 31, v114
	v_lshl_add_u64 v[158:159], v[114:115], 2, s[38:39]
	v_mov_b32_e32 v158, v1
	v_mov_b32_e32 v159, v1
	v_fmamk_f32 v115, v167, 0x3c000000, v236
	v_rsq_f32_e32 v148, v115
	s_nop 0
	v_pk_mul_f32 v[110:111], v[110:111], v[148:149] op_sel_hi:[1,0]
	v_pk_mul_f32 v[106:107], v[106:107], v[148:149] op_sel_hi:[1,0]
	v_cvt_pk_fp8_f32 v158, v110, v111
	v_cvt_pk_fp8_f32 v159, v106, v107
	v_pk_mul_f32 v[112:113], v[112:113], v[148:149] op_sel_hi:[1,0]
	v_pk_mul_f32 v[108:109], v[108:109], v[148:149] op_sel_hi:[1,0]
	v_cvt_pk_fp8_f32 v158, v112, v113 op_sel:[0,0,1]
	v_cvt_pk_fp8_f32 v159, v108, v109 op_sel:[0,0,1]
	v_mad_i64_i32 v[106:107], s[18:19], v114, s13, v[122:123]
	v_lshl_add_u64 v[106:107], v[106:107], 0, s[0:1]
	v_lshl_add_u64 v[106:107], v[106:107], 0, v[0:1]
	v_mul_f32_e32 v102, v102, v148
	v_mov_b32_e32 v112, v1
	flat_store_dwordx2 v[106:107], v[158:159]
	v_lshrrev_b32_e32 v106, 1, v116
	v_cvt_pk_fp8_f32 v112, v102, v102
	v_and_or_b32 v106, v106, 12, v153
	v_mov_b32_e32 v107, v1
	v_lshl_add_u64 v[108:109], v[144:145], 0, v[106:107]
	v_lshl_add_u64 v[110:111], v[108:109], 0, v[124:125]
	flat_store_byte v[110:111], v112
	v_mul_f32_e32 v102, v103, v148
	v_mov_b32_e32 v112, v1
	v_cvt_pk_fp8_f32 v112, v102, v102
	v_lshl_add_u64 v[102:103], v[108:109], 0, v[118:119]
	v_mul_f32_e32 v98, v98, v148
	flat_store_byte v[102:103], v112
	v_mul_f32_e32 v102, v104, v148
	v_mov_b32_e32 v103, v1
	v_cvt_pk_fp8_f32 v103, v102, v102
	v_mul_f32_e32 v102, v105, v148
	v_mov_b32_e32 v104, v1
; __device__ __forceinline__ unsigned pk4_fp8(float a, float b, float c, float d) { int w = 0; w = __builtin_amdgcn_cvt_pk_fp8_f32(a, b, w, false); w = __builtin_amdgcn_cvt_pk_fp8_f32(c, d, w, true); return (unsigned)w; }
; __device__ __forceinline__ unsigned char one_fp8(float a) { return (unsigned char)(__builtin_amdgcn_cvt_pk_fp8_f32(a, a, 0, false) & 0xFF); }
;     __device__ __forceinline__ void operator()(const AccT& acc, const Unit& u, int wr, int wc, int fr, int fq) const {
;     ...
;                 const int row = EPI_ROW(u, ai, m);
;                 const float r = __builtin_amdgcn_rsqf(ssq_kv[row] * (1.0f / 128.0f) + RMS_EPS);
;                 const int c = wc * 32 + 8 * fq;
;                 const f32x4 k0 = acc[ai][0][m][0] * r, k1 = acc[ai][0][m][1] * r;
;                 u32x2 w; w.x = pk4_fp8(k0[0], k0[1], k0[2], k0[3]); w.y = pk4_fp8(k1[0], k1[1], k1[2], k1[3]);
;                 *(u32x2*)(Kb + (size_t)row * LDK + 192 * u.pn + c) = w;
;                 const int tile = row >> 6, k = row & 63, a = k >> 5, cc = k & 31, pos = 32 * ((cc >> 2) & 1) + 16 * a + (cc & 3) + 4 * (cc >> 3);
;                 unsigned char* vt = VT + ((size_t)(u.pn * (T / 64) + tile) * 128 + c) * 64 + (pos & 15);
; #pragma unroll
;                 for (int e = 0; e < 8; ++e) { const float v = (e < 4 ? acc[ai][1][m][0][e & 3] : acc[ai][1][m][1][e & 3]) * r;
;                     vt[e * 64 + ((((pos >> 4) ^ (((c + e) >> 2) & 3)) & 3) << 4)] = one_fp8(v); }
	v_cvt_pk_fp8_f32 v104, v102, v102
	flat_store_byte v[110:111], v103 offset:128
	v_lshl_add_u64 v[102:103], v[108:109], 0, v[120:121]
	flat_store_byte v[102:103], v104
	v_mov_b32_e32 v104, v1
	v_cvt_pk_fp8_f32 v104, v98, v98
	v_mul_f32_e32 v98, v99, v148
	v_mov_b32_e32 v99, v1
	v_cvt_pk_fp8_f32 v99, v98, v98
	v_lshl_add_u64 v[102:103], v[108:109], 0, v[126:127]
	v_mul_f32_e32 v98, v100, v148
	flat_store_byte v[102:103], v104 offset:256
	flat_store_byte v[102:103], v99 offset:320
	v_mov_b32_e32 v99, v1
	v_cvt_pk_fp8_f32 v99, v98, v98
	v_mul_f32_e32 v98, v101, v148
	flat_store_byte v[102:103], v99 offset:384
	v_mov_b32_e32 v99, v1
	v_cvt_pk_fp8_f32 v99, v98, v98
	flat_store_byte v[102:103], v99 offset:448
	v_or_b32_e32 v99, 32, v151
	v_or_b32_e32 v100, v152, v99
	v_ashrrev_i32_e32 v101, 31, v100
	v_lshl_add_u64 v[102:103], v[100:101], 2, s[38:39]
	v_mov_b32_e32 v102, v1
	v_mov_b32_e32 v103, v1
	v_fmamk_f32 v98, v168, 0x3c000000, v236
	v_rsq_f32_e32 v98, v98
	s_nop 0
	v_pk_mul_f32 v[94:95], v[94:95], v[98:99] op_sel_hi:[1,0]
	v_pk_mul_f32 v[90:91], v[90:91], v[98:99] op_sel_hi:[1,0]
	v_cvt_pk_fp8_f32 v102, v94, v95
	v_cvt_pk_fp8_f32 v103, v90, v91
	v_pk_mul_f32 v[96:97], v[96:97], v[98:99] op_sel_hi:[1,0]
	v_pk_mul_f32 v[92:93], v[92:93], v[98:99] op_sel_hi:[1,0]
	v_cvt_pk_fp8_f32 v102, v96, v97 op_sel:[0,0,1]
	v_cvt_pk_fp8_f32 v103, v92, v93 op_sel:[0,0,1]
	v_mad_i64_i32 v[90:91], s[18:19], v100, s13, v[122:123]
	v_lshl_add_u64 v[90:91], v[90:91], 0, s[0:1]
	v_lshl_add_u64 v[90:91], v[90:91], 0, v[0:1]
	flat_store_dwordx2 v[90:91], v[102:103]
	v_or_b32_e32 v90, 1, v154
	v_mul_f32_e32 v86, v86, v98
	v_mov_b32_e32 v94, v1
	v_cvt_pk_fp8_f32 v94, v86, v86
	v_bitop3_b32 v86, v156, v90, 2 bitop3:0x6c
	v_lshlrev_b32_e32 v90, 4, v86
	v_mul_f32_e32 v86, v87, v98
	v_mov_b32_e32 v96, v1
	v_cvt_pk_fp8_f32 v96, v86, v86
	v_bitop3_b32 v86, v156, v154, 1 bitop3:0x1e
	v_mov_b32_e32 v91, v1
	v_lshlrev_b32_e32 v97, 4, v86
	v_lshl_add_u64 v[92:93], v[146:147], 0, v[90:91]
	v_or_b32_e32 v86, 64, v97
	v_mov_b32_e32 v87, v1
	flat_store_byte v[92:93], v94
	v_lshl_add_u64 v[94:95], v[146:147], 0, v[86:87]
	flat_store_byte v[94:95], v96
	v_mul_f32_e32 v88, v88, v98
	v_mov_b32_e32 v94, v1
	v_cvt_pk_fp8_f32 v94, v88, v88
	v_mul_f32_e32 v88, v89, v98
	v_mov_b32_e32 v89, v1
	v_mul_f32_e32 v82, v82, v98
	flat_store_byte v[92:93], v94 offset:128
	v_mov_b32_e32 v94, v1
	v_cvt_pk_fp8_f32 v94, v88, v88
	v_or_b32_e32 v88, 0xc0, v97
	v_mov_b32_e32 v96, v1
	v_lshl_add_u64 v[92:93], v[146:147], 0, v[88:89]
	v_cvt_pk_fp8_f32 v96, v82, v82
	v_bitop3_b32 v82, v155, v154, 1 bitop3:0x14
	flat_store_byte v[92:93], v94
	v_lshlrev_b32_e32 v92, 4, v82
	v_mul_f32_e32 v82, v83, v98
	v_mov_b32_e32 v83, v1
	v_cvt_pk_fp8_f32 v83, v82, v82
	v_mov_b32_e32 v93, v1
	v_lshl_add_u64 v[94:95], v[146:147], 0, v[92:93]
	v_mul_f32_e32 v82, v84, v98
	flat_store_byte v[94:95], v83 offset:320
	v_mov_b32_e32 v83, v1
	v_cvt_pk_fp8_f32 v83, v82, v82
	v_mul_f32_e32 v82, v85, v98
	flat_store_byte v[94:95], v96 offset:256
	v_mov_b32_e32 v96, v1
	flat_store_byte v[94:95], v83 offset:384
	v_mov_b32_e32 v83, v1
	v_cvt_pk_fp8_f32 v83, v82, v82
	v_or_b32_e32 v82, 48, v151
	v_or_b32_e32 v84, v152, v82
	v_ashrrev_i32_e32 v85, 31, v84
	flat_store_byte v[94:95], v83 offset:448
	v_lshl_add_u64 v[94:95], v[84:85], 2, s[38:39]
	v_mov_b32_e32 v97, v1
	v_fmamk_f32 v83, v169, 0x3c000000, v236
	v_rsq_f32_e32 v94, v83
	s_nop 0
	v_pk_mul_f32 v[78:79], v[78:79], v[94:95] op_sel_hi:[1,0]
	v_pk_mul_f32 v[74:75], v[74:75], v[94:95] op_sel_hi:[1,0]
	v_cvt_pk_fp8_f32 v96, v78, v79
	v_cvt_pk_fp8_f32 v97, v74, v75
	v_pk_mul_f32 v[80:81], v[80:81], v[94:95] op_sel_hi:[1,0]
	v_pk_mul_f32 v[76:77], v[76:77], v[94:95] op_sel_hi:[1,0]
	v_cvt_pk_fp8_f32 v96, v80, v81 op_sel:[0,0,1]
	v_cvt_pk_fp8_f32 v97, v76, v77 op_sel:[0,0,1]
	v_mad_i64_i32 v[74:75], s[18:19], v84, s13, v[122:123]
	v_lshl_add_u64 v[74:75], v[74:75], 0, s[0:1]
	v_lshl_add_u64 v[74:75], v[74:75], 0, v[0:1]
	v_mul_f32_e32 v70, v70, v94
	v_mov_b32_e32 v80, v1
	flat_store_dwordx2 v[74:75], v[96:97]
	v_lshrrev_b32_e32 v74, 1, v82
	v_cvt_pk_fp8_f32 v80, v70, v70
	v_and_or_b32 v74, v74, 12, v153
	v_mov_b32_e32 v75, v1
	v_lshl_add_u64 v[76:77], v[144:145], 0, v[74:75]
	v_lshl_add_u64 v[78:79], v[76:77], 0, v[90:91]
	flat_store_byte v[78:79], v80
	v_mul_f32_e32 v70, v71, v94
	v_mov_b32_e32 v80, v1
	v_cvt_pk_fp8_f32 v80, v70, v70
	v_lshl_add_u64 v[70:71], v[76:77], 0, v[86:87]
	v_mul_f32_e32 v66, v66, v94
	flat_store_byte v[70:71], v80
	v_mul_f32_e32 v70, v72, v94
	v_mov_b32_e32 v71, v1
	v_cvt_pk_fp8_f32 v71, v70, v70
	v_mul_f32_e32 v70, v73, v94
	v_mov_b32_e32 v72, v1
	v_cvt_pk_fp8_f32 v72, v70, v70
	flat_store_byte v[78:79], v71 offset:128
	v_lshl_add_u64 v[70:71], v[76:77], 0, v[88:89]
	flat_store_byte v[70:71], v72
	v_mov_b32_e32 v72, v1
	v_cvt_pk_fp8_f32 v72, v66, v66
	v_mul_f32_e32 v66, v67, v94
	v_mov_b32_e32 v67, v1
	v_cvt_pk_fp8_f32 v67, v66, v66
	v_lshl_add_u64 v[70:71], v[76:77], 0, v[92:93]
	v_mul_f32_e32 v66, v68, v94
	v_add_u32_e32 v68, 0x80, v152
	flat_store_byte v[70:71], v67 offset:320
	v_mov_b32_e32 v67, v1
	v_cvt_pk_fp8_f32 v67, v66, v66
	v_mul_f32_e32 v66, v69, v94
	flat_store_byte v[70:71], v72 offset:256
	v_mov_b32_e32 v76, v1
	flat_store_byte v[70:71], v67 offset:384
	v_mov_b32_e32 v67, v1
	v_cvt_pk_fp8_f32 v67, v66, v66
	v_mov_b32_e32 v77, v1
	v_ashrrev_i32_e32 v66, 6, v68
	v_add_u32_e32 v66, s2, v66
	flat_store_byte v[70:71], v67 offset:448
	v_or_b32_e32 v70, v68, v151
	v_ashrrev_i32_e32 v71, 31, v70
	v_lshl_add_u64 v[72:73], v[70:71], 2, s[38:39]
	v_ashrrev_i32_e32 v67, 31, v66
	v_lshlrev_b64 v[66:67], 13, v[66:67]
	v_fmamk_f32 v69, v170, 0x3c000000, v236
; __device__ __forceinline__ unsigned pk4_fp8(float a, float b, float c, float d) { int w = 0; w = __builtin_amdgcn_cvt_pk_fp8_f32(a, b, w, false); w = __builtin_amdgcn_cvt_pk_fp8_f32(c, d, w, true); return (unsigned)w; }
; __device__ __forceinline__ unsigned char one_fp8(float a) { return (unsigned char)(__builtin_amdgcn_cvt_pk_fp8_f32(a, a, 0, false) & 0xFF); }
;     __device__ __forceinline__ void operator()(const AccT& acc, const Unit& u, int wr, int wc, int fr, int fq) const {
;     ...
;                 const int row = EPI_ROW(u, ai, m);
;                 const float r = __builtin_amdgcn_rsqf(ssq_kv[row] * (1.0f / 128.0f) + RMS_EPS);
;                 const int c = wc * 32 + 8 * fq;
;                 const f32x4 k0 = acc[ai][0][m][0] * r, k1 = acc[ai][0][m][1] * r;
;                 u32x2 w; w.x = pk4_fp8(k0[0], k0[1], k0[2], k0[3]); w.y = pk4_fp8(k1[0], k1[1], k1[2], k1[3]);
;                 *(u32x2*)(Kb + (size_t)row * LDK + 192 * u.pn + c) = w;
;                 const int tile = row >> 6, k = row & 63, a = k >> 5, cc = k & 31, pos = 32 * ((cc >> 2) & 1) + 16 * a + (cc & 3) + 4 * (cc >> 3);
;                 unsigned char* vt = VT + ((size_t)(u.pn * (T / 64) + tile) * 128 + c) * 64 + (pos & 15);
; #pragma unroll
;                 for (int e = 0; e < 8; ++e) { const float v = (e < 4 ? acc[ai][1][m][0][e & 3] : acc[ai][1][m][1][e & 3]) * r;
;                     vt[e * 64 + ((((pos >> 4) ^ (((c + e) >> 2) & 3)) & 3) << 4)] = one_fp8(v); }
	v_rsq_f32_e32 v72, v69
	s_nop 0
	v_pk_mul_f32 v[62:63], v[62:63], v[72:73] op_sel_hi:[1,0]
	v_pk_mul_f32 v[58:59], v[58:59], v[72:73] op_sel_hi:[1,0]
	v_cvt_pk_fp8_f32 v76, v62, v63
	v_cvt_pk_fp8_f32 v77, v58, v59
	v_pk_mul_f32 v[64:65], v[64:65], v[72:73] op_sel_hi:[1,0]
	v_pk_mul_f32 v[60:61], v[60:61], v[72:73] op_sel_hi:[1,0]
	v_cvt_pk_fp8_f32 v76, v64, v65 op_sel:[0,0,1]
	v_cvt_pk_fp8_f32 v77, v60, v61 op_sel:[0,0,1]
	v_mad_i64_i32 v[58:59], s[2:3], v70, s13, v[122:123]
	v_lshl_add_u64 v[58:59], v[58:59], 0, s[0:1]
	v_lshl_add_u64 v[58:59], v[58:59], 0, v[0:1]
	v_mul_f32_e32 v54, v54, v72
	v_mov_b32_e32 v64, v1
	flat_store_dwordx2 v[58:59], v[76:77]
	v_lshl_add_u64 v[58:59], s[20:21], 0, v[66:67]
	v_cvt_pk_fp8_f32 v64, v54, v54
	v_lshl_add_u64 v[58:59], v[58:59], 0, v[142:143]
	v_lshl_add_u64 v[60:61], v[58:59], 0, v[128:129]
	v_lshl_add_u64 v[62:63], v[60:61], 0, v[124:125]
	flat_store_byte v[62:63], v64
	v_mul_f32_e32 v54, v55, v72
	v_mov_b32_e32 v64, v1
	v_cvt_pk_fp8_f32 v64, v54, v54
	v_lshl_add_u64 v[54:55], v[60:61], 0, v[118:119]
	v_mul_f32_e32 v50, v50, v72
	flat_store_byte v[54:55], v64
	v_mul_f32_e32 v54, v56, v72
	v_mov_b32_e32 v55, v1
	v_cvt_pk_fp8_f32 v55, v54, v54
	v_mul_f32_e32 v54, v57, v72
	v_mov_b32_e32 v56, v1
	v_cvt_pk_fp8_f32 v56, v54, v54
	flat_store_byte v[62:63], v55 offset:128
	v_lshl_add_u64 v[54:55], v[60:61], 0, v[120:121]
	flat_store_byte v[54:55], v56
	v_mov_b32_e32 v56, v1
	v_cvt_pk_fp8_f32 v56, v50, v50
	v_mul_f32_e32 v50, v51, v72
	v_mov_b32_e32 v51, v1
	v_cvt_pk_fp8_f32 v51, v50, v50
	v_lshl_add_u64 v[54:55], v[60:61], 0, v[126:127]
	v_mul_f32_e32 v50, v52, v72
	flat_store_byte v[54:55], v56 offset:256
	flat_store_byte v[54:55], v51 offset:320
	v_mov_b32_e32 v51, v1
	v_cvt_pk_fp8_f32 v51, v50, v50
	v_mul_f32_e32 v50, v53, v72
	flat_store_byte v[54:55], v51 offset:384
	v_mov_b32_e32 v51, v1
	v_cvt_pk_fp8_f32 v51, v50, v50
	v_or_b32_e32 v50, v68, v116
	flat_store_byte v[54:55], v51 offset:448
	v_ashrrev_i32_e32 v51, 31, v50
	v_lshl_add_u64 v[52:53], v[50:51], 2, s[38:39]
	v_mov_b32_e32 v54, v1
	v_mov_b32_e32 v55, v1
	v_fmamk_f32 v51, v171, 0x3c000000, v236
	v_rsq_f32_e32 v52, v51
	s_nop 0
	v_pk_mul_f32 v[46:47], v[46:47], v[52:53] op_sel_hi:[1,0]
	v_pk_mul_f32 v[42:43], v[42:43], v[52:53] op_sel_hi:[1,0]
	v_cvt_pk_fp8_f32 v54, v46, v47
	v_cvt_pk_fp8_f32 v55, v42, v43
	v_pk_mul_f32 v[48:49], v[48:49], v[52:53] op_sel_hi:[1,0]
	v_pk_mul_f32 v[44:45], v[44:45], v[52:53] op_sel_hi:[1,0]
	v_cvt_pk_fp8_f32 v54, v48, v49 op_sel:[0,0,1]
	v_cvt_pk_fp8_f32 v55, v44, v45 op_sel:[0,0,1]
	v_mad_i64_i32 v[42:43], s[2:3], v50, s13, v[122:123]
	v_mul_f32_e32 v38, v38, v52
	v_mov_b32_e32 v46, v1
	v_lshl_add_u64 v[42:43], v[42:43], 0, s[0:1]
	v_cvt_pk_fp8_f32 v46, v38, v38
	v_lshl_add_u64 v[42:43], v[42:43], 0, v[0:1]
	flat_store_dwordx2 v[42:43], v[54:55]
	v_lshl_add_u64 v[42:43], v[58:59], 0, v[106:107]
	v_lshl_add_u64 v[44:45], v[42:43], 0, v[124:125]
	flat_store_byte v[44:45], v46
	v_mul_f32_e32 v38, v39, v52
	v_mov_b32_e32 v46, v1
	v_cvt_pk_fp8_f32 v46, v38, v38
	v_lshl_add_u64 v[38:39], v[42:43], 0, v[118:119]
	v_mul_f32_e32 v34, v34, v52
	flat_store_byte v[38:39], v46
	v_mul_f32_e32 v38, v40, v52
	v_mov_b32_e32 v39, v1
	v_cvt_pk_fp8_f32 v39, v38, v38
	v_mul_f32_e32 v38, v41, v52
	v_mov_b32_e32 v40, v1
	v_cvt_pk_fp8_f32 v40, v38, v38
	flat_store_byte v[44:45], v39 offset:128
	v_lshl_add_u64 v[38:39], v[42:43], 0, v[120:121]
	flat_store_byte v[38:39], v40
	v_mov_b32_e32 v40, v1
	v_cvt_pk_fp8_f32 v40, v34, v34
	v_mul_f32_e32 v34, v35, v52
	v_mov_b32_e32 v35, v1
	v_cvt_pk_fp8_f32 v35, v34, v34
	v_lshl_add_u64 v[38:39], v[42:43], 0, v[126:127]
	v_mul_f32_e32 v34, v36, v52
	flat_store_byte v[38:39], v40 offset:256
	flat_store_byte v[38:39], v35 offset:320
	v_mov_b32_e32 v35, v1
	v_cvt_pk_fp8_f32 v35, v34, v34
	v_mul_f32_e32 v34, v37, v52
	flat_store_byte v[38:39], v35 offset:384
	v_mov_b32_e32 v35, v1
	v_cvt_pk_fp8_f32 v35, v34, v34
	v_or_b32_e32 v34, v68, v99
	flat_store_byte v[38:39], v35 offset:448
	v_ashrrev_i32_e32 v35, 31, v34
; __device__ __forceinline__ unsigned pk4_fp8(float a, float b, float c, float d) { int w = 0; w = __builtin_amdgcn_cvt_pk_fp8_f32(a, b, w, false); w = __builtin_amdgcn_cvt_pk_fp8_f32(c, d, w, true); return (unsigned)w; }
; __device__ __forceinline__ unsigned char one_fp8(float a) { return (unsigned char)(__builtin_amdgcn_cvt_pk_fp8_f32(a, a, 0, false) & 0xFF); }
;     __device__ __forceinline__ void operator()(const AccT& acc, const Unit& u, int wr, int wc, int fr, int fq) const {
;     ...
;                 const int row = EPI_ROW(u, ai, m);
;                 const float r = __builtin_amdgcn_rsqf(ssq_kv[row] * (1.0f / 128.0f) + RMS_EPS);
;                 const int c = wc * 32 + 8 * fq;
;                 const f32x4 k0 = acc[ai][0][m][0] * r, k1 = acc[ai][0][m][1] * r;
;                 u32x2 w; w.x = pk4_fp8(k0[0], k0[1], k0[2], k0[3]); w.y = pk4_fp8(k1[0], k1[1], k1[2], k1[3]);
;                 *(u32x2*)(Kb + (size_t)row * LDK + 192 * u.pn + c) = w;
;                 const int tile = row >> 6, k = row & 63, a = k >> 5, cc = k & 31, pos = 32 * ((cc >> 2) & 1) + 16 * a + (cc & 3) + 4 * (cc >> 3);
;                 unsigned char* vt = VT + ((size_t)(u.pn * (T / 64) + tile) * 128 + c) * 64 + (pos & 15);
; #pragma unroll
;                 for (int e = 0; e < 8; ++e) { const float v = (e < 4 ? acc[ai][1][m][0][e & 3] : acc[ai][1][m][1][e & 3]) * r;
;                     vt[e * 64 + ((((pos >> 4) ^ (((c + e) >> 2) & 3)) & 3) << 4)] = one_fp8(v); }
	v_lshl_add_u64 v[36:37], v[34:35], 2, s[38:39]
	v_mov_b32_e32 v38, v1
	v_mov_b32_e32 v39, v1
	v_fmamk_f32 v35, v172, 0x3c000000, v236
	v_rsq_f32_e32 v36, v35
	s_nop 0
	v_pk_mul_f32 v[30:31], v[30:31], v[36:37] op_sel_hi:[1,0]
	v_pk_mul_f32 v[26:27], v[26:27], v[36:37] op_sel_hi:[1,0]
	v_cvt_pk_fp8_f32 v38, v30, v31
	v_cvt_pk_fp8_f32 v39, v26, v27
	v_pk_mul_f32 v[32:33], v[32:33], v[36:37] op_sel_hi:[1,0]
	v_pk_mul_f32 v[28:29], v[28:29], v[36:37] op_sel_hi:[1,0]
	v_cvt_pk_fp8_f32 v38, v32, v33 op_sel:[0,0,1]
	v_cvt_pk_fp8_f32 v39, v28, v29 op_sel:[0,0,1]
	v_mul_f32_e32 v22, v22, v36
	v_mov_b32_e32 v28, v1
	v_mad_i64_i32 v[26:27], s[2:3], v34, s13, v[122:123]
	v_cvt_pk_fp8_f32 v28, v22, v22
	v_lshl_add_u64 v[26:27], v[26:27], 0, s[0:1]
	v_lshl_add_u64 v[26:27], v[26:27], 0, v[0:1]
	flat_store_dwordx2 v[26:27], v[38:39]
	v_lshl_add_u64 v[26:27], v[60:61], 0, v[90:91]
	flat_store_byte v[26:27], v28
	v_mul_f32_e32 v22, v23, v36
	v_mov_b32_e32 v28, v1
	v_cvt_pk_fp8_f32 v28, v22, v22
	v_lshl_add_u64 v[22:23], v[60:61], 0, v[86:87]
	v_mul_f32_e32 v18, v18, v36
	flat_store_byte v[22:23], v28
	v_mul_f32_e32 v22, v24, v36
	v_mov_b32_e32 v23, v1
	v_cvt_pk_fp8_f32 v23, v22, v22
	v_mul_f32_e32 v22, v25, v36
	v_mov_b32_e32 v24, v1
	v_cvt_pk_fp8_f32 v24, v22, v22
	flat_store_byte v[26:27], v23 offset:128
	v_lshl_add_u64 v[22:23], v[60:61], 0, v[88:89]
	flat_store_byte v[22:23], v24
	v_mov_b32_e32 v24, v1
	v_cvt_pk_fp8_f32 v24, v18, v18
	v_mul_f32_e32 v18, v19, v36
	v_mov_b32_e32 v19, v1
	v_cvt_pk_fp8_f32 v19, v18, v18
	v_lshl_add_u64 v[22:23], v[60:61], 0, v[92:93]
	v_mul_f32_e32 v18, v20, v36
	flat_store_byte v[22:23], v24 offset:256
	flat_store_byte v[22:23], v19 offset:320
	v_mov_b32_e32 v19, v1
	v_cvt_pk_fp8_f32 v19, v18, v18
	v_mul_f32_e32 v18, v21, v36
	flat_store_byte v[22:23], v19 offset:384
	v_mov_b32_e32 v19, v1
	v_cvt_pk_fp8_f32 v19, v18, v18
	v_or_b32_e32 v18, v68, v82
	flat_store_byte v[22:23], v19 offset:448
	v_ashrrev_i32_e32 v19, 31, v18
	v_lshl_add_u64 v[20:21], v[18:19], 2, s[38:39]
	v_mov_b32_e32 v22, v1
	v_mov_b32_e32 v23, v1
	v_fmamk_f32 v19, v173, 0x3c000000, v236
	v_rsq_f32_e32 v20, v19
	s_nop 0
	v_pk_mul_f32 v[14:15], v[14:15], v[20:21] op_sel_hi:[1,0]
	v_pk_mul_f32 v[10:11], v[10:11], v[20:21] op_sel_hi:[1,0]
	v_cvt_pk_fp8_f32 v22, v14, v15
	v_cvt_pk_fp8_f32 v23, v10, v11
	v_pk_mul_f32 v[16:17], v[16:17], v[20:21] op_sel_hi:[1,0]
	v_pk_mul_f32 v[12:13], v[12:13], v[20:21] op_sel_hi:[1,0]
	v_mad_i64_i32 v[10:11], s[2:3], v18, s13, v[122:123]
	v_cvt_pk_fp8_f32 v22, v16, v17 op_sel:[0,0,1]
	v_cvt_pk_fp8_f32 v23, v12, v13 op_sel:[0,0,1]
	v_lshl_add_u64 v[10:11], v[10:11], 0, s[0:1]
	v_lshl_add_u64 v[10:11], v[10:11], 0, v[0:1]
	v_mul_f32_e32 v0, v6, v20
	v_mov_b32_e32 v6, v1
	v_cvt_pk_fp8_f32 v6, v0, v0
	v_mul_f32_e32 v0, v7, v20
	v_mov_b32_e32 v14, v1
	v_cvt_pk_fp8_f32 v14, v0, v0
	flat_store_dwordx2 v[10:11], v[22:23]
	v_lshl_add_u64 v[10:11], v[58:59], 0, v[74:75]
	v_lshl_add_u64 v[12:13], v[10:11], 0, v[90:91]
	flat_store_byte v[12:13], v6
	v_lshl_add_u64 v[6:7], v[10:11], 0, v[86:87]
	flat_store_byte v[6:7], v14
	v_mul_f32_e32 v0, v8, v20
	v_mov_b32_e32 v6, v1
	v_cvt_pk_fp8_f32 v6, v0, v0
	v_mul_f32_e32 v0, v9, v20
	v_mov_b32_e32 v8, v1
	v_cvt_pk_fp8_f32 v8, v0, v0
	v_mul_f32_e32 v0, v2, v20
	v_mov_b32_e32 v2, v1
	v_cvt_pk_fp8_f32 v2, v0, v0
	flat_store_byte v[12:13], v6 offset:128
	v_lshl_add_u64 v[6:7], v[10:11], 0, v[88:89]
	flat_store_byte v[6:7], v8
	v_lshl_add_u64 v[6:7], v[10:11], 0, v[92:93]
	flat_store_byte v[6:7], v2 offset:256
	v_mul_f32_e32 v0, v3, v20
	v_mov_b32_e32 v2, v1
	v_cvt_pk_fp8_f32 v2, v0, v0
	v_mul_f32_e32 v0, v4, v20
	s_mov_b64 s[0:1], -1
	flat_store_byte v[6:7], v2 offset:320
	v_mov_b32_e32 v2, v1
	v_cvt_pk_fp8_f32 v2, v0, v0
	v_mul_f32_e32 v0, v5, v20
	flat_store_byte v[6:7], v2 offset:384
	v_mov_b32_e32 v2, v1
	v_cvt_pk_fp8_f32 v2, v0, v0
	flat_store_byte v[6:7], v2 offset:448
	s_cbranch_vccnz .LBB0_623
	s_andn2_b64 vcc, exec, s[6:7]
	s_cbranch_vccnz .LBB0_622
	s_barrier
	s_branch .LBB0_622

; __device__ __forceinline__ unsigned pk4_fp8(float a, float b, float c, float d) { int w = 0; w = __builtin_amdgcn_cvt_pk_fp8_f32(a, b, w, false); w = __builtin_amdgcn_cvt_pk_fp8_f32(c, d, w, true); return (unsigned)w; }
;     __device__ __forceinline__ void operator()(const AccT& acc, const Unit& u, int wr, int wc, int fr, int fq) const {
; #pragma unroll
;         for (int ai = 0; ai < 2; ++ai)
; #pragma unroll
;             for (int m = 0; m < 4; ++m) {
;                 const int row = EPI_ROW(u, ai, m);
;                 const float r = __builtin_amdgcn_rsqf(ssq_q[row] * (1.0f / 256.0f) + RMS_EPS);
;                 const int pos = posof(row);
; #pragma unroll
;                 for (int bj = 0; bj < 2; ++bj) {
;                     const int col = EPI_COL(u, bj), d = col % 192;
;                     f32x4 v0 = acc[ai][bj][m][0] * r, v1 = acc[ai][bj][m][1] * r;
;                     if (d >= 128) { const int j0 = (d - 128) >> 1;
;                         const f32x4 c4 = *(const f32x4*)(cosT + pos * 32 + j0), s4 = *(const f32x4*)(sinT + pos * 32 + j0);
;                         rope8(v0, v1, c4, s4); }
;                     u32x2 w; w.x = pk4_fp8(v0[0], v0[1], v0[2], v0[3]); w.y = pk4_fp8(v1[0], v1[1], v1[2], v1[3]);
;                     *(u32x2*)(Q + (size_t)row * LDQ + col) = w;
;                 }
;             }
;     }
.LBB0_663:
	v_mov_b32_e32 v0, v216
	s_nop 0
	v_ashrrev_i32_e32 v142, 2, v0
	v_and_b32_e32 v142, 0xffffffc0, v142
	v_lshl_add_u32 v142, s2, 8, v142
	v_and_or_b32 v144, v0, 15, v142
	v_lshrrev_b32_e32 v0, 1, v0
	v_ashrrev_i32_e32 v145, 31, v144
	v_and_b32_e32 v0, 0x78, v0
	v_lshl_add_u64 v[146:147], v[144:145], 2, s[0:1]
	v_lshl_or_b32 v142, s6, 8, v0
	global_load_dword v244, v[146:147], off
	global_load_dword v245, v[146:147], off offset:64
	global_load_dword v246, v[146:147], off offset:128
	global_load_dword v247, v[146:147], off offset:192
	global_load_dword v248, v[146:147], off offset:512
	global_load_dword v249, v[146:147], off offset:576
	global_load_dword v250, v[146:147], off offset:640
	global_load_dword v251, v[146:147], off offset:704
	v_cmp_gt_i32_e32 vcc, s63, v144
	s_movk_i32 s0, 0xc0
	s_waitcnt vmcnt(0) lgkmcnt(0)
	v_fmamk_f32 v0, v244, 0x3b800000, v236
	v_rsq_f32_e32 v148, v0
	v_lshlrev_b32_e32 v0, 5, v144
	v_and_b32_e32 v143, 0x1f9e0, v0
	v_cndmask_b32_e32 v156, v143, v0, vcc
	v_mul_hi_i32 v0, v142, s62
	v_lshrrev_b32_e32 v143, 31, v0
	v_lshrrev_b32_e32 v0, 5, v0
	v_add_u32_e32 v0, v0, v143
	v_mul_lo_u32 v0, v0, s0
	v_ashrrev_i32_e32 v157, 31, v156
	v_sub_u32_e32 v0, v142, v0
	v_pk_mul_f32 v[150:151], v[124:125], v[148:149] op_sel_hi:[1,0]
	v_cmp_lt_i32_e32 vcc, s49, v0
	v_add_u32_e32 v0, 0xffffff80, v0
	v_lshlrev_b64 v[124:125], 2, v[156:157]
	v_pk_mul_f32 v[152:153], v[128:129], v[148:149] op_sel_hi:[1,0]
	v_pk_mul_f32 v[128:129], v[126:127], v[148:149] op_sel_hi:[1,0]
	v_pk_mul_f32 v[126:127], v[122:123], v[148:149] op_sel_hi:[1,0]
	v_lshrrev_b32_e32 v0, 1, v0
	v_lshl_add_u64 v[122:123], s[40:41], 0, v[124:125]
	v_lshl_add_u64 v[124:125], s[42:43], 0, v[124:125]
	s_and_saveexec_b64 s[0:1], vcc
	s_cbranch_execz .LBB0_665
	v_lshlrev_b64 v[162:163], 2, v[0:1]
	v_lshl_add_u64 v[156:157], v[122:123], 0, v[162:163]
	v_lshl_add_u64 v[162:163], v[124:125], 0, v[162:163]
	global_load_dwordx4 v[156:159], v[156:157], off
	s_nop 0
	global_load_dwordx4 v[162:165], v[162:163], off
	s_waitcnt vmcnt(0) lgkmcnt(0)
	v_pk_mul_f32 v[168:169], v[128:129], v[156:157]
	v_pk_mul_f32 v[166:167], v[128:129], v[162:163] op_sel:[1,0] op_sel_hi:[0,0]
	v_pk_fma_f32 v[128:129], v[128:129], v[156:157], v[166:167] op_sel_hi:[1,0,1]
	v_mov_b32_e32 v162, v157
	v_mul_f32_e32 v128, v153, v163
	v_pk_fma_f32 v[170:171], v[152:153], v[162:163], v[128:129] op_sel_hi:[1,1,0] neg_lo:[0,0,1] neg_hi:[0,0,1]
	v_mov_b32_e32 v156, v163
	v_mul_f32_e32 v128, v153, v157
	v_pk_fma_f32 v[156:157], v[152:153], v[156:157], v[128:129] op_sel_hi:[1,1,0]
	v_pk_mul_f32 v[152:153], v[126:127], v[164:165] op_sel:[1,0] op_sel_hi:[0,0]
	v_pk_mul_f32 v[162:163], v[126:127], v[158:159]
	v_pk_fma_f32 v[126:127], v[126:127], v[158:159], v[152:153] op_sel_hi:[1,0,1]
	v_mov_b32_e32 v164, v159
	v_mul_f32_e32 v126, v151, v165
	v_pk_fma_f32 v[172:173], v[150:151], v[164:165], v[126:127] op_sel_hi:[1,1,0] neg_lo:[0,0,1] neg_hi:[0,0,1]
	v_mov_b32_e32 v158, v165
	v_mul_f32_e32 v126, v151, v159
	v_pk_fma_f32 v[158:159], v[150:151], v[158:159], v[126:127] op_sel_hi:[1,1,0]
	v_sub_f32_e32 v126, v162, v152
	v_sub_f32_e32 v128, v168, v166
	v_mov_b32_e32 v150, v172
	v_mov_b32_e32 v151, v158
	v_mov_b32_e32 v152, v170
	v_mov_b32_e32 v153, v156
.LBB0_665:
	s_or_b64 exec, exec, s[0:1]
	v_mov_b32_e32 v156, v1
	v_mov_b32_e32 v157, v1
	v_cvt_pk_fp8_f32 v156, v128, v129
	v_cvt_pk_fp8_f32 v157, v126, v127
	v_or_b32_e32 v128, 0x80, v142
	v_mov_b64_e32 v[126:127], s[34:35]
	s_movk_i32 s0, 0x300
	v_mul_hi_i32 v129, v128, s62
	v_mad_i64_i32 v[126:127], s[0:1], v144, s0, v[126:127]
	v_lshrrev_b32_e32 v145, 31, v129
	v_lshrrev_b32_e32 v129, 5, v129
	v_add_u32_e32 v129, v129, v145
	s_movk_i32 s0, 0xc0
	v_cvt_pk_fp8_f32 v156, v152, v153 op_sel:[0,0,1]
	v_cvt_pk_fp8_f32 v157, v150, v151 op_sel:[0,0,1]
	v_mul_lo_u32 v129, v129, s0
	v_mov_b32_e32 v149, v148
	v_sub_u32_e32 v145, v128, v129
	v_mov_b32_e32 v150, v148
	v_mov_b32_e32 v151, v148
	v_ashrrev_i32_e32 v143, 31, v142
	v_pk_mul_f32 v[128:129], v[120:121], v[150:151]
	v_pk_mul_f32 v[120:121], v[116:117], v[150:151]
	v_pk_mul_f32 v[116:117], v[114:115], v[148:149]
	v_add_u32_e32 v114, 0xffffff80, v145
	v_lshl_add_u64 v[126:127], v[126:127], 0, v[142:143]
	v_pk_mul_f32 v[118:119], v[118:119], v[148:149]
	v_cmp_lt_i32_e64 s[6:7], s49, v145
	v_lshrrev_b32_e32 v114, 1, v114
	flat_store_dwordx2 v[126:127], v[156:157]
	s_and_saveexec_b64 s[0:1], s[6:7]
	s_cbranch_execz .LBB0_667
	v_mov_b32_e32 v115, v1
	v_lshlrev_b64 v[152:153], 2, v[114:115]
	v_lshl_add_u64 v[122:123], v[122:123], 0, v[152:153]
	global_load_dwordx4 v[148:151], v[122:123], off
	v_lshl_add_u64 v[122:123], v[124:125], 0, v[152:153]
	global_load_dwordx4 v[122:125], v[122:123], off
	s_waitcnt vmcnt(0) lgkmcnt(0)
	v_pk_mul_f32 v[156:157], v[118:119], v[148:149]
	v_pk_mul_f32 v[152:153], v[118:119], v[122:123] op_sel:[1,0] op_sel_hi:[0,0]
	v_pk_fma_f32 v[118:119], v[118:119], v[148:149], v[152:153] op_sel_hi:[1,0,1]
	v_mov_b32_e32 v122, v149
	v_mul_f32_e32 v118, v129, v123
	v_pk_fma_f32 v[158:159], v[128:129], v[122:123], v[118:119] op_sel_hi:[1,1,0] neg_lo:[0,0,1] neg_hi:[0,0,1]
	v_mov_b32_e32 v148, v123
	v_mul_f32_e32 v118, v129, v149
	v_pk_fma_f32 v[122:123], v[128:129], v[148:149], v[118:119] op_sel_hi:[1,1,0]
	v_pk_mul_f32 v[128:129], v[116:117], v[124:125] op_sel:[1,0] op_sel_hi:[0,0]
	v_pk_mul_f32 v[148:149], v[116:117], v[150:151]
	v_pk_fma_f32 v[116:117], v[116:117], v[150:151], v[128:129] op_sel_hi:[1,0,1]
	v_mov_b32_e32 v124, v151
	v_mul_f32_e32 v116, v121, v125
	v_pk_fma_f32 v[162:163], v[120:121], v[124:125], v[116:117] op_sel_hi:[1,1,0] neg_lo:[0,0,1] neg_hi:[0,0,1]
	v_mov_b32_e32 v150, v125
	v_mul_f32_e32 v116, v121, v151
	v_pk_fma_f32 v[124:125], v[120:121], v[150:151], v[116:117] op_sel_hi:[1,1,0]
	v_sub_f32_e32 v116, v148, v128
	v_sub_f32_e32 v118, v156, v152
	v_mov_b32_e32 v120, v162
	v_mov_b32_e32 v121, v124
	v_mov_b32_e32 v128, v158
	v_mov_b32_e32 v129, v122
; __device__ __forceinline__ unsigned pk4_fp8(float a, float b, float c, float d) { int w = 0; w = __builtin_amdgcn_cvt_pk_fp8_f32(a, b, w, false); w = __builtin_amdgcn_cvt_pk_fp8_f32(c, d, w, true); return (unsigned)w; }
;     __device__ __forceinline__ void operator()(const AccT& acc, const Unit& u, int wr, int wc, int fr, int fq) const {
; #pragma unroll
;         for (int ai = 0; ai < 2; ++ai)
; #pragma unroll
;             for (int m = 0; m < 4; ++m) {
;                 const int row = EPI_ROW(u, ai, m);
;                 const float r = __builtin_amdgcn_rsqf(ssq_q[row] * (1.0f / 256.0f) + RMS_EPS);
;                 const int pos = posof(row);
; #pragma unroll
;                 for (int bj = 0; bj < 2; ++bj) {
;                     const int col = EPI_COL(u, bj), d = col % 192;
;                     f32x4 v0 = acc[ai][bj][m][0] * r, v1 = acc[ai][bj][m][1] * r;
;                     if (d >= 128) { const int j0 = (d - 128) >> 1;
;                         const f32x4 c4 = *(const f32x4*)(cosT + pos * 32 + j0), s4 = *(const f32x4*)(sinT + pos * 32 + j0);
;                         rope8(v0, v1, c4, s4); }
;                     u32x2 w; w.x = pk4_fp8(v0[0], v0[1], v0[2], v0[3]); w.y = pk4_fp8(v1[0], v1[1], v1[2], v1[3]);
;                     *(u32x2*)(Q + (size_t)row * LDQ + col) = w;
;                 }
;             }
;     }
.LBB0_667:
	s_or_b64 exec, exec, s[0:1]
	v_mov_b32_e32 v122, v1
	v_mov_b32_e32 v123, v1
	v_cvt_pk_fp8_f32 v122, v118, v119
	v_cvt_pk_fp8_f32 v123, v116, v117
	v_or_b32_e32 v115, 16, v144
	v_lshlrev_b32_e32 v116, 5, v115
	v_cvt_pk_fp8_f32 v122, v128, v129 op_sel:[0,0,1]
	v_cvt_pk_fp8_f32 v123, v120, v121 op_sel:[0,0,1]
	v_and_b32_e32 v118, 0x1fbe0, v116
	v_cmp_gt_i32_e64 s[0:1], s63, v115
	flat_store_dwordx2 v[126:127], v[122:123] offset:128
	v_cndmask_b32_e64 v116, v118, v116, s[0:1]
	v_fmamk_f32 v117, v245, 0x3b800000, v236
	v_rsq_f32_e32 v118, v117
	v_ashrrev_i32_e32 v117, 31, v116
	v_lshlrev_b64 v[122:123], 2, v[116:117]
	v_lshl_add_u64 v[116:117], s[40:41], 0, v[122:123]
	v_pk_mul_f32 v[120:121], v[112:113], v[118:119] op_sel_hi:[1,0]
	v_pk_mul_f32 v[110:111], v[110:111], v[118:119] op_sel_hi:[1,0]
	v_pk_mul_f32 v[112:113], v[108:109], v[118:119] op_sel_hi:[1,0]
	v_pk_mul_f32 v[108:109], v[106:107], v[118:119] op_sel_hi:[1,0]
	v_lshl_add_u64 v[106:107], s[42:43], 0, v[122:123]
	s_and_saveexec_b64 s[0:1], vcc
	s_cbranch_execz .LBB0_669
	v_lshlrev_b64 v[126:127], 2, v[0:1]
	v_lshl_add_u64 v[122:123], v[116:117], 0, v[126:127]
	v_lshl_add_u64 v[126:127], v[106:107], 0, v[126:127]
	global_load_dwordx4 v[122:125], v[122:123], off
	s_nop 0
	global_load_dwordx4 v[126:129], v[126:127], off
	s_waitcnt vmcnt(0) lgkmcnt(0)
	v_pk_mul_f32 v[150:151], v[110:111], v[122:123]
	v_pk_mul_f32 v[148:149], v[110:111], v[126:127] op_sel:[1,0] op_sel_hi:[0,0]
	v_pk_fma_f32 v[110:111], v[110:111], v[122:123], v[148:149] op_sel_hi:[1,0,1]
	v_mov_b32_e32 v126, v123
	v_mul_f32_e32 v110, v121, v127
	v_pk_fma_f32 v[152:153], v[120:121], v[126:127], v[110:111] op_sel_hi:[1,1,0] neg_lo:[0,0,1] neg_hi:[0,0,1]
	v_mov_b32_e32 v122, v127
	v_mul_f32_e32 v110, v121, v123
	v_pk_fma_f32 v[122:123], v[120:121], v[122:123], v[110:111] op_sel_hi:[1,1,0]
	v_pk_mul_f32 v[120:121], v[108:109], v[128:129] op_sel:[1,0] op_sel_hi:[0,0]
	v_pk_mul_f32 v[126:127], v[108:109], v[124:125]
	v_pk_fma_f32 v[108:109], v[108:109], v[124:125], v[120:121] op_sel_hi:[1,0,1]
	v_mov_b32_e32 v128, v125
	v_mul_f32_e32 v108, v113, v129
	v_pk_fma_f32 v[156:157], v[112:113], v[128:129], v[108:109] op_sel_hi:[1,1,0] neg_lo:[0,0,1] neg_hi:[0,0,1]
	v_mov_b32_e32 v124, v129
	v_mul_f32_e32 v108, v113, v125
	v_pk_fma_f32 v[124:125], v[112:113], v[124:125], v[108:109] op_sel_hi:[1,1,0]
	v_sub_f32_e32 v108, v126, v120
	v_sub_f32_e32 v110, v150, v148
	v_mov_b32_e32 v112, v156
	v_mov_b32_e32 v113, v124
	v_mov_b32_e32 v120, v152
	v_mov_b32_e32 v121, v122
.LBB0_669:
	s_or_b64 exec, exec, s[0:1]
	v_mov_b32_e32 v122, v1
	v_mov_b32_e32 v123, v1
	v_cvt_pk_fp8_f32 v122, v110, v111
	v_cvt_pk_fp8_f32 v123, v108, v109
	v_mov_b64_e32 v[108:109], s[34:35]
	s_movk_i32 s0, 0x300
	v_cvt_pk_fp8_f32 v122, v120, v121 op_sel:[0,0,1]
	v_cvt_pk_fp8_f32 v123, v112, v113 op_sel:[0,0,1]
	v_mov_b32_e32 v119, v118
	v_mad_i64_i32 v[108:109], s[0:1], v115, s0, v[108:109]
	v_mov_b32_e32 v110, v118
	v_mov_b32_e32 v111, v118
	v_lshl_add_u64 v[108:109], v[108:109], 0, v[142:143]
	v_pk_mul_f32 v[104:105], v[104:105], v[110:111]
	v_pk_mul_f32 v[102:103], v[102:103], v[118:119]
	v_pk_mul_f32 v[100:101], v[100:101], v[110:111]
	v_pk_mul_f32 v[98:99], v[98:99], v[118:119]
	flat_store_dwordx2 v[108:109], v[122:123]
	s_and_saveexec_b64 s[0:1], s[6:7]
	s_cbranch_execz .LBB0_671
	v_mov_b32_e32 v115, v1
	v_lshlrev_b64 v[118:119], 2, v[114:115]
	v_lshl_add_u64 v[110:111], v[116:117], 0, v[118:119]
	v_lshl_add_u64 v[106:107], v[106:107], 0, v[118:119]
	global_load_dwordx4 v[110:113], v[110:111], off
	s_nop 0
	global_load_dwordx4 v[116:119], v[106:107], off
	s_waitcnt vmcnt(0) lgkmcnt(0)
	v_pk_mul_f32 v[120:121], v[102:103], v[110:111]
	v_pk_mul_f32 v[106:107], v[102:103], v[116:117] op_sel:[1,0] op_sel_hi:[0,0]
	v_pk_fma_f32 v[102:103], v[102:103], v[110:111], v[106:107] op_sel_hi:[1,0,1]
	v_mov_b32_e32 v116, v111
	v_mul_f32_e32 v102, v105, v117
	v_pk_fma_f32 v[122:123], v[104:105], v[116:117], v[102:103] op_sel_hi:[1,1,0] neg_lo:[0,0,1] neg_hi:[0,0,1]
	v_mov_b32_e32 v110, v117
	v_mul_f32_e32 v102, v105, v111
	v_pk_fma_f32 v[110:111], v[104:105], v[110:111], v[102:103] op_sel_hi:[1,1,0]
	v_pk_mul_f32 v[104:105], v[98:99], v[118:119] op_sel:[1,0] op_sel_hi:[0,0]
	v_pk_mul_f32 v[116:117], v[98:99], v[112:113]
	v_pk_fma_f32 v[98:99], v[98:99], v[112:113], v[104:105] op_sel_hi:[1,0,1]
	v_mov_b32_e32 v118, v113
	v_mul_f32_e32 v98, v101, v119
	v_pk_fma_f32 v[124:125], v[100:101], v[118:119], v[98:99] op_sel_hi:[1,1,0] neg_lo:[0,0,1] neg_hi:[0,0,1]
	v_mov_b32_e32 v112, v119
	v_mul_f32_e32 v98, v101, v113
	v_pk_fma_f32 v[112:113], v[100:101], v[112:113], v[98:99] op_sel_hi:[1,1,0]
	v_sub_f32_e32 v98, v116, v104
	v_sub_f32_e32 v102, v120, v106
	v_mov_b32_e32 v100, v124
	v_mov_b32_e32 v101, v112
	v_mov_b32_e32 v104, v122
	v_mov_b32_e32 v105, v110
; __device__ __forceinline__ unsigned pk4_fp8(float a, float b, float c, float d) { int w = 0; w = __builtin_amdgcn_cvt_pk_fp8_f32(a, b, w, false); w = __builtin_amdgcn_cvt_pk_fp8_f32(c, d, w, true); return (unsigned)w; }
;     __device__ __forceinline__ void operator()(const AccT& acc, const Unit& u, int wr, int wc, int fr, int fq) const {
; #pragma unroll
;         for (int ai = 0; ai < 2; ++ai)
; #pragma unroll
;             for (int m = 0; m < 4; ++m) {
;                 const int row = EPI_ROW(u, ai, m);
;                 const float r = __builtin_amdgcn_rsqf(ssq_q[row] * (1.0f / 256.0f) + RMS_EPS);
;                 const int pos = posof(row);
; #pragma unroll
;                 for (int bj = 0; bj < 2; ++bj) {
;                     const int col = EPI_COL(u, bj), d = col % 192;
;                     f32x4 v0 = acc[ai][bj][m][0] * r, v1 = acc[ai][bj][m][1] * r;
;                     if (d >= 128) { const int j0 = (d - 128) >> 1;
;                         const f32x4 c4 = *(const f32x4*)(cosT + pos * 32 + j0), s4 = *(const f32x4*)(sinT + pos * 32 + j0);
;                         rope8(v0, v1, c4, s4); }
;                     u32x2 w; w.x = pk4_fp8(v0[0], v0[1], v0[2], v0[3]); w.y = pk4_fp8(v1[0], v1[1], v1[2], v1[3]);
;                     *(u32x2*)(Q + (size_t)row * LDQ + col) = w;
;                 }
;             }
;     }
.LBB0_671:
	s_or_b64 exec, exec, s[0:1]
	v_mov_b32_e32 v106, v1
	v_mov_b32_e32 v107, v1
	v_cvt_pk_fp8_f32 v106, v102, v103
	v_cvt_pk_fp8_f32 v107, v98, v99
	v_cvt_pk_fp8_f32 v106, v104, v105 op_sel:[0,0,1]
	v_cvt_pk_fp8_f32 v107, v100, v101 op_sel:[0,0,1]
	v_or_b32_e32 v104, 32, v144
	v_lshlrev_b32_e32 v98, 5, v104
	v_and_b32_e32 v100, 0x1fde0, v98
	flat_store_dwordx2 v[108:109], v[106:107] offset:128
	v_cmp_gt_i32_e64 s[0:1], s63, v104
	v_fmamk_f32 v99, v246, 0x3b800000, v236
	v_cndmask_b32_e64 v98, v100, v98, s[0:1]
	v_rsq_f32_e32 v100, v99
	v_ashrrev_i32_e32 v99, 31, v98
	v_lshlrev_b64 v[106:107], 2, v[98:99]
	v_lshl_add_u64 v[98:99], s[40:41], 0, v[106:107]
	v_pk_mul_f32 v[102:103], v[96:97], v[100:101] op_sel_hi:[1,0]
	v_pk_mul_f32 v[94:95], v[94:95], v[100:101] op_sel_hi:[1,0]
	v_pk_mul_f32 v[96:97], v[92:93], v[100:101] op_sel_hi:[1,0]
	v_pk_mul_f32 v[92:93], v[90:91], v[100:101] op_sel_hi:[1,0]
	v_lshl_add_u64 v[90:91], s[42:43], 0, v[106:107]
	s_and_saveexec_b64 s[0:1], vcc
	s_cbranch_execz .LBB0_673
	v_lshlrev_b64 v[110:111], 2, v[0:1]
	v_lshl_add_u64 v[106:107], v[98:99], 0, v[110:111]
	v_lshl_add_u64 v[110:111], v[90:91], 0, v[110:111]
	global_load_dwordx4 v[106:109], v[106:107], off
	s_nop 0
	global_load_dwordx4 v[110:113], v[110:111], off
	s_waitcnt vmcnt(0) lgkmcnt(0)
	v_pk_mul_f32 v[118:119], v[94:95], v[106:107]
	v_pk_mul_f32 v[116:117], v[94:95], v[110:111] op_sel:[1,0] op_sel_hi:[0,0]
	v_pk_fma_f32 v[94:95], v[94:95], v[106:107], v[116:117] op_sel_hi:[1,0,1]
	v_mov_b32_e32 v110, v107
	v_mul_f32_e32 v94, v103, v111
	v_pk_fma_f32 v[120:121], v[102:103], v[110:111], v[94:95] op_sel_hi:[1,1,0] neg_lo:[0,0,1] neg_hi:[0,0,1]
	v_mov_b32_e32 v106, v111
	v_mul_f32_e32 v94, v103, v107
	v_pk_fma_f32 v[106:107], v[102:103], v[106:107], v[94:95] op_sel_hi:[1,1,0]
	v_pk_mul_f32 v[102:103], v[92:93], v[112:113] op_sel:[1,0] op_sel_hi:[0,0]
	v_pk_mul_f32 v[110:111], v[92:93], v[108:109]
	v_pk_fma_f32 v[92:93], v[92:93], v[108:109], v[102:103] op_sel_hi:[1,0,1]
	v_mov_b32_e32 v112, v109
	v_mul_f32_e32 v92, v97, v113
	v_pk_fma_f32 v[122:123], v[96:97], v[112:113], v[92:93] op_sel_hi:[1,1,0] neg_lo:[0,0,1] neg_hi:[0,0,1]
	v_mov_b32_e32 v108, v113
	v_mul_f32_e32 v92, v97, v109
	v_pk_fma_f32 v[108:109], v[96:97], v[108:109], v[92:93] op_sel_hi:[1,1,0]
	v_sub_f32_e32 v92, v110, v102
	v_sub_f32_e32 v94, v118, v116
	v_mov_b32_e32 v96, v122
	v_mov_b32_e32 v97, v108
	v_mov_b32_e32 v102, v120
	v_mov_b32_e32 v103, v106
.LBB0_673:
	s_or_b64 exec, exec, s[0:1]
	v_mov_b32_e32 v106, v1
	v_mov_b32_e32 v107, v1
	v_cvt_pk_fp8_f32 v106, v94, v95
	v_cvt_pk_fp8_f32 v107, v92, v93
	v_mov_b64_e32 v[92:93], s[34:35]
	s_movk_i32 s0, 0x300
	v_cvt_pk_fp8_f32 v106, v102, v103 op_sel:[0,0,1]
	v_cvt_pk_fp8_f32 v107, v96, v97 op_sel:[0,0,1]
	v_mov_b32_e32 v101, v100
	v_mad_i64_i32 v[92:93], s[0:1], v104, s0, v[92:93]
	v_mov_b32_e32 v94, v100
	v_mov_b32_e32 v95, v100
	v_lshl_add_u64 v[92:93], v[92:93], 0, v[142:143]
	v_pk_mul_f32 v[88:89], v[88:89], v[94:95]
	v_pk_mul_f32 v[86:87], v[86:87], v[100:101]
	v_pk_mul_f32 v[84:85], v[84:85], v[94:95]
	v_pk_mul_f32 v[82:83], v[82:83], v[100:101]
	flat_store_dwordx2 v[92:93], v[106:107]
	s_and_saveexec_b64 s[0:1], s[6:7]
	s_cbranch_execz .LBB0_675
	v_mov_b32_e32 v115, v1
	v_lshlrev_b64 v[100:101], 2, v[114:115]
	v_lshl_add_u64 v[94:95], v[98:99], 0, v[100:101]
	v_lshl_add_u64 v[90:91], v[90:91], 0, v[100:101]
	global_load_dwordx4 v[94:97], v[94:95], off
	s_nop 0
	global_load_dwordx4 v[98:101], v[90:91], off
	s_waitcnt vmcnt(0) lgkmcnt(0)
	v_pk_mul_f32 v[102:103], v[86:87], v[94:95]
	v_pk_mul_f32 v[90:91], v[86:87], v[98:99] op_sel:[1,0] op_sel_hi:[0,0]
	v_pk_fma_f32 v[86:87], v[86:87], v[94:95], v[90:91] op_sel_hi:[1,0,1]
	v_mov_b32_e32 v98, v95
	v_mul_f32_e32 v86, v89, v99
	v_pk_fma_f32 v[104:105], v[88:89], v[98:99], v[86:87] op_sel_hi:[1,1,0] neg_lo:[0,0,1] neg_hi:[0,0,1]
	v_mov_b32_e32 v94, v99
	v_mul_f32_e32 v86, v89, v95
	v_pk_fma_f32 v[94:95], v[88:89], v[94:95], v[86:87] op_sel_hi:[1,1,0]
	v_pk_mul_f32 v[88:89], v[82:83], v[100:101] op_sel:[1,0] op_sel_hi:[0,0]
	v_pk_mul_f32 v[98:99], v[82:83], v[96:97]
	v_pk_fma_f32 v[82:83], v[82:83], v[96:97], v[88:89] op_sel_hi:[1,0,1]
	v_mov_b32_e32 v100, v97
	v_mul_f32_e32 v82, v85, v101
	v_pk_fma_f32 v[106:107], v[84:85], v[100:101], v[82:83] op_sel_hi:[1,1,0] neg_lo:[0,0,1] neg_hi:[0,0,1]
	v_mov_b32_e32 v96, v101
	v_mul_f32_e32 v82, v85, v97
	v_pk_fma_f32 v[96:97], v[84:85], v[96:97], v[82:83] op_sel_hi:[1,1,0]
	v_sub_f32_e32 v82, v98, v88
	v_sub_f32_e32 v86, v102, v90
	v_mov_b32_e32 v84, v106
	v_mov_b32_e32 v85, v96
	v_mov_b32_e32 v88, v104
	v_mov_b32_e32 v89, v94
; __device__ __forceinline__ unsigned pk4_fp8(float a, float b, float c, float d) { int w = 0; w = __builtin_amdgcn_cvt_pk_fp8_f32(a, b, w, false); w = __builtin_amdgcn_cvt_pk_fp8_f32(c, d, w, true); return (unsigned)w; }
;     __device__ __forceinline__ void operator()(const AccT& acc, const Unit& u, int wr, int wc, int fr, int fq) const {
; #pragma unroll
;         for (int ai = 0; ai < 2; ++ai)
; #pragma unroll
;             for (int m = 0; m < 4; ++m) {
;                 const int row = EPI_ROW(u, ai, m);
;                 const float r = __builtin_amdgcn_rsqf(ssq_q[row] * (1.0f / 256.0f) + RMS_EPS);
;                 const int pos = posof(row);
; #pragma unroll
;                 for (int bj = 0; bj < 2; ++bj) {
;                     const int col = EPI_COL(u, bj), d = col % 192;
;                     f32x4 v0 = acc[ai][bj][m][0] * r, v1 = acc[ai][bj][m][1] * r;
;                     if (d >= 128) { const int j0 = (d - 128) >> 1;
;                         const f32x4 c4 = *(const f32x4*)(cosT + pos * 32 + j0), s4 = *(const f32x4*)(sinT + pos * 32 + j0);
;                         rope8(v0, v1, c4, s4); }
;                     u32x2 w; w.x = pk4_fp8(v0[0], v0[1], v0[2], v0[3]); w.y = pk4_fp8(v1[0], v1[1], v1[2], v1[3]);
;                     *(u32x2*)(Q + (size_t)row * LDQ + col) = w;
;                 }
;             }
;     }
.LBB0_675:
	s_or_b64 exec, exec, s[0:1]
	v_mov_b32_e32 v90, v1
	v_mov_b32_e32 v91, v1
	v_cvt_pk_fp8_f32 v90, v86, v87
	v_cvt_pk_fp8_f32 v91, v82, v83
	v_cvt_pk_fp8_f32 v90, v88, v89 op_sel:[0,0,1]
	v_cvt_pk_fp8_f32 v91, v84, v85 op_sel:[0,0,1]
	v_or_b32_e32 v88, 48, v144
	v_lshlrev_b32_e32 v82, 5, v88
	v_and_b32_e32 v84, 0x1ffe0, v82
	flat_store_dwordx2 v[92:93], v[90:91] offset:128
	v_cmp_gt_i32_e64 s[0:1], s63, v88
	v_fmamk_f32 v83, v247, 0x3b800000, v236
	v_cndmask_b32_e64 v82, v84, v82, s[0:1]
	v_rsq_f32_e32 v84, v83
	v_ashrrev_i32_e32 v83, 31, v82
	v_lshlrev_b64 v[90:91], 2, v[82:83]
	v_lshl_add_u64 v[82:83], s[40:41], 0, v[90:91]
	v_pk_mul_f32 v[86:87], v[80:81], v[84:85] op_sel_hi:[1,0]
	v_pk_mul_f32 v[78:79], v[78:79], v[84:85] op_sel_hi:[1,0]
	v_pk_mul_f32 v[80:81], v[76:77], v[84:85] op_sel_hi:[1,0]
	v_pk_mul_f32 v[76:77], v[74:75], v[84:85] op_sel_hi:[1,0]
	v_lshl_add_u64 v[74:75], s[42:43], 0, v[90:91]
	s_and_saveexec_b64 s[0:1], vcc
	s_cbranch_execz .LBB0_677
	v_lshlrev_b64 v[94:95], 2, v[0:1]
	v_lshl_add_u64 v[90:91], v[82:83], 0, v[94:95]
	v_lshl_add_u64 v[94:95], v[74:75], 0, v[94:95]
	global_load_dwordx4 v[90:93], v[90:91], off
	s_nop 0
	global_load_dwordx4 v[94:97], v[94:95], off
	s_waitcnt vmcnt(0) lgkmcnt(0)
	v_pk_mul_f32 v[100:101], v[78:79], v[90:91]
	v_pk_mul_f32 v[98:99], v[78:79], v[94:95] op_sel:[1,0] op_sel_hi:[0,0]
	v_pk_fma_f32 v[78:79], v[78:79], v[90:91], v[98:99] op_sel_hi:[1,0,1]
	v_mov_b32_e32 v94, v91
	v_mul_f32_e32 v78, v87, v95
	v_pk_fma_f32 v[102:103], v[86:87], v[94:95], v[78:79] op_sel_hi:[1,1,0] neg_lo:[0,0,1] neg_hi:[0,0,1]
	v_mov_b32_e32 v90, v95
	v_mul_f32_e32 v78, v87, v91
	v_pk_fma_f32 v[90:91], v[86:87], v[90:91], v[78:79] op_sel_hi:[1,1,0]
	v_pk_mul_f32 v[86:87], v[76:77], v[96:97] op_sel:[1,0] op_sel_hi:[0,0]
	v_pk_mul_f32 v[94:95], v[76:77], v[92:93]
	v_pk_fma_f32 v[76:77], v[76:77], v[92:93], v[86:87] op_sel_hi:[1,0,1]
	v_mov_b32_e32 v96, v93
	v_mul_f32_e32 v76, v81, v97
	v_pk_fma_f32 v[104:105], v[80:81], v[96:97], v[76:77] op_sel_hi:[1,1,0] neg_lo:[0,0,1] neg_hi:[0,0,1]
	v_mov_b32_e32 v92, v97
	v_mul_f32_e32 v76, v81, v93
	v_pk_fma_f32 v[92:93], v[80:81], v[92:93], v[76:77] op_sel_hi:[1,1,0]
	v_sub_f32_e32 v76, v94, v86
	v_sub_f32_e32 v78, v100, v98
	v_mov_b32_e32 v80, v104
	v_mov_b32_e32 v81, v92
	v_mov_b32_e32 v86, v102
	v_mov_b32_e32 v87, v90
.LBB0_677:
	s_or_b64 exec, exec, s[0:1]
	v_mov_b32_e32 v90, v1
	v_mov_b32_e32 v91, v1
	v_cvt_pk_fp8_f32 v90, v78, v79
	v_cvt_pk_fp8_f32 v91, v76, v77
	v_mov_b64_e32 v[76:77], s[34:35]
	s_movk_i32 s0, 0x300
	v_cvt_pk_fp8_f32 v90, v86, v87 op_sel:[0,0,1]
	v_cvt_pk_fp8_f32 v91, v80, v81 op_sel:[0,0,1]
	v_mov_b32_e32 v85, v84
	v_mad_i64_i32 v[76:77], s[0:1], v88, s0, v[76:77]
	v_mov_b32_e32 v78, v84
	v_mov_b32_e32 v79, v84
	v_lshl_add_u64 v[76:77], v[76:77], 0, v[142:143]
	v_pk_mul_f32 v[72:73], v[72:73], v[78:79]
	v_pk_mul_f32 v[70:71], v[70:71], v[84:85]
	v_pk_mul_f32 v[68:69], v[68:69], v[78:79]
	v_pk_mul_f32 v[66:67], v[66:67], v[84:85]
	flat_store_dwordx2 v[76:77], v[90:91]
	s_and_saveexec_b64 s[0:1], s[6:7]
	s_cbranch_execz .LBB0_679
	v_mov_b32_e32 v115, v1
	v_lshlrev_b64 v[84:85], 2, v[114:115]
	v_lshl_add_u64 v[78:79], v[82:83], 0, v[84:85]
	v_lshl_add_u64 v[74:75], v[74:75], 0, v[84:85]
	global_load_dwordx4 v[78:81], v[78:79], off
	s_nop 0
	global_load_dwordx4 v[82:85], v[74:75], off
	s_waitcnt vmcnt(0) lgkmcnt(0)
	v_pk_mul_f32 v[86:87], v[70:71], v[78:79]
	v_pk_mul_f32 v[74:75], v[70:71], v[82:83] op_sel:[1,0] op_sel_hi:[0,0]
	v_pk_fma_f32 v[70:71], v[70:71], v[78:79], v[74:75] op_sel_hi:[1,0,1]
	v_mov_b32_e32 v82, v79
	v_mul_f32_e32 v70, v73, v83
	v_pk_fma_f32 v[88:89], v[72:73], v[82:83], v[70:71] op_sel_hi:[1,1,0] neg_lo:[0,0,1] neg_hi:[0,0,1]
	v_mov_b32_e32 v78, v83
	v_mul_f32_e32 v70, v73, v79
	v_pk_fma_f32 v[78:79], v[72:73], v[78:79], v[70:71] op_sel_hi:[1,1,0]
	v_pk_mul_f32 v[72:73], v[66:67], v[84:85] op_sel:[1,0] op_sel_hi:[0,0]
	v_pk_mul_f32 v[82:83], v[66:67], v[80:81]
	v_pk_fma_f32 v[66:67], v[66:67], v[80:81], v[72:73] op_sel_hi:[1,0,1]
	v_mov_b32_e32 v84, v81
	v_mul_f32_e32 v66, v69, v85
	v_pk_fma_f32 v[90:91], v[68:69], v[84:85], v[66:67] op_sel_hi:[1,1,0] neg_lo:[0,0,1] neg_hi:[0,0,1]
	v_mov_b32_e32 v80, v85
	v_mul_f32_e32 v66, v69, v81
	v_pk_fma_f32 v[80:81], v[68:69], v[80:81], v[66:67] op_sel_hi:[1,1,0]
	v_sub_f32_e32 v66, v82, v72
	v_sub_f32_e32 v70, v86, v74
	v_mov_b32_e32 v68, v90
	v_mov_b32_e32 v69, v80
	v_mov_b32_e32 v72, v88
	v_mov_b32_e32 v73, v78
.LBB0_679:
	s_or_b64 exec, exec, s[0:1]
	v_mov_b32_e32 v74, v1
	v_mov_b32_e32 v75, v1
	v_cvt_pk_fp8_f32 v74, v70, v71
	v_cvt_pk_fp8_f32 v75, v66, v67
	v_cvt_pk_fp8_f32 v74, v72, v73 op_sel:[0,0,1]
	v_cvt_pk_fp8_f32 v75, v68, v69 op_sel:[0,0,1]
	v_add_u32_e32 v72, 0x80, v144
	v_lshlrev_b32_e32 v66, 5, v72
	v_and_b32_e32 v68, 0x1f9e0, v66
	flat_store_dwordx2 v[76:77], v[74:75] offset:128
	v_cmp_gt_i32_e64 s[0:1], s63, v72
	v_fmamk_f32 v67, v248, 0x3b800000, v236
	v_cndmask_b32_e64 v66, v68, v66, s[0:1]
	v_rsq_f32_e32 v68, v67
	v_ashrrev_i32_e32 v67, 31, v66
	v_lshlrev_b64 v[74:75], 2, v[66:67]
	v_lshl_add_u64 v[66:67], s[40:41], 0, v[74:75]
	v_pk_mul_f32 v[70:71], v[64:65], v[68:69] op_sel_hi:[1,0]
	v_pk_mul_f32 v[62:63], v[62:63], v[68:69] op_sel_hi:[1,0]
	v_pk_mul_f32 v[64:65], v[60:61], v[68:69] op_sel_hi:[1,0]
	v_pk_mul_f32 v[60:61], v[58:59], v[68:69] op_sel_hi:[1,0]
	v_lshl_add_u64 v[58:59], s[42:43], 0, v[74:75]
	s_and_saveexec_b64 s[0:1], vcc
	s_cbranch_execz .LBB0_681
	v_lshlrev_b64 v[78:79], 2, v[0:1]
	v_lshl_add_u64 v[74:75], v[66:67], 0, v[78:79]
	v_lshl_add_u64 v[78:79], v[58:59], 0, v[78:79]
	global_load_dwordx4 v[74:77], v[74:75], off
	s_nop 0
	global_load_dwordx4 v[78:81], v[78:79], off
	s_waitcnt vmcnt(0) lgkmcnt(0)
	v_pk_mul_f32 v[84:85], v[62:63], v[74:75]
	v_pk_mul_f32 v[82:83], v[62:63], v[78:79] op_sel:[1,0] op_sel_hi:[0,0]
	v_pk_fma_f32 v[62:63], v[62:63], v[74:75], v[82:83] op_sel_hi:[1,0,1]
	v_mov_b32_e32 v78, v75
	v_mul_f32_e32 v62, v71, v79
	v_pk_fma_f32 v[86:87], v[70:71], v[78:79], v[62:63] op_sel_hi:[1,1,0] neg_lo:[0,0,1] neg_hi:[0,0,1]
	v_mov_b32_e32 v74, v79
	v_mul_f32_e32 v62, v71, v75
	v_pk_fma_f32 v[74:75], v[70:71], v[74:75], v[62:63] op_sel_hi:[1,1,0]
	v_pk_mul_f32 v[70:71], v[60:61], v[80:81] op_sel:[1,0] op_sel_hi:[0,0]
	v_pk_mul_f32 v[78:79], v[60:61], v[76:77]
	v_pk_fma_f32 v[60:61], v[60:61], v[76:77], v[70:71] op_sel_hi:[1,0,1]
	v_mov_b32_e32 v80, v77
	v_mul_f32_e32 v60, v65, v81
	v_pk_fma_f32 v[88:89], v[64:65], v[80:81], v[60:61] op_sel_hi:[1,1,0] neg_lo:[0,0,1] neg_hi:[0,0,1]
	v_mov_b32_e32 v76, v81
	v_mul_f32_e32 v60, v65, v77
	v_pk_fma_f32 v[76:77], v[64:65], v[76:77], v[60:61] op_sel_hi:[1,1,0]
	v_sub_f32_e32 v60, v78, v70
	v_sub_f32_e32 v62, v84, v82
	v_mov_b32_e32 v64, v88
	v_mov_b32_e32 v65, v76
	v_mov_b32_e32 v70, v86
	v_mov_b32_e32 v71, v74
; __device__ __forceinline__ unsigned pk4_fp8(float a, float b, float c, float d) { int w = 0; w = __builtin_amdgcn_cvt_pk_fp8_f32(a, b, w, false); w = __builtin_amdgcn_cvt_pk_fp8_f32(c, d, w, true); return (unsigned)w; }
;     __device__ __forceinline__ void operator()(const AccT& acc, const Unit& u, int wr, int wc, int fr, int fq) const {
; #pragma unroll
;         for (int ai = 0; ai < 2; ++ai)
; #pragma unroll
;             for (int m = 0; m < 4; ++m) {
;                 const int row = EPI_ROW(u, ai, m);
;                 const float r = __builtin_amdgcn_rsqf(ssq_q[row] * (1.0f / 256.0f) + RMS_EPS);
;                 const int pos = posof(row);
; #pragma unroll
;                 for (int bj = 0; bj < 2; ++bj) {
;                     const int col = EPI_COL(u, bj), d = col % 192;
;                     f32x4 v0 = acc[ai][bj][m][0] * r, v1 = acc[ai][bj][m][1] * r;
;                     if (d >= 128) { const int j0 = (d - 128) >> 1;
;                         const f32x4 c4 = *(const f32x4*)(cosT + pos * 32 + j0), s4 = *(const f32x4*)(sinT + pos * 32 + j0);
;                         rope8(v0, v1, c4, s4); }
;                     u32x2 w; w.x = pk4_fp8(v0[0], v0[1], v0[2], v0[3]); w.y = pk4_fp8(v1[0], v1[1], v1[2], v1[3]);
;                     *(u32x2*)(Q + (size_t)row * LDQ + col) = w;
;                 }
;             }
;     }
.LBB0_681:
	s_or_b64 exec, exec, s[0:1]
	v_mov_b32_e32 v74, v1
	v_mov_b32_e32 v75, v1
	v_cvt_pk_fp8_f32 v74, v62, v63
	v_cvt_pk_fp8_f32 v75, v60, v61
	v_mov_b64_e32 v[60:61], s[34:35]
	s_movk_i32 s0, 0x300
	v_cvt_pk_fp8_f32 v74, v70, v71 op_sel:[0,0,1]
	v_cvt_pk_fp8_f32 v75, v64, v65 op_sel:[0,0,1]
	v_mov_b32_e32 v69, v68
	v_mad_i64_i32 v[60:61], s[0:1], v72, s0, v[60:61]
	v_mov_b32_e32 v62, v68
	v_mov_b32_e32 v63, v68
	v_lshl_add_u64 v[60:61], v[60:61], 0, v[142:143]
	v_pk_mul_f32 v[56:57], v[56:57], v[62:63]
	v_pk_mul_f32 v[54:55], v[54:55], v[68:69]
	v_pk_mul_f32 v[52:53], v[52:53], v[62:63]
	v_pk_mul_f32 v[50:51], v[50:51], v[68:69]
	flat_store_dwordx2 v[60:61], v[74:75]
	s_and_saveexec_b64 s[0:1], s[6:7]
	s_cbranch_execz .LBB0_683
	v_mov_b32_e32 v115, v1
	v_lshlrev_b64 v[68:69], 2, v[114:115]
	v_lshl_add_u64 v[62:63], v[66:67], 0, v[68:69]
	v_lshl_add_u64 v[58:59], v[58:59], 0, v[68:69]
	global_load_dwordx4 v[62:65], v[62:63], off
	s_nop 0
	global_load_dwordx4 v[66:69], v[58:59], off
	s_waitcnt vmcnt(0) lgkmcnt(0)
	v_pk_mul_f32 v[70:71], v[54:55], v[62:63]
	v_pk_mul_f32 v[58:59], v[54:55], v[66:67] op_sel:[1,0] op_sel_hi:[0,0]
	v_pk_fma_f32 v[54:55], v[54:55], v[62:63], v[58:59] op_sel_hi:[1,0,1]
	v_mov_b32_e32 v66, v63
	v_mul_f32_e32 v54, v57, v67
	v_pk_fma_f32 v[72:73], v[56:57], v[66:67], v[54:55] op_sel_hi:[1,1,0] neg_lo:[0,0,1] neg_hi:[0,0,1]
	v_mov_b32_e32 v62, v67
	v_mul_f32_e32 v54, v57, v63
	v_pk_fma_f32 v[62:63], v[56:57], v[62:63], v[54:55] op_sel_hi:[1,1,0]
	v_pk_mul_f32 v[56:57], v[50:51], v[68:69] op_sel:[1,0] op_sel_hi:[0,0]
	v_pk_mul_f32 v[66:67], v[50:51], v[64:65]
	v_pk_fma_f32 v[50:51], v[50:51], v[64:65], v[56:57] op_sel_hi:[1,0,1]
	v_mov_b32_e32 v68, v65
	v_mul_f32_e32 v50, v53, v69
	v_pk_fma_f32 v[74:75], v[52:53], v[68:69], v[50:51] op_sel_hi:[1,1,0] neg_lo:[0,0,1] neg_hi:[0,0,1]
	v_mov_b32_e32 v64, v69
	v_mul_f32_e32 v50, v53, v65
	v_pk_fma_f32 v[64:65], v[52:53], v[64:65], v[50:51] op_sel_hi:[1,1,0]
	v_sub_f32_e32 v50, v66, v56
	v_sub_f32_e32 v54, v70, v58
	v_mov_b32_e32 v52, v74
	v_mov_b32_e32 v53, v64
	v_mov_b32_e32 v56, v72
	v_mov_b32_e32 v57, v62
.LBB0_683:
	s_or_b64 exec, exec, s[0:1]
	v_mov_b32_e32 v58, v1
	v_mov_b32_e32 v59, v1
	v_cvt_pk_fp8_f32 v58, v54, v55
	v_cvt_pk_fp8_f32 v59, v50, v51
	v_cvt_pk_fp8_f32 v58, v56, v57 op_sel:[0,0,1]
	v_cvt_pk_fp8_f32 v59, v52, v53 op_sel:[0,0,1]
	v_add_u32_e32 v56, 0x90, v144
	v_lshlrev_b32_e32 v50, 5, v56
	v_and_b32_e32 v52, 0x1fbe0, v50
	flat_store_dwordx2 v[60:61], v[58:59] offset:128
	v_cmp_gt_i32_e64 s[0:1], s63, v56
	v_fmamk_f32 v51, v249, 0x3b800000, v236
	v_cndmask_b32_e64 v50, v52, v50, s[0:1]
	v_rsq_f32_e32 v52, v51
	v_ashrrev_i32_e32 v51, 31, v50
	v_lshlrev_b64 v[58:59], 2, v[50:51]
	v_lshl_add_u64 v[50:51], s[40:41], 0, v[58:59]
	v_pk_mul_f32 v[54:55], v[48:49], v[52:53] op_sel_hi:[1,0]
	v_pk_mul_f32 v[46:47], v[46:47], v[52:53] op_sel_hi:[1,0]
	v_pk_mul_f32 v[48:49], v[44:45], v[52:53] op_sel_hi:[1,0]
	v_pk_mul_f32 v[44:45], v[42:43], v[52:53] op_sel_hi:[1,0]
	v_lshl_add_u64 v[42:43], s[42:43], 0, v[58:59]
	s_and_saveexec_b64 s[0:1], vcc
	s_cbranch_execz .LBB0_685
	v_lshlrev_b64 v[62:63], 2, v[0:1]
	v_lshl_add_u64 v[58:59], v[50:51], 0, v[62:63]
	v_lshl_add_u64 v[62:63], v[42:43], 0, v[62:63]
	global_load_dwordx4 v[58:61], v[58:59], off
	s_nop 0
	global_load_dwordx4 v[62:65], v[62:63], off
	s_waitcnt vmcnt(0) lgkmcnt(0)
	v_pk_mul_f32 v[68:69], v[46:47], v[58:59]
	v_pk_mul_f32 v[66:67], v[46:47], v[62:63] op_sel:[1,0] op_sel_hi:[0,0]
	v_pk_fma_f32 v[46:47], v[46:47], v[58:59], v[66:67] op_sel_hi:[1,0,1]
	v_mov_b32_e32 v62, v59
	v_mul_f32_e32 v46, v55, v63
	v_pk_fma_f32 v[70:71], v[54:55], v[62:63], v[46:47] op_sel_hi:[1,1,0] neg_lo:[0,0,1] neg_hi:[0,0,1]
	v_mov_b32_e32 v58, v63
	v_mul_f32_e32 v46, v55, v59
	v_pk_fma_f32 v[58:59], v[54:55], v[58:59], v[46:47] op_sel_hi:[1,1,0]
	v_pk_mul_f32 v[54:55], v[44:45], v[64:65] op_sel:[1,0] op_sel_hi:[0,0]
	v_pk_mul_f32 v[62:63], v[44:45], v[60:61]
	v_pk_fma_f32 v[44:45], v[44:45], v[60:61], v[54:55] op_sel_hi:[1,0,1]
	v_mov_b32_e32 v64, v61
	v_mul_f32_e32 v44, v49, v65
	v_pk_fma_f32 v[72:73], v[48:49], v[64:65], v[44:45] op_sel_hi:[1,1,0] neg_lo:[0,0,1] neg_hi:[0,0,1]
	v_mov_b32_e32 v60, v65
	v_mul_f32_e32 v44, v49, v61
	v_pk_fma_f32 v[60:61], v[48:49], v[60:61], v[44:45] op_sel_hi:[1,1,0]
	v_sub_f32_e32 v44, v62, v54
	v_sub_f32_e32 v46, v68, v66
	v_mov_b32_e32 v48, v72
	v_mov_b32_e32 v49, v60
	v_mov_b32_e32 v54, v70
	v_mov_b32_e32 v55, v58
.LBB0_685:
	s_or_b64 exec, exec, s[0:1]
	v_mov_b32_e32 v58, v1
	v_mov_b32_e32 v59, v1
	v_cvt_pk_fp8_f32 v58, v46, v47
	v_cvt_pk_fp8_f32 v59, v44, v45
	v_mov_b64_e32 v[44:45], s[34:35]
	s_movk_i32 s0, 0x300
	v_cvt_pk_fp8_f32 v58, v54, v55 op_sel:[0,0,1]
	v_cvt_pk_fp8_f32 v59, v48, v49 op_sel:[0,0,1]
	v_mov_b32_e32 v53, v52
	v_mad_i64_i32 v[44:45], s[0:1], v56, s0, v[44:45]
	v_mov_b32_e32 v46, v52
	v_mov_b32_e32 v47, v52
	v_lshl_add_u64 v[44:45], v[44:45], 0, v[142:143]
	v_pk_mul_f32 v[40:41], v[40:41], v[46:47]
	v_pk_mul_f32 v[38:39], v[38:39], v[52:53]
	v_pk_mul_f32 v[36:37], v[36:37], v[46:47]
	v_pk_mul_f32 v[34:35], v[34:35], v[52:53]
	flat_store_dwordx2 v[44:45], v[58:59]
	s_and_saveexec_b64 s[0:1], s[6:7]
	s_cbranch_execz .LBB0_687
	v_mov_b32_e32 v115, v1
	v_lshlrev_b64 v[52:53], 2, v[114:115]
	v_lshl_add_u64 v[46:47], v[50:51], 0, v[52:53]
	v_lshl_add_u64 v[42:43], v[42:43], 0, v[52:53]
	global_load_dwordx4 v[46:49], v[46:47], off
	s_nop 0
	global_load_dwordx4 v[50:53], v[42:43], off
	s_waitcnt vmcnt(0) lgkmcnt(0)
	v_pk_mul_f32 v[54:55], v[38:39], v[46:47]
	v_pk_mul_f32 v[42:43], v[38:39], v[50:51] op_sel:[1,0] op_sel_hi:[0,0]
	v_pk_fma_f32 v[38:39], v[38:39], v[46:47], v[42:43] op_sel_hi:[1,0,1]
	v_mov_b32_e32 v50, v47
	v_mul_f32_e32 v38, v41, v51
	v_pk_fma_f32 v[56:57], v[40:41], v[50:51], v[38:39] op_sel_hi:[1,1,0] neg_lo:[0,0,1] neg_hi:[0,0,1]
	v_mov_b32_e32 v46, v51
	v_mul_f32_e32 v38, v41, v47
	v_pk_fma_f32 v[46:47], v[40:41], v[46:47], v[38:39] op_sel_hi:[1,1,0]
	v_pk_mul_f32 v[40:41], v[34:35], v[52:53] op_sel:[1,0] op_sel_hi:[0,0]
	v_pk_mul_f32 v[50:51], v[34:35], v[48:49]
	v_pk_fma_f32 v[34:35], v[34:35], v[48:49], v[40:41] op_sel_hi:[1,0,1]
	v_mov_b32_e32 v52, v49
	v_mul_f32_e32 v34, v37, v53
	v_pk_fma_f32 v[58:59], v[36:37], v[52:53], v[34:35] op_sel_hi:[1,1,0] neg_lo:[0,0,1] neg_hi:[0,0,1]
	v_mov_b32_e32 v48, v53
	v_mul_f32_e32 v34, v37, v49
	v_pk_fma_f32 v[48:49], v[36:37], v[48:49], v[34:35] op_sel_hi:[1,1,0]
	v_sub_f32_e32 v34, v50, v40
	v_sub_f32_e32 v38, v54, v42
	v_mov_b32_e32 v36, v58
	v_mov_b32_e32 v37, v48
	v_mov_b32_e32 v40, v56
	v_mov_b32_e32 v41, v46
; __device__ __forceinline__ unsigned pk4_fp8(float a, float b, float c, float d) { int w = 0; w = __builtin_amdgcn_cvt_pk_fp8_f32(a, b, w, false); w = __builtin_amdgcn_cvt_pk_fp8_f32(c, d, w, true); return (unsigned)w; }
;     __device__ __forceinline__ void operator()(const AccT& acc, const Unit& u, int wr, int wc, int fr, int fq) const {
; #pragma unroll
;         for (int ai = 0; ai < 2; ++ai)
; #pragma unroll
;             for (int m = 0; m < 4; ++m) {
;                 const int row = EPI_ROW(u, ai, m);
;                 const float r = __builtin_amdgcn_rsqf(ssq_q[row] * (1.0f / 256.0f) + RMS_EPS);
;                 const int pos = posof(row);
; #pragma unroll
;                 for (int bj = 0; bj < 2; ++bj) {
;                     const int col = EPI_COL(u, bj), d = col % 192;
;                     f32x4 v0 = acc[ai][bj][m][0] * r, v1 = acc[ai][bj][m][1] * r;
;                     if (d >= 128) { const int j0 = (d - 128) >> 1;
;                         const f32x4 c4 = *(const f32x4*)(cosT + pos * 32 + j0), s4 = *(const f32x4*)(sinT + pos * 32 + j0);
;                         rope8(v0, v1, c4, s4); }
;                     u32x2 w; w.x = pk4_fp8(v0[0], v0[1], v0[2], v0[3]); w.y = pk4_fp8(v1[0], v1[1], v1[2], v1[3]);
;                     *(u32x2*)(Q + (size_t)row * LDQ + col) = w;
;                 }
;             }
;     }
.LBB0_687:
	s_or_b64 exec, exec, s[0:1]
	v_mov_b32_e32 v42, v1
	v_mov_b32_e32 v43, v1
	v_cvt_pk_fp8_f32 v42, v38, v39
	v_cvt_pk_fp8_f32 v43, v34, v35
	v_cvt_pk_fp8_f32 v42, v40, v41 op_sel:[0,0,1]
	v_cvt_pk_fp8_f32 v43, v36, v37 op_sel:[0,0,1]
	v_add_u32_e32 v40, 0xa0, v144
	v_lshlrev_b32_e32 v34, 5, v40
	v_and_b32_e32 v36, 0x1fde0, v34
	flat_store_dwordx2 v[44:45], v[42:43] offset:128
	v_cmp_gt_i32_e64 s[0:1], s63, v40
	v_fmamk_f32 v35, v250, 0x3b800000, v236
	v_cndmask_b32_e64 v34, v36, v34, s[0:1]
	v_rsq_f32_e32 v36, v35
	v_ashrrev_i32_e32 v35, 31, v34
	v_lshlrev_b64 v[42:43], 2, v[34:35]
	v_lshl_add_u64 v[34:35], s[40:41], 0, v[42:43]
	v_pk_mul_f32 v[38:39], v[32:33], v[36:37] op_sel_hi:[1,0]
	v_pk_mul_f32 v[30:31], v[30:31], v[36:37] op_sel_hi:[1,0]
	v_pk_mul_f32 v[32:33], v[28:29], v[36:37] op_sel_hi:[1,0]
	v_pk_mul_f32 v[28:29], v[26:27], v[36:37] op_sel_hi:[1,0]
	v_lshl_add_u64 v[26:27], s[42:43], 0, v[42:43]
	s_and_saveexec_b64 s[0:1], vcc
	s_cbranch_execz .LBB0_689
	v_lshlrev_b64 v[46:47], 2, v[0:1]
	v_lshl_add_u64 v[42:43], v[34:35], 0, v[46:47]
	v_lshl_add_u64 v[46:47], v[26:27], 0, v[46:47]
	global_load_dwordx4 v[42:45], v[42:43], off
	s_nop 0
	global_load_dwordx4 v[46:49], v[46:47], off
	s_waitcnt vmcnt(0) lgkmcnt(0)
	v_pk_mul_f32 v[52:53], v[30:31], v[42:43]
	v_pk_mul_f32 v[50:51], v[30:31], v[46:47] op_sel:[1,0] op_sel_hi:[0,0]
	v_pk_fma_f32 v[30:31], v[30:31], v[42:43], v[50:51] op_sel_hi:[1,0,1]
	v_mov_b32_e32 v46, v43
	v_mul_f32_e32 v30, v39, v47
	v_pk_fma_f32 v[54:55], v[38:39], v[46:47], v[30:31] op_sel_hi:[1,1,0] neg_lo:[0,0,1] neg_hi:[0,0,1]
	v_mov_b32_e32 v42, v47
	v_mul_f32_e32 v30, v39, v43
	v_pk_fma_f32 v[42:43], v[38:39], v[42:43], v[30:31] op_sel_hi:[1,1,0]
	v_pk_mul_f32 v[38:39], v[28:29], v[48:49] op_sel:[1,0] op_sel_hi:[0,0]
	v_pk_mul_f32 v[46:47], v[28:29], v[44:45]
	v_pk_fma_f32 v[28:29], v[28:29], v[44:45], v[38:39] op_sel_hi:[1,0,1]
	v_mov_b32_e32 v48, v45
	v_mul_f32_e32 v28, v33, v49
	v_pk_fma_f32 v[56:57], v[32:33], v[48:49], v[28:29] op_sel_hi:[1,1,0] neg_lo:[0,0,1] neg_hi:[0,0,1]
	v_mov_b32_e32 v44, v49
	v_mul_f32_e32 v28, v33, v45
	v_pk_fma_f32 v[44:45], v[32:33], v[44:45], v[28:29] op_sel_hi:[1,1,0]
	v_sub_f32_e32 v28, v46, v38
	v_sub_f32_e32 v30, v52, v50
	v_mov_b32_e32 v32, v56
	v_mov_b32_e32 v33, v44
	v_mov_b32_e32 v38, v54
	v_mov_b32_e32 v39, v42
.LBB0_689:
	s_or_b64 exec, exec, s[0:1]
	v_mov_b32_e32 v42, v1
	v_mov_b32_e32 v43, v1
	v_cvt_pk_fp8_f32 v42, v30, v31
	v_cvt_pk_fp8_f32 v43, v28, v29
	v_mov_b64_e32 v[28:29], s[34:35]
	s_movk_i32 s0, 0x300
	v_cvt_pk_fp8_f32 v42, v38, v39 op_sel:[0,0,1]
	v_cvt_pk_fp8_f32 v43, v32, v33 op_sel:[0,0,1]
	v_mov_b32_e32 v37, v36
	v_mad_i64_i32 v[28:29], s[0:1], v40, s0, v[28:29]
	v_mov_b32_e32 v30, v36
	v_mov_b32_e32 v31, v36
	v_lshl_add_u64 v[28:29], v[28:29], 0, v[142:143]
	v_pk_mul_f32 v[24:25], v[24:25], v[30:31]
	v_pk_mul_f32 v[22:23], v[22:23], v[36:37]
	v_pk_mul_f32 v[20:21], v[20:21], v[30:31]
	v_pk_mul_f32 v[18:19], v[18:19], v[36:37]
	flat_store_dwordx2 v[28:29], v[42:43]
	s_and_saveexec_b64 s[0:1], s[6:7]
	s_cbranch_execz .LBB0_691
	v_mov_b32_e32 v115, v1
	v_lshlrev_b64 v[36:37], 2, v[114:115]
	v_lshl_add_u64 v[30:31], v[34:35], 0, v[36:37]
	v_lshl_add_u64 v[26:27], v[26:27], 0, v[36:37]
	global_load_dwordx4 v[30:33], v[30:31], off
	s_nop 0
	global_load_dwordx4 v[34:37], v[26:27], off
	s_waitcnt vmcnt(0) lgkmcnt(0)
	v_pk_mul_f32 v[38:39], v[22:23], v[30:31]
	v_pk_mul_f32 v[26:27], v[22:23], v[34:35] op_sel:[1,0] op_sel_hi:[0,0]
	v_pk_fma_f32 v[22:23], v[22:23], v[30:31], v[26:27] op_sel_hi:[1,0,1]
	v_mov_b32_e32 v34, v31
	v_mul_f32_e32 v22, v25, v35
	v_pk_fma_f32 v[40:41], v[24:25], v[34:35], v[22:23] op_sel_hi:[1,1,0] neg_lo:[0,0,1] neg_hi:[0,0,1]
	v_mov_b32_e32 v30, v35
	v_mul_f32_e32 v22, v25, v31
	v_pk_fma_f32 v[30:31], v[24:25], v[30:31], v[22:23] op_sel_hi:[1,1,0]
	v_pk_mul_f32 v[24:25], v[18:19], v[36:37] op_sel:[1,0] op_sel_hi:[0,0]
	v_pk_mul_f32 v[34:35], v[18:19], v[32:33]
	v_pk_fma_f32 v[18:19], v[18:19], v[32:33], v[24:25] op_sel_hi:[1,0,1]
	v_mov_b32_e32 v36, v33
	v_mul_f32_e32 v18, v21, v37
	v_pk_fma_f32 v[42:43], v[20:21], v[36:37], v[18:19] op_sel_hi:[1,1,0] neg_lo:[0,0,1] neg_hi:[0,0,1]
	v_mov_b32_e32 v32, v37
	v_mul_f32_e32 v18, v21, v33
	v_pk_fma_f32 v[32:33], v[20:21], v[32:33], v[18:19] op_sel_hi:[1,1,0]
	v_sub_f32_e32 v18, v34, v24
	v_sub_f32_e32 v22, v38, v26
	v_mov_b32_e32 v20, v42
	v_mov_b32_e32 v21, v32
	v_mov_b32_e32 v24, v40
	v_mov_b32_e32 v25, v30
; __device__ __forceinline__ unsigned pk4_fp8(float a, float b, float c, float d) { int w = 0; w = __builtin_amdgcn_cvt_pk_fp8_f32(a, b, w, false); w = __builtin_amdgcn_cvt_pk_fp8_f32(c, d, w, true); return (unsigned)w; }
;     __device__ __forceinline__ void operator()(const AccT& acc, const Unit& u, int wr, int wc, int fr, int fq) const {
; #pragma unroll
;         for (int ai = 0; ai < 2; ++ai)
; #pragma unroll
;             for (int m = 0; m < 4; ++m) {
;                 const int row = EPI_ROW(u, ai, m);
;                 const float r = __builtin_amdgcn_rsqf(ssq_q[row] * (1.0f / 256.0f) + RMS_EPS);
;                 const int pos = posof(row);
; #pragma unroll
;                 for (int bj = 0; bj < 2; ++bj) {
;                     const int col = EPI_COL(u, bj), d = col % 192;
;                     f32x4 v0 = acc[ai][bj][m][0] * r, v1 = acc[ai][bj][m][1] * r;
;                     if (d >= 128) { const int j0 = (d - 128) >> 1;
;                         const f32x4 c4 = *(const f32x4*)(cosT + pos * 32 + j0), s4 = *(const f32x4*)(sinT + pos * 32 + j0);
;                         rope8(v0, v1, c4, s4); }
;                     u32x2 w; w.x = pk4_fp8(v0[0], v0[1], v0[2], v0[3]); w.y = pk4_fp8(v1[0], v1[1], v1[2], v1[3]);
;                     *(u32x2*)(Q + (size_t)row * LDQ + col) = w;
;                 }
;             }
;     }
.LBB0_691:
	s_or_b64 exec, exec, s[0:1]
	v_mov_b32_e32 v26, v1
	v_mov_b32_e32 v27, v1
	v_cvt_pk_fp8_f32 v26, v22, v23
	v_cvt_pk_fp8_f32 v27, v18, v19
	v_cvt_pk_fp8_f32 v26, v24, v25 op_sel:[0,0,1]
	v_cvt_pk_fp8_f32 v27, v20, v21 op_sel:[0,0,1]
	v_add_u32_e32 v24, 0xb0, v144
	v_lshlrev_b32_e32 v18, 5, v24
	v_and_b32_e32 v20, 0x1ffe0, v18
	flat_store_dwordx2 v[28:29], v[26:27] offset:128
	v_cmp_gt_i32_e64 s[0:1], s63, v24
	v_fmamk_f32 v19, v251, 0x3b800000, v236
	v_cndmask_b32_e64 v18, v20, v18, s[0:1]
	v_rsq_f32_e32 v20, v19
	v_ashrrev_i32_e32 v19, 31, v18
	v_lshlrev_b64 v[26:27], 2, v[18:19]
	v_lshl_add_u64 v[18:19], s[40:41], 0, v[26:27]
	v_pk_mul_f32 v[22:23], v[16:17], v[20:21] op_sel_hi:[1,0]
	v_pk_mul_f32 v[14:15], v[14:15], v[20:21] op_sel_hi:[1,0]
	v_pk_mul_f32 v[16:17], v[12:13], v[20:21] op_sel_hi:[1,0]
	v_pk_mul_f32 v[12:13], v[10:11], v[20:21] op_sel_hi:[1,0]
	v_lshl_add_u64 v[10:11], s[42:43], 0, v[26:27]
	s_and_saveexec_b64 s[0:1], vcc
	s_cbranch_execz .LBB0_693
	v_lshlrev_b64 v[30:31], 2, v[0:1]
	v_lshl_add_u64 v[26:27], v[18:19], 0, v[30:31]
	v_lshl_add_u64 v[30:31], v[10:11], 0, v[30:31]
	global_load_dwordx4 v[26:29], v[26:27], off
	s_nop 0
	global_load_dwordx4 v[30:33], v[30:31], off
	s_waitcnt vmcnt(0) lgkmcnt(0)
	v_pk_mul_f32 v[36:37], v[14:15], v[26:27]
	v_pk_mul_f32 v[34:35], v[14:15], v[30:31] op_sel:[1,0] op_sel_hi:[0,0]
	v_mov_b32_e32 v30, v27
	v_mul_f32_e32 v0, v23, v31
	v_pk_fma_f32 v[14:15], v[14:15], v[26:27], v[34:35] op_sel_hi:[1,0,1]
	v_pk_fma_f32 v[38:39], v[22:23], v[30:31], v[0:1] op_sel_hi:[1,1,0] neg_lo:[0,0,1] neg_hi:[0,0,1]
	v_mov_b32_e32 v26, v31
	v_mul_f32_e32 v0, v23, v27
	v_pk_fma_f32 v[26:27], v[22:23], v[26:27], v[0:1] op_sel_hi:[1,1,0]
	v_pk_mul_f32 v[22:23], v[12:13], v[32:33] op_sel:[1,0] op_sel_hi:[0,0]
	v_mov_b32_e32 v32, v29
	v_mul_f32_e32 v0, v17, v33
	v_pk_mul_f32 v[30:31], v[12:13], v[28:29]
	v_pk_fma_f32 v[12:13], v[12:13], v[28:29], v[22:23] op_sel_hi:[1,0,1]
	v_pk_fma_f32 v[40:41], v[16:17], v[32:33], v[0:1] op_sel_hi:[1,1,0] neg_lo:[0,0,1] neg_hi:[0,0,1]
	v_mov_b32_e32 v28, v33
	v_mul_f32_e32 v0, v17, v29
	v_pk_fma_f32 v[28:29], v[16:17], v[28:29], v[0:1] op_sel_hi:[1,1,0]
	v_sub_f32_e32 v12, v30, v22
	v_sub_f32_e32 v14, v36, v34
	v_mov_b32_e32 v16, v40
	v_mov_b32_e32 v17, v28
	v_mov_b32_e32 v22, v38
	v_mov_b32_e32 v23, v26
.LBB0_693:
	s_or_b64 exec, exec, s[0:1]
	v_mov_b32_e32 v26, v1
	v_mov_b32_e32 v27, v1
	v_cvt_pk_fp8_f32 v26, v14, v15
	v_cvt_pk_fp8_f32 v27, v12, v13
	v_mov_b64_e32 v[12:13], s[34:35]
	s_movk_i32 s0, 0x300
	v_cvt_pk_fp8_f32 v26, v22, v23 op_sel:[0,0,1]
	v_cvt_pk_fp8_f32 v27, v16, v17 op_sel:[0,0,1]
	v_mov_b32_e32 v21, v20
	v_mad_i64_i32 v[12:13], s[0:1], v24, s0, v[12:13]
	v_mov_b32_e32 v14, v20
	v_mov_b32_e32 v15, v20
	v_lshl_add_u64 v[12:13], v[12:13], 0, v[142:143]
	v_pk_mul_f32 v[8:9], v[8:9], v[14:15]
	v_pk_mul_f32 v[6:7], v[6:7], v[20:21]
	v_pk_mul_f32 v[4:5], v[4:5], v[14:15]
	v_pk_mul_f32 v[2:3], v[2:3], v[20:21]
	flat_store_dwordx2 v[12:13], v[26:27]
	s_and_saveexec_b64 s[0:1], s[6:7]
	s_cbranch_execz .LBB0_695
	v_mov_b32_e32 v115, v1
	v_lshlrev_b64 v[20:21], 2, v[114:115]
	v_lshl_add_u64 v[14:15], v[18:19], 0, v[20:21]
	v_lshl_add_u64 v[10:11], v[10:11], 0, v[20:21]
	global_load_dwordx4 v[14:17], v[14:15], off
	s_nop 0
	global_load_dwordx4 v[18:21], v[10:11], off
	s_waitcnt vmcnt(0) lgkmcnt(0)
	v_pk_mul_f32 v[22:23], v[6:7], v[14:15]
	v_pk_mul_f32 v[10:11], v[6:7], v[18:19] op_sel:[1,0] op_sel_hi:[0,0]
	v_mov_b32_e32 v18, v15
	v_mul_f32_e32 v0, v9, v19
	v_pk_fma_f32 v[6:7], v[6:7], v[14:15], v[10:11] op_sel_hi:[1,0,1]
	v_pk_fma_f32 v[24:25], v[8:9], v[18:19], v[0:1] op_sel_hi:[1,1,0] neg_lo:[0,0,1] neg_hi:[0,0,1]
	v_mov_b32_e32 v14, v19
	v_mul_f32_e32 v0, v9, v15
	v_pk_fma_f32 v[14:15], v[8:9], v[14:15], v[0:1] op_sel_hi:[1,1,0]
	v_pk_mul_f32 v[8:9], v[2:3], v[20:21] op_sel:[1,0] op_sel_hi:[0,0]
	v_mov_b32_e32 v20, v17
	v_mul_f32_e32 v0, v5, v21
	v_pk_mul_f32 v[18:19], v[2:3], v[16:17]
	v_pk_fma_f32 v[2:3], v[2:3], v[16:17], v[8:9] op_sel_hi:[1,0,1]
	v_pk_fma_f32 v[26:27], v[4:5], v[20:21], v[0:1] op_sel_hi:[1,1,0] neg_lo:[0,0,1] neg_hi:[0,0,1]
	v_mov_b32_e32 v16, v21
	v_mul_f32_e32 v0, v5, v17
	v_pk_fma_f32 v[16:17], v[4:5], v[16:17], v[0:1] op_sel_hi:[1,1,0]
	v_sub_f32_e32 v2, v18, v8
	v_sub_f32_e32 v6, v22, v10
	v_mov_b32_e32 v4, v26
	v_mov_b32_e32 v5, v16
	v_mov_b32_e32 v8, v24
	v_mov_b32_e32 v9, v14

; __device__ __forceinline__ void tr_load(const TrDesc& d, int tid, float (&v)[8]) {
;     const int nn = tid & 63, np = d.n0 + nn; int col = np; const float* s = d.src;
;     if (d.mode == 1) { if (np >= 1216) col = -1; else if (np >= 1152) { const int i = np - 1152; col = 1152 + (i >> 1) + 32 * (i & 1); } }
;     else if (d.mode == 2) { const int h = np / 192, dd = np % 192; if (dd >= 128) { const int i = dd - 128; col = 192 * h + 128 + (i >> 1) + 32 * (i & 1); } }
;     else if (d.mode == 3) { col = (np >> 8) * 128 + (np & 127); if ((np >> 7) & 1) s = d.src2; }
; #pragma unroll
;     for (int i = 0; i < 8; ++i) { const int kk = (tid >> 6) + 8 * i; float x = 0.f;
;         if (col >= 0) { x = s[(size_t)(d.k0 + kk) * d.ld_src + col]; if (d.rs) x *= d.rs[d.k0 + kk]; if (d.mode == 2) x *= QSCALE * 8.0f; }
;         v[i] = x; }
; }
.LBB0_738:
	v_add_u32_e32 v0, 16, v21
	v_mad_i64_i32 v[2:3], s[14:15], s4, v0, 0
	v_add_u32_e32 v0, 24, v21
	v_lshl_add_u64 v[2:3], v[2:3], 2, v[18:19]
	v_mad_i64_i32 v[4:5], s[14:15], s4, v0, 0
	v_lshl_add_u64 v[4:5], v[4:5], 2, v[18:19]
	global_load_dword v12, v[2:3], off
	global_load_dword v0, v[4:5], off
	s_waitcnt vmcnt(0) lgkmcnt(0)
	v_mov_b64_e32 v[2:3], v[10:11]
	v_mov_b64_e32 v[4:5], v[12:13]
	v_mov_b64_e32 v[6:7], v[14:15]
	v_mov_b64_e32 v[8:9], v[16:17]
	v_mov_b32_e32 v5, v0

; __device__ __forceinline__ void tr_load(const TrDesc& d, int tid, float (&v)[8]) {
;     const int nn = tid & 63, np = d.n0 + nn; int col = np; const float* s = d.src;
;     if (d.mode == 1) { if (np >= 1216) col = -1; else if (np >= 1152) { const int i = np - 1152; col = 1152 + (i >> 1) + 32 * (i & 1); } }
;     else if (d.mode == 2) { const int h = np / 192, dd = np % 192; if (dd >= 128) { const int i = dd - 128; col = 192 * h + 128 + (i >> 1) + 32 * (i & 1); } }
;     else if (d.mode == 3) { col = (np >> 8) * 128 + (np & 127); if ((np >> 7) & 1) s = d.src2; }
; #pragma unroll
;     for (int i = 0; i < 8; ++i) { const int kk = (tid >> 6) + 8 * i; float x = 0.f;
;         if (col >= 0) { x = s[(size_t)(d.k0 + kk) * d.ld_src + col]; if (d.rs) x *= d.rs[d.k0 + kk]; if (d.mode == 2) x *= QSCALE * 8.0f; }
;         v[i] = x; }
; }
.LBB0_742:
	v_add_u32_e32 v0, 32, v21
	s_waitcnt vmcnt(0) lgkmcnt(0)
	v_mad_i64_i32 v[10:11], s[14:15], s4, v0, 0
	v_add_u32_e32 v0, 40, v21
	v_lshl_add_u64 v[10:11], v[10:11], 2, v[18:19]
	v_mad_i64_i32 v[12:13], s[14:15], s4, v0, 0
	v_lshl_add_u64 v[12:13], v[12:13], 2, v[18:19]
	global_load_dword v6, v[10:11], off
	global_load_dword v0, v[12:13], off
	s_waitcnt vmcnt(0) lgkmcnt(0)
	v_mov_b64_e32 v[16:17], v[8:9]
	v_mov_b64_e32 v[14:15], v[6:7]
	v_mov_b64_e32 v[12:13], v[4:5]
	v_mov_b64_e32 v[10:11], v[2:3]
	v_mov_b32_e32 v15, v0

; __device__ __forceinline__ void tr_load(const TrDesc& d, int tid, float (&v)[8]) {
;     const int nn = tid & 63, np = d.n0 + nn; int col = np; const float* s = d.src;
;     if (d.mode == 1) { if (np >= 1216) col = -1; else if (np >= 1152) { const int i = np - 1152; col = 1152 + (i >> 1) + 32 * (i & 1); } }
;     else if (d.mode == 2) { const int h = np / 192, dd = np % 192; if (dd >= 128) { const int i = dd - 128; col = 192 * h + 128 + (i >> 1) + 32 * (i & 1); } }
;     else if (d.mode == 3) { col = (np >> 8) * 128 + (np & 127); if ((np >> 7) & 1) s = d.src2; }
; #pragma unroll
;     for (int i = 0; i < 8; ++i) { const int kk = (tid >> 6) + 8 * i; float x = 0.f;
;         if (col >= 0) { x = s[(size_t)(d.k0 + kk) * d.ld_src + col]; if (d.rs) x *= d.rs[d.k0 + kk]; if (d.mode == 2) x *= QSCALE * 8.0f; }
;         v[i] = x; }
; }
.LBB0_746:
	v_add_u32_e32 v0, 48, v21
	v_mad_i64_i32 v[2:3], s[14:15], s4, v0, 0
	v_add_u32_e32 v0, 56, v21
	v_lshl_add_u64 v[2:3], v[2:3], 2, v[18:19]
	v_mad_i64_i32 v[4:5], s[4:5], s4, v0, 0
	v_lshl_add_u64 v[4:5], v[4:5], 2, v[18:19]
	global_load_dword v16, v[2:3], off
	global_load_dword v0, v[4:5], off
	s_waitcnt vmcnt(0) lgkmcnt(0)
	v_mov_b64_e32 v[2:3], v[10:11]
	v_mov_b64_e32 v[8:9], v[16:17]
	v_mov_b64_e32 v[4:5], v[12:13]
	v_mov_b64_e32 v[6:7], v[14:15]
	v_mov_b32_e32 v9, v0

; __device__ __forceinline__ void tr_load(const TrDesc& d, int tid, float (&v)[8]) {
;     const int nn = tid & 63, np = d.n0 + nn; int col = np; const float* s = d.src;
;     if (d.mode == 1) { if (np >= 1216) col = -1; else if (np >= 1152) { const int i = np - 1152; col = 1152 + (i >> 1) + 32 * (i & 1); } }
;     else if (d.mode == 2) { const int h = np / 192, dd = np % 192; if (dd >= 128) { const int i = dd - 128; col = 192 * h + 128 + (i >> 1) + 32 * (i & 1); } }
;     else if (d.mode == 3) { col = (np >> 8) * 128 + (np & 127); if ((np >> 7) & 1) s = d.src2; }
; #pragma unroll
;     for (int i = 0; i < 8; ++i) { const int kk = (tid >> 6) + 8 * i; float x = 0.f;
;         if (col >= 0) { x = s[(size_t)(d.k0 + kk) * d.ld_src + col]; if (d.rs) x *= d.rs[d.k0 + kk]; if (d.mode == 2) x *= QSCALE * 8.0f; }
;         v[i] = x; }
; }
.LBB0_763:
	v_add_u32_e32 v0, 16, v27
	v_mad_i64_i32 v[10:11], s[4:5], s18, v0, 0
	v_add_u32_e32 v0, 24, v27
	v_lshl_add_u64 v[10:11], v[10:11], 2, v[28:29]
	v_mad_i64_i32 v[12:13], s[4:5], s18, v0, 0
	v_lshl_add_u64 v[12:13], v[12:13], 2, v[28:29]
	global_load_dword v4, v[10:11], off
	global_load_dword v0, v[12:13], off
	s_waitcnt vmcnt(0) lgkmcnt(0)
	v_mov_b64_e32 v[24:25], v[8:9]
	v_mov_b64_e32 v[20:21], v[4:5]
	v_mov_b64_e32 v[22:23], v[6:7]
	v_mov_b64_e32 v[18:19], v[2:3]
	v_mov_b32_e32 v21, v0

; __device__ __forceinline__ void tr_load(const TrDesc& d, int tid, float (&v)[8]) {
;     const int nn = tid & 63, np = d.n0 + nn; int col = np; const float* s = d.src;
;     if (d.mode == 1) { if (np >= 1216) col = -1; else if (np >= 1152) { const int i = np - 1152; col = 1152 + (i >> 1) + 32 * (i & 1); } }
;     else if (d.mode == 2) { const int h = np / 192, dd = np % 192; if (dd >= 128) { const int i = dd - 128; col = 192 * h + 128 + (i >> 1) + 32 * (i & 1); } }
;     else if (d.mode == 3) { col = (np >> 8) * 128 + (np & 127); if ((np >> 7) & 1) s = d.src2; }
; #pragma unroll
;     for (int i = 0; i < 8; ++i) { const int kk = (tid >> 6) + 8 * i; float x = 0.f;
;         if (col >= 0) { x = s[(size_t)(d.k0 + kk) * d.ld_src + col]; if (d.rs) x *= d.rs[d.k0 + kk]; if (d.mode == 2) x *= QSCALE * 8.0f; }
;         v[i] = x; }
; }
.LBB0_767:
	v_add_u32_e32 v0, 32, v27
	s_waitcnt vmcnt(0) lgkmcnt(0)
	v_mad_i64_i32 v[2:3], s[4:5], s18, v0, 0
	v_add_u32_e32 v0, 40, v27
	v_lshl_add_u64 v[2:3], v[2:3], 2, v[28:29]
	v_mad_i64_i32 v[4:5], s[4:5], s18, v0, 0
	v_lshl_add_u64 v[4:5], v[4:5], 2, v[28:29]
	global_load_dword v22, v[2:3], off
	global_load_dword v0, v[4:5], off
	s_waitcnt vmcnt(0) lgkmcnt(0)
	v_mov_b64_e32 v[10:11], v[18:19]
	v_mov_b64_e32 v[14:15], v[22:23]
	v_mov_b64_e32 v[12:13], v[20:21]
	v_mov_b64_e32 v[16:17], v[24:25]
	v_mov_b32_e32 v15, v0

; __device__ __forceinline__ void tr_load(const TrDesc& d, int tid, float (&v)[8]) {
;     const int nn = tid & 63, np = d.n0 + nn; int col = np; const float* s = d.src;
;     if (d.mode == 1) { if (np >= 1216) col = -1; else if (np >= 1152) { const int i = np - 1152; col = 1152 + (i >> 1) + 32 * (i & 1); } }
;     else if (d.mode == 2) { const int h = np / 192, dd = np % 192; if (dd >= 128) { const int i = dd - 128; col = 192 * h + 128 + (i >> 1) + 32 * (i & 1); } }
;     else if (d.mode == 3) { col = (np >> 8) * 128 + (np & 127); if ((np >> 7) & 1) s = d.src2; }
; #pragma unroll
;     for (int i = 0; i < 8; ++i) { const int kk = (tid >> 6) + 8 * i; float x = 0.f;
;         if (col >= 0) { x = s[(size_t)(d.k0 + kk) * d.ld_src + col]; if (d.rs) x *= d.rs[d.k0 + kk]; if (d.mode == 2) x *= QSCALE * 8.0f; }
;         v[i] = x; }
; }
.LBB0_771:
	v_add_u32_e32 v0, 48, v27
	s_waitcnt vmcnt(0) lgkmcnt(0)
	v_mad_i64_i32 v[2:3], s[4:5], s18, v0, 0
	v_add_u32_e32 v0, 56, v27
	v_lshl_add_u64 v[2:3], v[2:3], 2, v[28:29]
	v_mad_i64_i32 v[4:5], s[4:5], s18, v0, 0
	v_lshl_add_u64 v[4:5], v[4:5], 2, v[28:29]
	global_load_dword v16, v[2:3], off
	global_load_dword v0, v[4:5], off
	s_waitcnt vmcnt(0) lgkmcnt(0)
	v_mov_b64_e32 v[2:3], v[10:11]
	v_mov_b64_e32 v[8:9], v[16:17]
	v_mov_b64_e32 v[4:5], v[12:13]
	v_mov_b64_e32 v[6:7], v[14:15]
	v_mov_b32_e32 v9, v0
	s_branch .LBB0_748

; __device__ __forceinline__ void tr_load(const TrDesc& d, int tid, float (&v)[8]) {
;     const int nn = tid & 63, np = d.n0 + nn; int col = np; const float* s = d.src;
;     if (d.mode == 1) { if (np >= 1216) col = -1; else if (np >= 1152) { const int i = np - 1152; col = 1152 + (i >> 1) + 32 * (i & 1); } }
;     else if (d.mode == 2) { const int h = np / 192, dd = np % 192; if (dd >= 128) { const int i = dd - 128; col = 192 * h + 128 + (i >> 1) + 32 * (i & 1); } }
;     else if (d.mode == 3) { col = (np >> 8) * 128 + (np & 127); if ((np >> 7) & 1) s = d.src2; }
; #pragma unroll
;     for (int i = 0; i < 8; ++i) { const int kk = (tid >> 6) + 8 * i; float x = 0.f;
;         if (col >= 0) { x = s[(size_t)(d.k0 + kk) * d.ld_src + col]; if (d.rs) x *= d.rs[d.k0 + kk]; if (d.mode == 2) x *= QSCALE * 8.0f; }
;         v[i] = x; }
; }
.LBB0_780:
	v_add_u32_e32 v0, 32, v21
	s_movk_i32 s14, 0x2c00
	v_mad_i64_i32 v[10:11], s[12:13], v0, s14, v[18:19]
	v_add_u32_e32 v0, 40, v21
	v_mad_i64_i32 v[12:13], s[12:13], v0, s14, v[18:19]
	global_load_dword v6, v[10:11], off
	global_load_dword v0, v[12:13], off
	s_waitcnt vmcnt(0) lgkmcnt(0)
	v_mov_b64_e32 v[16:17], v[8:9]
	v_mov_b64_e32 v[14:15], v[6:7]
	v_mov_b64_e32 v[12:13], v[4:5]
	v_mov_b64_e32 v[10:11], v[2:3]
	v_mov_b32_e32 v15, v0
	s_mov_b64 s[12:13], -1
	s_and_b64 vcc, exec, s[4:5]
	s_cbranch_vccnz .LBB0_811

; __device__ __forceinline__ void tr_load(const TrDesc& d, int tid, float (&v)[8]) {
;     const int nn = tid & 63, np = d.n0 + nn; int col = np; const float* s = d.src;
;     if (d.mode == 1) { if (np >= 1216) col = -1; else if (np >= 1152) { const int i = np - 1152; col = 1152 + (i >> 1) + 32 * (i & 1); } }
;     else if (d.mode == 2) { const int h = np / 192, dd = np % 192; if (dd >= 128) { const int i = dd - 128; col = 192 * h + 128 + (i >> 1) + 32 * (i & 1); } }
;     else if (d.mode == 3) { col = (np >> 8) * 128 + (np & 127); if ((np >> 7) & 1) s = d.src2; }
; #pragma unroll
;     for (int i = 0; i < 8; ++i) { const int kk = (tid >> 6) + 8 * i; float x = 0.f;
;         if (col >= 0) { x = s[(size_t)(d.k0 + kk) * d.ld_src + col]; if (d.rs) x *= d.rs[d.k0 + kk]; if (d.mode == 2) x *= QSCALE * 8.0f; }
;         v[i] = x; }
; }
.LBB0_782:
	v_add_u32_e32 v0, 48, v21
	s_movk_i32 s12, 0x2c00
	s_waitcnt vmcnt(0) lgkmcnt(0)
	v_mad_i64_i32 v[2:3], s[4:5], v0, s12, v[18:19]
	v_add_u32_e32 v0, 56, v21
	v_mad_i64_i32 v[4:5], s[4:5], v0, s12, v[18:19]
	global_load_dword v16, v[2:3], off
	global_load_dword v0, v[4:5], off
	s_waitcnt vmcnt(0) lgkmcnt(0)
	v_mov_b64_e32 v[2:3], v[10:11]
	v_mov_b64_e32 v[8:9], v[16:17]
	v_mov_b64_e32 v[4:5], v[12:13]
	v_mov_b64_e32 v[6:7], v[14:15]
	v_mov_b32_e32 v9, v0

; __device__ __forceinline__ void tr_load(const TrDesc& d, int tid, float (&v)[8]) {
;     const int nn = tid & 63, np = d.n0 + nn; int col = np; const float* s = d.src;
;     if (d.mode == 1) { if (np >= 1216) col = -1; else if (np >= 1152) { const int i = np - 1152; col = 1152 + (i >> 1) + 32 * (i & 1); } }
;     else if (d.mode == 2) { const int h = np / 192, dd = np % 192; if (dd >= 128) { const int i = dd - 128; col = 192 * h + 128 + (i >> 1) + 32 * (i & 1); } }
;     else if (d.mode == 3) { col = (np >> 8) * 128 + (np & 127); if ((np >> 7) & 1) s = d.src2; }
; #pragma unroll
;     for (int i = 0; i < 8; ++i) { const int kk = (tid >> 6) + 8 * i; float x = 0.f;
;         if (col >= 0) { x = s[(size_t)(d.k0 + kk) * d.ld_src + col]; if (d.rs) x *= d.rs[d.k0 + kk]; if (d.mode == 2) x *= QSCALE * 8.0f; }
;         v[i] = x; }
; }
.LBB0_792:
	v_add_u32_e32 v0, 16, v27
	s_movk_i32 s22, 0x2c00
	v_mad_i64_i32 v[10:11], s[14:15], v0, s22, v[28:29]
	v_add_u32_e32 v0, 24, v27
	v_mad_i64_i32 v[12:13], s[14:15], v0, s22, v[28:29]
	global_load_dword v4, v[10:11], off
	global_load_dword v0, v[12:13], off
	s_waitcnt vmcnt(0) lgkmcnt(0)
	v_mov_b64_e32 v[16:17], v[8:9]
	v_mov_b64_e32 v[12:13], v[4:5]
	v_mov_b64_e32 v[14:15], v[6:7]
	v_mov_b64_e32 v[10:11], v[2:3]
	v_mov_b32_e32 v13, v0
	s_mov_b64 s[14:15], -1
	s_and_b64 vcc, exec, s[12:13]
	s_cbranch_vccnz .LBB0_799

; __device__ __forceinline__ void tr_load(const TrDesc& d, int tid, float (&v)[8]) {
;     const int nn = tid & 63, np = d.n0 + nn; int col = np; const float* s = d.src;
;     if (d.mode == 1) { if (np >= 1216) col = -1; else if (np >= 1152) { const int i = np - 1152; col = 1152 + (i >> 1) + 32 * (i & 1); } }
;     else if (d.mode == 2) { const int h = np / 192, dd = np % 192; if (dd >= 128) { const int i = dd - 128; col = 192 * h + 128 + (i >> 1) + 32 * (i & 1); } }
;     else if (d.mode == 3) { col = (np >> 8) * 128 + (np & 127); if ((np >> 7) & 1) s = d.src2; }
; #pragma unroll
;     for (int i = 0; i < 8; ++i) { const int kk = (tid >> 6) + 8 * i; float x = 0.f;
;         if (col >= 0) { x = s[(size_t)(d.k0 + kk) * d.ld_src + col]; if (d.rs) x *= d.rs[d.k0 + kk]; if (d.mode == 2) x *= QSCALE * 8.0f; }
;         v[i] = x; }
; }
.LBB0_794:
	v_add_u32_e32 v0, 32, v27
	s_movk_i32 s22, 0x2c00
	s_waitcnt vmcnt(0) lgkmcnt(0)
	v_mad_i64_i32 v[2:3], s[14:15], v0, s22, v[28:29]
	v_add_u32_e32 v0, 40, v27
	v_mad_i64_i32 v[4:5], s[14:15], v0, s22, v[28:29]
	global_load_dword v14, v[2:3], off
	global_load_dword v0, v[4:5], off
	s_waitcnt vmcnt(0) lgkmcnt(0)
	v_mov_b64_e32 v[24:25], v[16:17]
	v_mov_b64_e32 v[22:23], v[14:15]
	v_mov_b64_e32 v[20:21], v[12:13]
	v_mov_b64_e32 v[18:19], v[10:11]
	v_mov_b32_e32 v23, v0
	s_mov_b64 s[14:15], -1
	s_and_b64 vcc, exec, s[12:13]
	s_cbranch_vccnz .LBB0_801

; __device__ __forceinline__ void tr_load(const TrDesc& d, int tid, float (&v)[8]) {
;     const int nn = tid & 63, np = d.n0 + nn; int col = np; const float* s = d.src;
;     if (d.mode == 1) { if (np >= 1216) col = -1; else if (np >= 1152) { const int i = np - 1152; col = 1152 + (i >> 1) + 32 * (i & 1); } }
;     else if (d.mode == 2) { const int h = np / 192, dd = np % 192; if (dd >= 128) { const int i = dd - 128; col = 192 * h + 128 + (i >> 1) + 32 * (i & 1); } }
;     else if (d.mode == 3) { col = (np >> 8) * 128 + (np & 127); if ((np >> 7) & 1) s = d.src2; }
; #pragma unroll
;     for (int i = 0; i < 8; ++i) { const int kk = (tid >> 6) + 8 * i; float x = 0.f;
;         if (col >= 0) { x = s[(size_t)(d.k0 + kk) * d.ld_src + col]; if (d.rs) x *= d.rs[d.k0 + kk]; if (d.mode == 2) x *= QSCALE * 8.0f; }
;         v[i] = x; }
; }
.LBB0_802:
	v_add_u32_e32 v0, 48, v27
	s_movk_i32 s14, 0x2c00
	s_waitcnt vmcnt(0) lgkmcnt(0)
	v_mad_i64_i32 v[2:3], s[12:13], v0, s14, v[28:29]
	v_add_u32_e32 v0, 56, v27
	v_mad_i64_i32 v[4:5], s[12:13], v0, s14, v[28:29]
	global_load_dword v24, v[2:3], off
	global_load_dword v0, v[4:5], off
	s_waitcnt vmcnt(0) lgkmcnt(0)
	v_mov_b64_e32 v[2:3], v[18:19]
	v_mov_b64_e32 v[8:9], v[24:25]
	v_mov_b64_e32 v[4:5], v[20:21]
	v_mov_b64_e32 v[6:7], v[22:23]
	v_mov_b32_e32 v9, v0
	s_branch .LBB0_784

; __device__ __forceinline__ void tr_load(const TrDesc& d, int tid, float (&v)[8]) {
;     const int nn = tid & 63, np = d.n0 + nn; int col = np; const float* s = d.src;
;     if (d.mode == 1) { if (np >= 1216) col = -1; else if (np >= 1152) { const int i = np - 1152; col = 1152 + (i >> 1) + 32 * (i & 1); } }
;     else if (d.mode == 2) { const int h = np / 192, dd = np % 192; if (dd >= 128) { const int i = dd - 128; col = 192 * h + 128 + (i >> 1) + 32 * (i & 1); } }
;     else if (d.mode == 3) { col = (np >> 8) * 128 + (np & 127); if ((np >> 7) & 1) s = d.src2; }
; #pragma unroll
;     for (int i = 0; i < 8; ++i) { const int kk = (tid >> 6) + 8 * i; float x = 0.f;
;         if (col >= 0) { x = s[(size_t)(d.k0 + kk) * d.ld_src + col]; if (d.rs) x *= d.rs[d.k0 + kk]; if (d.mode == 2) x *= QSCALE * 8.0f; }
;         v[i] = x; }
; }
.LBB0_931:
	s_cmp_lg_u64 s[10:11], 0
	v_ashrrev_i32_e32 v2, 6, v14
	v_lshl_add_u64 v[12:13], v[0:1], 2, s[6:7]
	s_cselect_b64 s[6:7], -1, 0
	v_cmp_gt_i32_e64 s[8:9], 0, v0
	v_cmp_lt_i32_e32 vcc, -1, v0
	v_add_u32_e32 v10, s88, v2
	v_mov_b32_e32 v2, 0
	v_cndmask_b32_e64 v0, 0, 1, s[6:7]
	v_ashrrev_i32_e32 v11, 31, v10
	v_cmp_ne_u32_e64 s[6:7], 1, v0
	s_waitcnt lgkmcnt(0)
	v_mov_b32_e32 v3, v2
	s_and_saveexec_b64 s[14:15], vcc
	s_cbranch_execz .LBB0_952
	v_mul_lo_u32 v0, s13, v10
	v_mul_lo_u32 v4, s12, v11
	v_mad_u64_u32 v[2:3], s[16:17], s12, v10, 0
	v_add3_u32 v3, v3, v4, v0
	v_lshl_add_u64 v[2:3], v[2:3], 2, v[12:13]
	flat_load_dword v0, v[2:3]
	s_and_b64 vcc, exec, s[6:7]
	v_lshl_add_u64 v[2:3], v[10:11], 2, s[10:11]
	s_cbranch_vccnz .LBB0_934
	global_load_dword v4, v[2:3], off
	s_waitcnt vmcnt(0) lgkmcnt(0)
	v_mul_f32_e32 v0, v0, v4
.LBB0_934:
	v_add_u32_e32 v4, 8, v10
	v_ashrrev_i32_e32 v5, 31, v4
	v_mul_lo_u32 v6, s12, v5
	v_mul_lo_u32 v7, s13, v4
	v_mad_u64_u32 v[4:5], s[16:17], s12, v4, 0
	v_add3_u32 v5, v5, v6, v7
	v_lshl_add_u64 v[4:5], v[4:5], 2, v[12:13]
	flat_load_dword v4, v[4:5]
	s_and_b64 vcc, exec, s[6:7]
	s_cbranch_vccnz .LBB0_936
	global_load_dword v2, v[2:3], off offset:32
	s_waitcnt vmcnt(0) lgkmcnt(0)
	v_mul_f32_e32 v4, v4, v2

; __device__ __forceinline__ void tr_load(const TrDesc& d, int tid, float (&v)[8]) {
;     const int nn = tid & 63, np = d.n0 + nn; int col = np; const float* s = d.src;
;     if (d.mode == 1) { if (np >= 1216) col = -1; else if (np >= 1152) { const int i = np - 1152; col = 1152 + (i >> 1) + 32 * (i & 1); } }
;     else if (d.mode == 2) { const int h = np / 192, dd = np % 192; if (dd >= 128) { const int i = dd - 128; col = 192 * h + 128 + (i >> 1) + 32 * (i & 1); } }
;     else if (d.mode == 3) { col = (np >> 8) * 128 + (np & 127); if ((np >> 7) & 1) s = d.src2; }
; #pragma unroll
;     for (int i = 0; i < 8; ++i) { const int kk = (tid >> 6) + 8 * i; float x = 0.f;
;         if (col >= 0) { x = s[(size_t)(d.k0 + kk) * d.ld_src + col]; if (d.rs) x *= d.rs[d.k0 + kk]; if (d.mode == 2) x *= QSCALE * 8.0f; }
;         v[i] = x; }
; }
.LBB0_938:
	v_add_u32_e32 v0, 16, v10
	v_ashrrev_i32_e32 v4, 31, v0
	v_mul_lo_u32 v7, s12, v4
	v_mul_lo_u32 v9, s13, v0
	v_mad_u64_u32 v[4:5], s[16:17], s12, v0, 0
	v_add3_u32 v5, v5, v7, v9
	v_lshl_add_u64 v[4:5], v[4:5], 2, v[12:13]
	flat_load_dword v0, v[4:5]
	s_and_b64 vcc, exec, s[6:7]
	s_cbranch_vccnz .LBB0_940
	v_lshl_add_u64 v[4:5], v[10:11], 2, s[10:11]
	global_load_dword v4, v[4:5], off offset:64
	s_waitcnt vmcnt(0) lgkmcnt(0)
	v_mul_f32_e32 v0, v0, v4
.LBB0_940:
	v_add_u32_e32 v4, 24, v10
	v_ashrrev_i32_e32 v5, 31, v4
	v_mul_lo_u32 v7, s12, v5
	v_mul_lo_u32 v9, s13, v4
	v_mad_u64_u32 v[4:5], s[16:17], s12, v4, 0
	v_add3_u32 v5, v5, v7, v9
	v_lshl_add_u64 v[4:5], v[4:5], 2, v[12:13]
	flat_load_dword v5, v[4:5]
	s_and_b64 vcc, exec, s[6:7]
	s_cbranch_vccnz .LBB0_942
	v_lshl_add_u64 v[18:19], v[10:11], 2, s[10:11]
	global_load_dword v4, v[18:19], off offset:96
	s_waitcnt vmcnt(0) lgkmcnt(0)
	v_mul_f32_e32 v5, v5, v4

; __device__ __forceinline__ void tr_load(const TrDesc& d, int tid, float (&v)[8]) {
;     const int nn = tid & 63, np = d.n0 + nn; int col = np; const float* s = d.src;
;     if (d.mode == 1) { if (np >= 1216) col = -1; else if (np >= 1152) { const int i = np - 1152; col = 1152 + (i >> 1) + 32 * (i & 1); } }
;     else if (d.mode == 2) { const int h = np / 192, dd = np % 192; if (dd >= 128) { const int i = dd - 128; col = 192 * h + 128 + (i >> 1) + 32 * (i & 1); } }
;     else if (d.mode == 3) { col = (np >> 8) * 128 + (np & 127); if ((np >> 7) & 1) s = d.src2; }
; #pragma unroll
;     for (int i = 0; i < 8; ++i) { const int kk = (tid >> 6) + 8 * i; float x = 0.f;
;         if (col >= 0) { x = s[(size_t)(d.k0 + kk) * d.ld_src + col]; if (d.rs) x *= d.rs[d.k0 + kk]; if (d.mode == 2) x *= QSCALE * 8.0f; }
;         v[i] = x; }
; }
.LBB0_944:
	v_add_u32_e32 v0, 32, v10
	v_ashrrev_i32_e32 v6, 31, v0
	v_mul_lo_u32 v9, s12, v6
	v_mul_lo_u32 v15, s13, v0
	v_mad_u64_u32 v[6:7], s[16:17], s12, v0, 0
	v_add3_u32 v7, v7, v9, v15
	v_lshl_add_u64 v[6:7], v[6:7], 2, v[12:13]
	flat_load_dword v0, v[6:7]
	s_and_b64 vcc, exec, s[6:7]
	s_cbranch_vccnz .LBB0_946
	v_lshl_add_u64 v[6:7], v[10:11], 2, s[10:11]
	global_load_dword v6, v[6:7], off offset:128
	s_waitcnt vmcnt(0) lgkmcnt(0)
	v_mul_f32_e32 v0, v0, v6
.LBB0_946:
	v_add_u32_e32 v6, 40, v10
	v_ashrrev_i32_e32 v7, 31, v6
	v_mul_lo_u32 v9, s12, v7
	v_mul_lo_u32 v15, s13, v6
	v_mad_u64_u32 v[6:7], s[16:17], s12, v6, 0
	v_add3_u32 v7, v7, v9, v15
	v_lshl_add_u64 v[6:7], v[6:7], 2, v[12:13]
	flat_load_dword v7, v[6:7]
	s_and_b64 vcc, exec, s[6:7]
	s_cbranch_vccnz .LBB0_948
	v_lshl_add_u64 v[18:19], v[10:11], 2, s[10:11]
	global_load_dword v6, v[18:19], off offset:160
	s_waitcnt vmcnt(0) lgkmcnt(0)
	v_mul_f32_e32 v7, v7, v6

; __device__ __forceinline__ void tr_load(const TrDesc& d, int tid, float (&v)[8]) {
;     const int nn = tid & 63, np = d.n0 + nn; int col = np; const float* s = d.src;
;     if (d.mode == 1) { if (np >= 1216) col = -1; else if (np >= 1152) { const int i = np - 1152; col = 1152 + (i >> 1) + 32 * (i & 1); } }
;     else if (d.mode == 2) { const int h = np / 192, dd = np % 192; if (dd >= 128) { const int i = dd - 128; col = 192 * h + 128 + (i >> 1) + 32 * (i & 1); } }
;     else if (d.mode == 3) { col = (np >> 8) * 128 + (np & 127); if ((np >> 7) & 1) s = d.src2; }
; #pragma unroll
;     for (int i = 0; i < 8; ++i) { const int kk = (tid >> 6) + 8 * i; float x = 0.f;
;         if (col >= 0) { x = s[(size_t)(d.k0 + kk) * d.ld_src + col]; if (d.rs) x *= d.rs[d.k0 + kk]; if (d.mode == 2) x *= QSCALE * 8.0f; }
;         v[i] = x; }
; }
.LBB0_958:
	v_add_u32_e32 v0, 48, v10
	v_ashrrev_i32_e32 v8, 31, v0
	v_mul_lo_u32 v15, s12, v8
	v_mul_lo_u32 v17, s13, v0
	v_mad_u64_u32 v[8:9], s[14:15], s12, v0, 0
	v_add3_u32 v9, v9, v15, v17
	v_lshl_add_u64 v[8:9], v[8:9], 2, v[12:13]
	flat_load_dword v0, v[8:9]
	s_and_b64 vcc, exec, s[6:7]
	s_cbranch_vccnz .LBB0_960
	v_lshl_add_u64 v[8:9], v[10:11], 2, s[10:11]
	global_load_dword v8, v[8:9], off offset:192
	s_waitcnt vmcnt(0) lgkmcnt(0)
	v_mul_f32_e32 v0, v0, v8
.LBB0_960:
	v_add_u32_e32 v8, 56, v10
	v_ashrrev_i32_e32 v9, 31, v8
	v_mul_lo_u32 v15, s12, v9
	v_mul_lo_u32 v17, s13, v8
	v_mad_u64_u32 v[8:9], s[12:13], s12, v8, 0
	v_add3_u32 v9, v9, v15, v17
	v_lshl_add_u64 v[8:9], v[8:9], 2, v[12:13]
	flat_load_dword v9, v[8:9]
	s_and_b64 vcc, exec, s[6:7]
	s_cbranch_vccnz .LBB0_962
	v_lshl_add_u64 v[10:11], v[10:11], 2, s[10:11]
	global_load_dword v8, v[10:11], off offset:224
	s_waitcnt vmcnt(0) lgkmcnt(0)
	v_mul_f32_e32 v9, v9, v8

; __device__ __forceinline__ void tr_load(const TrDesc& d, int tid, float (&v)[8]) {
;     const int nn = tid & 63, np = d.n0 + nn; int col = np; const float* s = d.src;
;     if (d.mode == 1) { if (np >= 1216) col = -1; else if (np >= 1152) { const int i = np - 1152; col = 1152 + (i >> 1) + 32 * (i & 1); } }
;     else if (d.mode == 2) { const int h = np / 192, dd = np % 192; if (dd >= 128) { const int i = dd - 128; col = 192 * h + 128 + (i >> 1) + 32 * (i & 1); } }
;     else if (d.mode == 3) { col = (np >> 8) * 128 + (np & 127); if ((np >> 7) & 1) s = d.src2; }
; #pragma unroll
;     for (int i = 0; i < 8; ++i) { const int kk = (tid >> 6) + 8 * i; float x = 0.f;
;         if (col >= 0) { x = s[(size_t)(d.k0 + kk) * d.ld_src + col]; if (d.rs) x *= d.rs[d.k0 + kk]; if (d.mode == 2) x *= QSCALE * 8.0f; }
;         v[i] = x; }
; }
.LBB0_988:
	s_cmp_lg_u64 s[12:13], 0
	v_cmp_gt_i32_e64 s[6:7], 0, v0
	s_cselect_b64 s[18:19], -1, 0
	s_and_saveexec_b64 s[16:17], s[6:7]
	s_xor_b64 s[16:17], exec, s[16:17]
	v_mov_b32_e32 v2, s89
	s_or_saveexec_b64 s[16:17], s[16:17]
	v_add_u32_e32 v12, s41, v17
	v_lshl_add_u64 v[14:15], v[0:1], 2, s[4:5]
	v_cndmask_b32_e64 v0, 0, 1, s[18:19]
	v_mov_b32_e32 v3, 0
	v_ashrrev_i32_e32 v13, 31, v12
	v_cmp_ne_u32_e64 s[4:5], 1, v0
	s_xor_b64 exec, exec, s[16:17]
	s_cbranch_execz .LBB0_1009
	v_mul_lo_u32 v0, s15, v12
	v_mul_lo_u32 v4, s14, v13
	v_mad_u64_u32 v[2:3], s[18:19], s14, v12, 0
	v_add3_u32 v3, v3, v4, v0
	v_lshl_add_u64 v[2:3], v[2:3], 2, v[14:15]
	flat_load_dword v0, v[2:3]
	s_and_b64 vcc, exec, s[4:5]
	v_lshl_add_u64 v[2:3], v[12:13], 2, s[12:13]
	s_cbranch_vccnz .LBB0_993
	global_load_dword v4, v[2:3], off
	s_waitcnt vmcnt(0) lgkmcnt(0)
	v_mul_f32_e32 v0, v0, v4
.LBB0_993:
	v_add_u32_e32 v4, 8, v12
	v_ashrrev_i32_e32 v5, 31, v4
	v_mul_lo_u32 v6, s14, v5
	v_mul_lo_u32 v7, s15, v4
	v_mad_u64_u32 v[4:5], s[18:19], s14, v4, 0
	v_add3_u32 v5, v5, v6, v7
	v_lshl_add_u64 v[4:5], v[4:5], 2, v[14:15]
	flat_load_dword v4, v[4:5]
	s_and_b64 vcc, exec, s[4:5]
	s_cbranch_vccnz .LBB0_995
	global_load_dword v2, v[2:3], off offset:32
	s_waitcnt vmcnt(0) lgkmcnt(0)
	v_mul_f32_e32 v4, v4, v2

; __device__ __forceinline__ void tr_load(const TrDesc& d, int tid, float (&v)[8]) {
;     const int nn = tid & 63, np = d.n0 + nn; int col = np; const float* s = d.src;
;     if (d.mode == 1) { if (np >= 1216) col = -1; else if (np >= 1152) { const int i = np - 1152; col = 1152 + (i >> 1) + 32 * (i & 1); } }
;     else if (d.mode == 2) { const int h = np / 192, dd = np % 192; if (dd >= 128) { const int i = dd - 128; col = 192 * h + 128 + (i >> 1) + 32 * (i & 1); } }
;     else if (d.mode == 3) { col = (np >> 8) * 128 + (np & 127); if ((np >> 7) & 1) s = d.src2; }
; #pragma unroll
;     for (int i = 0; i < 8; ++i) { const int kk = (tid >> 6) + 8 * i; float x = 0.f;
;         if (col >= 0) { x = s[(size_t)(d.k0 + kk) * d.ld_src + col]; if (d.rs) x *= d.rs[d.k0 + kk]; if (d.mode == 2) x *= QSCALE * 8.0f; }
;         v[i] = x; }
; }
.LBB0_997:
	v_add_u32_e32 v0, 16, v12
	v_ashrrev_i32_e32 v4, 31, v0
	v_mul_lo_u32 v7, s14, v4
	v_mul_lo_u32 v9, s15, v0
	v_mad_u64_u32 v[4:5], s[18:19], s14, v0, 0
	v_add3_u32 v5, v5, v7, v9
	v_lshl_add_u64 v[4:5], v[4:5], 2, v[14:15]
	flat_load_dword v0, v[4:5]
	s_and_b64 vcc, exec, s[4:5]
	s_cbranch_vccnz .LBB0_999
	v_lshl_add_u64 v[4:5], v[12:13], 2, s[12:13]
	global_load_dword v4, v[4:5], off offset:64
	s_waitcnt vmcnt(0) lgkmcnt(0)
	v_mul_f32_e32 v0, v0, v4
.LBB0_999:
	v_add_u32_e32 v4, 24, v12
	v_ashrrev_i32_e32 v5, 31, v4
	v_mul_lo_u32 v7, s14, v5
	v_mul_lo_u32 v9, s15, v4
	v_mad_u64_u32 v[4:5], s[18:19], s14, v4, 0
	v_add3_u32 v5, v5, v7, v9
	v_lshl_add_u64 v[4:5], v[4:5], 2, v[14:15]
	flat_load_dword v5, v[4:5]
	s_and_b64 vcc, exec, s[4:5]
	s_cbranch_vccnz .LBB0_1001
	v_lshl_add_u64 v[22:23], v[12:13], 2, s[12:13]
	global_load_dword v4, v[22:23], off offset:96
	s_waitcnt vmcnt(0) lgkmcnt(0)
	v_mul_f32_e32 v5, v5, v4

; __device__ __forceinline__ void tr_load(const TrDesc& d, int tid, float (&v)[8]) {
;     const int nn = tid & 63, np = d.n0 + nn; int col = np; const float* s = d.src;
;     if (d.mode == 1) { if (np >= 1216) col = -1; else if (np >= 1152) { const int i = np - 1152; col = 1152 + (i >> 1) + 32 * (i & 1); } }
;     else if (d.mode == 2) { const int h = np / 192, dd = np % 192; if (dd >= 128) { const int i = dd - 128; col = 192 * h + 128 + (i >> 1) + 32 * (i & 1); } }
;     else if (d.mode == 3) { col = (np >> 8) * 128 + (np & 127); if ((np >> 7) & 1) s = d.src2; }
; #pragma unroll
;     for (int i = 0; i < 8; ++i) { const int kk = (tid >> 6) + 8 * i; float x = 0.f;
;         if (col >= 0) { x = s[(size_t)(d.k0 + kk) * d.ld_src + col]; if (d.rs) x *= d.rs[d.k0 + kk]; if (d.mode == 2) x *= QSCALE * 8.0f; }
;         v[i] = x; }
; }
.LBB0_1003:
	v_add_u32_e32 v0, 32, v12
	v_ashrrev_i32_e32 v6, 31, v0
	v_mul_lo_u32 v9, s14, v6
	v_mul_lo_u32 v11, s15, v0
	v_mad_u64_u32 v[6:7], s[18:19], s14, v0, 0
	v_add3_u32 v7, v7, v9, v11
	v_lshl_add_u64 v[6:7], v[6:7], 2, v[14:15]
	flat_load_dword v0, v[6:7]
	s_and_b64 vcc, exec, s[4:5]
	s_cbranch_vccnz .LBB0_1005
	v_lshl_add_u64 v[6:7], v[12:13], 2, s[12:13]
	global_load_dword v6, v[6:7], off offset:128
	s_waitcnt vmcnt(0) lgkmcnt(0)
	v_mul_f32_e32 v0, v0, v6
.LBB0_1005:
	v_add_u32_e32 v6, 40, v12
	v_ashrrev_i32_e32 v7, 31, v6
	v_mul_lo_u32 v9, s14, v7
	v_mul_lo_u32 v11, s15, v6
	v_mad_u64_u32 v[6:7], s[18:19], s14, v6, 0
	v_add3_u32 v7, v7, v9, v11
	v_lshl_add_u64 v[6:7], v[6:7], 2, v[14:15]
	flat_load_dword v7, v[6:7]
	s_and_b64 vcc, exec, s[4:5]
	s_cbranch_vccnz .LBB0_1007
	v_lshl_add_u64 v[22:23], v[12:13], 2, s[12:13]
	global_load_dword v6, v[22:23], off offset:160
	s_waitcnt vmcnt(0) lgkmcnt(0)
	v_mul_f32_e32 v7, v7, v6

; __device__ __forceinline__ void tr_load(const TrDesc& d, int tid, float (&v)[8]) {
;     const int nn = tid & 63, np = d.n0 + nn; int col = np; const float* s = d.src;
;     if (d.mode == 1) { if (np >= 1216) col = -1; else if (np >= 1152) { const int i = np - 1152; col = 1152 + (i >> 1) + 32 * (i & 1); } }
;     else if (d.mode == 2) { const int h = np / 192, dd = np % 192; if (dd >= 128) { const int i = dd - 128; col = 192 * h + 128 + (i >> 1) + 32 * (i & 1); } }
;     else if (d.mode == 3) { col = (np >> 8) * 128 + (np & 127); if ((np >> 7) & 1) s = d.src2; }
; #pragma unroll
;     for (int i = 0; i < 8; ++i) { const int kk = (tid >> 6) + 8 * i; float x = 0.f;
;         if (col >= 0) { x = s[(size_t)(d.k0 + kk) * d.ld_src + col]; if (d.rs) x *= d.rs[d.k0 + kk]; if (d.mode == 2) x *= QSCALE * 8.0f; }
;         v[i] = x; }
; }
.LBB0_1015:
	v_add_u32_e32 v0, 48, v12
	v_ashrrev_i32_e32 v8, 31, v0
	v_mul_lo_u32 v11, s14, v8
	v_mul_lo_u32 v21, s15, v0
	v_mad_u64_u32 v[8:9], s[16:17], s14, v0, 0
	v_add3_u32 v9, v9, v11, v21
	v_lshl_add_u64 v[8:9], v[8:9], 2, v[14:15]
	flat_load_dword v0, v[8:9]
	s_and_b64 vcc, exec, s[4:5]
	s_cbranch_vccnz .LBB0_1017
	v_lshl_add_u64 v[8:9], v[12:13], 2, s[12:13]
	global_load_dword v8, v[8:9], off offset:192
	s_waitcnt vmcnt(0) lgkmcnt(0)
	v_mul_f32_e32 v0, v0, v8
.LBB0_1017:
	v_add_u32_e32 v8, 56, v12
	v_ashrrev_i32_e32 v9, 31, v8
	v_mul_lo_u32 v11, s14, v9
	v_mul_lo_u32 v21, s15, v8
	v_mad_u64_u32 v[8:9], s[14:15], s14, v8, 0
	v_add3_u32 v9, v9, v11, v21
	v_lshl_add_u64 v[8:9], v[8:9], 2, v[14:15]
	flat_load_dword v9, v[8:9]
	s_and_b64 vcc, exec, s[4:5]
	s_cbranch_vccnz .LBB0_964
	v_lshl_add_u64 v[12:13], v[12:13], 2, s[12:13]
	global_load_dword v8, v[12:13], off offset:224
	s_waitcnt vmcnt(0) lgkmcnt(0)
	v_mul_f32_e32 v9, v9, v8
	s_branch .LBB0_964

; __device__ __forceinline__ void conv_weights_A(const Params& p, int l, LAS float* scr) {
;     ...
;         else { const int g = (k0 - 256) >> 6, c = (k0 - 256) & 63; const float* wp = w_pool + (g * 64 + c) * 64; const float* sc = psc + 64 * g; const float* wo = w_out + (size_t)(256 + 64 * g) * DM + n;
; #pragma unroll 32
;                for (int j = 0; j < 64; ++j) { const float bv = sc[j] * wo[(size_t)j * DM]; a0 += wp[j] * bv; a1 += wp[64 + j] * bv; a2 += wp[128 + j] * bv; a3 += wp[192 + j] * bv; } }
.LBB0_1026:
	v_add_co_u32_e32 v8, vcc, 0xfffe1000, v26
	v_lshl_add_u64 v[2:3], v[24:25], 0, s[8:9]
	s_nop 0
	v_addc_co_u32_e32 v9, vcc, -1, v27, vcc
	v_lshl_add_u64 v[18:19], v[22:23], 0, s[8:9]
	global_load_dwordx4 v[4:7], v[2:3], off
	global_load_dword v0, v[8:9], off
	s_nop 0
	global_load_dwordx4 v[8:11], v[18:19], off
	global_load_dwordx4 v[32:35], v[18:19], off offset:256
	s_add_u32 s8, s8, 0x80
	s_addc_u32 s9, s9, 0
	s_cmpk_lg_i32 s8, 0x100
	s_waitcnt vmcnt(0) lgkmcnt(0)
	v_mov_b32_e32 v12, v8
	v_mul_f32_e32 v0, v4, v0
	v_mov_b32_e32 v13, v32
	v_pk_fma_f32 v[12:13], v[0:1], v[12:13], v[36:37] op_sel_hi:[0,1,1]
	global_load_dwordx4 v[36:39], v[18:19], off offset:512
	global_load_dwordx4 v[40:43], v[18:19], off offset:768
	v_mov_b32_e32 v32, v9
	s_waitcnt vmcnt(0) lgkmcnt(0)
	v_mov_b32_e32 v16, v36
	v_mov_b32_e32 v17, v40
	v_pk_fma_f32 v[14:15], v[0:1], v[16:17], v[14:15] op_sel_hi:[0,1,1]
	v_add_co_u32_e32 v16, vcc, s19, v26
	v_mov_b32_e32 v40, v37
	s_nop 0
	v_addc_co_u32_e32 v17, vcc, -1, v27, vcc
	global_load_dword v0, v[16:17], off
	s_waitcnt vmcnt(0) lgkmcnt(0)
	v_mul_f32_e32 v0, v5, v0
	v_pk_fma_f32 v[4:5], v[0:1], v[32:33], v[12:13] op_sel_hi:[0,1,1]
	v_add_co_u32_e32 v12, vcc, s24, v26
	v_pk_fma_f32 v[8:9], v[0:1], v[40:41], v[14:15] op_sel_hi:[0,1,1]
	s_nop 0
	v_addc_co_u32_e32 v13, vcc, -1, v27, vcc
	global_load_dword v0, v[12:13], off
	v_mov_b32_e32 v12, v10
	v_mov_b32_e32 v13, v34
	v_mov_b32_e32 v34, v11
	s_waitcnt vmcnt(0) lgkmcnt(0)
	v_mul_f32_e32 v0, v6, v0
	v_pk_fma_f32 v[4:5], v[0:1], v[12:13], v[4:5] op_sel_hi:[0,1,1]
	v_mov_b32_e32 v12, v38
	v_mov_b32_e32 v13, v42
	v_pk_fma_f32 v[8:9], v[0:1], v[12:13], v[8:9] op_sel_hi:[0,1,1]
	v_add_co_u32_e32 v12, vcc, s25, v26
	v_mov_b32_e32 v42, v39
	s_nop 0
	v_addc_co_u32_e32 v13, vcc, -1, v27, vcc
	global_load_dword v0, v[12:13], off
	s_waitcnt vmcnt(0) lgkmcnt(0)
	v_mul_f32_e32 v0, v7, v0
	v_pk_fma_f32 v[20:21], v[0:1], v[42:43], v[8:9] op_sel_hi:[0,1,1]
	v_add_co_u32_e32 v8, vcc, s68, v26
	v_pk_fma_f32 v[16:17], v[0:1], v[34:35], v[4:5] op_sel_hi:[0,1,1]
	s_nop 0
	v_addc_co_u32_e32 v9, vcc, -1, v27, vcc
	global_load_dwordx4 v[4:7], v[2:3], off offset:16
	global_load_dword v0, v[8:9], off
	s_nop 0
	global_load_dwordx4 v[8:11], v[18:19], off offset:16
	global_load_dwordx4 v[12:15], v[18:19], off offset:272
	global_load_dwordx4 v[32:35], v[18:19], off offset:528
	global_load_dwordx4 v[36:39], v[18:19], off offset:784
	s_waitcnt vmcnt(0) lgkmcnt(0)
	v_mov_b32_e32 v28, v8
	v_mul_f32_e32 v0, v4, v0
	v_mov_b32_e32 v29, v12
	v_pk_fma_f32 v[16:17], v[0:1], v[28:29], v[16:17] op_sel_hi:[0,1,1]
	v_mov_b32_e32 v28, v32
	v_mov_b32_e32 v29, v36
	v_pk_fma_f32 v[20:21], v[0:1], v[28:29], v[20:21] op_sel_hi:[0,1,1]
	v_add_co_u32_e32 v28, vcc, s69, v26
	v_mov_b32_e32 v12, v9
	s_nop 0
	v_addc_co_u32_e32 v29, vcc, -1, v27, vcc
	global_load_dword v0, v[28:29], off
	v_mov_b32_e32 v36, v33
	s_waitcnt vmcnt(0) lgkmcnt(0)
	v_mul_f32_e32 v0, v5, v0
	v_pk_fma_f32 v[4:5], v[0:1], v[12:13], v[16:17] op_sel_hi:[0,1,1]
	v_add_co_u32_e32 v12, vcc, s70, v26
	v_pk_fma_f32 v[8:9], v[0:1], v[36:37], v[20:21] op_sel_hi:[0,1,1]
	s_nop 0
	v_addc_co_u32_e32 v13, vcc, -1, v27, vcc
	global_load_dword v0, v[12:13], off
	v_mov_b32_e32 v12, v10
	v_mov_b32_e32 v13, v14
	v_mov_b32_e32 v14, v11
	s_waitcnt vmcnt(0) lgkmcnt(0)
	v_mul_f32_e32 v0, v6, v0
	v_pk_fma_f32 v[4:5], v[0:1], v[12:13], v[4:5] op_sel_hi:[0,1,1]
	v_mov_b32_e32 v12, v34
	v_mov_b32_e32 v13, v38
	v_pk_fma_f32 v[8:9], v[0:1], v[12:13], v[8:9] op_sel_hi:[0,1,1]
	v_add_co_u32_e32 v12, vcc, s71, v26
	v_mov_b32_e32 v38, v35
	s_nop 0
	v_addc_co_u32_e32 v13, vcc, -1, v27, vcc
	global_load_dword v0, v[12:13], off
	s_waitcnt vmcnt(0) lgkmcnt(0)
	v_mul_f32_e32 v0, v7, v0
	v_pk_fma_f32 v[20:21], v[0:1], v[38:39], v[8:9] op_sel_hi:[0,1,1]
	v_add_co_u32_e32 v8, vcc, s72, v26
	v_pk_fma_f32 v[16:17], v[0:1], v[14:15], v[4:5] op_sel_hi:[0,1,1]
	s_nop 0
	v_addc_co_u32_e32 v9, vcc, -1, v27, vcc
	global_load_dwordx4 v[4:7], v[2:3], off offset:32
	global_load_dword v0, v[8:9], off
	s_nop 0
	global_load_dwordx4 v[8:11], v[18:19], off offset:32
	global_load_dwordx4 v[12:15], v[18:19], off offset:288
	global_load_dwordx4 v[32:35], v[18:19], off offset:544
	global_load_dwordx4 v[36:39], v[18:19], off offset:800
	s_waitcnt vmcnt(0) lgkmcnt(0)
	v_mov_b32_e32 v28, v8
	v_mul_f32_e32 v0, v4, v0
	v_mov_b32_e32 v29, v12
	v_pk_fma_f32 v[16:17], v[0:1], v[28:29], v[16:17] op_sel_hi:[0,1,1]
	v_mov_b32_e32 v28, v32
	v_mov_b32_e32 v29, v36
	v_pk_fma_f32 v[20:21], v[0:1], v[28:29], v[20:21] op_sel_hi:[0,1,1]
	v_add_co_u32_e32 v28, vcc, s73, v26
	v_mov_b32_e32 v12, v9
	s_nop 0
	v_addc_co_u32_e32 v29, vcc, -1, v27, vcc
	global_load_dword v0, v[28:29], off
	v_mov_b32_e32 v36, v33
	s_waitcnt vmcnt(0) lgkmcnt(0)
	v_mul_f32_e32 v0, v5, v0
	v_pk_fma_f32 v[4:5], v[0:1], v[12:13], v[16:17] op_sel_hi:[0,1,1]
	v_add_co_u32_e32 v12, vcc, s74, v26
	v_pk_fma_f32 v[8:9], v[0:1], v[36:37], v[20:21] op_sel_hi:[0,1,1]
	s_nop 0
	v_addc_co_u32_e32 v13, vcc, -1, v27, vcc
	global_load_dword v0, v[12:13], off
	v_mov_b32_e32 v12, v10
	v_mov_b32_e32 v13, v14
	v_mov_b32_e32 v14, v11
	s_waitcnt vmcnt(0) lgkmcnt(0)
	v_mul_f32_e32 v0, v6, v0
	v_pk_fma_f32 v[4:5], v[0:1], v[12:13], v[4:5] op_sel_hi:[0,1,1]
	v_mov_b32_e32 v12, v34
	v_mov_b32_e32 v13, v38
	v_pk_fma_f32 v[8:9], v[0:1], v[12:13], v[8:9] op_sel_hi:[0,1,1]
	v_add_co_u32_e32 v12, vcc, s75, v26
	v_mov_b32_e32 v38, v35
	s_nop 0
	v_addc_co_u32_e32 v13, vcc, -1, v27, vcc
	global_load_dword v0, v[12:13], off
	s_waitcnt vmcnt(0) lgkmcnt(0)
; __device__ __forceinline__ void conv_weights_A(const Params& p, int l, LAS float* scr) {
;     ...
;         else { const int g = (k0 - 256) >> 6, c = (k0 - 256) & 63; const float* wp = w_pool + (g * 64 + c) * 64; const float* sc = psc + 64 * g; const float* wo = w_out + (size_t)(256 + 64 * g) * DM + n;
; #pragma unroll 32
;                for (int j = 0; j < 64; ++j) { const float bv = sc[j] * wo[(size_t)j * DM]; a0 += wp[j] * bv; a1 += wp[64 + j] * bv; a2 += wp[128 + j] * bv; a3 += wp[192 + j] * bv; } }
	v_mul_f32_e32 v0, v7, v0
	v_pk_fma_f32 v[20:21], v[0:1], v[38:39], v[8:9] op_sel_hi:[0,1,1]
	v_add_co_u32_e32 v8, vcc, s76, v26
	v_pk_fma_f32 v[16:17], v[0:1], v[14:15], v[4:5] op_sel_hi:[0,1,1]
	s_nop 0
	v_addc_co_u32_e32 v9, vcc, -1, v27, vcc
	global_load_dwordx4 v[4:7], v[2:3], off offset:48
	global_load_dword v0, v[8:9], off
	s_nop 0
	global_load_dwordx4 v[8:11], v[18:19], off offset:48
	global_load_dwordx4 v[12:15], v[18:19], off offset:304
	global_load_dwordx4 v[32:35], v[18:19], off offset:560
	global_load_dwordx4 v[36:39], v[18:19], off offset:816
	s_waitcnt vmcnt(0) lgkmcnt(0)
	v_mov_b32_e32 v28, v8
	v_mul_f32_e32 v0, v4, v0
	v_mov_b32_e32 v29, v12
	v_pk_fma_f32 v[16:17], v[0:1], v[28:29], v[16:17] op_sel_hi:[0,1,1]
	v_mov_b32_e32 v28, v32
	v_mov_b32_e32 v29, v36
	v_pk_fma_f32 v[20:21], v[0:1], v[28:29], v[20:21] op_sel_hi:[0,1,1]
	v_add_co_u32_e32 v28, vcc, s77, v26
	v_mov_b32_e32 v12, v9
	s_nop 0
	v_addc_co_u32_e32 v29, vcc, -1, v27, vcc
	global_load_dword v0, v[28:29], off
	v_mov_b32_e32 v36, v33
	s_waitcnt vmcnt(0) lgkmcnt(0)
	v_mul_f32_e32 v0, v5, v0
	v_pk_fma_f32 v[4:5], v[0:1], v[12:13], v[16:17] op_sel_hi:[0,1,1]
	v_add_co_u32_e32 v12, vcc, s78, v26
	v_pk_fma_f32 v[8:9], v[0:1], v[36:37], v[20:21] op_sel_hi:[0,1,1]
	s_nop 0
	v_addc_co_u32_e32 v13, vcc, -1, v27, vcc
	global_load_dword v0, v[12:13], off
	v_mov_b32_e32 v12, v10
	v_mov_b32_e32 v13, v14
	v_mov_b32_e32 v14, v11
	s_waitcnt vmcnt(0) lgkmcnt(0)
	v_mul_f32_e32 v0, v6, v0
	v_pk_fma_f32 v[4:5], v[0:1], v[12:13], v[4:5] op_sel_hi:[0,1,1]
	v_mov_b32_e32 v12, v34
	v_mov_b32_e32 v13, v38
	v_pk_fma_f32 v[8:9], v[0:1], v[12:13], v[8:9] op_sel_hi:[0,1,1]
	v_add_co_u32_e32 v12, vcc, s79, v26
	v_mov_b32_e32 v38, v35
	s_nop 0
	v_addc_co_u32_e32 v13, vcc, -1, v27, vcc
	global_load_dword v0, v[12:13], off
	s_waitcnt vmcnt(0) lgkmcnt(0)
	v_mul_f32_e32 v0, v7, v0
	v_pk_fma_f32 v[20:21], v[0:1], v[38:39], v[8:9] op_sel_hi:[0,1,1]
	v_add_co_u32_e32 v8, vcc, s80, v26
	v_pk_fma_f32 v[16:17], v[0:1], v[14:15], v[4:5] op_sel_hi:[0,1,1]
	s_nop 0
	v_addc_co_u32_e32 v9, vcc, -1, v27, vcc
	global_load_dwordx4 v[4:7], v[2:3], off offset:64
	global_load_dword v0, v[8:9], off
	s_nop 0
	global_load_dwordx4 v[8:11], v[18:19], off offset:64
	global_load_dwordx4 v[12:15], v[18:19], off offset:320
	global_load_dwordx4 v[32:35], v[18:19], off offset:576
	global_load_dwordx4 v[36:39], v[18:19], off offset:832
	s_waitcnt vmcnt(0) lgkmcnt(0)
	v_mul_f32_e32 v0, v4, v0
	v_mov_b32_e32 v28, v8
	v_mov_b32_e32 v29, v12
	v_pk_fma_f32 v[16:17], v[0:1], v[28:29], v[16:17] op_sel_hi:[0,1,1]
	v_mov_b32_e32 v28, v32
	v_mov_b32_e32 v29, v36
	v_pk_fma_f32 v[20:21], v[0:1], v[28:29], v[20:21] op_sel_hi:[0,1,1]
	v_add_co_u32_e32 v28, vcc, s81, v26
	v_mov_b32_e32 v12, v9
	s_nop 0
	v_addc_co_u32_e32 v29, vcc, -1, v27, vcc
	global_load_dword v0, v[28:29], off
	v_mov_b32_e32 v36, v33
	s_waitcnt vmcnt(0) lgkmcnt(0)
	v_mul_f32_e32 v0, v5, v0
	v_pk_fma_f32 v[4:5], v[0:1], v[12:13], v[16:17] op_sel_hi:[0,1,1]
	v_add_co_u32_e32 v12, vcc, s82, v26
	v_pk_fma_f32 v[8:9], v[0:1], v[36:37], v[20:21] op_sel_hi:[0,1,1]
	s_nop 0
	v_addc_co_u32_e32 v13, vcc, -1, v27, vcc
	global_load_dword v0, v[12:13], off
	v_mov_b32_e32 v12, v10
	v_mov_b32_e32 v13, v14
	v_mov_b32_e32 v14, v11
	s_waitcnt vmcnt(0) lgkmcnt(0)
	v_mul_f32_e32 v0, v6, v0
	v_pk_fma_f32 v[4:5], v[0:1], v[12:13], v[4:5] op_sel_hi:[0,1,1]
	v_mov_b32_e32 v12, v34
	v_mov_b32_e32 v13, v38
	v_pk_fma_f32 v[8:9], v[0:1], v[12:13], v[8:9] op_sel_hi:[0,1,1]
	v_add_co_u32_e32 v12, vcc, s83, v26
	v_mov_b32_e32 v38, v35
	s_nop 0
	v_addc_co_u32_e32 v13, vcc, -1, v27, vcc
	global_load_dword v0, v[12:13], off
	s_waitcnt vmcnt(0) lgkmcnt(0)
	v_mul_f32_e32 v0, v7, v0
	v_pk_fma_f32 v[20:21], v[0:1], v[38:39], v[8:9] op_sel_hi:[0,1,1]
	v_add_co_u32_e32 v8, vcc, s86, v26
	v_pk_fma_f32 v[16:17], v[0:1], v[14:15], v[4:5] op_sel_hi:[0,1,1]
	s_nop 0
	v_addc_co_u32_e32 v9, vcc, -1, v27, vcc
	global_load_dwordx4 v[4:7], v[2:3], off offset:80
	global_load_dword v0, v[8:9], off
	s_nop 0
	global_load_dwordx4 v[8:11], v[18:19], off offset:80
	global_load_dwordx4 v[12:15], v[18:19], off offset:336
	global_load_dwordx4 v[32:35], v[18:19], off offset:592
	global_load_dwordx4 v[36:39], v[18:19], off offset:848
	s_waitcnt vmcnt(0) lgkmcnt(0)
	v_mul_f32_e32 v0, v4, v0
	v_mov_b32_e32 v28, v8
	v_mov_b32_e32 v29, v12
	v_pk_fma_f32 v[16:17], v[0:1], v[28:29], v[16:17] op_sel_hi:[0,1,1]
	v_mov_b32_e32 v28, v32
	v_mov_b32_e32 v29, v36
	v_pk_fma_f32 v[20:21], v[0:1], v[28:29], v[20:21] op_sel_hi:[0,1,1]
	v_add_co_u32_e32 v28, vcc, s87, v26
	v_mov_b32_e32 v12, v9
	s_nop 0
	v_addc_co_u32_e32 v29, vcc, -1, v27, vcc
	global_load_dword v0, v[28:29], off
	v_mov_b32_e32 v36, v33
	s_waitcnt vmcnt(0) lgkmcnt(0)
; __device__ __forceinline__ void conv_weights_A(const Params& p, int l, LAS float* scr) {
;     ...
;         else { const int g = (k0 - 256) >> 6, c = (k0 - 256) & 63; const float* wp = w_pool + (g * 64 + c) * 64; const float* sc = psc + 64 * g; const float* wo = w_out + (size_t)(256 + 64 * g) * DM + n;
; #pragma unroll 32
;                for (int j = 0; j < 64; ++j) { const float bv = sc[j] * wo[(size_t)j * DM]; a0 += wp[j] * bv; a1 += wp[64 + j] * bv; a2 += wp[128 + j] * bv; a3 += wp[192 + j] * bv; } }
	v_mul_f32_e32 v0, v5, v0
	v_pk_fma_f32 v[4:5], v[0:1], v[12:13], v[16:17] op_sel_hi:[0,1,1]
	v_add_co_u32_e32 v12, vcc, s84, v26
	v_pk_fma_f32 v[8:9], v[0:1], v[36:37], v[20:21] op_sel_hi:[0,1,1]
	s_nop 0
	v_addc_co_u32_e32 v13, vcc, -1, v27, vcc
	global_load_dword v0, v[12:13], off
	v_mov_b32_e32 v12, v10
	v_mov_b32_e32 v13, v14
	v_mov_b32_e32 v14, v11
	s_waitcnt vmcnt(0) lgkmcnt(0)
	v_mul_f32_e32 v0, v6, v0
	v_pk_fma_f32 v[4:5], v[0:1], v[12:13], v[4:5] op_sel_hi:[0,1,1]
	v_mov_b32_e32 v12, v34
	v_mov_b32_e32 v13, v38
	v_pk_fma_f32 v[8:9], v[0:1], v[12:13], v[8:9] op_sel_hi:[0,1,1]
	v_add_co_u32_e32 v12, vcc, s85, v26
	v_mov_b32_e32 v38, v35
	s_nop 0
	v_addc_co_u32_e32 v13, vcc, -1, v27, vcc
	global_load_dword v0, v[12:13], off
	s_waitcnt vmcnt(0) lgkmcnt(0)
	v_mul_f32_e32 v0, v7, v0
	v_pk_fma_f32 v[20:21], v[0:1], v[38:39], v[8:9] op_sel_hi:[0,1,1]
	v_add_co_u32_e32 v8, vcc, s97, v26
	v_pk_fma_f32 v[16:17], v[0:1], v[14:15], v[4:5] op_sel_hi:[0,1,1]
	s_nop 0
	v_addc_co_u32_e32 v9, vcc, -1, v27, vcc
	global_load_dwordx4 v[4:7], v[2:3], off offset:96
	global_load_dword v0, v[8:9], off
	s_nop 0
	global_load_dwordx4 v[8:11], v[18:19], off offset:96
	global_load_dwordx4 v[12:15], v[18:19], off offset:352
	global_load_dwordx4 v[32:35], v[18:19], off offset:608
	global_load_dwordx4 v[36:39], v[18:19], off offset:864
	s_waitcnt vmcnt(0) lgkmcnt(0)
	v_mul_f32_e32 v0, v4, v0
	v_mov_b32_e32 v28, v8
	v_mov_b32_e32 v29, v12
	v_pk_fma_f32 v[16:17], v[0:1], v[28:29], v[16:17] op_sel_hi:[0,1,1]
	v_mov_b32_e32 v28, v32
	v_mov_b32_e32 v29, v36
	v_pk_fma_f32 v[20:21], v[0:1], v[28:29], v[20:21] op_sel_hi:[0,1,1]
	v_add_co_u32_e32 v28, vcc, s90, v26
	v_mov_b32_e32 v12, v9
	s_nop 0
	v_addc_co_u32_e32 v29, vcc, -1, v27, vcc
	global_load_dword v0, v[28:29], off
	v_mov_b32_e32 v36, v33
	s_waitcnt vmcnt(0) lgkmcnt(0)
	v_mul_f32_e32 v0, v5, v0
	v_pk_fma_f32 v[4:5], v[0:1], v[12:13], v[16:17] op_sel_hi:[0,1,1]
	v_add_co_u32_e32 v12, vcc, s91, v26
	v_pk_fma_f32 v[8:9], v[0:1], v[36:37], v[20:21] op_sel_hi:[0,1,1]
	s_nop 0
	v_addc_co_u32_e32 v13, vcc, -1, v27, vcc
	global_load_dword v0, v[12:13], off
	v_mov_b32_e32 v12, v10
	v_mov_b32_e32 v13, v14
	v_mov_b32_e32 v14, v11
	s_waitcnt vmcnt(0) lgkmcnt(0)
	v_mul_f32_e32 v0, v6, v0
	v_pk_fma_f32 v[4:5], v[0:1], v[12:13], v[4:5] op_sel_hi:[0,1,1]
	v_mov_b32_e32 v12, v34
	v_mov_b32_e32 v13, v38
	v_pk_fma_f32 v[8:9], v[0:1], v[12:13], v[8:9] op_sel_hi:[0,1,1]
	v_add_co_u32_e32 v12, vcc, s36, v26
	v_mov_b32_e32 v38, v35
	s_nop 0
	v_addc_co_u32_e32 v13, vcc, -1, v27, vcc
	global_load_dword v0, v[12:13], off
	v_add_co_u32_e32 v6, vcc, s37, v26
	s_waitcnt vmcnt(0) lgkmcnt(0)
	v_mul_f32_e32 v0, v7, v0
	v_addc_co_u32_e32 v7, vcc, -1, v27, vcc
	v_pk_fma_f32 v[14:15], v[0:1], v[14:15], v[4:5] op_sel_hi:[0,1,1]
	v_pk_fma_f32 v[28:29], v[0:1], v[38:39], v[8:9] op_sel_hi:[0,1,1]
	global_load_dwordx4 v[2:5], v[2:3], off offset:112
	s_nop 0
	global_load_dword v0, v[6:7], off
	s_nop 0
	global_load_dwordx4 v[6:9], v[18:19], off offset:112
	global_load_dwordx4 v[10:13], v[18:19], off offset:368
	s_waitcnt vmcnt(0) lgkmcnt(0)
	v_mul_f32_e32 v0, v2, v0
	v_mov_b32_e32 v16, v6
	v_mov_b32_e32 v17, v10
	v_pk_fma_f32 v[32:33], v[0:1], v[16:17], v[14:15] op_sel_hi:[0,1,1]
	global_load_dwordx4 v[14:17], v[18:19], off offset:624
	s_nop 0
	global_load_dwordx4 v[18:21], v[18:19], off offset:880
	v_mov_b32_e32 v10, v7
	s_waitcnt vmcnt(0) lgkmcnt(0)
	v_mov_b32_e32 v34, v14
	v_mov_b32_e32 v35, v18
	v_pk_fma_f32 v[28:29], v[0:1], v[34:35], v[28:29] op_sel_hi:[0,1,1]
	v_add_co_u32_e32 v34, vcc, s96, v26
	v_mov_b32_e32 v18, v15
	s_nop 0
	v_addc_co_u32_e32 v35, vcc, -1, v27, vcc
	global_load_dword v0, v[34:35], off
	s_waitcnt vmcnt(0) lgkmcnt(0)
	v_mul_f32_e32 v0, v3, v0
	v_pk_fma_f32 v[2:3], v[0:1], v[10:11], v[32:33] op_sel_hi:[0,1,1]
	v_add_co_u32_e32 v10, vcc, s48, v26
	v_pk_fma_f32 v[6:7], v[0:1], v[18:19], v[28:29] op_sel_hi:[0,1,1]
	s_nop 0
	v_addc_co_u32_e32 v11, vcc, -1, v27, vcc
	global_load_dword v0, v[10:11], off
	v_mov_b32_e32 v10, v8
	v_mov_b32_e32 v11, v12
	v_mov_b32_e32 v12, v9
	s_waitcnt vmcnt(0) lgkmcnt(0)
	v_mul_f32_e32 v0, v4, v0
	v_pk_fma_f32 v[2:3], v[0:1], v[10:11], v[2:3] op_sel_hi:[0,1,1]
	v_mov_b32_e32 v10, v16
	v_mov_b32_e32 v11, v20
	v_pk_fma_f32 v[6:7], v[0:1], v[10:11], v[6:7] op_sel_hi:[0,1,1]
	global_load_dword v0, v[26:27], off
	v_mov_b32_e32 v20, v17
	v_lshl_add_u64 v[26:27], v[26:27], 0, s[94:95]
	s_waitcnt vmcnt(0) lgkmcnt(0)
	v_mul_f32_e32 v0, v5, v0
	v_pk_fma_f32 v[36:37], v[0:1], v[12:13], v[2:3] op_sel_hi:[0,1,1]
	v_pk_fma_f32 v[14:15], v[0:1], v[20:21], v[6:7] op_sel_hi:[0,1,1]
	s_cbranch_scc1 .LBB0_1026

; __device__ __forceinline__ void conv_weights_A(const Params& p, int l, LAS float* scr) {
;     ...
;         if (k0 < 256) { const float* wp = w_pw + k0 * 256; const float* wo = w_out + n;
; #pragma unroll 32
;             for (int j = 0; j < 256; ++j) { const float bv = wo[(size_t)j * DM]; a0 += wp[j] * bv; a1 += wp[256 + j] * bv; a2 += wp[512 + j] * bv; a3 += wp[768 + j] * bv; } }
.LBB0_1029:
	v_add_co_u32_e32 v48, vcc, 0xfffe1000, v32
	v_lshl_add_u64 v[38:39], v[34:35], 0, s[10:11]
	s_nop 0
	v_addc_co_u32_e32 v49, vcc, -1, v33, vcc
	global_load_dwordx4 v[44:47], v[38:39], off
	global_load_dwordx4 v[10:13], v[38:39], off offset:1024
	global_load_dwordx4 v[60:63], v[38:39], off offset:2048
	global_load_dwordx4 v[26:29], v[38:39], off offset:3072
	global_load_dwordx4 v[16:19], v[38:39], off offset:16
	global_load_dwordx4 v[6:9], v[38:39], off offset:1040
	global_load_dwordx4 v[2:5], v[38:39], off offset:2064
	global_load_dwordx4 v[22:25], v[38:39], off offset:3088
	global_load_dword v0, v[48:49], off
	v_add_co_u32_e64 v20, s[0:1], s19, v32
	s_add_u32 s10, s10, 0x80
	s_nop 0
	v_addc_co_u32_e64 v21, s[0:1], -1, v33, s[0:1]
	v_add_co_u32_e64 v52, s[0:1], s24, v32
	s_addc_u32 s11, s11, 0
	s_nop 0
	v_addc_co_u32_e64 v53, s[0:1], -1, v33, s[0:1]
	v_add_co_u32_e64 v54, s[0:1], s25, v32
	s_cmpk_eq_i32 s10, 0x400
	s_nop 0
	v_addc_co_u32_e64 v55, s[0:1], -1, v33, s[0:1]
	v_add_co_u32_e64 v56, s[0:1], s68, v32
	s_waitcnt vmcnt(0) lgkmcnt(0)
	v_mov_b32_e32 v50, v44
	v_addc_co_u32_e64 v57, s[0:1], -1, v33, s[0:1]
	v_add_co_u32_e64 v58, s[0:1], s69, v32
	v_mov_b32_e32 v51, v10
	s_nop 0
	v_addc_co_u32_e64 v59, s[0:1], -1, v33, s[0:1]
	v_add_co_u32_e64 v64, s[0:1], s70, v32
	v_mov_b32_e32 v74, v60
	s_nop 0
	v_addc_co_u32_e64 v65, s[0:1], -1, v33, s[0:1]
	v_add_co_u32_e64 v66, s[0:1], s71, v32
	v_mov_b32_e32 v75, v26
	s_nop 0
	v_addc_co_u32_e64 v67, s[0:1], -1, v33, s[0:1]
	v_add_co_u32_e64 v70, s[0:1], s72, v32
	v_mov_b32_e32 v26, v61
	s_nop 0
	v_addc_co_u32_e64 v71, s[0:1], -1, v33, s[0:1]
	v_mov_b32_e32 v60, v62
	v_mov_b32_e32 v61, v28
	v_mov_b32_e32 v28, v63
	v_pk_fma_f32 v[62:63], v[0:1], v[50:51], v[36:37] op_sel_hi:[0,1,1]
	v_pk_fma_f32 v[14:15], v[0:1], v[74:75], v[14:15] op_sel_hi:[0,1,1]
	global_load_dword v20, v[20:21], off
	s_nop 0
	global_load_dword v74, v[52:53], off
	global_load_dword v76, v[54:55], off
	global_load_dword v78, v[56:57], off
	global_load_dword v80, v[58:59], off
	global_load_dword v82, v[64:65], off
	s_nop 0
	global_load_dword v66, v[66:67], off
	s_nop 0
	global_load_dword v0, v[70:71], off
	v_mov_b32_e32 v10, v45
	v_mov_b32_e32 v72, v46
	v_mov_b32_e32 v73, v12
	v_mov_b32_e32 v12, v47
	v_add_co_u32_e64 v40, s[0:1], s73, v32
	v_add_co_u32_e32 v36, vcc, s77, v32
	s_nop 0
	v_addc_co_u32_e64 v41, s[0:1], -1, v33, s[0:1]
	v_addc_co_u32_e32 v37, vcc, -1, v33, vcc
	v_add_co_u32_e64 v42, s[0:1], s74, v32
	v_add_co_u32_e32 v48, vcc, s78, v32
	s_nop 0
	v_addc_co_u32_e64 v43, s[0:1], -1, v33, s[0:1]
	v_addc_co_u32_e32 v49, vcc, -1, v33, vcc
	v_add_co_u32_e64 v44, s[0:1], s75, v32
	v_add_co_u32_e32 v50, vcc, s79, v32
	s_nop 0
	v_addc_co_u32_e64 v45, s[0:1], -1, v33, s[0:1]
	v_addc_co_u32_e32 v51, vcc, -1, v33, vcc
	v_add_co_u32_e64 v46, s[0:1], s76, v32
	v_add_co_u32_e32 v56, vcc, s80, v32
	s_nop 0
	v_addc_co_u32_e64 v47, s[0:1], -1, v33, s[0:1]
	v_addc_co_u32_e32 v57, vcc, -1, v33, vcc
	v_add_co_u32_e32 v52, vcc, s81, v32
	s_waitcnt vmcnt(0) lgkmcnt(0)
	v_pk_fma_f32 v[10:11], v[20:21], v[10:11], v[62:63] op_sel_hi:[0,1,1]
	v_pk_fma_f32 v[14:15], v[20:21], v[26:27], v[14:15] op_sel_hi:[0,1,1]
	v_pk_fma_f32 v[10:11], v[74:75], v[72:73], v[10:11] op_sel_hi:[0,1,1]
	v_pk_fma_f32 v[14:15], v[74:75], v[60:61], v[14:15] op_sel_hi:[0,1,1]
	v_pk_fma_f32 v[10:11], v[76:77], v[12:13], v[10:11] op_sel_hi:[0,1,1]
	v_mov_b32_e32 v26, v16
	v_mov_b32_e32 v27, v6
	global_load_dwordx4 v[58:61], v[38:39], off offset:32
	v_pk_fma_f32 v[20:21], v[76:77], v[28:29], v[14:15] op_sel_hi:[0,1,1]
	global_load_dwordx4 v[12:15], v[38:39], off offset:1056
	v_mov_b32_e32 v6, v17
	v_mov_b32_e32 v16, v18
	v_mov_b32_e32 v17, v8
	v_mov_b32_e32 v8, v19
	v_mov_b32_e32 v18, v2
	v_mov_b32_e32 v19, v22
	v_mov_b32_e32 v22, v3
	v_mov_b32_e32 v2, v4
	v_mov_b32_e32 v3, v24
	v_mov_b32_e32 v24, v5
	global_load_dwordx4 v[62:65], v[38:39], off offset:2080
	v_pk_fma_f32 v[4:5], v[78:79], v[26:27], v[10:11] op_sel_hi:[0,1,1]
	global_load_dwordx4 v[26:29], v[38:39], off offset:3104
	v_pk_fma_f32 v[10:11], v[78:79], v[18:19], v[20:21] op_sel_hi:[0,1,1]
	v_pk_fma_f32 v[4:5], v[80:81], v[6:7], v[4:5] op_sel_hi:[0,1,1]
	v_pk_fma_f32 v[6:7], v[80:81], v[22:23], v[10:11] op_sel_hi:[0,1,1]
	global_load_dwordx4 v[20:23], v[38:39], off offset:48
	v_pk_fma_f32 v[10:11], v[82:83], v[16:17], v[4:5] op_sel_hi:[0,1,1]
	v_pk_fma_f32 v[2:3], v[82:83], v[2:3], v[6:7] op_sel_hi:[0,1,1]
	global_load_dwordx4 v[4:7], v[38:39], off offset:1072
	global_load_dwordx4 v[16:19], v[38:39], off offset:2096
	v_pk_fma_f32 v[70:71], v[66:67], v[8:9], v[10:11] op_sel_hi:[0,1,1]
	v_pk_fma_f32 v[66:67], v[66:67], v[24:25], v[2:3] op_sel_hi:[0,1,1]
	global_load_dwordx4 v[8:11], v[38:39], off offset:3120
	v_addc_co_u32_e32 v53, vcc, -1, v33, vcc
	v_add_co_u32_e32 v54, vcc, s82, v32
	s_waitcnt vmcnt(0) lgkmcnt(0)
	v_mov_b32_e32 v72, v58
	v_mov_b32_e32 v2, v60
	v_mov_b32_e32 v73, v12
	v_mov_b32_e32 v12, v59
	v_mov_b32_e32 v3, v14
	v_mov_b32_e32 v14, v61
	v_addc_co_u32_e32 v55, vcc, -1, v33, vcc
	v_add_co_u32_e32 v60, vcc, s83, v32
	v_mov_b32_e32 v58, v62
	v_mov_b32_e32 v24, v64
	v_mov_b32_e32 v59, v26
	v_mov_b32_e32 v25, v28
	v_mov_b32_e32 v28, v65
	v_pk_fma_f32 v[64:65], v[0:1], v[72:73], v[70:71] op_sel_hi:[0,1,1]
	v_pk_fma_f32 v[58:59], v[0:1], v[58:59], v[66:67] op_sel_hi:[0,1,1]
	global_load_dword v0, v[40:41], off
	s_nop 0
	global_load_dword v40, v[42:43], off
	s_nop 0
	global_load_dword v44, v[44:45], off
	s_nop 0
	global_load_dword v46, v[46:47], off
	s_nop 0
	global_load_dword v36, v[36:37], off
	s_nop 0
	global_load_dword v48, v[48:49], off
	s_nop 0
	global_load_dword v50, v[50:51], off
	s_nop 0
	global_load_dword v56, v[56:57], off
	v_mov_b32_e32 v26, v63
	v_addc_co_u32_e32 v61, vcc, -1, v33, vcc
	v_mov_b32_e32 v70, v16
	v_mov_b32_e32 v16, v18
	v_add_co_u32_e32 v62, vcc, s86, v32
	v_mov_b32_e32 v71, v8
	s_nop 0
	v_addc_co_u32_e32 v63, vcc, -1, v33, vcc
	v_add_co_u32_e32 v78, vcc, s87, v32
	v_mov_b32_e32 v8, v17
	s_nop 0
	v_addc_co_u32_e32 v79, vcc, -1, v33, vcc
	v_mov_b32_e32 v17, v10
	v_add_co_u32_e32 v66, vcc, s84, v32
	v_mov_b32_e32 v10, v19
	s_nop 0
	v_addc_co_u32_e32 v67, vcc, -1, v33, vcc
	v_add_co_u32_e32 v80, vcc, s85, v32
	s_waitcnt vmcnt(0) lgkmcnt(0)
; __device__ __forceinline__ void conv_weights_A(const Params& p, int l, LAS float* scr) {
;     ...
;         if (k0 < 256) { const float* wp = w_pw + k0 * 256; const float* wo = w_out + n;
; #pragma unroll 32
;             for (int j = 0; j < 256; ++j) { const float bv = wo[(size_t)j * DM]; a0 += wp[j] * bv; a1 += wp[256 + j] * bv; a2 += wp[512 + j] * bv; a3 += wp[768 + j] * bv; } }
	v_pk_fma_f32 v[12:13], v[0:1], v[12:13], v[64:65] op_sel_hi:[0,1,1]
	v_pk_fma_f32 v[26:27], v[0:1], v[26:27], v[58:59] op_sel_hi:[0,1,1]
	v_pk_fma_f32 v[2:3], v[40:41], v[2:3], v[12:13] op_sel_hi:[0,1,1]
	v_pk_fma_f32 v[12:13], v[40:41], v[24:25], v[26:27] op_sel_hi:[0,1,1]
	global_load_dwordx4 v[24:27], v[38:39], off offset:64
	global_load_dwordx4 v[40:43], v[38:39], off offset:1088
	v_pk_fma_f32 v[2:3], v[44:45], v[14:15], v[2:3] op_sel_hi:[0,1,1]
	v_pk_fma_f32 v[28:29], v[44:45], v[28:29], v[12:13] op_sel_hi:[0,1,1]
	global_load_dwordx4 v[12:15], v[38:39], off offset:2112
	v_mov_b32_e32 v44, v20
	v_mov_b32_e32 v45, v4
	v_mov_b32_e32 v4, v21
	v_mov_b32_e32 v64, v22
	v_mov_b32_e32 v65, v6
	v_mov_b32_e32 v6, v23
	global_load_dwordx4 v[20:23], v[38:39], off offset:3136
	global_load_dword v18, v[52:53], off
	s_nop 0
	global_load_dword v52, v[54:55], off
	s_nop 0
	global_load_dword v60, v[60:61], off
	v_pk_fma_f32 v[2:3], v[46:47], v[44:45], v[2:3] op_sel_hi:[0,1,1]
	v_pk_fma_f32 v[28:29], v[46:47], v[70:71], v[28:29] op_sel_hi:[0,1,1]
	v_pk_fma_f32 v[54:55], v[36:37], v[4:5], v[2:3] op_sel_hi:[0,1,1]
	v_pk_fma_f32 v[8:9], v[36:37], v[8:9], v[28:29] op_sel_hi:[0,1,1]
	global_load_dwordx4 v[2:5], v[38:39], off offset:1104
	global_load_dwordx4 v[70:73], v[38:39], off offset:2128
	v_pk_fma_f32 v[28:29], v[48:49], v[64:65], v[54:55] op_sel_hi:[0,1,1]
	global_load_dwordx4 v[44:47], v[38:39], off offset:80
	global_load_dwordx4 v[74:77], v[38:39], off offset:96
	v_pk_fma_f32 v[16:17], v[48:49], v[16:17], v[8:9] op_sel_hi:[0,1,1]
	v_pk_fma_f32 v[28:29], v[50:51], v[6:7], v[28:29] op_sel_hi:[0,1,1]
	global_load_dwordx4 v[6:9], v[38:39], off offset:3152
	v_addc_co_u32_e32 v81, vcc, -1, v33, vcc
	v_add_co_u32_e32 v58, vcc, s97, v32
	v_pk_fma_f32 v[16:17], v[50:51], v[10:11], v[16:17] op_sel_hi:[0,1,1]
	s_nop 0
	v_addc_co_u32_e32 v59, vcc, -1, v33, vcc
	s_waitcnt vmcnt(0) lgkmcnt(0)
	v_mov_b32_e32 v36, v24
	v_mov_b32_e32 v24, v26
	v_mov_b32_e32 v37, v40
	v_mov_b32_e32 v40, v25
	v_mov_b32_e32 v48, v12
	v_mov_b32_e32 v64, v14
	v_mov_b32_e32 v25, v42
	v_mov_b32_e32 v42, v27
	v_mov_b32_e32 v49, v20
	v_mov_b32_e32 v20, v13
	global_load_dwordx4 v[10:13], v[38:39], off offset:1120
	global_load_dword v54, v[62:63], off
	global_load_dword v50, v[78:79], off
	s_nop 0
	global_load_dword v62, v[66:67], off
	global_load_dword v26, v[80:81], off
	global_load_dword v0, v[58:59], off
	v_mov_b32_e32 v65, v22
	v_mov_b32_e32 v22, v15
	v_pk_fma_f32 v[14:15], v[56:57], v[36:37], v[28:29] op_sel_hi:[0,1,1]
	v_pk_fma_f32 v[16:17], v[56:57], v[48:49], v[16:17] op_sel_hi:[0,1,1]
	v_pk_fma_f32 v[14:15], v[18:19], v[40:41], v[14:15] op_sel_hi:[0,1,1]
	v_pk_fma_f32 v[16:17], v[18:19], v[20:21], v[16:17] op_sel_hi:[0,1,1]
	v_pk_fma_f32 v[14:15], v[52:53], v[24:25], v[14:15] op_sel_hi:[0,1,1]
	v_pk_fma_f32 v[24:25], v[52:53], v[64:65], v[16:17] op_sel_hi:[0,1,1]
	v_pk_fma_f32 v[58:59], v[60:61], v[42:43], v[14:15] op_sel_hi:[0,1,1]
	v_pk_fma_f32 v[56:57], v[60:61], v[22:23], v[24:25] op_sel_hi:[0,1,1]
	v_mov_b32_e32 v60, v70
	v_add_co_u32_e32 v70, vcc, s90, v32
	v_mov_b32_e32 v66, v44
	v_mov_b32_e32 v67, v2
	v_mov_b32_e32 v61, v6
	v_mov_b32_e32 v6, v71
	v_addc_co_u32_e32 v71, vcc, -1, v33, vcc
	global_load_dwordx4 v[78:81], v[38:39], off offset:2144
	global_load_dwordx4 v[86:89], v[38:39], off offset:2160
	global_load_dwordx4 v[18:21], v[38:39], off offset:3168
	global_load_dwordx4 v[22:25], v[38:39], off offset:3184
	v_mov_b32_e32 v64, v72
	v_mov_b32_e32 v2, v45
	v_mov_b32_e32 v65, v8
	v_mov_b32_e32 v8, v73
	global_load_dwordx4 v[82:85], v[38:39], off offset:112
	global_load_dwordx4 v[14:17], v[38:39], off offset:1136
	v_mov_b32_e32 v52, v46
	v_mov_b32_e32 v53, v4
	v_mov_b32_e32 v4, v47
	v_mov_b32_e32 v36, v74
	v_mov_b32_e32 v28, v76
	s_waitcnt vmcnt(0) lgkmcnt(0)
	v_mov_b32_e32 v37, v10
	v_pk_fma_f32 v[58:59], v[54:55], v[66:67], v[58:59] op_sel_hi:[0,1,1]
	v_add_co_u32_e32 v66, vcc, s91, v32
	v_pk_fma_f32 v[54:55], v[54:55], v[60:61], v[56:57] op_sel_hi:[0,1,1]
	s_nop 0
	v_addc_co_u32_e32 v67, vcc, -1, v33, vcc
	v_add_co_u32_e32 v56, vcc, s36, v32
	v_pk_fma_f32 v[2:3], v[50:51], v[2:3], v[58:59] op_sel_hi:[0,1,1]
	s_nop 0
	v_addc_co_u32_e32 v57, vcc, -1, v33, vcc
	v_add_co_u32_e32 v72, vcc, s37, v32
	v_pk_fma_f32 v[6:7], v[50:51], v[6:7], v[54:55] op_sel_hi:[0,1,1]
	s_nop 0
	v_addc_co_u32_e32 v73, vcc, -1, v33, vcc
	v_add_co_u32_e32 v50, vcc, s96, v32
	v_pk_fma_f32 v[52:53], v[62:63], v[52:53], v[2:3] op_sel_hi:[0,1,1]
	s_nop 0
	v_addc_co_u32_e32 v51, vcc, -1, v33, vcc
	v_add_co_u32_e32 v2, vcc, s48, v32
	v_pk_fma_f32 v[62:63], v[62:63], v[64:65], v[6:7] op_sel_hi:[0,1,1]
	s_nop 0
	v_addc_co_u32_e32 v3, vcc, -1, v33, vcc
	global_load_dword v60, v[70:71], off
	global_load_dword v58, v[66:67], off
	s_nop 0
	global_load_dword v56, v[56:57], off
	s_nop 0
	global_load_dword v54, v[72:73], off
	s_nop 0
	global_load_dword v50, v[50:51], off
	s_nop 0
	global_load_dword v2, v[2:3], off
	v_mov_b32_e32 v44, v78
	global_load_dword v6, v[32:33], off
	v_mov_b32_e32 v45, v18
	v_pk_fma_f32 v[4:5], v[26:27], v[4:5], v[52:53] op_sel_hi:[0,1,1]
	v_pk_fma_f32 v[8:9], v[26:27], v[8:9], v[62:63] op_sel_hi:[0,1,1]
	v_mov_b32_e32 v10, v75
	v_mov_b32_e32 v18, v79
	v_pk_fma_f32 v[4:5], v[0:1], v[36:37], v[4:5] op_sel_hi:[0,1,1]
	v_pk_fma_f32 v[8:9], v[0:1], v[44:45], v[8:9] op_sel_hi:[0,1,1]
	v_mov_b32_e32 v29, v12
	v_mov_b32_e32 v42, v80
	v_mov_b32_e32 v43, v20
	v_mov_b32_e32 v12, v77
	v_mov_b32_e32 v20, v81
	v_mov_b32_e32 v40, v82
	v_mov_b32_e32 v41, v14
	v_mov_b32_e32 v48, v86
	v_mov_b32_e32 v49, v22
	v_mov_b32_e32 v14, v83
	v_mov_b32_e32 v22, v87
	v_mov_b32_e32 v38, v84
	v_mov_b32_e32 v39, v16
	v_mov_b32_e32 v46, v88
	v_mov_b32_e32 v47, v24
	v_mov_b32_e32 v16, v85
	v_mov_b32_e32 v24, v89
	v_lshl_add_u64 v[32:33], v[32:33], 0, s[94:95]
	s_waitcnt vmcnt(0) lgkmcnt(0)
	v_pk_fma_f32 v[4:5], v[60:61], v[10:11], v[4:5] op_sel_hi:[0,1,1]
	v_pk_fma_f32 v[8:9], v[60:61], v[18:19], v[8:9] op_sel_hi:[0,1,1]
	v_pk_fma_f32 v[4:5], v[58:59], v[28:29], v[4:5] op_sel_hi:[0,1,1]
	v_pk_fma_f32 v[8:9], v[58:59], v[42:43], v[8:9] op_sel_hi:[0,1,1]
	v_pk_fma_f32 v[4:5], v[56:57], v[12:13], v[4:5] op_sel_hi:[0,1,1]
	v_pk_fma_f32 v[8:9], v[56:57], v[20:21], v[8:9] op_sel_hi:[0,1,1]
	v_pk_fma_f32 v[4:5], v[54:55], v[40:41], v[4:5] op_sel_hi:[0,1,1]
	v_pk_fma_f32 v[8:9], v[54:55], v[48:49], v[8:9] op_sel_hi:[0,1,1]
	v_pk_fma_f32 v[4:5], v[50:51], v[14:15], v[4:5] op_sel_hi:[0,1,1]
	v_pk_fma_f32 v[8:9], v[50:51], v[22:23], v[8:9] op_sel_hi:[0,1,1]
	v_pk_fma_f32 v[4:5], v[2:3], v[38:39], v[4:5] op_sel_hi:[0,1,1]
	v_pk_fma_f32 v[2:3], v[2:3], v[46:47], v[8:9] op_sel_hi:[0,1,1]
	v_pk_fma_f32 v[36:37], v[6:7], v[16:17], v[4:5] op_sel_hi:[0,1,1]
	v_pk_fma_f32 v[14:15], v[6:7], v[24:25], v[2:3] op_sel_hi:[0,1,1]
	s_cbranch_scc0 .LBB0_1029
	s_branch .LBB0_1023

; __device__ __forceinline__ void tr_load(const TrDesc& d, int tid, float (&v)[8]) {
;     const int nn = tid & 63, np = d.n0 + nn; int col = np; const float* s = d.src;
;     if (d.mode == 1) { if (np >= 1216) col = -1; else if (np >= 1152) { const int i = np - 1152; col = 1152 + (i >> 1) + 32 * (i & 1); } }
;     else if (d.mode == 2) { const int h = np / 192, dd = np % 192; if (dd >= 128) { const int i = dd - 128; col = 192 * h + 128 + (i >> 1) + 32 * (i & 1); } }
;     else if (d.mode == 3) { col = (np >> 8) * 128 + (np & 127); if ((np >> 7) & 1) s = d.src2; }
; #pragma unroll
;     for (int i = 0; i < 8; ++i) { const int kk = (tid >> 6) + 8 * i; float x = 0.f;
;         if (col >= 0) { x = s[(size_t)(d.k0 + kk) * d.ld_src + col]; if (d.rs) x *= d.rs[d.k0 + kk]; if (d.mode == 2) x *= QSCALE * 8.0f; }
;         v[i] = x; }
; }
.LBB0_1054:
	v_add_u32_e32 v0, 16, v21
	v_mad_i64_i32 v[2:3], s[6:7], s4, v0, 0
	v_add_u32_e32 v0, 24, v21
	v_lshl_add_u64 v[2:3], v[2:3], 2, v[18:19]
	v_mad_i64_i32 v[4:5], s[6:7], s4, v0, 0
	v_lshl_add_u64 v[4:5], v[4:5], 2, v[18:19]
	global_load_dword v12, v[2:3], off
	global_load_dword v0, v[4:5], off
	s_waitcnt vmcnt(0) lgkmcnt(0)
	v_mov_b64_e32 v[2:3], v[10:11]
	v_mov_b64_e32 v[4:5], v[12:13]
	v_mov_b64_e32 v[6:7], v[14:15]
	v_mov_b64_e32 v[8:9], v[16:17]
	v_mov_b32_e32 v5, v0

; __device__ __forceinline__ void tr_load(const TrDesc& d, int tid, float (&v)[8]) {
;     const int nn = tid & 63, np = d.n0 + nn; int col = np; const float* s = d.src;
;     if (d.mode == 1) { if (np >= 1216) col = -1; else if (np >= 1152) { const int i = np - 1152; col = 1152 + (i >> 1) + 32 * (i & 1); } }
;     else if (d.mode == 2) { const int h = np / 192, dd = np % 192; if (dd >= 128) { const int i = dd - 128; col = 192 * h + 128 + (i >> 1) + 32 * (i & 1); } }
;     else if (d.mode == 3) { col = (np >> 8) * 128 + (np & 127); if ((np >> 7) & 1) s = d.src2; }
; #pragma unroll
;     for (int i = 0; i < 8; ++i) { const int kk = (tid >> 6) + 8 * i; float x = 0.f;
;         if (col >= 0) { x = s[(size_t)(d.k0 + kk) * d.ld_src + col]; if (d.rs) x *= d.rs[d.k0 + kk]; if (d.mode == 2) x *= QSCALE * 8.0f; }
;         v[i] = x; }
; }
.LBB0_1058:
	v_add_u32_e32 v0, 32, v21
	s_waitcnt vmcnt(0) lgkmcnt(0)
	v_mad_i64_i32 v[10:11], s[6:7], s4, v0, 0
	v_add_u32_e32 v0, 40, v21
	v_lshl_add_u64 v[10:11], v[10:11], 2, v[18:19]
	v_mad_i64_i32 v[12:13], s[6:7], s4, v0, 0
	v_lshl_add_u64 v[12:13], v[12:13], 2, v[18:19]
	global_load_dword v6, v[10:11], off
	global_load_dword v0, v[12:13], off
	s_waitcnt vmcnt(0) lgkmcnt(0)
	v_mov_b64_e32 v[16:17], v[8:9]
	v_mov_b64_e32 v[14:15], v[6:7]
	v_mov_b64_e32 v[12:13], v[4:5]
	v_mov_b64_e32 v[10:11], v[2:3]
	v_mov_b32_e32 v15, v0

; __device__ __forceinline__ void tr_load(const TrDesc& d, int tid, float (&v)[8]) {
;     const int nn = tid & 63, np = d.n0 + nn; int col = np; const float* s = d.src;
;     if (d.mode == 1) { if (np >= 1216) col = -1; else if (np >= 1152) { const int i = np - 1152; col = 1152 + (i >> 1) + 32 * (i & 1); } }
;     else if (d.mode == 2) { const int h = np / 192, dd = np % 192; if (dd >= 128) { const int i = dd - 128; col = 192 * h + 128 + (i >> 1) + 32 * (i & 1); } }
;     else if (d.mode == 3) { col = (np >> 8) * 128 + (np & 127); if ((np >> 7) & 1) s = d.src2; }
; #pragma unroll
;     for (int i = 0; i < 8; ++i) { const int kk = (tid >> 6) + 8 * i; float x = 0.f;
;         if (col >= 0) { x = s[(size_t)(d.k0 + kk) * d.ld_src + col]; if (d.rs) x *= d.rs[d.k0 + kk]; if (d.mode == 2) x *= QSCALE * 8.0f; }
;         v[i] = x; }
; }
.LBB0_1062:
	v_add_u32_e32 v0, 48, v21
	v_mad_i64_i32 v[2:3], s[6:7], s4, v0, 0
	v_add_u32_e32 v0, 56, v21
	v_lshl_add_u64 v[2:3], v[2:3], 2, v[18:19]
	v_mad_i64_i32 v[4:5], s[4:5], s4, v0, 0
	v_lshl_add_u64 v[4:5], v[4:5], 2, v[18:19]
	global_load_dword v16, v[2:3], off
	global_load_dword v0, v[4:5], off
	s_waitcnt vmcnt(0) lgkmcnt(0)
	v_mov_b64_e32 v[2:3], v[10:11]
	v_mov_b64_e32 v[8:9], v[16:17]
	v_mov_b64_e32 v[4:5], v[12:13]
	v_mov_b64_e32 v[6:7], v[14:15]
	v_mov_b32_e32 v9, v0

; __device__ __forceinline__ void tr_load(const TrDesc& d, int tid, float (&v)[8]) {
;     const int nn = tid & 63, np = d.n0 + nn; int col = np; const float* s = d.src;
;     if (d.mode == 1) { if (np >= 1216) col = -1; else if (np >= 1152) { const int i = np - 1152; col = 1152 + (i >> 1) + 32 * (i & 1); } }
;     else if (d.mode == 2) { const int h = np / 192, dd = np % 192; if (dd >= 128) { const int i = dd - 128; col = 192 * h + 128 + (i >> 1) + 32 * (i & 1); } }
;     else if (d.mode == 3) { col = (np >> 8) * 128 + (np & 127); if ((np >> 7) & 1) s = d.src2; }
; #pragma unroll
;     for (int i = 0; i < 8; ++i) { const int kk = (tid >> 6) + 8 * i; float x = 0.f;
;         if (col >= 0) { x = s[(size_t)(d.k0 + kk) * d.ld_src + col]; if (d.rs) x *= d.rs[d.k0 + kk]; if (d.mode == 2) x *= QSCALE * 8.0f; }
;         v[i] = x; }
; }
.LBB0_1079:
	v_add_u32_e32 v0, 16, v27
	v_mad_i64_i32 v[10:11], s[4:5], s10, v0, 0
	v_add_u32_e32 v0, 24, v27
	v_lshl_add_u64 v[10:11], v[10:11], 2, v[28:29]
	v_mad_i64_i32 v[12:13], s[4:5], s10, v0, 0
	v_lshl_add_u64 v[12:13], v[12:13], 2, v[28:29]
	global_load_dword v4, v[10:11], off
	global_load_dword v0, v[12:13], off
	s_waitcnt vmcnt(0) lgkmcnt(0)
	v_mov_b64_e32 v[24:25], v[8:9]
	v_mov_b64_e32 v[20:21], v[4:5]
	v_mov_b64_e32 v[22:23], v[6:7]
	v_mov_b64_e32 v[18:19], v[2:3]
	v_mov_b32_e32 v21, v0

; __device__ __forceinline__ void tr_load(const TrDesc& d, int tid, float (&v)[8]) {
;     const int nn = tid & 63, np = d.n0 + nn; int col = np; const float* s = d.src;
;     if (d.mode == 1) { if (np >= 1216) col = -1; else if (np >= 1152) { const int i = np - 1152; col = 1152 + (i >> 1) + 32 * (i & 1); } }
;     else if (d.mode == 2) { const int h = np / 192, dd = np % 192; if (dd >= 128) { const int i = dd - 128; col = 192 * h + 128 + (i >> 1) + 32 * (i & 1); } }
;     else if (d.mode == 3) { col = (np >> 8) * 128 + (np & 127); if ((np >> 7) & 1) s = d.src2; }
; #pragma unroll
;     for (int i = 0; i < 8; ++i) { const int kk = (tid >> 6) + 8 * i; float x = 0.f;
;         if (col >= 0) { x = s[(size_t)(d.k0 + kk) * d.ld_src + col]; if (d.rs) x *= d.rs[d.k0 + kk]; if (d.mode == 2) x *= QSCALE * 8.0f; }
;         v[i] = x; }
; }
.LBB0_1083:
	v_add_u32_e32 v0, 32, v27
	s_waitcnt vmcnt(0) lgkmcnt(0)
	v_mad_i64_i32 v[2:3], s[4:5], s10, v0, 0
	v_add_u32_e32 v0, 40, v27
	v_lshl_add_u64 v[2:3], v[2:3], 2, v[28:29]
	v_mad_i64_i32 v[4:5], s[4:5], s10, v0, 0
	v_lshl_add_u64 v[4:5], v[4:5], 2, v[28:29]
	global_load_dword v22, v[2:3], off
	global_load_dword v0, v[4:5], off
	s_waitcnt vmcnt(0) lgkmcnt(0)
	v_mov_b64_e32 v[10:11], v[18:19]
	v_mov_b64_e32 v[14:15], v[22:23]
	v_mov_b64_e32 v[12:13], v[20:21]
	v_mov_b64_e32 v[16:17], v[24:25]
	v_mov_b32_e32 v15, v0

; __device__ __forceinline__ void tr_load(const TrDesc& d, int tid, float (&v)[8]) {
;     const int nn = tid & 63, np = d.n0 + nn; int col = np; const float* s = d.src;
;     if (d.mode == 1) { if (np >= 1216) col = -1; else if (np >= 1152) { const int i = np - 1152; col = 1152 + (i >> 1) + 32 * (i & 1); } }
;     else if (d.mode == 2) { const int h = np / 192, dd = np % 192; if (dd >= 128) { const int i = dd - 128; col = 192 * h + 128 + (i >> 1) + 32 * (i & 1); } }
;     else if (d.mode == 3) { col = (np >> 8) * 128 + (np & 127); if ((np >> 7) & 1) s = d.src2; }
; #pragma unroll
;     for (int i = 0; i < 8; ++i) { const int kk = (tid >> 6) + 8 * i; float x = 0.f;
;         if (col >= 0) { x = s[(size_t)(d.k0 + kk) * d.ld_src + col]; if (d.rs) x *= d.rs[d.k0 + kk]; if (d.mode == 2) x *= QSCALE * 8.0f; }
;         v[i] = x; }
; }
.LBB0_1087:
	v_add_u32_e32 v0, 48, v27
	s_waitcnt vmcnt(0) lgkmcnt(0)
	v_mad_i64_i32 v[2:3], s[4:5], s10, v0, 0
	v_add_u32_e32 v0, 56, v27
	v_lshl_add_u64 v[2:3], v[2:3], 2, v[28:29]
	v_mad_i64_i32 v[4:5], s[4:5], s10, v0, 0
	v_lshl_add_u64 v[4:5], v[4:5], 2, v[28:29]
	global_load_dword v16, v[2:3], off
	global_load_dword v0, v[4:5], off
	s_waitcnt vmcnt(0) lgkmcnt(0)
	v_mov_b64_e32 v[2:3], v[10:11]
	v_mov_b64_e32 v[8:9], v[16:17]
	v_mov_b64_e32 v[4:5], v[12:13]
	v_mov_b64_e32 v[6:7], v[14:15]
	v_mov_b32_e32 v9, v0
	s_branch .LBB0_1064

; __device__ __forceinline__ unsigned xb_ld(unsigned* p)              { return __hip_atomic_load(p, __ATOMIC_RELAXED, __HIP_MEMORY_SCOPE_AGENT); }
; __device__ __forceinline__ void xcd_barrier_complete(unsigned* bar, unsigned x, unsigned& nloc, unsigned& nx) {
;     const unsigned G = gridDim.x * gridDim.y * gridDim.z;
;     unsigned sum, cnt, mine, sp = 0u;
;     for (;;) {
;         sum = 0u; cnt = 0u; mine = 0u;
; #pragma unroll
;         for (unsigned j = 0; j < 16; ++j) { const unsigned c = xb_ld(&bar[XB_XCNT(j)]); sum += c; cnt += (c > 0u) ? 1u : 0u; mine = (j == x) ? c : mine; }
;         if (sum == G) break;
;         __builtin_amdgcn_s_sleep(1);
;         if ((++sp & 255u) == 0u) { if (xb_ld(&bar[XB_TMO])) break; if (sp > XB_SPIN_CAP) { atomicAdd(&bar[XB_TMO], 1u); break; } }
;     }
;     nloc = mine > 0u ? mine : 1u; nx = cnt > 0u ? cnt : 1u;
; }
.LBB0_1096:
	v_mov_b64_e32 v[12:13], s[38:39]
	flat_load_dword v2, v[12:13] offset:1024 sc1
	s_waitcnt lgkmcnt(0)
	global_load_dword v0, v[12:13], off offset:1280 sc1
	global_load_dword v3, v[12:13], off offset:1536 sc1
	v_readlane_b32 s18, v253, 4
	s_or_b64 s[16:17], s[16:17], exec
	s_or_b64 s[14:15], s[14:15], exec
	s_waitcnt vmcnt(0) lgkmcnt(0)
	v_add_u32_e32 v4, v0, v2
	v_add_u32_e32 v5, v4, v3
	global_load_dword v4, v[12:13], off offset:1792 sc1
	s_waitcnt vmcnt(0) lgkmcnt(0)
	v_add_u32_e32 v6, v5, v4
	global_load_dword v5, v[12:13], off offset:2048 sc1
	s_waitcnt vmcnt(0) lgkmcnt(0)
	v_add_u32_e32 v7, v6, v5
	global_load_dword v6, v[12:13], off offset:2304 sc1
	s_waitcnt vmcnt(0) lgkmcnt(0)
	v_add_u32_e32 v8, v7, v6
	global_load_dword v7, v[12:13], off offset:2560 sc1
	s_waitcnt vmcnt(0) lgkmcnt(0)
	v_add_u32_e32 v9, v8, v7
	global_load_dword v8, v[12:13], off offset:2816 sc1
	s_waitcnt vmcnt(0) lgkmcnt(0)
	v_add_u32_e32 v10, v9, v8
	global_load_dword v9, v[12:13], off offset:3072 sc1
	s_waitcnt vmcnt(0) lgkmcnt(0)
	v_add_u32_e32 v11, v10, v9
	global_load_dword v10, v[12:13], off offset:3328 sc1
	s_waitcnt vmcnt(0) lgkmcnt(0)
	v_add_u32_e32 v14, v11, v10
	global_load_dword v11, v[12:13], off offset:3584 sc1
	s_waitcnt vmcnt(0) lgkmcnt(0)
	v_add_u32_e32 v14, v14, v11
	global_load_dword v12, v[12:13], off offset:3840 sc1
	s_waitcnt vmcnt(0) lgkmcnt(0)
	v_add_u32_e32 v16, v14, v12
	v_mov_b64_e32 v[14:15], s[0:1]
	global_load_dword v13, v[14:15], off sc1
	v_mov_b64_e32 v[14:15], s[4:5]
	global_load_dword v14, v[14:15], off sc1
	s_waitcnt vmcnt(0) lgkmcnt(0)
	v_add_u32_e32 v16, v16, v13
	v_add_u32_e32 v18, v16, v14
	v_mov_b64_e32 v[16:17], s[6:7]
	global_load_dword v15, v[16:17], off sc1
	v_mov_b64_e32 v[16:17], s[8:9]
	global_load_dword v16, v[16:17], off sc1
	s_waitcnt vmcnt(0) lgkmcnt(0)
	v_add_u32_e32 v18, v18, v15
	v_add_u32_e32 v17, v18, v16
	v_cmp_ne_u32_e32 vcc, s18, v17
	s_and_saveexec_b64 s[18:19], vcc
	s_cbranch_execz .LBB0_1095
	s_and_b32 s24, s30, 0xff
	s_mov_b64 s[22:23], -1
	s_cmp_eq_u32 s24, 0
	s_mov_b64 s[26:27], -1
	s_mov_b64 s[24:25], -1
	s_sleep 1
	s_cbranch_scc1 .LBB0_1099
	s_and_saveexec_b64 s[28:29], s[26:27]
	s_cbranch_execz .LBB0_1094
	s_branch .LBB0_1102
.LBB0_1099:
	v_mov_b64_e32 v[18:19], s[38:39]
	global_load_dword v17, v[18:19], off offset:512 sc1
	s_mov_b64 s[26:27], 0
	s_waitcnt vmcnt(0) lgkmcnt(0)
	v_cmp_eq_u32_e32 vcc, 0, v17
	s_and_saveexec_b64 s[28:29], vcc
	s_cmp_lt_u32 s30, 0x40001
	s_cselect_b64 s[26:27], -1, 0
	s_xor_b64 s[24:25], exec, -1
	s_and_b64 s[26:27], s[26:27], exec
	s_or_b64 exec, exec, s[28:29]
	s_and_saveexec_b64 s[28:29], s[26:27]
	s_cbranch_execz .LBB0_1094

; __device__ __forceinline__ unsigned xb_ld(unsigned* p)              { return __hip_atomic_load(p, __ATOMIC_RELAXED, __HIP_MEMORY_SCOPE_AGENT); }
; __device__ __forceinline__ unsigned xb_add(unsigned* p, unsigned v) { return __hip_atomic_fetch_add(p, v, __ATOMIC_RELAXED, __HIP_MEMORY_SCOPE_AGENT); }
; #define XB_SPIN(cond, bar) do { unsigned _sp = 0; while (cond) { __builtin_amdgcn_s_sleep(1); \
;     if ((++_sp & 255u) == 0u) { if (xb_ld(&(bar)[XB_TMO])) break; if (_sp > XB_SPIN_CAP) { atomicAdd(&(bar)[XB_TMO], 1u); break; } } } } while (0)
; __device__ __forceinline__ void xcd_barrier(const XcdBarrier& b) {
;     ...
;         const unsigned old = xb_add(&bar[XB_XSUB(b.x)], 1u);
;         const unsigned gen = old / nloc;
;         if (old + 1u == (gen + 1u) * nloc) {
;             __builtin_amdgcn_fence(__ATOMIC_RELEASE, "agent");
;             asm volatile("s_waitcnt vmcnt(0)" ::: "memory");
;             const unsigned og = xb_add(&bar[XB_TOP], 1u);
;             const unsigned tg = og / nx;
;             if (og + 1u == (tg + 1u) * nx) xb_add(&bar[XB_TOPGEN], 1u);
;             else XB_SPIN(xb_ld(&bar[XB_TOPGEN]) == tg, bar);
;             __builtin_amdgcn_fence(__ATOMIC_ACQUIRE, "agent");
;             xb_add(&bar[XB_XGEN(b.x)], 1u);
;             asm volatile("s_waitcnt vmcnt(0)" ::: "memory");
;         } else {
;             XB_SPIN(xb_ld(&bar[XB_XGEN(b.x)]) == gen, bar);
.LBB0_1107:
	s_lshl_b32 s24, s33, 6
	s_add_i32 s88, s24, 0x500
	s_lshl_b64 s[0:1], s[88:89], 2
	s_add_u32 s0, s38, s0
	s_addc_u32 s1, s39, s1
	v_mov_b64_e32 v[4:5], s[0:1]
	flat_atomic_add v4, v[4:5], v230 sc0
	v_cvt_f32_u32_e32 v3, v2
	v_sub_u32_e32 v5, 0, v2
	v_rcp_iflag_f32_e32 v3, v3
	s_nop 0
	v_mul_f32_e32 v3, 0x4f7ffffe, v3
	v_cvt_u32_f32_e32 v3, v3
	v_mul_lo_u32 v5, v5, v3
	v_mul_hi_u32 v5, v3, v5
	v_add_u32_e32 v3, v3, v5
	s_waitcnt vmcnt(0) lgkmcnt(0)
	v_mul_hi_u32 v3, v4, v3
	v_mul_lo_u32 v5, v3, v2
	v_sub_u32_e32 v5, v4, v5
	v_cmp_ge_u32_e32 vcc, v5, v2
	v_add_u32_e32 v6, 1, v3
	s_nop 0
	v_cndmask_b32_e32 v3, v3, v6, vcc
	v_sub_u32_e32 v6, v5, v2
	v_cndmask_b32_e32 v5, v5, v6, vcc
	v_cmp_ge_u32_e32 vcc, v5, v2
	v_add_u32_e32 v5, 1, v3
	v_add_u32_e32 v6, 1, v4
	v_cndmask_b32_e32 v3, v3, v5, vcc
	v_mad_u64_u32 v[4:5], s[0:1], v2, v3, v[2:3]
	v_cmp_ne_u32_e32 vcc, v6, v4
	s_and_saveexec_b64 s[0:1], vcc
	s_xor_b64 s[0:1], exec, s[0:1]
	s_cbranch_execz .LBB0_1120
	s_add_i32 s88, s24, 0x900
	s_lshl_b64 s[4:5], s[88:89], 2
	s_add_u32 s6, s38, s4
	s_addc_u32 s7, s39, s5
	v_mov_b64_e32 v[4:5], s[6:7]
	global_load_dword v0, v[4:5], off sc1
	s_waitcnt vmcnt(0) lgkmcnt(0)
	v_cmp_eq_u32_e32 vcc, v0, v3
	s_and_saveexec_b64 s[4:5], vcc
	s_cbranch_execz .LBB0_1119
	s_mov_b32 s25, 1
	s_mov_b64 s[8:9], 0
	s_branch .LBB0_1111

; __device__ __forceinline__ unsigned xb_ld(unsigned* p)              { return __hip_atomic_load(p, __ATOMIC_RELAXED, __HIP_MEMORY_SCOPE_AGENT); }
; #define XB_SPIN(cond, bar) do { unsigned _sp = 0; while (cond) { __builtin_amdgcn_s_sleep(1); \
;     if ((++_sp & 255u) == 0u) { if (xb_ld(&(bar)[XB_TMO])) break; if (_sp > XB_SPIN_CAP) { atomicAdd(&(bar)[XB_TMO], 1u); break; } } } } while (0)
; __device__ __forceinline__ void xcd_barrier(const XcdBarrier& b) {
;     ...
;             XB_SPIN(xb_ld(&bar[XB_XGEN(b.x)]) == gen, bar);
.LBB0_1111:
	s_and_b32 s16, s25, 0xff
	s_mov_b64 s[14:15], -1
	s_cmp_lg_u32 s16, 0
	s_mov_b64 s[16:17], -1
	s_sleep 1
	s_cbranch_scc1 .LBB0_1115
	v_mov_b64_e32 v[4:5], s[38:39]
	global_load_dword v0, v[4:5], off offset:512 sc1
	s_mov_b64 s[16:17], 0
	s_mov_b64 s[18:19], -1
	s_waitcnt vmcnt(0) lgkmcnt(0)
	v_cmp_eq_u32_e32 vcc, 0, v0
	s_and_saveexec_b64 s[22:23], vcc
	s_cmp_lt_u32 s25, 0x40001
	s_cselect_b64 s[16:17], -1, 0
	s_xor_b64 s[18:19], exec, -1
	s_and_b64 s[16:17], s[16:17], exec
	s_or_b64 exec, exec, s[22:23]
.LBB0_1115:
	s_andn2_b64 s[12:13], s[12:13], exec
	s_and_b64 s[18:19], s[18:19], exec
	s_or_b64 s[12:13], s[12:13], s[18:19]
	s_and_saveexec_b64 s[18:19], s[16:17]
	s_cbranch_execz .LBB0_1110
	v_mov_b64_e32 v[4:5], s[6:7]
	global_load_dword v0, v[4:5], off sc1
	s_add_i32 s25, s25, 1
	s_or_b64 s[12:13], s[12:13], exec
	s_waitcnt vmcnt(0) lgkmcnt(0)
	v_cmp_ne_u32_e32 vcc, v0, v3
	s_orn2_b64 s[14:15], vcc, exec
	s_branch .LBB0_1110

; __device__ __forceinline__ unsigned xb_ld(unsigned* p)              { return __hip_atomic_load(p, __ATOMIC_RELAXED, __HIP_MEMORY_SCOPE_AGENT); }
; __device__ __forceinline__ unsigned xb_add(unsigned* p, unsigned v) { return __hip_atomic_fetch_add(p, v, __ATOMIC_RELAXED, __HIP_MEMORY_SCOPE_AGENT); }
; #define XB_SPIN(cond, bar) do { unsigned _sp = 0; while (cond) { __builtin_amdgcn_s_sleep(1); \
;     if ((++_sp & 255u) == 0u) { if (xb_ld(&(bar)[XB_TMO])) break; if (_sp > XB_SPIN_CAP) { atomicAdd(&(bar)[XB_TMO], 1u); break; } } } } while (0)
; __device__ __forceinline__ void xcd_barrier(const XcdBarrier& b) {
;     ...
;         if (old + 1u == (gen + 1u) * nloc) {
;             __builtin_amdgcn_fence(__ATOMIC_RELEASE, "agent");
;             asm volatile("s_waitcnt vmcnt(0)" ::: "memory");
;             const unsigned og = xb_add(&bar[XB_TOP], 1u);
;             const unsigned tg = og / nx;
;             if (og + 1u == (tg + 1u) * nx) xb_add(&bar[XB_TOPGEN], 1u);
;             else XB_SPIN(xb_ld(&bar[XB_TOPGEN]) == tg, bar);
.LBB0_1120:
	s_andn2_saveexec_b64 s[0:1], s[0:1]
	s_cbranch_execz .LBB0_1136
	v_mov_b32_e32 v2, s38
	v_add_co_u32_e32 v2, vcc, 0x3000, v2
	v_mov_b32_e32 v3, s39
	buffer_wbl2 sc1
	s_waitcnt vmcnt(0)
	v_addc_co_u32_e32 v3, vcc, 0, v3, vcc
	flat_atomic_add v2, v[2:3], v230 offset:1024 sc0
	v_cvt_f32_u32_e32 v3, v0
	v_sub_u32_e32 v4, 0, v0
	s_mov_b64 s[6:7], -1
	v_rcp_iflag_f32_e32 v3, v3
	s_nop 0
	v_mul_f32_e32 v3, 0x4f7ffffe, v3
	v_cvt_u32_f32_e32 v3, v3
	v_mul_lo_u32 v4, v4, v3
	v_mul_hi_u32 v4, v3, v4
	v_add_u32_e32 v3, v3, v4
	s_waitcnt vmcnt(0) lgkmcnt(0)
	v_mul_hi_u32 v3, v2, v3
	v_mul_lo_u32 v4, v3, v0
	v_sub_u32_e32 v4, v2, v4
	v_cmp_ge_u32_e32 vcc, v4, v0
	v_add_u32_e32 v5, 1, v3
	s_nop 0
	v_cndmask_b32_e32 v3, v3, v5, vcc
	v_sub_u32_e32 v5, v4, v0
	v_cndmask_b32_e32 v4, v4, v5, vcc
	v_cmp_ge_u32_e32 vcc, v4, v0
	v_add_u32_e32 v4, 1, v3
	v_add_u32_e32 v5, 1, v2
	v_cndmask_b32_e32 v4, v3, v4, vcc
	v_mad_u64_u32 v[2:3], s[0:1], v0, v4, v[0:1]
	s_add_u32 s0, s38, 0x3500
	s_addc_u32 s1, s39, 0
	v_cmp_ne_u32_e32 vcc, v5, v2
	v_mov_b64_e32 v[2:3], s[0:1]
	s_and_saveexec_b64 s[4:5], vcc
	s_cbranch_execz .LBB0_1133
	v_mov_b64_e32 v[2:3], s[0:1]
	global_load_dword v0, v[2:3], off sc1
	s_mov_b64 s[10:11], 0
	s_waitcnt vmcnt(0) lgkmcnt(0)
	v_cmp_eq_u32_e32 vcc, v0, v4
	s_and_saveexec_b64 s[8:9], vcc
	s_cbranch_execz .LBB0_1132
	s_add_u32 s6, s38, 0x200
	s_addc_u32 s7, s39, 0
	s_mov_b32 s25, 1
	s_branch .LBB0_1125

; __device__ __forceinline__ unsigned xb_ld(unsigned* p)              { return __hip_atomic_load(p, __ATOMIC_RELAXED, __HIP_MEMORY_SCOPE_AGENT); }
; #define XB_SPIN(cond, bar) do { unsigned _sp = 0; while (cond) { __builtin_amdgcn_s_sleep(1); \
;     if ((++_sp & 255u) == 0u) { if (xb_ld(&(bar)[XB_TMO])) break; if (_sp > XB_SPIN_CAP) { atomicAdd(&(bar)[XB_TMO], 1u); break; } } } } while (0)
; __device__ __forceinline__ void xcd_barrier(const XcdBarrier& b) {
;     ...
;             else XB_SPIN(xb_ld(&bar[XB_TOPGEN]) == tg, bar);
.LBB0_1127:
	v_mov_b64_e32 v[2:3], s[6:7]
	global_load_dword v0, v[2:3], off sc1
	s_mov_b64 s[18:19], 0
	s_mov_b64 s[16:17], -1
	s_waitcnt vmcnt(0) lgkmcnt(0)
	v_cmp_eq_u32_e32 vcc, 0, v0
	s_and_saveexec_b64 s[22:23], vcc
	s_cmp_lt_u32 s25, 0x40001
	s_cselect_b64 s[18:19], -1, 0
	s_xor_b64 s[16:17], exec, -1
	s_and_b64 s[18:19], s[18:19], exec
	s_or_b64 exec, exec, s[22:23]
	s_and_saveexec_b64 s[22:23], s[18:19]
	s_cbranch_execz .LBB0_1124
.LBB0_1130:
	v_mov_b64_e32 v[2:3], s[0:1]
	global_load_dword v0, v[2:3], off sc1
	s_add_i32 s25, s25, 1
	s_or_b64 s[16:17], s[16:17], exec
	s_waitcnt vmcnt(0) lgkmcnt(0)
	v_cmp_ne_u32_e32 vcc, v0, v4
	s_orn2_b64 s[14:15], vcc, exec
	s_branch .LBB0_1124
